# combined: P8+P12 sample piece first, first barrier non-blocking for conversion workgroups, duplicate lgkmcnt waits removed from the K loops
# speedup vs baseline: 1.0036x; 1.0036x over previous
; #define PG8_STAGE(bufoff, gbase, voff) do { _Pragma("unroll") for (int _i = 0; _i < 2; ++_i) \
;         __builtin_amdgcn_global_load_lds((const unsigned*)((const char*)(gbase) + (voff)[_i]), (LAS unsigned*)(lds + (bufoff) + ldsw + _i * 8192), 16, 0, 0); } while (0)
; #define PG8_LDA(dst, b, h) do { _Pragma("unroll") for (int m = 0; m < 4; ++m) _Pragma("unroll") for (int k = 0; k < 2; ++k) dst[m][k] = *(const LAS bf16x8*)(lds + PG8_SA(b, h) + aoff + m * 2048 + k * 1024); } while (0)
; #define PG8_LDB(dst, b, h) do { _Pragma("unroll") for (int n = 0; n < 2; ++n) _Pragma("unroll") for (int k = 0; k < 2; ++k) dst[n][k] = *(const LAS bf16x8*)(lds + PG8_SB(b, h) + boff + n * 2048 + k * 1024); } while (0)
; #define PG8_MMA(ai, bj, At, Bt) do { __builtin_amdgcn_s_setprio(1); _Pragma("unroll") for (int m = 0; m < 4; ++m) _Pragma("unroll") for (int n = 0; n < 2; ++n) _Pragma("unroll") for (int k = 0; k < 2; ++k) \
;         acc[ai][bj][m][n] = __builtin_amdgcn_mfma_f32_16x16x32_bf16(Bt[n][k], At[m][k], acc[ai][bj][m][n], 0, 0, 0); __builtin_amdgcn_s_setprio(0); } while (0)
; #define PG8_WAIT_V(n) asm volatile("s_waitcnt vmcnt(" #n ")" ::: "memory")
; #define PG8_WAIT_L(n) asm volatile("s_waitcnt lgkmcnt(" #n ")" ::: "memory")
; #define PG8_BAR __builtin_amdgcn_s_barrier()
; #define PG8_SCHED __builtin_amdgcn_sched_barrier(0)
; template <class Epi, class S_t>
; __device__ __forceinline__ void gemm_phase(LAS unsigned char* lds, int lda, int ldb, const S_t& S, const Epi& E) {
;     ...
;             PG8_LDB(B0, 0, 0); PG8_SCHED; PG8_LDA(At, 0, 0); PG8_STAGE(PG8_SA(1, 1), a1 + hstepA, voffA);
;             PG8_WAIT_L(8); PG8_BAR; PG8_WAIT_L(0); PG8_MMA(0, 0, At, B0); PG8_BAR; PG8_SCHED;
;             PG8_LDB(B1, 0, 1); PG8_STAGE(PG8_SB(0, 0), b2, voffB);
;             PG8_BAR; PG8_WAIT_L(0); PG8_MMA(0, 1, At, B1); PG8_BAR;
;             PG8_LDA(At, 0, 1); PG8_STAGE(PG8_SA(0, 0), a2, voffA);
;             PG8_BAR; PG8_WAIT_L(0); PG8_MMA(1, 0, At, B0); PG8_BAR; PG8_SCHED;
;             PG8_STAGE(PG8_SB(0, 1), b2 + hstepB, voffB);
;             PG8_WAIT_V(6); PG8_BAR; PG8_MMA(1, 1, At, B1); PG8_BAR;
.LBB0_133:
	ds_read_b128 v[152:155], v175
	ds_read_b128 v[156:159], v175 offset:1024
	ds_read_b128 v[160:163], v175 offset:2048
	ds_read_b128 v[164:167], v175 offset:3072
	s_add_u32 s18, s16, 0xfff80080
	s_addc_u32 s19, s17, -1
	s_cmp_eq_u32 s9, 28
	s_cselect_b32 s21, s11, s19
	s_cselect_b32 s20, s10, s18
	s_cselect_b32 s19, s13, s1
	s_cselect_b32 s18, s12, s0
	s_add_i32 m0, s53, 0xc000
	ds_read_b128 v[186:189], v178
	ds_read_b128 v[190:193], v178 offset:1024
	ds_read_b128 v[194:197], v178 offset:2048
	ds_read_b128 v[198:201], v178 offset:3072
	ds_read_b128 v[202:205], v178 offset:4096
	ds_read_b128 v[206:209], v178 offset:5120
	ds_read_b128 v[214:217], v178 offset:6144
	ds_read_b128 v[218:221], v178 offset:7168
	global_load_lds_dwordx4 v148, s[16:17]
	s_add_i32 m0, s53, 0xe000
	s_nop 0
	global_load_lds_dwordx4 v150, s[16:17]
	s_waitcnt lgkmcnt(8)
	s_barrier
	s_waitcnt lgkmcnt(0)
	s_setprio 1
	v_mfma_f32_16x16x32_bf16 v[124:127], v[152:155], v[186:189], v[124:127]
	v_mfma_f32_16x16x32_bf16 v[92:95], v[160:163], v[186:189], v[92:95]
	v_mfma_f32_16x16x32_bf16 v[120:123], v[152:155], v[194:197], v[120:123]
	v_mfma_f32_16x16x32_bf16 v[88:91], v[160:163], v[194:197], v[88:91]
	v_mfma_f32_16x16x32_bf16 v[116:119], v[152:155], v[202:205], v[116:119]
	v_mfma_f32_16x16x32_bf16 v[84:87], v[160:163], v[202:205], v[84:87]
	v_mfma_f32_16x16x32_bf16 v[112:115], v[152:155], v[214:217], v[112:115]
	v_mfma_f32_16x16x32_bf16 v[80:83], v[160:163], v[214:217], v[80:83]
	v_mfma_f32_16x16x32_bf16 v[124:127], v[156:159], v[190:193], v[124:127]
	v_mfma_f32_16x16x32_bf16 v[92:95], v[164:167], v[190:193], v[92:95]
	v_mfma_f32_16x16x32_bf16 v[120:123], v[156:159], v[198:201], v[120:123]
	v_mfma_f32_16x16x32_bf16 v[88:91], v[164:167], v[198:201], v[88:91]
	v_mfma_f32_16x16x32_bf16 v[116:119], v[156:159], v[206:209], v[116:119]
	v_mfma_f32_16x16x32_bf16 v[84:87], v[164:167], v[206:209], v[84:87]
	v_mfma_f32_16x16x32_bf16 v[112:115], v[156:159], v[218:221], v[112:115]
	v_mfma_f32_16x16x32_bf16 v[80:83], v[164:167], v[218:221], v[80:83]
	s_setprio 0
	s_barrier
	s_add_i32 s33, s62, s43
	s_add_u32 s98, s18, s6
	s_addc_u32 s99, s19, s7
	s_mov_b32 m0, s33
	ds_read_b128 v[222:225], v179
	ds_read_b128 v[226:229], v179 offset:1024
	ds_read_b128 v[230:233], v179 offset:2048
	ds_read_b128 v[234:237], v179 offset:3072
	global_load_lds_dwordx4 v128, s[18:19]
	s_add_i32 m0, s33, 0x2000
	s_nop 0
	global_load_lds_dwordx4 v130, s[18:19]
	s_barrier
	s_waitcnt lgkmcnt(0)
	s_setprio 1
	v_mfma_f32_16x16x32_bf16 v[60:63], v[222:225], v[186:189], v[60:63]
	v_mfma_f32_16x16x32_bf16 v[28:31], v[230:233], v[186:189], v[28:31]
	v_mfma_f32_16x16x32_bf16 v[56:59], v[222:225], v[194:197], v[56:59]
	v_mfma_f32_16x16x32_bf16 v[24:27], v[230:233], v[194:197], v[24:27]
	v_mfma_f32_16x16x32_bf16 v[52:55], v[222:225], v[202:205], v[52:55]
	v_mfma_f32_16x16x32_bf16 v[20:23], v[230:233], v[202:205], v[20:23]
	v_mfma_f32_16x16x32_bf16 v[48:51], v[222:225], v[214:217], v[48:51]
	v_mfma_f32_16x16x32_bf16 v[16:19], v[230:233], v[214:217], v[16:19]
	v_mfma_f32_16x16x32_bf16 v[60:63], v[226:229], v[190:193], v[60:63]
	v_mfma_f32_16x16x32_bf16 v[28:31], v[234:237], v[190:193], v[28:31]
	v_mfma_f32_16x16x32_bf16 v[56:59], v[226:229], v[198:201], v[56:59]
	v_mfma_f32_16x16x32_bf16 v[24:27], v[234:237], v[198:201], v[24:27]
	v_mfma_f32_16x16x32_bf16 v[52:55], v[226:229], v[206:209], v[52:55]
	v_mfma_f32_16x16x32_bf16 v[20:23], v[234:237], v[206:209], v[20:23]
	v_mfma_f32_16x16x32_bf16 v[48:51], v[226:229], v[218:221], v[48:51]
	v_mfma_f32_16x16x32_bf16 v[16:19], v[234:237], v[218:221], v[16:19]
	s_setprio 0
	s_mov_b32 m0, s53
	s_add_u32 s100, s20, s6
	s_addc_u32 s101, s21, s7
	s_barrier
	ds_read_b128 v[186:189], v178 offset:16384
	ds_read_b128 v[190:193], v178 offset:17408
	ds_read_b128 v[194:197], v178 offset:18432
	ds_read_b128 v[198:201], v178 offset:19456
	ds_read_b128 v[202:205], v178 offset:20480
	ds_read_b128 v[206:209], v178 offset:21504
	ds_read_b128 v[214:217], v178 offset:22528
	ds_read_b128 v[218:221], v178 offset:23552
	global_load_lds_dwordx4 v128, s[20:21]
	s_mov_b32 m0, s54
	s_nop 0
	global_load_lds_dwordx4 v130, s[20:21]
	s_barrier
	s_waitcnt lgkmcnt(0)
	s_setprio 1
	v_mfma_f32_16x16x32_bf16 v[108:111], v[152:155], v[186:189], v[108:111]
	v_mfma_f32_16x16x32_bf16 v[76:79], v[160:163], v[186:189], v[76:79]
	v_mfma_f32_16x16x32_bf16 v[104:107], v[152:155], v[194:197], v[104:107]
	v_mfma_f32_16x16x32_bf16 v[72:75], v[160:163], v[194:197], v[72:75]
	v_mfma_f32_16x16x32_bf16 v[100:103], v[152:155], v[202:205], v[100:103]
	v_mfma_f32_16x16x32_bf16 v[68:71], v[160:163], v[202:205], v[68:71]
	v_mfma_f32_16x16x32_bf16 v[96:99], v[152:155], v[214:217], v[96:99]
	v_mfma_f32_16x16x32_bf16 v[64:67], v[160:163], v[214:217], v[64:67]
	v_mfma_f32_16x16x32_bf16 v[108:111], v[156:159], v[190:193], v[108:111]
	v_mfma_f32_16x16x32_bf16 v[76:79], v[164:167], v[190:193], v[76:79]
	v_mfma_f32_16x16x32_bf16 v[104:107], v[156:159], v[198:201], v[104:107]
	v_mfma_f32_16x16x32_bf16 v[72:75], v[164:167], v[198:201], v[72:75]
	v_mfma_f32_16x16x32_bf16 v[100:103], v[156:159], v[206:209], v[100:103]
	v_mfma_f32_16x16x32_bf16 v[68:71], v[164:167], v[206:209], v[68:71]
	v_mfma_f32_16x16x32_bf16 v[96:99], v[156:159], v[218:221], v[96:99]
	v_mfma_f32_16x16x32_bf16 v[64:67], v[164:167], v[218:221], v[64:67]
	s_setprio 0
	s_barrier
	s_add_u32 s66, s18, 0x80000
	s_addc_u32 s67, s19, 0
	s_add_i32 s33, s63, s43
	s_mov_b32 m0, s33
	s_nop 0
	global_load_lds_dwordx4 v128, s[66:67]
	s_add_i32 m0, s33, 0x2000
	s_nop 0
	global_load_lds_dwordx4 v130, s[66:67]
	s_waitcnt vmcnt(6)
	s_barrier
; #define PG8_STAGE(bufoff, gbase, voff) do { _Pragma("unroll") for (int _i = 0; _i < 2; ++_i) \
;         __builtin_amdgcn_global_load_lds((const unsigned*)((const char*)(gbase) + (voff)[_i]), (LAS unsigned*)(lds + (bufoff) + ldsw + _i * 8192), 16, 0, 0); } while (0)
; #define PG8_LDA(dst, b, h) do { _Pragma("unroll") for (int m = 0; m < 4; ++m) _Pragma("unroll") for (int k = 0; k < 2; ++k) dst[m][k] = *(const LAS bf16x8*)(lds + PG8_SA(b, h) + aoff + m * 2048 + k * 1024); } while (0)
; #define PG8_LDB(dst, b, h) do { _Pragma("unroll") for (int n = 0; n < 2; ++n) _Pragma("unroll") for (int k = 0; k < 2; ++k) dst[n][k] = *(const LAS bf16x8*)(lds + PG8_SB(b, h) + boff + n * 2048 + k * 1024); } while (0)
; #define PG8_MMA(ai, bj, At, Bt) do { __builtin_amdgcn_s_setprio(1); _Pragma("unroll") for (int m = 0; m < 4; ++m) _Pragma("unroll") for (int n = 0; n < 2; ++n) _Pragma("unroll") for (int k = 0; k < 2; ++k) \
;         acc[ai][bj][m][n] = __builtin_amdgcn_mfma_f32_16x16x32_bf16(Bt[n][k], At[m][k], acc[ai][bj][m][n], 0, 0, 0); __builtin_amdgcn_s_setprio(0); } while (0)
; #define PG8_WAIT_V(n) asm volatile("s_waitcnt vmcnt(" #n ")" ::: "memory")
; #define PG8_WAIT_L(n) asm volatile("s_waitcnt lgkmcnt(" #n ")" ::: "memory")
; #define PG8_BAR __builtin_amdgcn_s_barrier()
; #define PG8_SCHED __builtin_amdgcn_sched_barrier(0)
; template <class Epi, class S_t>
; __device__ __forceinline__ void gemm_phase(LAS unsigned char* lds, int lda, int ldb, const S_t& S, const Epi& E) {
;     ...
;             PG8_WAIT_V(6); PG8_BAR; PG8_MMA(1, 1, At, B1); PG8_BAR;
;             PG8_LDB(B0, 1, 0); PG8_SCHED; PG8_LDA(At, 1, 0); PG8_STAGE(PG8_SA(0, 1), a2 + hstepA, voffA);
;             PG8_WAIT_L(8); PG8_BAR; PG8_WAIT_L(0); PG8_MMA(0, 0, At, B0); PG8_BAR; PG8_SCHED;
;             PG8_LDB(B1, 1, 1); PG8_STAGE(PG8_SB(1, 0), b3, voffB);
;             PG8_BAR; PG8_WAIT_L(0); PG8_MMA(0, 1, At, B1); PG8_BAR;
;             PG8_LDA(At, 1, 1); PG8_STAGE(PG8_SA(1, 0), a3, voffA);
;             PG8_BAR; PG8_WAIT_L(0); PG8_MMA(1, 0, At, B0); PG8_BAR; PG8_SCHED;
	s_setprio 1
	v_mfma_f32_16x16x32_bf16 v[44:47], v[222:225], v[186:189], v[44:47]
	v_mfma_f32_16x16x32_bf16 v[12:15], v[230:233], v[186:189], v[12:15]
	v_mfma_f32_16x16x32_bf16 v[40:43], v[222:225], v[194:197], v[40:43]
	v_mfma_f32_16x16x32_bf16 v[8:11], v[230:233], v[194:197], v[8:11]
	v_mfma_f32_16x16x32_bf16 v[36:39], v[222:225], v[202:205], v[36:39]
	v_mfma_f32_16x16x32_bf16 v[4:7], v[230:233], v[202:205], v[4:7]
	v_mfma_f32_16x16x32_bf16 v[32:35], v[222:225], v[214:217], v[32:35]
	v_mfma_f32_16x16x32_bf16 v[0:3], v[230:233], v[214:217], v[0:3]
	v_mfma_f32_16x16x32_bf16 v[44:47], v[226:229], v[190:193], v[44:47]
	v_mfma_f32_16x16x32_bf16 v[12:15], v[234:237], v[190:193], v[12:15]
	v_mfma_f32_16x16x32_bf16 v[40:43], v[226:229], v[198:201], v[40:43]
	v_mfma_f32_16x16x32_bf16 v[8:11], v[234:237], v[198:201], v[8:11]
	v_mfma_f32_16x16x32_bf16 v[36:39], v[226:229], v[206:209], v[36:39]
	v_mfma_f32_16x16x32_bf16 v[4:7], v[234:237], v[206:209], v[4:7]
	v_mfma_f32_16x16x32_bf16 v[32:35], v[226:229], v[218:221], v[32:35]
	v_mfma_f32_16x16x32_bf16 v[0:3], v[234:237], v[218:221], v[0:3]
	s_setprio 0
	s_add_i32 s33, 0, 0x18000
	v_add_u32_e32 v164, s33, v171
	s_barrier
	ds_read_b128 v[152:155], v164
	ds_read_b128 v[156:159], v164 offset:1024
	ds_read_b128 v[160:163], v164 offset:2048
	ds_read_b128 v[164:167], v164 offset:3072
	s_add_u32 s20, s20, 0x80000
	s_addc_u32 s21, s21, 0
	s_mov_b32 m0, s55
	ds_read_b128 v[186:189], v178 offset:32768
	ds_read_b128 v[190:193], v178 offset:33792
	ds_read_b128 v[194:197], v178 offset:34816
	ds_read_b128 v[198:201], v178 offset:35840
	ds_read_b128 v[202:205], v178 offset:36864
	ds_read_b128 v[206:209], v178 offset:37888
	ds_read_b128 v[214:217], v178 offset:38912
	ds_read_b128 v[218:221], v178 offset:39936
	global_load_lds_dwordx4 v128, s[20:21]
	s_mov_b32 m0, s56
	s_nop 0
	global_load_lds_dwordx4 v130, s[20:21]
	s_waitcnt lgkmcnt(8)
	s_barrier
	s_waitcnt lgkmcnt(0)
	s_setprio 1
	v_mfma_f32_16x16x32_bf16 v[124:127], v[152:155], v[186:189], v[124:127]
	v_mfma_f32_16x16x32_bf16 v[92:95], v[160:163], v[186:189], v[92:95]
	v_mfma_f32_16x16x32_bf16 v[120:123], v[152:155], v[194:197], v[120:123]
	v_mfma_f32_16x16x32_bf16 v[88:91], v[160:163], v[194:197], v[88:91]
	v_mfma_f32_16x16x32_bf16 v[116:119], v[152:155], v[202:205], v[116:119]
	v_mfma_f32_16x16x32_bf16 v[84:87], v[160:163], v[202:205], v[84:87]
	v_mfma_f32_16x16x32_bf16 v[112:115], v[152:155], v[214:217], v[112:115]
	v_mfma_f32_16x16x32_bf16 v[80:83], v[160:163], v[214:217], v[80:83]
	v_mfma_f32_16x16x32_bf16 v[124:127], v[156:159], v[190:193], v[124:127]
	v_mfma_f32_16x16x32_bf16 v[92:95], v[164:167], v[190:193], v[92:95]
	v_mfma_f32_16x16x32_bf16 v[120:123], v[156:159], v[198:201], v[120:123]
	v_mfma_f32_16x16x32_bf16 v[88:91], v[164:167], v[198:201], v[88:91]
	v_mfma_f32_16x16x32_bf16 v[116:119], v[156:159], v[206:209], v[116:119]
	v_mfma_f32_16x16x32_bf16 v[84:87], v[164:167], v[206:209], v[84:87]
	v_mfma_f32_16x16x32_bf16 v[112:115], v[156:159], v[218:221], v[112:115]
	v_mfma_f32_16x16x32_bf16 v[80:83], v[164:167], v[218:221], v[80:83]
	s_setprio 0
	s_barrier
	s_add_i32 s20, 0, 0x1c000
	s_add_i32 s21, s33, s43
	v_add_u32_e32 v170, s20, v171
	s_mov_b32 m0, s21
	ds_read_b128 v[222:225], v170
	ds_read_b128 v[226:229], v170 offset:1024
	ds_read_b128 v[230:233], v170 offset:2048
	ds_read_b128 v[234:237], v170 offset:3072
	global_load_lds_dwordx4 v128, s[98:99]
	s_add_i32 m0, s21, 0x2000
	s_nop 0
	global_load_lds_dwordx4 v130, s[98:99]
	s_barrier
	s_waitcnt lgkmcnt(0)
	s_setprio 1
	v_mfma_f32_16x16x32_bf16 v[60:63], v[222:225], v[186:189], v[60:63]
	v_mfma_f32_16x16x32_bf16 v[28:31], v[230:233], v[186:189], v[28:31]
	v_mfma_f32_16x16x32_bf16 v[56:59], v[222:225], v[194:197], v[56:59]
	v_mfma_f32_16x16x32_bf16 v[24:27], v[230:233], v[194:197], v[24:27]
	v_mfma_f32_16x16x32_bf16 v[52:55], v[222:225], v[202:205], v[52:55]
	v_mfma_f32_16x16x32_bf16 v[20:23], v[230:233], v[202:205], v[20:23]
	v_mfma_f32_16x16x32_bf16 v[48:51], v[222:225], v[214:217], v[48:51]
	v_mfma_f32_16x16x32_bf16 v[16:19], v[230:233], v[214:217], v[16:19]
	v_mfma_f32_16x16x32_bf16 v[60:63], v[226:229], v[190:193], v[60:63]
	v_mfma_f32_16x16x32_bf16 v[28:31], v[234:237], v[190:193], v[28:31]
	v_mfma_f32_16x16x32_bf16 v[56:59], v[226:229], v[198:201], v[56:59]
	v_mfma_f32_16x16x32_bf16 v[24:27], v[234:237], v[198:201], v[24:27]
	v_mfma_f32_16x16x32_bf16 v[52:55], v[226:229], v[206:209], v[52:55]
	v_mfma_f32_16x16x32_bf16 v[20:23], v[234:237], v[206:209], v[20:23]
	v_mfma_f32_16x16x32_bf16 v[48:51], v[226:229], v[218:221], v[48:51]
	v_mfma_f32_16x16x32_bf16 v[16:19], v[234:237], v[218:221], v[16:19]
	s_setprio 0
	s_mov_b32 m0, s58
	s_barrier
; #define PG8_STAGE(bufoff, gbase, voff) do { _Pragma("unroll") for (int _i = 0; _i < 2; ++_i) \
;         __builtin_amdgcn_global_load_lds((const unsigned*)((const char*)(gbase) + (voff)[_i]), (LAS unsigned*)(lds + (bufoff) + ldsw + _i * 8192), 16, 0, 0); } while (0)
; #define PG8_LDA(dst, b, h) do { _Pragma("unroll") for (int m = 0; m < 4; ++m) _Pragma("unroll") for (int k = 0; k < 2; ++k) dst[m][k] = *(const LAS bf16x8*)(lds + PG8_SA(b, h) + aoff + m * 2048 + k * 1024); } while (0)
; #define PG8_MMA(ai, bj, At, Bt) do { __builtin_amdgcn_s_setprio(1); _Pragma("unroll") for (int m = 0; m < 4; ++m) _Pragma("unroll") for (int n = 0; n < 2; ++n) _Pragma("unroll") for (int k = 0; k < 2; ++k) \
;         acc[ai][bj][m][n] = __builtin_amdgcn_mfma_f32_16x16x32_bf16(Bt[n][k], At[m][k], acc[ai][bj][m][n], 0, 0, 0); __builtin_amdgcn_s_setprio(0); } while (0)
; #define PG8_WAIT_V(n) asm volatile("s_waitcnt vmcnt(" #n ")" ::: "memory")
; #define PG8_WAIT_L(n) asm volatile("s_waitcnt lgkmcnt(" #n ")" ::: "memory")
; #define PG8_BAR __builtin_amdgcn_s_barrier()
; #define PG8_SCHED __builtin_amdgcn_sched_barrier(0)
; template <class Epi, class S_t>
; __device__ __forceinline__ void gemm_phase(LAS unsigned char* lds, int lda, int ldb, const S_t& S, const Epi& E) {
;     ...
;             PG8_BAR; PG8_WAIT_L(0); PG8_MMA(0, 1, At, B1); PG8_BAR;
;             PG8_LDA(At, 1, 1); PG8_STAGE(PG8_SA(1, 0), a3, voffA);
;             PG8_BAR; PG8_WAIT_L(0); PG8_MMA(1, 0, At, B0); PG8_BAR; PG8_SCHED;
;             PG8_STAGE(PG8_SB(1, 1), b3 + hstepB, voffB);
;             PG8_WAIT_V(6); PG8_BAR; PG8_MMA(1, 1, At, B1); PG8_BAR;
;     __device__ __forceinline__ void operator()(const f32x4 (&acc)[2][2][4][2], const Unit& u, int wr, int wc, int fr, int fq) const {
;         const int row0 = wr * 64 + fr, col0 = u.pn * BM + wc * 32 + 4 * fq, kind = u.pn >> 3;
;         const float* gm = kind == 2 ? g2 : kind == 4 ? g4 : kind == 5 ? g5 : g1;
;         const float one = (kind == 1 || kind == 4) ? 1.0f : 0.0f, gs = (kind == 0 || kind == 3) ? 0.0f : 1.0f;
	ds_read_b128 v[186:189], v178 offset:49152
	ds_read_b128 v[190:193], v178 offset:50176
	ds_read_b128 v[194:197], v178 offset:51200
	ds_read_b128 v[198:201], v178 offset:52224
	ds_read_b128 v[202:205], v178 offset:53248
	ds_read_b128 v[206:209], v178 offset:54272
	ds_read_b128 v[214:217], v178 offset:55296
	ds_read_b128 v[218:221], v178 offset:56320
	global_load_lds_dwordx4 v128, s[100:101]
	s_mov_b32 m0, s59
	s_nop 0
	global_load_lds_dwordx4 v130, s[100:101]
	s_barrier
	s_waitcnt lgkmcnt(0)
	s_setprio 1
	v_mfma_f32_16x16x32_bf16 v[108:111], v[152:155], v[186:189], v[108:111]
	v_mfma_f32_16x16x32_bf16 v[76:79], v[160:163], v[186:189], v[76:79]
	v_mfma_f32_16x16x32_bf16 v[104:107], v[152:155], v[194:197], v[104:107]
	v_mfma_f32_16x16x32_bf16 v[72:75], v[160:163], v[194:197], v[72:75]
	v_mfma_f32_16x16x32_bf16 v[100:103], v[152:155], v[202:205], v[100:103]
	v_mfma_f32_16x16x32_bf16 v[68:71], v[160:163], v[202:205], v[68:71]
	v_mfma_f32_16x16x32_bf16 v[96:99], v[152:155], v[214:217], v[96:99]
	v_mfma_f32_16x16x32_bf16 v[64:67], v[160:163], v[214:217], v[64:67]
	v_mfma_f32_16x16x32_bf16 v[108:111], v[156:159], v[190:193], v[108:111]
	v_mfma_f32_16x16x32_bf16 v[76:79], v[164:167], v[190:193], v[76:79]
	v_mfma_f32_16x16x32_bf16 v[104:107], v[156:159], v[198:201], v[104:107]
	v_mfma_f32_16x16x32_bf16 v[72:75], v[164:167], v[198:201], v[72:75]
	v_mfma_f32_16x16x32_bf16 v[100:103], v[156:159], v[206:209], v[100:103]
	v_mfma_f32_16x16x32_bf16 v[68:71], v[164:167], v[206:209], v[68:71]
	v_mfma_f32_16x16x32_bf16 v[96:99], v[156:159], v[218:221], v[96:99]
	v_mfma_f32_16x16x32_bf16 v[64:67], v[164:167], v[218:221], v[64:67]
	s_setprio 0
	s_barrier
	s_add_u32 s18, s18, 0x80080
	s_addc_u32 s19, s19, 0
	s_add_i32 s20, s20, s43
	s_mov_b32 m0, s20
	s_nop 0
	global_load_lds_dwordx4 v128, s[18:19]
	s_add_i32 m0, s20, 0x2000
	s_nop 0
	global_load_lds_dwordx4 v130, s[18:19]
	s_waitcnt vmcnt(6)
	s_barrier
	s_setprio 1
	v_mfma_f32_16x16x32_bf16 v[44:47], v[222:225], v[186:189], v[44:47]
	v_mfma_f32_16x16x32_bf16 v[12:15], v[230:233], v[186:189], v[12:15]
	v_mfma_f32_16x16x32_bf16 v[40:43], v[222:225], v[194:197], v[40:43]
	v_mfma_f32_16x16x32_bf16 v[8:11], v[230:233], v[194:197], v[8:11]
	v_mfma_f32_16x16x32_bf16 v[36:39], v[222:225], v[202:205], v[36:39]
	v_mfma_f32_16x16x32_bf16 v[4:7], v[230:233], v[202:205], v[4:7]
	v_mfma_f32_16x16x32_bf16 v[32:35], v[222:225], v[214:217], v[32:35]
	v_mfma_f32_16x16x32_bf16 v[0:3], v[230:233], v[214:217], v[0:3]
	v_mfma_f32_16x16x32_bf16 v[44:47], v[226:229], v[190:193], v[44:47]
	v_mfma_f32_16x16x32_bf16 v[12:15], v[234:237], v[190:193], v[12:15]
	v_mfma_f32_16x16x32_bf16 v[40:43], v[226:229], v[198:201], v[40:43]
	v_mfma_f32_16x16x32_bf16 v[8:11], v[234:237], v[198:201], v[8:11]
	v_mfma_f32_16x16x32_bf16 v[36:39], v[226:229], v[206:209], v[36:39]
	v_mfma_f32_16x16x32_bf16 v[4:7], v[234:237], v[206:209], v[4:7]
	v_mfma_f32_16x16x32_bf16 v[32:35], v[226:229], v[218:221], v[32:35]
	v_mfma_f32_16x16x32_bf16 v[0:3], v[234:237], v[218:221], v[0:3]
	s_setprio 0
	s_add_i32 s9, s9, 2
	s_add_u32 s16, s16, 0x100
	s_addc_u32 s17, s17, 0
	s_add_u32 s0, s0, 0x100
	s_addc_u32 s1, s1, 0
	s_cmp_gt_u32 s9, 29
	s_barrier
	s_cbranch_scc0 .LBB0_133
	s_ashr_i32 s9, s64, 3
	s_cmp_lt_i32 s9, 4
	s_cbranch_scc1 .LBB0_138
	v_readlane_b32 s68, v254, 17
	v_readlane_b32 s76, v254, 25
	v_readlane_b32 s77, v254, 26
	s_cmp_gt_i32 s9, 4
	s_mov_b64 s[18:19], 0
	s_mov_b64 s[16:17], s[76:77]
	s_mov_b64 s[0:1], 0
	v_readlane_b32 s69, v254, 18
	v_readlane_b32 s70, v254, 19
	v_readlane_b32 s71, v254, 20
	v_readlane_b32 s72, v254, 21
	v_readlane_b32 s73, v254, 22
	v_readlane_b32 s74, v254, 23
	v_readlane_b32 s75, v254, 24
	v_readlane_b32 s78, v254, 27
	v_readlane_b32 s79, v254, 28
	v_readlane_b32 s80, v254, 29
	v_readlane_b32 s81, v254, 30
	v_readlane_b32 s82, v254, 31
	v_readlane_b32 s83, v254, 32
	s_cbranch_scc0 .LBB0_139
	s_cmp_eq_u32 s9, 5
	s_mov_b64 s[0:1], -1
	s_cbranch_scc0 .LBB0_139
	v_readlane_b32 s68, v254, 17
	v_readlane_b32 s78, v254, 27
	v_readlane_b32 s79, v254, 28
	s_mov_b64 s[0:1], 0
	v_readlane_b32 s69, v254, 18
	v_readlane_b32 s70, v254, 19
	v_readlane_b32 s71, v254, 20
	v_readlane_b32 s72, v254, 21
	v_readlane_b32 s73, v254, 22
	v_readlane_b32 s74, v254, 23
	v_readlane_b32 s75, v254, 24
	v_readlane_b32 s76, v254, 25
	v_readlane_b32 s77, v254, 26
	v_readlane_b32 s80, v254, 29
	v_readlane_b32 s81, v254, 30
	v_readlane_b32 s82, v254, 31
	v_readlane_b32 s83, v254, 32
	s_mov_b64 s[16:17], s[78:79]
	s_branch .LBB0_139

; #define PG8_STAGE(bufoff, gbase, voff) do { _Pragma("unroll") for (int _i = 0; _i < 2; ++_i) \
;         __builtin_amdgcn_global_load_lds((const unsigned*)((const char*)(gbase) + (voff)[_i]), (LAS unsigned*)(lds + (bufoff) + ldsw + _i * 8192), 16, 0, 0); } while (0)
; #define PG8_LDA(dst, b, h) do { _Pragma("unroll") for (int m = 0; m < 4; ++m) _Pragma("unroll") for (int k = 0; k < 2; ++k) dst[m][k] = *(const LAS bf16x8*)(lds + PG8_SA(b, h) + aoff + m * 2048 + k * 1024); } while (0)
; #define PG8_LDB(dst, b, h) do { _Pragma("unroll") for (int n = 0; n < 2; ++n) _Pragma("unroll") for (int k = 0; k < 2; ++k) dst[n][k] = *(const LAS bf16x8*)(lds + PG8_SB(b, h) + boff + n * 2048 + k * 1024); } while (0)
; #define PG8_MMA(ai, bj, At, Bt) do { __builtin_amdgcn_s_setprio(1); _Pragma("unroll") for (int m = 0; m < 4; ++m) _Pragma("unroll") for (int n = 0; n < 2; ++n) _Pragma("unroll") for (int k = 0; k < 2; ++k) \
;         acc[ai][bj][m][n] = __builtin_amdgcn_mfma_f32_16x16x32_bf16(Bt[n][k], At[m][k], acc[ai][bj][m][n], 0, 0, 0); __builtin_amdgcn_s_setprio(0); } while (0)
; #define PG8_WAIT_V(n) asm volatile("s_waitcnt vmcnt(" #n ")" ::: "memory")
; #define PG8_WAIT_L(n) asm volatile("s_waitcnt lgkmcnt(" #n ")" ::: "memory")
; #define PG8_BAR __builtin_amdgcn_s_barrier()
; #define PG8_SCHED __builtin_amdgcn_sched_barrier(0)
; template <class Epi, class S_t>
; __device__ __forceinline__ void gemm_phase(LAS unsigned char* lds, int lda, int ldb, const S_t& S, const Epi& E) {
;     ...
;             PG8_LDB(B0, 0, 0); PG8_SCHED; PG8_LDA(At, 0, 0); PG8_STAGE(PG8_SA(1, 1), a1 + hstepA, voffA);
;             PG8_WAIT_L(8); PG8_BAR; PG8_WAIT_L(0); PG8_MMA(0, 0, At, B0); PG8_BAR; PG8_SCHED;
;             PG8_LDB(B1, 0, 1); PG8_STAGE(PG8_SB(0, 0), b2, voffB);
;             PG8_BAR; PG8_WAIT_L(0); PG8_MMA(0, 1, At, B1); PG8_BAR;
;             PG8_LDA(At, 0, 1); PG8_STAGE(PG8_SA(0, 0), a2, voffA);
;             PG8_BAR; PG8_WAIT_L(0); PG8_MMA(1, 0, At, B0); PG8_BAR; PG8_SCHED;
;             PG8_STAGE(PG8_SB(0, 1), b2 + hstepB, voffB);
;             PG8_WAIT_V(6); PG8_BAR; PG8_MMA(1, 1, At, B1); PG8_BAR;
.LBB0_236:
	ds_read_b128 v[142:145], v149
	ds_read_b128 v[152:155], v149 offset:1024
	ds_read_b128 v[156:159], v149 offset:2048
	ds_read_b128 v[160:163], v149 offset:3072
	s_add_u32 s11, s54, 0xfff80080
	s_addc_u32 s13, s55, -1
	s_cmp_eq_u32 s7, 28
	s_cselect_b32 s59, s15, s13
	s_cselect_b32 s58, s14, s11
	s_cselect_b32 s57, s19, s1
	s_cselect_b32 s56, s18, s0
	s_add_i32 m0, s21, 0xc000
	ds_read_b128 v[164:167], v150
	ds_read_b128 v[168:171], v150 offset:1024
	ds_read_b128 v[172:175], v150 offset:2048
	ds_read_b128 v[176:179], v150 offset:3072
	ds_read_b128 v[180:183], v150 offset:4096
	ds_read_b128 v[186:189], v150 offset:5120
	ds_read_b128 v[190:193], v150 offset:6144
	ds_read_b128 v[194:197], v150 offset:7168
	global_load_lds_dwordx4 v136, s[54:55]
	s_add_i32 m0, s21, 0xe000
	s_nop 0
	global_load_lds_dwordx4 v138, s[54:55]
	s_waitcnt lgkmcnt(8)
	s_barrier
	s_waitcnt lgkmcnt(0)
	s_setprio 1
	v_mfma_f32_16x16x32_bf16 v[124:127], v[142:145], v[164:167], v[124:127]
	v_mfma_f32_16x16x32_bf16 v[120:123], v[156:159], v[164:167], v[120:123]
	v_mfma_f32_16x16x32_bf16 v[108:111], v[142:145], v[172:175], v[108:111]
	v_mfma_f32_16x16x32_bf16 v[104:107], v[156:159], v[172:175], v[104:107]
	v_mfma_f32_16x16x32_bf16 v[92:95], v[142:145], v[180:183], v[92:95]
	v_mfma_f32_16x16x32_bf16 v[88:91], v[156:159], v[180:183], v[88:91]
	v_mfma_f32_16x16x32_bf16 v[76:79], v[142:145], v[190:193], v[76:79]
	v_mfma_f32_16x16x32_bf16 v[72:75], v[156:159], v[190:193], v[72:75]
	v_mfma_f32_16x16x32_bf16 v[124:127], v[152:155], v[168:171], v[124:127]
	v_mfma_f32_16x16x32_bf16 v[120:123], v[160:163], v[168:171], v[120:123]
	v_mfma_f32_16x16x32_bf16 v[108:111], v[152:155], v[176:179], v[108:111]
	v_mfma_f32_16x16x32_bf16 v[104:107], v[160:163], v[176:179], v[104:107]
	v_mfma_f32_16x16x32_bf16 v[92:95], v[152:155], v[186:189], v[92:95]
	v_mfma_f32_16x16x32_bf16 v[88:91], v[160:163], v[186:189], v[88:91]
	v_mfma_f32_16x16x32_bf16 v[76:79], v[152:155], v[194:197], v[76:79]
	v_mfma_f32_16x16x32_bf16 v[72:75], v[160:163], v[194:197], v[72:75]
	s_setprio 0
	s_barrier
	s_add_i32 s11, s67, s20
	s_add_u32 s98, s56, s8
	s_addc_u32 s99, s57, s9
	s_mov_b32 m0, s11
	ds_read_b128 v[198:201], v151
	ds_read_b128 v[202:205], v151 offset:1024
	ds_read_b128 v[206:209], v151 offset:2048
	ds_read_b128 v[220:223], v151 offset:3072
	global_load_lds_dwordx4 v130, s[56:57]
	s_add_i32 m0, s11, 0x2000
	s_nop 0
	global_load_lds_dwordx4 v134, s[56:57]
	s_barrier
	s_waitcnt lgkmcnt(0)
	s_setprio 1
	v_mfma_f32_16x16x32_bf16 v[116:119], v[198:201], v[164:167], v[116:119]
	v_mfma_f32_16x16x32_bf16 v[112:115], v[206:209], v[164:167], v[112:115]
	v_mfma_f32_16x16x32_bf16 v[100:103], v[198:201], v[172:175], v[100:103]
	v_mfma_f32_16x16x32_bf16 v[96:99], v[206:209], v[172:175], v[96:99]
	v_mfma_f32_16x16x32_bf16 v[84:87], v[198:201], v[180:183], v[84:87]
	v_mfma_f32_16x16x32_bf16 v[80:83], v[206:209], v[180:183], v[80:83]
	v_mfma_f32_16x16x32_bf16 v[68:71], v[198:201], v[190:193], v[68:71]
	v_mfma_f32_16x16x32_bf16 v[64:67], v[206:209], v[190:193], v[64:67]
	v_mfma_f32_16x16x32_bf16 v[116:119], v[202:205], v[168:171], v[116:119]
	v_mfma_f32_16x16x32_bf16 v[112:115], v[220:223], v[168:171], v[112:115]
	v_mfma_f32_16x16x32_bf16 v[100:103], v[202:205], v[176:179], v[100:103]
	v_mfma_f32_16x16x32_bf16 v[96:99], v[220:223], v[176:179], v[96:99]
	v_mfma_f32_16x16x32_bf16 v[84:87], v[202:205], v[186:189], v[84:87]
	v_mfma_f32_16x16x32_bf16 v[80:83], v[220:223], v[186:189], v[80:83]
	v_mfma_f32_16x16x32_bf16 v[68:71], v[202:205], v[194:197], v[68:71]
	v_mfma_f32_16x16x32_bf16 v[64:67], v[220:223], v[194:197], v[64:67]
	s_setprio 0
	s_mov_b32 m0, s21
	s_add_u32 s100, s58, s8
	s_addc_u32 s101, s59, s9
	s_barrier
	ds_read_b128 v[164:167], v150 offset:16384
	ds_read_b128 v[168:171], v150 offset:17408
	ds_read_b128 v[172:175], v150 offset:18432
	ds_read_b128 v[176:179], v150 offset:19456
	ds_read_b128 v[180:183], v150 offset:20480
	ds_read_b128 v[186:189], v150 offset:21504
	ds_read_b128 v[190:193], v150 offset:22528
	ds_read_b128 v[194:197], v150 offset:23552
	global_load_lds_dwordx4 v128, s[58:59]
	s_mov_b32 m0, s35
	s_nop 0
	global_load_lds_dwordx4 v132, s[58:59]
	s_barrier
	s_waitcnt lgkmcnt(0)
	s_setprio 1
	v_mfma_f32_16x16x32_bf16 v[60:63], v[142:145], v[164:167], v[60:63]
	v_mfma_f32_16x16x32_bf16 v[56:59], v[156:159], v[164:167], v[56:59]
	v_mfma_f32_16x16x32_bf16 v[44:47], v[142:145], v[172:175], v[44:47]
	v_mfma_f32_16x16x32_bf16 v[40:43], v[156:159], v[172:175], v[40:43]
	v_mfma_f32_16x16x32_bf16 v[28:31], v[142:145], v[180:183], v[28:31]
	v_mfma_f32_16x16x32_bf16 v[24:27], v[156:159], v[180:183], v[24:27]
	v_mfma_f32_16x16x32_bf16 v[12:15], v[142:145], v[190:193], v[12:15]
	v_mfma_f32_16x16x32_bf16 v[8:11], v[156:159], v[190:193], v[8:11]
	v_mfma_f32_16x16x32_bf16 v[60:63], v[152:155], v[168:171], v[60:63]
	v_mfma_f32_16x16x32_bf16 v[56:59], v[160:163], v[168:171], v[56:59]
	v_mfma_f32_16x16x32_bf16 v[44:47], v[152:155], v[176:179], v[44:47]
	v_mfma_f32_16x16x32_bf16 v[40:43], v[160:163], v[176:179], v[40:43]
	v_mfma_f32_16x16x32_bf16 v[28:31], v[152:155], v[186:189], v[28:31]
	v_mfma_f32_16x16x32_bf16 v[24:27], v[160:163], v[186:189], v[24:27]
	v_mfma_f32_16x16x32_bf16 v[12:15], v[152:155], v[194:197], v[12:15]
	v_mfma_f32_16x16x32_bf16 v[8:11], v[160:163], v[194:197], v[8:11]
	s_setprio 0
	s_barrier
	s_add_u32 s42, s56, 0x80000
	s_addc_u32 s43, s57, 0
	s_add_i32 s11, s74, s20
	s_mov_b32 m0, s11
	s_nop 0
	global_load_lds_dwordx4 v130, s[42:43]
	s_add_i32 m0, s11, 0x2000
	s_nop 0
	global_load_lds_dwordx4 v134, s[42:43]
	s_waitcnt vmcnt(6)
	s_barrier
; #define PG8_STAGE(bufoff, gbase, voff) do { _Pragma("unroll") for (int _i = 0; _i < 2; ++_i) \
;         __builtin_amdgcn_global_load_lds((const unsigned*)((const char*)(gbase) + (voff)[_i]), (LAS unsigned*)(lds + (bufoff) + ldsw + _i * 8192), 16, 0, 0); } while (0)
; #define PG8_LDA(dst, b, h) do { _Pragma("unroll") for (int m = 0; m < 4; ++m) _Pragma("unroll") for (int k = 0; k < 2; ++k) dst[m][k] = *(const LAS bf16x8*)(lds + PG8_SA(b, h) + aoff + m * 2048 + k * 1024); } while (0)
; #define PG8_LDB(dst, b, h) do { _Pragma("unroll") for (int n = 0; n < 2; ++n) _Pragma("unroll") for (int k = 0; k < 2; ++k) dst[n][k] = *(const LAS bf16x8*)(lds + PG8_SB(b, h) + boff + n * 2048 + k * 1024); } while (0)
; #define PG8_MMA(ai, bj, At, Bt) do { __builtin_amdgcn_s_setprio(1); _Pragma("unroll") for (int m = 0; m < 4; ++m) _Pragma("unroll") for (int n = 0; n < 2; ++n) _Pragma("unroll") for (int k = 0; k < 2; ++k) \
;         acc[ai][bj][m][n] = __builtin_amdgcn_mfma_f32_16x16x32_bf16(Bt[n][k], At[m][k], acc[ai][bj][m][n], 0, 0, 0); __builtin_amdgcn_s_setprio(0); } while (0)
; #define PG8_WAIT_V(n) asm volatile("s_waitcnt vmcnt(" #n ")" ::: "memory")
; #define PG8_WAIT_L(n) asm volatile("s_waitcnt lgkmcnt(" #n ")" ::: "memory")
; #define PG8_BAR __builtin_amdgcn_s_barrier()
; #define PG8_SCHED __builtin_amdgcn_sched_barrier(0)
; template <class Epi, class S_t>
; __device__ __forceinline__ void gemm_phase(LAS unsigned char* lds, int lda, int ldb, const S_t& S, const Epi& E) {
;     ...
;             PG8_WAIT_V(6); PG8_BAR; PG8_MMA(1, 1, At, B1); PG8_BAR;
;             PG8_LDB(B0, 1, 0); PG8_SCHED; PG8_LDA(At, 1, 0); PG8_STAGE(PG8_SA(0, 1), a2 + hstepA, voffA);
;             PG8_WAIT_L(8); PG8_BAR; PG8_WAIT_L(0); PG8_MMA(0, 0, At, B0); PG8_BAR; PG8_SCHED;
;             PG8_LDB(B1, 1, 1); PG8_STAGE(PG8_SB(1, 0), b3, voffB);
;             PG8_BAR; PG8_WAIT_L(0); PG8_MMA(0, 1, At, B1); PG8_BAR;
;             PG8_LDA(At, 1, 1); PG8_STAGE(PG8_SA(1, 0), a3, voffA);
;             PG8_BAR; PG8_WAIT_L(0); PG8_MMA(1, 0, At, B0); PG8_BAR; PG8_SCHED;
	s_setprio 1
	v_mfma_f32_16x16x32_bf16 v[52:55], v[198:201], v[164:167], v[52:55]
	v_mfma_f32_16x16x32_bf16 v[48:51], v[206:209], v[164:167], v[48:51]
	v_mfma_f32_16x16x32_bf16 v[36:39], v[198:201], v[172:175], v[36:39]
	v_mfma_f32_16x16x32_bf16 v[32:35], v[206:209], v[172:175], v[32:35]
	v_mfma_f32_16x16x32_bf16 v[20:23], v[198:201], v[180:183], v[20:23]
	v_mfma_f32_16x16x32_bf16 v[16:19], v[206:209], v[180:183], v[16:19]
	v_mfma_f32_16x16x32_bf16 v[4:7], v[198:201], v[190:193], v[4:7]
	v_mfma_f32_16x16x32_bf16 v[0:3], v[206:209], v[190:193], v[0:3]
	v_mfma_f32_16x16x32_bf16 v[52:55], v[202:205], v[168:171], v[52:55]
	v_mfma_f32_16x16x32_bf16 v[48:51], v[220:223], v[168:171], v[48:51]
	v_mfma_f32_16x16x32_bf16 v[36:39], v[202:205], v[176:179], v[36:39]
	v_mfma_f32_16x16x32_bf16 v[32:35], v[220:223], v[176:179], v[32:35]
	v_mfma_f32_16x16x32_bf16 v[20:23], v[202:205], v[186:189], v[20:23]
	v_mfma_f32_16x16x32_bf16 v[16:19], v[220:223], v[186:189], v[16:19]
	v_mfma_f32_16x16x32_bf16 v[4:7], v[202:205], v[194:197], v[4:7]
	v_mfma_f32_16x16x32_bf16 v[0:3], v[220:223], v[194:197], v[0:3]
	s_setprio 0
	s_add_i32 s11, 0, 0x18000
	v_add_u32_e32 v160, s11, v147
	s_barrier
	ds_read_b128 v[142:145], v160
	ds_read_b128 v[152:155], v160 offset:1024
	ds_read_b128 v[156:159], v160 offset:2048
	ds_read_b128 v[160:163], v160 offset:3072
	s_add_u32 s42, s58, 0x80000
	s_addc_u32 s43, s59, 0
	s_mov_b32 m0, s52
	ds_read_b128 v[164:167], v150 offset:32768
	ds_read_b128 v[168:171], v150 offset:33792
	ds_read_b128 v[172:175], v150 offset:34816
	ds_read_b128 v[176:179], v150 offset:35840
	ds_read_b128 v[180:183], v150 offset:36864
	ds_read_b128 v[186:189], v150 offset:37888
	ds_read_b128 v[190:193], v150 offset:38912
	ds_read_b128 v[194:197], v150 offset:39936
	global_load_lds_dwordx4 v128, s[42:43]
	s_mov_b32 m0, s53
	s_nop 0
	global_load_lds_dwordx4 v132, s[42:43]
	s_waitcnt lgkmcnt(8)
	s_barrier
	s_waitcnt lgkmcnt(0)
	s_setprio 1
	v_mfma_f32_16x16x32_bf16 v[124:127], v[142:145], v[164:167], v[124:127]
	v_mfma_f32_16x16x32_bf16 v[120:123], v[156:159], v[164:167], v[120:123]
	v_mfma_f32_16x16x32_bf16 v[108:111], v[142:145], v[172:175], v[108:111]
	v_mfma_f32_16x16x32_bf16 v[104:107], v[156:159], v[172:175], v[104:107]
	v_mfma_f32_16x16x32_bf16 v[92:95], v[142:145], v[180:183], v[92:95]
	v_mfma_f32_16x16x32_bf16 v[88:91], v[156:159], v[180:183], v[88:91]
	v_mfma_f32_16x16x32_bf16 v[76:79], v[142:145], v[190:193], v[76:79]
	v_mfma_f32_16x16x32_bf16 v[72:75], v[156:159], v[190:193], v[72:75]
	v_mfma_f32_16x16x32_bf16 v[124:127], v[152:155], v[168:171], v[124:127]
	v_mfma_f32_16x16x32_bf16 v[120:123], v[160:163], v[168:171], v[120:123]
	v_mfma_f32_16x16x32_bf16 v[108:111], v[152:155], v[176:179], v[108:111]
	v_mfma_f32_16x16x32_bf16 v[104:107], v[160:163], v[176:179], v[104:107]
	v_mfma_f32_16x16x32_bf16 v[92:95], v[152:155], v[186:189], v[92:95]
	v_mfma_f32_16x16x32_bf16 v[88:91], v[160:163], v[186:189], v[88:91]
	v_mfma_f32_16x16x32_bf16 v[76:79], v[152:155], v[194:197], v[76:79]
	v_mfma_f32_16x16x32_bf16 v[72:75], v[160:163], v[194:197], v[72:75]
	s_setprio 0
	s_barrier
	s_add_i32 s13, 0, 0x1c000
	s_add_i32 s11, s11, s20
	v_add_u32_e32 v215, s13, v147
	s_mov_b32 m0, s11
	ds_read_b128 v[198:201], v215
	ds_read_b128 v[202:205], v215 offset:1024
	ds_read_b128 v[206:209], v215 offset:2048
	ds_read_b128 v[220:223], v215 offset:3072
	global_load_lds_dwordx4 v130, s[98:99]
	s_add_i32 m0, s11, 0x2000
	s_nop 0
	global_load_lds_dwordx4 v134, s[98:99]
	s_barrier
	s_waitcnt lgkmcnt(0)
	s_setprio 1
	v_mfma_f32_16x16x32_bf16 v[116:119], v[198:201], v[164:167], v[116:119]
	v_mfma_f32_16x16x32_bf16 v[112:115], v[206:209], v[164:167], v[112:115]
	v_mfma_f32_16x16x32_bf16 v[100:103], v[198:201], v[172:175], v[100:103]
	v_mfma_f32_16x16x32_bf16 v[96:99], v[206:209], v[172:175], v[96:99]
	v_mfma_f32_16x16x32_bf16 v[84:87], v[198:201], v[180:183], v[84:87]
	v_mfma_f32_16x16x32_bf16 v[80:83], v[206:209], v[180:183], v[80:83]
	v_mfma_f32_16x16x32_bf16 v[68:71], v[198:201], v[190:193], v[68:71]
	v_mfma_f32_16x16x32_bf16 v[64:67], v[206:209], v[190:193], v[64:67]
	v_mfma_f32_16x16x32_bf16 v[116:119], v[202:205], v[168:171], v[116:119]
	v_mfma_f32_16x16x32_bf16 v[112:115], v[220:223], v[168:171], v[112:115]
	v_mfma_f32_16x16x32_bf16 v[100:103], v[202:205], v[176:179], v[100:103]
	v_mfma_f32_16x16x32_bf16 v[96:99], v[220:223], v[176:179], v[96:99]
	v_mfma_f32_16x16x32_bf16 v[84:87], v[202:205], v[186:189], v[84:87]
	v_mfma_f32_16x16x32_bf16 v[80:83], v[220:223], v[186:189], v[80:83]
	v_mfma_f32_16x16x32_bf16 v[68:71], v[202:205], v[194:197], v[68:71]
	v_mfma_f32_16x16x32_bf16 v[64:67], v[220:223], v[194:197], v[64:67]
	s_setprio 0
	s_mov_b32 m0, s61
	s_barrier
; __device__ __forceinline__ float sigmoidf_(float x) { return __builtin_amdgcn_rcpf(1.0f + __expf(-x)); }
; #define PG8_STAGE(bufoff, gbase, voff) do { _Pragma("unroll") for (int _i = 0; _i < 2; ++_i) \
;         __builtin_amdgcn_global_load_lds((const unsigned*)((const char*)(gbase) + (voff)[_i]), (LAS unsigned*)(lds + (bufoff) + ldsw + _i * 8192), 16, 0, 0); } while (0)
; #define PG8_LDA(dst, b, h) do { _Pragma("unroll") for (int m = 0; m < 4; ++m) _Pragma("unroll") for (int k = 0; k < 2; ++k) dst[m][k] = *(const LAS bf16x8*)(lds + PG8_SA(b, h) + aoff + m * 2048 + k * 1024); } while (0)
; #define PG8_MMA(ai, bj, At, Bt) do { __builtin_amdgcn_s_setprio(1); _Pragma("unroll") for (int m = 0; m < 4; ++m) _Pragma("unroll") for (int n = 0; n < 2; ++n) _Pragma("unroll") for (int k = 0; k < 2; ++k) \
;         acc[ai][bj][m][n] = __builtin_amdgcn_mfma_f32_16x16x32_bf16(Bt[n][k], At[m][k], acc[ai][bj][m][n], 0, 0, 0); __builtin_amdgcn_s_setprio(0); } while (0)
; #define PG8_WAIT_V(n) asm volatile("s_waitcnt vmcnt(" #n ")" ::: "memory")
; #define PG8_WAIT_L(n) asm volatile("s_waitcnt lgkmcnt(" #n ")" ::: "memory")
; template <class Epi, class S_t>
; __device__ __forceinline__ void gemm_phase(LAS unsigned char* lds, int lda, int ldb, const S_t& S, const Epi& E) {
;     ...
;             PG8_BAR; PG8_WAIT_L(0); PG8_MMA(0, 1, At, B1); PG8_BAR;
;             PG8_LDA(At, 1, 1); PG8_STAGE(PG8_SA(1, 0), a3, voffA);
;             PG8_BAR; PG8_WAIT_L(0); PG8_MMA(1, 0, At, B0); PG8_BAR; PG8_SCHED;
;             PG8_STAGE(PG8_SB(1, 1), b3 + hstepB, voffB);
;             PG8_WAIT_V(6); PG8_BAR; PG8_MMA(1, 1, At, B1); PG8_BAR;
;     __device__ __forceinline__ void operator()(const f32x4 (&acc)[2][2][4][2], const Unit& u, int wr, int wc, int fr, int fq) const {
;         const int row0 = u.pm * BM + wr * 64 + fr, col0 = u.pn * BM + wc * 32 + 8 * fq;
;         const bool sg = u.pn >= sig_pn;
; #pragma unroll
;         for (int ai = 0; ai < 2; ++ai)
; #pragma unroll
;             for (int m = 0; m < 4; ++m) { bf16_t* rowp = O + (size_t)(row0 + ai * HALF + m * 16) * ldc + col0;
; #pragma unroll
;                 for (int bj = 0; bj < 2; ++bj) { f32x4 v0 = acc[ai][bj][m][0], v1 = acc[ai][bj][m][1];
;                     if (sg) {
; #pragma unroll
;                         for (int j = 0; j < 4; ++j) { v0[j] = sigmoidf_(v0[j]); v1[j] = sigmoidf_(v1[j]); } }
	ds_read_b128 v[164:167], v150 offset:49152
	ds_read_b128 v[168:171], v150 offset:50176
	ds_read_b128 v[172:175], v150 offset:51200
	ds_read_b128 v[176:179], v150 offset:52224
	ds_read_b128 v[180:183], v150 offset:53248
	ds_read_b128 v[186:189], v150 offset:54272
	ds_read_b128 v[190:193], v150 offset:55296
	ds_read_b128 v[194:197], v150 offset:56320
	global_load_lds_dwordx4 v128, s[100:101]
	s_mov_b32 m0, s62
	s_nop 0
	global_load_lds_dwordx4 v132, s[100:101]
	s_barrier
	s_waitcnt lgkmcnt(0)
	s_setprio 1
	v_mfma_f32_16x16x32_bf16 v[60:63], v[142:145], v[164:167], v[60:63]
	v_mfma_f32_16x16x32_bf16 v[56:59], v[156:159], v[164:167], v[56:59]
	v_mfma_f32_16x16x32_bf16 v[44:47], v[142:145], v[172:175], v[44:47]
	v_mfma_f32_16x16x32_bf16 v[40:43], v[156:159], v[172:175], v[40:43]
	v_mfma_f32_16x16x32_bf16 v[28:31], v[142:145], v[180:183], v[28:31]
	v_mfma_f32_16x16x32_bf16 v[24:27], v[156:159], v[180:183], v[24:27]
	v_mfma_f32_16x16x32_bf16 v[12:15], v[142:145], v[190:193], v[12:15]
	v_mfma_f32_16x16x32_bf16 v[8:11], v[156:159], v[190:193], v[8:11]
	v_mfma_f32_16x16x32_bf16 v[60:63], v[152:155], v[168:171], v[60:63]
	v_mfma_f32_16x16x32_bf16 v[56:59], v[160:163], v[168:171], v[56:59]
	v_mfma_f32_16x16x32_bf16 v[44:47], v[152:155], v[176:179], v[44:47]
	v_mfma_f32_16x16x32_bf16 v[40:43], v[160:163], v[176:179], v[40:43]
	v_mfma_f32_16x16x32_bf16 v[28:31], v[152:155], v[186:189], v[28:31]
	v_mfma_f32_16x16x32_bf16 v[24:27], v[160:163], v[186:189], v[24:27]
	v_mfma_f32_16x16x32_bf16 v[12:15], v[152:155], v[194:197], v[12:15]
	v_mfma_f32_16x16x32_bf16 v[8:11], v[160:163], v[194:197], v[8:11]
	s_setprio 0
	s_barrier
	s_add_u32 s42, s56, 0x80080
	s_addc_u32 s43, s57, 0
	s_add_i32 s11, s13, s20
	s_mov_b32 m0, s11
	s_nop 0
	global_load_lds_dwordx4 v130, s[42:43]
	s_add_i32 m0, s11, 0x2000
	s_nop 0
	global_load_lds_dwordx4 v134, s[42:43]
	s_waitcnt vmcnt(6)
	s_barrier
	s_setprio 1
	v_mfma_f32_16x16x32_bf16 v[52:55], v[198:201], v[164:167], v[52:55]
	v_mfma_f32_16x16x32_bf16 v[48:51], v[206:209], v[164:167], v[48:51]
	v_mfma_f32_16x16x32_bf16 v[36:39], v[198:201], v[172:175], v[36:39]
	v_mfma_f32_16x16x32_bf16 v[32:35], v[206:209], v[172:175], v[32:35]
	v_mfma_f32_16x16x32_bf16 v[20:23], v[198:201], v[180:183], v[20:23]
	v_mfma_f32_16x16x32_bf16 v[16:19], v[206:209], v[180:183], v[16:19]
	v_mfma_f32_16x16x32_bf16 v[4:7], v[198:201], v[190:193], v[4:7]
	v_mfma_f32_16x16x32_bf16 v[0:3], v[206:209], v[190:193], v[0:3]
	v_mfma_f32_16x16x32_bf16 v[52:55], v[202:205], v[168:171], v[52:55]
	v_mfma_f32_16x16x32_bf16 v[48:51], v[220:223], v[168:171], v[48:51]
	v_mfma_f32_16x16x32_bf16 v[36:39], v[202:205], v[176:179], v[36:39]
	v_mfma_f32_16x16x32_bf16 v[32:35], v[220:223], v[176:179], v[32:35]
	v_mfma_f32_16x16x32_bf16 v[20:23], v[202:205], v[186:189], v[20:23]
	v_mfma_f32_16x16x32_bf16 v[16:19], v[220:223], v[186:189], v[16:19]
	v_mfma_f32_16x16x32_bf16 v[4:7], v[202:205], v[194:197], v[4:7]
	v_mfma_f32_16x16x32_bf16 v[0:3], v[220:223], v[194:197], v[0:3]
	s_setprio 0
	s_add_i32 s7, s7, 2
	s_add_u32 s54, s54, 0x100
	s_addc_u32 s55, s55, 0
	s_add_u32 s0, s0, 0x100
	s_addc_u32 s1, s1, 0
	s_cmp_gt_u32 s7, 29
	s_barrier
	s_cbranch_scc0 .LBB0_236
	s_cmp_gt_i32 s78, 11
	s_cselect_b64 s[0:1], -1, 0
	s_cmp_lt_i32 s78, 12
	s_cbranch_scc1 .LBB0_239
	v_mul_f32_e32 v124, 0xbfb8aa3b, v124
	v_mul_f32_e32 v120, 0xbfb8aa3b, v120
	v_mul_f32_e32 v125, 0xbfb8aa3b, v125
	v_mul_f32_e32 v121, 0xbfb8aa3b, v121
	v_mul_f32_e32 v126, 0xbfb8aa3b, v126
	v_mul_f32_e32 v122, 0xbfb8aa3b, v122
	v_mul_f32_e32 v127, 0xbfb8aa3b, v127
	v_mul_f32_e32 v123, 0xbfb8aa3b, v123
	v_exp_f32_e32 v124, v124
	v_exp_f32_e32 v120, v120
	v_exp_f32_e32 v125, v125
	v_exp_f32_e32 v121, v121
	v_exp_f32_e32 v126, v126
	v_exp_f32_e32 v122, v122
	v_exp_f32_e32 v127, v127
	v_exp_f32_e32 v123, v123
	v_add_f32_e32 v124, 1.0, v124
	v_add_f32_e32 v120, 1.0, v120
	v_add_f32_e32 v125, 1.0, v125
	v_add_f32_e32 v121, 1.0, v121
	v_add_f32_e32 v126, 1.0, v126
	v_add_f32_e32 v122, 1.0, v122
	v_add_f32_e32 v127, 1.0, v127
	v_add_f32_e32 v123, 1.0, v123
	v_rcp_f32_e32 v124, v124
	v_rcp_f32_e32 v120, v120
	v_rcp_f32_e32 v125, v125
	v_rcp_f32_e32 v121, v121
	v_rcp_f32_e32 v126, v126
	v_rcp_f32_e32 v122, v122
	v_rcp_f32_e32 v127, v127
	v_rcp_f32_e32 v123, v123

; #define PG8_STAGE(bufoff, gbase, voff) do { _Pragma("unroll") for (int _i = 0; _i < 2; ++_i) \
;         __builtin_amdgcn_global_load_lds((const unsigned*)((const char*)(gbase) + (voff)[_i]), (LAS unsigned*)(lds + (bufoff) + ldsw + _i * 8192), 16, 0, 0); } while (0)
; #define PG8_LDA(dst, b, h) do { _Pragma("unroll") for (int m = 0; m < 4; ++m) _Pragma("unroll") for (int k = 0; k < 2; ++k) dst[m][k] = *(const LAS bf16x8*)(lds + PG8_SA(b, h) + aoff + m * 2048 + k * 1024); } while (0)
; #define PG8_LDB(dst, b, h) do { _Pragma("unroll") for (int n = 0; n < 2; ++n) _Pragma("unroll") for (int k = 0; k < 2; ++k) dst[n][k] = *(const LAS bf16x8*)(lds + PG8_SB(b, h) + boff + n * 2048 + k * 1024); } while (0)
; #define PG8_MMA(ai, bj, At, Bt) do { __builtin_amdgcn_s_setprio(1); _Pragma("unroll") for (int m = 0; m < 4; ++m) _Pragma("unroll") for (int n = 0; n < 2; ++n) _Pragma("unroll") for (int k = 0; k < 2; ++k) \
;         acc[ai][bj][m][n] = __builtin_amdgcn_mfma_f32_16x16x32_bf16(Bt[n][k], At[m][k], acc[ai][bj][m][n], 0, 0, 0); __builtin_amdgcn_s_setprio(0); } while (0)
; template <class Epi, class S_t>
; __device__ __forceinline__ void gemm_phase(LAS unsigned char* lds, int lda, int ldb, const S_t& S, const Epi& E) {
;     ...
;         const bool has_next = S.next(ui + 1, nxt);
;         const char* nA = has_next ? nxt.A : cA; const char* nB = has_next ? nxt.B : cB;
;         const int nt = cur.nt;
;         for (int t = 0; t < nt; t += 2) {
;             const bool last = (t == nt - 2);
;             const char* a1 = cA + (size_t)(t + 1) * kstep;
;             const char* a2 = last ? nA : cA + (size_t)(t + 2) * kstep; const char* b2 = last ? nB : cB + (size_t)(t + 2) * kstep;
;             const char* a3 = a2 + kstep; const char* b3 = b2 + kstep;
;             PG8_LDB(B0, 0, 0); PG8_SCHED; PG8_LDA(At, 0, 0); PG8_STAGE(PG8_SA(1, 1), a1 + hstepA, voffA);
;             PG8_WAIT_L(8); PG8_BAR; PG8_WAIT_L(0); PG8_MMA(0, 0, At, B0); PG8_BAR; PG8_SCHED;
;             PG8_LDB(B1, 0, 1); PG8_STAGE(PG8_SB(0, 0), b2, voffB);
;             PG8_BAR; PG8_WAIT_L(0); PG8_MMA(0, 1, At, B1); PG8_BAR;
;             PG8_LDA(At, 0, 1); PG8_STAGE(PG8_SA(0, 0), a2, voffA);
;             PG8_BAR; PG8_WAIT_L(0); PG8_MMA(1, 0, At, B0); PG8_BAR; PG8_SCHED;
;             PG8_STAGE(PG8_SB(0, 1), b2 + hstepB, voffB);
;             PG8_WAIT_V(6); PG8_BAR; PG8_MMA(1, 1, At, B1); PG8_BAR;
.LBB0_535:
	s_add_u32 s13, s58, s0
	s_addc_u32 s15, s59, 0
	s_add_u32 s1, s13, 0x100
	s_addc_u32 s33, s15, 0
	s_and_b64 s[42:43], s[66:67], exec
	s_cselect_b32 s75, s19, s33
	s_cselect_b32 s74, s18, s1
	s_add_u32 s0, s60, s0
	s_addc_u32 s1, s61, 0
	s_add_u32 s33, s0, 0x100
	s_addc_u32 s42, s1, 0
	s_and_b64 s[0:1], s[66:67], exec
	s_cselect_b32 s79, s45, s42
	s_cselect_b32 s78, s44, s33
	s_add_u32 s82, s13, 0x40080
	s_addc_u32 s83, s15, 0
	s_add_i32 s96, s90, s17
	s_add_i32 m0, s21, 0xc000
	s_add_i32 s33, s21, 0xe000
	s_add_i32 s95, s96, 0x2000
	s_add_u32 s72, s78, 0x10000
	s_addc_u32 s73, s79, 0
	s_add_i32 s94, s91, s17
	s_add_i32 s93, s94, 0x2000
	s_add_i32 s43, 0, 0x18000
	ds_read_b128 v[128:131], v163
	ds_read_b128 v[132:135], v163 offset:1024
	ds_read_b128 v[136:139], v163 offset:2048
	ds_read_b128 v[140:143], v163 offset:3072
	s_add_u32 s70, s74, 0x40000
	s_addc_u32 s71, s75, 0
	s_add_i32 s42, s43, s17
	s_add_i32 s15, 0, 0x1c000
	s_add_i32 s13, s42, 0x2000
	s_add_u32 s66, s78, 0x10080
	s_addc_u32 s67, s79, 0
	s_add_i32 s1, s15, s17
	s_add_i32 s0, s1, 0x2000
	ds_read_b128 v[154:157], v164
	ds_read_b128 v[166:169], v164 offset:1024
	ds_read_b128 v[170:173], v164 offset:2048
	ds_read_b128 v[174:177], v164 offset:3072
	ds_read_b128 v[178:181], v164 offset:4096
	ds_read_b128 v[186:189], v164 offset:5120
	ds_read_b128 v[190:193], v164 offset:6144
	ds_read_b128 v[194:197], v164 offset:7168
	global_load_lds_dwordx4 v150, s[82:83]
	s_mov_b32 m0, s33
	s_nop 0
	global_load_lds_dwordx4 v146, s[82:83]
	s_waitcnt lgkmcnt(8)
	s_barrier
	s_waitcnt lgkmcnt(0)
	s_setprio 1
	v_mfma_f32_16x16x32_bf16 v[124:127], v[128:131], v[154:157], v[124:127]
	v_mfma_f32_16x16x32_bf16 v[120:123], v[136:139], v[154:157], v[120:123]
	v_mfma_f32_16x16x32_bf16 v[116:119], v[128:131], v[170:173], v[116:119]
	v_mfma_f32_16x16x32_bf16 v[112:115], v[136:139], v[170:173], v[112:115]
	v_mfma_f32_16x16x32_bf16 v[108:111], v[128:131], v[178:181], v[108:111]
	v_mfma_f32_16x16x32_bf16 v[100:103], v[136:139], v[178:181], v[100:103]
	v_mfma_f32_16x16x32_bf16 v[76:79], v[128:131], v[190:193], v[76:79]
	v_mfma_f32_16x16x32_bf16 v[72:75], v[136:139], v[190:193], v[72:75]
	v_mfma_f32_16x16x32_bf16 v[124:127], v[132:135], v[166:169], v[124:127]
	v_mfma_f32_16x16x32_bf16 v[120:123], v[140:143], v[166:169], v[120:123]
	v_mfma_f32_16x16x32_bf16 v[116:119], v[132:135], v[174:177], v[116:119]
	v_mfma_f32_16x16x32_bf16 v[112:115], v[140:143], v[174:177], v[112:115]
	v_mfma_f32_16x16x32_bf16 v[108:111], v[132:135], v[186:189], v[108:111]
	v_mfma_f32_16x16x32_bf16 v[100:103], v[140:143], v[186:189], v[100:103]
	v_mfma_f32_16x16x32_bf16 v[76:79], v[132:135], v[194:197], v[76:79]
	v_mfma_f32_16x16x32_bf16 v[72:75], v[140:143], v[194:197], v[72:75]
	s_setprio 0
	s_barrier
	s_mov_b32 m0, s96
	s_add_u32 s100, s78, s10
	s_addc_u32 s101, s79, s11
	ds_read_b128 v[198:201], v165
	ds_read_b128 v[202:205], v165 offset:1024
	ds_read_b128 v[206:209], v165 offset:2048
	ds_read_b128 v[222:225], v165 offset:3072
	global_load_lds_dwordx4 v148, s[78:79]
	s_mov_b32 m0, s95
	s_nop 0
	global_load_lds_dwordx4 v144, s[78:79]
	s_barrier
	s_waitcnt lgkmcnt(0)
	s_setprio 1
	v_mfma_f32_16x16x32_bf16 v[104:107], v[198:201], v[154:157], v[104:107]
	v_mfma_f32_16x16x32_bf16 v[96:99], v[206:209], v[154:157], v[96:99]
	v_mfma_f32_16x16x32_bf16 v[92:95], v[198:201], v[170:173], v[92:95]
	v_mfma_f32_16x16x32_bf16 v[88:91], v[206:209], v[170:173], v[88:91]
	v_mfma_f32_16x16x32_bf16 v[84:87], v[198:201], v[178:181], v[84:87]
	v_mfma_f32_16x16x32_bf16 v[80:83], v[206:209], v[178:181], v[80:83]
	v_mfma_f32_16x16x32_bf16 v[68:71], v[198:201], v[190:193], v[68:71]
	v_mfma_f32_16x16x32_bf16 v[64:67], v[206:209], v[190:193], v[64:67]
	v_mfma_f32_16x16x32_bf16 v[104:107], v[202:205], v[166:169], v[104:107]
	v_mfma_f32_16x16x32_bf16 v[96:99], v[222:225], v[166:169], v[96:99]
	v_mfma_f32_16x16x32_bf16 v[92:95], v[202:205], v[174:177], v[92:95]
	v_mfma_f32_16x16x32_bf16 v[88:91], v[222:225], v[174:177], v[88:91]
	v_mfma_f32_16x16x32_bf16 v[84:87], v[202:205], v[186:189], v[84:87]
	v_mfma_f32_16x16x32_bf16 v[80:83], v[222:225], v[186:189], v[80:83]
	v_mfma_f32_16x16x32_bf16 v[68:71], v[202:205], v[194:197], v[68:71]
	v_mfma_f32_16x16x32_bf16 v[64:67], v[222:225], v[194:197], v[64:67]
	s_setprio 0
	s_mov_b32 m0, s21
	s_add_u32 s98, s74, s10
	s_addc_u32 s99, s75, s11
	s_barrier
	ds_read_b128 v[154:157], v164 offset:16384
	ds_read_b128 v[166:169], v164 offset:17408
	ds_read_b128 v[170:173], v164 offset:18432
	ds_read_b128 v[174:177], v164 offset:19456
	ds_read_b128 v[178:181], v164 offset:20480
	ds_read_b128 v[186:189], v164 offset:21504
	ds_read_b128 v[190:193], v164 offset:22528
	ds_read_b128 v[194:197], v164 offset:23552
	global_load_lds_dwordx4 v150, s[74:75]
	s_mov_b32 m0, s35
	s_nop 0
	global_load_lds_dwordx4 v146, s[74:75]
	s_barrier
	s_waitcnt lgkmcnt(0)
	s_setprio 1
	v_mfma_f32_16x16x32_bf16 v[60:63], v[128:131], v[154:157], v[60:63]
	v_mfma_f32_16x16x32_bf16 v[56:59], v[136:139], v[154:157], v[56:59]
	v_mfma_f32_16x16x32_bf16 v[48:51], v[128:131], v[170:173], v[48:51]
	v_mfma_f32_16x16x32_bf16 v[40:43], v[136:139], v[170:173], v[40:43]
	v_mfma_f32_16x16x32_bf16 v[32:35], v[128:131], v[178:181], v[32:35]
	v_mfma_f32_16x16x32_bf16 v[24:27], v[136:139], v[178:181], v[24:27]
	v_mfma_f32_16x16x32_bf16 v[16:19], v[128:131], v[190:193], v[16:19]
	v_mfma_f32_16x16x32_bf16 v[8:11], v[136:139], v[190:193], v[8:11]
	v_mfma_f32_16x16x32_bf16 v[60:63], v[132:135], v[166:169], v[60:63]
	v_mfma_f32_16x16x32_bf16 v[56:59], v[140:143], v[166:169], v[56:59]
	v_mfma_f32_16x16x32_bf16 v[48:51], v[132:135], v[174:177], v[48:51]
	v_mfma_f32_16x16x32_bf16 v[40:43], v[140:143], v[174:177], v[40:43]
	v_mfma_f32_16x16x32_bf16 v[32:35], v[132:135], v[186:189], v[32:35]
	v_mfma_f32_16x16x32_bf16 v[24:27], v[140:143], v[186:189], v[24:27]
	v_mfma_f32_16x16x32_bf16 v[16:19], v[132:135], v[194:197], v[16:19]
	v_mfma_f32_16x16x32_bf16 v[8:11], v[140:143], v[194:197], v[8:11]
	s_setprio 0
	s_barrier
; #define PG8_STAGE(bufoff, gbase, voff) do { _Pragma("unroll") for (int _i = 0; _i < 2; ++_i) \
;         __builtin_amdgcn_global_load_lds((const unsigned*)((const char*)(gbase) + (voff)[_i]), (LAS unsigned*)(lds + (bufoff) + ldsw + _i * 8192), 16, 0, 0); } while (0)
; #define PG8_LDA(dst, b, h) do { _Pragma("unroll") for (int m = 0; m < 4; ++m) _Pragma("unroll") for (int k = 0; k < 2; ++k) dst[m][k] = *(const LAS bf16x8*)(lds + PG8_SA(b, h) + aoff + m * 2048 + k * 1024); } while (0)
; #define PG8_LDB(dst, b, h) do { _Pragma("unroll") for (int n = 0; n < 2; ++n) _Pragma("unroll") for (int k = 0; k < 2; ++k) dst[n][k] = *(const LAS bf16x8*)(lds + PG8_SB(b, h) + boff + n * 2048 + k * 1024); } while (0)
; #define PG8_MMA(ai, bj, At, Bt) do { __builtin_amdgcn_s_setprio(1); _Pragma("unroll") for (int m = 0; m < 4; ++m) _Pragma("unroll") for (int n = 0; n < 2; ++n) _Pragma("unroll") for (int k = 0; k < 2; ++k) \
;         acc[ai][bj][m][n] = __builtin_amdgcn_mfma_f32_16x16x32_bf16(Bt[n][k], At[m][k], acc[ai][bj][m][n], 0, 0, 0); __builtin_amdgcn_s_setprio(0); } while (0)
; #define PG8_WAIT_V(n) asm volatile("s_waitcnt vmcnt(" #n ")" ::: "memory")
; #define PG8_WAIT_L(n) asm volatile("s_waitcnt lgkmcnt(" #n ")" ::: "memory")
; #define PG8_BAR __builtin_amdgcn_s_barrier()
; #define PG8_SCHED __builtin_amdgcn_sched_barrier(0)
; template <class Epi, class S_t>
; __device__ __forceinline__ void gemm_phase(LAS unsigned char* lds, int lda, int ldb, const S_t& S, const Epi& E) {
;     ...
;             PG8_STAGE(PG8_SB(0, 1), b2 + hstepB, voffB);
;             PG8_WAIT_V(6); PG8_BAR; PG8_MMA(1, 1, At, B1); PG8_BAR;
;             PG8_LDB(B0, 1, 0); PG8_SCHED; PG8_LDA(At, 1, 0); PG8_STAGE(PG8_SA(0, 1), a2 + hstepA, voffA);
;             PG8_WAIT_L(8); PG8_BAR; PG8_WAIT_L(0); PG8_MMA(0, 0, At, B0); PG8_BAR; PG8_SCHED;
;             PG8_LDB(B1, 1, 1); PG8_STAGE(PG8_SB(1, 0), b3, voffB);
;             PG8_BAR; PG8_WAIT_L(0); PG8_MMA(0, 1, At, B1); PG8_BAR;
;             PG8_LDA(At, 1, 1); PG8_STAGE(PG8_SA(1, 0), a3, voffA);
;             PG8_BAR; PG8_WAIT_L(0); PG8_MMA(1, 0, At, B0); PG8_BAR; PG8_SCHED;
	s_mov_b32 m0, s94
	global_load_lds_dwordx4 v148, s[72:73]
	s_mov_b32 m0, s93
	s_nop 0
	global_load_lds_dwordx4 v144, s[72:73]
	s_waitcnt vmcnt(6)
	s_barrier
	s_setprio 1
	v_mfma_f32_16x16x32_bf16 v[52:55], v[198:201], v[154:157], v[52:55]
	v_mfma_f32_16x16x32_bf16 v[44:47], v[206:209], v[154:157], v[44:47]
	v_mfma_f32_16x16x32_bf16 v[36:39], v[198:201], v[170:173], v[36:39]
	v_mfma_f32_16x16x32_bf16 v[28:31], v[206:209], v[170:173], v[28:31]
	v_mfma_f32_16x16x32_bf16 v[20:23], v[198:201], v[178:181], v[20:23]
	v_mfma_f32_16x16x32_bf16 v[12:15], v[206:209], v[178:181], v[12:15]
	v_mfma_f32_16x16x32_bf16 v[4:7], v[198:201], v[190:193], v[4:7]
	v_mfma_f32_16x16x32_bf16 v[0:3], v[206:209], v[190:193], v[0:3]
	v_mfma_f32_16x16x32_bf16 v[52:55], v[202:205], v[166:169], v[52:55]
	v_mfma_f32_16x16x32_bf16 v[44:47], v[222:225], v[166:169], v[44:47]
	v_mfma_f32_16x16x32_bf16 v[36:39], v[202:205], v[174:177], v[36:39]
	v_mfma_f32_16x16x32_bf16 v[28:31], v[222:225], v[174:177], v[28:31]
	v_mfma_f32_16x16x32_bf16 v[20:23], v[202:205], v[186:189], v[20:23]
	v_mfma_f32_16x16x32_bf16 v[12:15], v[222:225], v[186:189], v[12:15]
	v_mfma_f32_16x16x32_bf16 v[4:7], v[202:205], v[194:197], v[4:7]
	v_mfma_f32_16x16x32_bf16 v[0:3], v[222:225], v[194:197], v[0:3]
	s_setprio 0
	v_add_u32_e32 v140, s43, v161
	s_barrier
	ds_read_b128 v[128:131], v140
	ds_read_b128 v[132:135], v140 offset:1024
	ds_read_b128 v[136:139], v140 offset:2048
	ds_read_b128 v[140:143], v140 offset:3072
	s_mov_b32 m0, s52
	ds_read_b128 v[154:157], v164 offset:32768
	ds_read_b128 v[166:169], v164 offset:33792
	ds_read_b128 v[170:173], v164 offset:34816
	ds_read_b128 v[174:177], v164 offset:35840
	ds_read_b128 v[178:181], v164 offset:36864
	ds_read_b128 v[186:189], v164 offset:37888
	ds_read_b128 v[190:193], v164 offset:38912
	ds_read_b128 v[194:197], v164 offset:39936
	global_load_lds_dwordx4 v150, s[70:71]
	s_mov_b32 m0, s53
	s_nop 0
	global_load_lds_dwordx4 v146, s[70:71]
	s_waitcnt lgkmcnt(8)
	s_barrier
	s_waitcnt lgkmcnt(0)
	s_setprio 1
	v_mfma_f32_16x16x32_bf16 v[124:127], v[128:131], v[154:157], v[124:127]
	v_mfma_f32_16x16x32_bf16 v[120:123], v[136:139], v[154:157], v[120:123]
	v_mfma_f32_16x16x32_bf16 v[116:119], v[128:131], v[170:173], v[116:119]
	v_mfma_f32_16x16x32_bf16 v[112:115], v[136:139], v[170:173], v[112:115]
	v_mfma_f32_16x16x32_bf16 v[108:111], v[128:131], v[178:181], v[108:111]
	v_mfma_f32_16x16x32_bf16 v[100:103], v[136:139], v[178:181], v[100:103]
	v_mfma_f32_16x16x32_bf16 v[76:79], v[128:131], v[190:193], v[76:79]
	v_mfma_f32_16x16x32_bf16 v[72:75], v[136:139], v[190:193], v[72:75]
	v_mfma_f32_16x16x32_bf16 v[124:127], v[132:135], v[166:169], v[124:127]
	v_mfma_f32_16x16x32_bf16 v[120:123], v[140:143], v[166:169], v[120:123]
	v_mfma_f32_16x16x32_bf16 v[116:119], v[132:135], v[174:177], v[116:119]
	v_mfma_f32_16x16x32_bf16 v[112:115], v[140:143], v[174:177], v[112:115]
	v_mfma_f32_16x16x32_bf16 v[108:111], v[132:135], v[186:189], v[108:111]
	v_mfma_f32_16x16x32_bf16 v[100:103], v[140:143], v[186:189], v[100:103]
	v_mfma_f32_16x16x32_bf16 v[76:79], v[132:135], v[194:197], v[76:79]
	v_mfma_f32_16x16x32_bf16 v[72:75], v[140:143], v[194:197], v[72:75]
	s_setprio 0
	s_barrier
	s_mov_b32 m0, s42
	v_add_u32_e32 v215, s15, v161
	ds_read_b128 v[198:201], v215
	ds_read_b128 v[202:205], v215 offset:1024
	ds_read_b128 v[206:209], v215 offset:2048
	ds_read_b128 v[222:225], v215 offset:3072
	global_load_lds_dwordx4 v148, s[100:101]
	s_mov_b32 m0, s13
	s_nop 0
	global_load_lds_dwordx4 v144, s[100:101]
	s_barrier
	s_waitcnt lgkmcnt(0)
	s_setprio 1
	v_mfma_f32_16x16x32_bf16 v[104:107], v[198:201], v[154:157], v[104:107]
	v_mfma_f32_16x16x32_bf16 v[96:99], v[206:209], v[154:157], v[96:99]
	v_mfma_f32_16x16x32_bf16 v[92:95], v[198:201], v[170:173], v[92:95]
	v_mfma_f32_16x16x32_bf16 v[88:91], v[206:209], v[170:173], v[88:91]
	v_mfma_f32_16x16x32_bf16 v[84:87], v[198:201], v[178:181], v[84:87]
	v_mfma_f32_16x16x32_bf16 v[80:83], v[206:209], v[178:181], v[80:83]
	v_mfma_f32_16x16x32_bf16 v[68:71], v[198:201], v[190:193], v[68:71]
	v_mfma_f32_16x16x32_bf16 v[64:67], v[206:209], v[190:193], v[64:67]
	v_mfma_f32_16x16x32_bf16 v[104:107], v[202:205], v[166:169], v[104:107]
	v_mfma_f32_16x16x32_bf16 v[96:99], v[222:225], v[166:169], v[96:99]
	v_mfma_f32_16x16x32_bf16 v[92:95], v[202:205], v[174:177], v[92:95]
	v_mfma_f32_16x16x32_bf16 v[88:91], v[222:225], v[174:177], v[88:91]
	v_mfma_f32_16x16x32_bf16 v[84:87], v[202:205], v[186:189], v[84:87]
	v_mfma_f32_16x16x32_bf16 v[80:83], v[222:225], v[186:189], v[80:83]
	v_mfma_f32_16x16x32_bf16 v[68:71], v[202:205], v[194:197], v[68:71]
	v_mfma_f32_16x16x32_bf16 v[64:67], v[222:225], v[194:197], v[64:67]
	s_setprio 0
	s_mov_b32 m0, s64
	s_barrier
	ds_read_b128 v[154:157], v164 offset:49152
	ds_read_b128 v[166:169], v164 offset:50176
	ds_read_b128 v[170:173], v164 offset:51200
	ds_read_b128 v[174:177], v164 offset:52224
	ds_read_b128 v[178:181], v164 offset:53248
	ds_read_b128 v[186:189], v164 offset:54272
	ds_read_b128 v[190:193], v164 offset:55296
	ds_read_b128 v[194:197], v164 offset:56320
	global_load_lds_dwordx4 v150, s[98:99]
	s_mov_b32 m0, s65
	s_nop 0
	global_load_lds_dwordx4 v146, s[98:99]
	s_barrier
; #define PG8_STAGE(bufoff, gbase, voff) do { _Pragma("unroll") for (int _i = 0; _i < 2; ++_i) \
;         __builtin_amdgcn_global_load_lds((const unsigned*)((const char*)(gbase) + (voff)[_i]), (LAS unsigned*)(lds + (bufoff) + ldsw + _i * 8192), 16, 0, 0); } while (0)
; #define PG8_LDA(dst, b, h) do { _Pragma("unroll") for (int m = 0; m < 4; ++m) _Pragma("unroll") for (int k = 0; k < 2; ++k) dst[m][k] = *(const LAS bf16x8*)(lds + PG8_SA(b, h) + aoff + m * 2048 + k * 1024); } while (0)
; #define PG8_MMA(ai, bj, At, Bt) do { __builtin_amdgcn_s_setprio(1); _Pragma("unroll") for (int m = 0; m < 4; ++m) _Pragma("unroll") for (int n = 0; n < 2; ++n) _Pragma("unroll") for (int k = 0; k < 2; ++k) \
;         acc[ai][bj][m][n] = __builtin_amdgcn_mfma_f32_16x16x32_bf16(Bt[n][k], At[m][k], acc[ai][bj][m][n], 0, 0, 0); __builtin_amdgcn_s_setprio(0); } while (0)
; #define PG8_WAIT_V(n) asm volatile("s_waitcnt vmcnt(" #n ")" ::: "memory")
; #define PG8_WAIT_L(n) asm volatile("s_waitcnt lgkmcnt(" #n ")" ::: "memory")
; #define PG8_BAR __builtin_amdgcn_s_barrier()
; #define PG8_SCHED __builtin_amdgcn_sched_barrier(0)
; template <class Epi, class S_t>
; __device__ __forceinline__ void gemm_phase(LAS unsigned char* lds, int lda, int ldb, const S_t& S, const Epi& E) {
;     ...
;             PG8_LDA(At, 1, 1); PG8_STAGE(PG8_SA(1, 0), a3, voffA);
;             PG8_BAR; PG8_WAIT_L(0); PG8_MMA(1, 0, At, B0); PG8_BAR; PG8_SCHED;
;             PG8_STAGE(PG8_SB(1, 1), b3 + hstepB, voffB);
;             PG8_WAIT_V(6); PG8_BAR; PG8_MMA(1, 1, At, B1); PG8_BAR;
;     __device__ __forceinline__ void operator()(const f32x4 (&acc)[2][2][4][2], const Unit& u, int wr, int wc, int fr, int fq) const {
;         const int row0 = u.pm * BM + wr * 64 + fr, col0 = u.pn * BM + wc * 32 + 8 * fq;
;         f32x4 sv[2][2];
; #pragma unroll
;         for (int bj = 0; bj < 2; ++bj)
; #pragma unroll
;             for (int n = 0; n < 2; ++n) sv[bj][n] = *(const f32x4*)(scale + col0 + bj * HALF + 4 * n);
	s_waitcnt lgkmcnt(0)
	s_setprio 1
	v_mfma_f32_16x16x32_bf16 v[60:63], v[128:131], v[154:157], v[60:63]
	v_mfma_f32_16x16x32_bf16 v[56:59], v[136:139], v[154:157], v[56:59]
	v_mfma_f32_16x16x32_bf16 v[48:51], v[128:131], v[170:173], v[48:51]
	v_mfma_f32_16x16x32_bf16 v[40:43], v[136:139], v[170:173], v[40:43]
	v_mfma_f32_16x16x32_bf16 v[32:35], v[128:131], v[178:181], v[32:35]
	v_mfma_f32_16x16x32_bf16 v[24:27], v[136:139], v[178:181], v[24:27]
	v_mfma_f32_16x16x32_bf16 v[16:19], v[128:131], v[190:193], v[16:19]
	v_mfma_f32_16x16x32_bf16 v[8:11], v[136:139], v[190:193], v[8:11]
	v_mfma_f32_16x16x32_bf16 v[60:63], v[132:135], v[166:169], v[60:63]
	v_mfma_f32_16x16x32_bf16 v[56:59], v[140:143], v[166:169], v[56:59]
	v_mfma_f32_16x16x32_bf16 v[48:51], v[132:135], v[174:177], v[48:51]
	v_mfma_f32_16x16x32_bf16 v[40:43], v[140:143], v[174:177], v[40:43]
	v_mfma_f32_16x16x32_bf16 v[32:35], v[132:135], v[186:189], v[32:35]
	v_mfma_f32_16x16x32_bf16 v[24:27], v[140:143], v[186:189], v[24:27]
	v_mfma_f32_16x16x32_bf16 v[16:19], v[132:135], v[194:197], v[16:19]
	v_mfma_f32_16x16x32_bf16 v[8:11], v[140:143], v[194:197], v[8:11]
	s_setprio 0
	s_barrier
	s_mov_b32 m0, s1
	global_load_lds_dwordx4 v148, s[66:67]
	s_mov_b32 m0, s0
	s_nop 0
	global_load_lds_dwordx4 v144, s[66:67]
	s_waitcnt vmcnt(6)
	s_barrier
	s_setprio 1
	v_mfma_f32_16x16x32_bf16 v[52:55], v[198:201], v[154:157], v[52:55]
	v_mfma_f32_16x16x32_bf16 v[44:47], v[206:209], v[154:157], v[44:47]
	v_mfma_f32_16x16x32_bf16 v[36:39], v[198:201], v[170:173], v[36:39]
	v_mfma_f32_16x16x32_bf16 v[28:31], v[206:209], v[170:173], v[28:31]
	v_mfma_f32_16x16x32_bf16 v[20:23], v[198:201], v[178:181], v[20:23]
	v_mfma_f32_16x16x32_bf16 v[12:15], v[206:209], v[178:181], v[12:15]
	v_mfma_f32_16x16x32_bf16 v[4:7], v[198:201], v[190:193], v[4:7]
	v_mfma_f32_16x16x32_bf16 v[0:3], v[206:209], v[190:193], v[0:3]
	v_mfma_f32_16x16x32_bf16 v[52:55], v[202:205], v[166:169], v[52:55]
	v_mfma_f32_16x16x32_bf16 v[44:47], v[222:225], v[166:169], v[44:47]
	v_mfma_f32_16x16x32_bf16 v[36:39], v[202:205], v[174:177], v[36:39]
	v_mfma_f32_16x16x32_bf16 v[28:31], v[222:225], v[174:177], v[28:31]
	v_mfma_f32_16x16x32_bf16 v[20:23], v[202:205], v[186:189], v[20:23]
	v_mfma_f32_16x16x32_bf16 v[12:15], v[222:225], v[186:189], v[12:15]
	v_mfma_f32_16x16x32_bf16 v[4:7], v[202:205], v[194:197], v[4:7]
	v_mfma_f32_16x16x32_bf16 v[0:3], v[222:225], v[194:197], v[0:3]
	s_setprio 0
	s_movk_i32 s0, 0x100
	s_andn2_b64 vcc, exec, s[62:63]
	s_mov_b64 s[66:67], -1
	s_mov_b64 s[62:63], 0
	s_barrier
	s_cbranch_vccz .LBB0_535
	v_lshl_or_b32 v154, s92, 8, v162
	v_readlane_b32 s68, v254, 49
	v_ashrrev_i32_e32 v155, 31, v154
	v_readlane_b32 s69, v254, 50
	v_lshl_add_u32 v156, s56, 8, v160
	v_ashrrev_i32_e32 v157, 31, v156
	v_lshl_add_u64 v[128:129], v[154:155], 2, s[68:69]
	global_load_dwordx4 v[140:143], v[128:129], off
	global_load_dwordx4 v[136:139], v[128:129], off offset:16
	global_load_dwordx4 v[132:135], v[128:129], off offset:512
	s_nop 0
	global_load_dwordx4 v[128:131], v[128:129], off offset:528
	v_or_b32_e32 v158, 16, v156
	v_or_b32_e32 v166, 32, v156
	v_or_b32_e32 v168, 48, v156
	v_lshlrev_b64 v[156:157], 11, v[156:157]
	v_ashrrev_i32_e32 v159, 31, v158
	v_ashrrev_i32_e32 v167, 31, v166
	v_ashrrev_i32_e32 v169, 31, v168
	v_lshlrev_b64 v[170:171], 1, v[154:155]
	v_lshl_add_u64 v[154:155], s[46:47], 0, v[156:157]
	v_lshlrev_b64 v[156:157], 11, v[158:159]
	v_lshlrev_b64 v[158:159], 11, v[166:167]
	v_lshlrev_b64 v[166:167], 11, v[168:169]
	v_lshl_add_u64 v[154:155], v[154:155], 0, v[170:171]
	v_lshl_add_u64 v[156:157], s[46:47], 0, v[156:157]
	v_lshl_add_u64 v[158:159], s[46:47], 0, v[158:159]
	v_lshl_add_u64 v[166:167], s[46:47], 0, v[166:167]
	v_lshl_add_u64 v[168:169], v[156:157], 0, v[170:171]
	v_lshl_add_u64 v[158:159], v[158:159], 0, v[170:171]
	v_lshl_add_u64 v[156:157], v[166:167], 0, v[170:171]
	s_mov_b64 s[0:1], 0x40000
	s_mov_b32 s92, s12
	s_mov_b32 s56, s14
	s_mov_b64 s[60:61], s[44:45]
	s_mov_b64 s[58:59], s[18:19]
	v_readlane_b32 s70, v254, 51
	v_readlane_b32 s71, v254, 52
	v_readlane_b32 s72, v254, 53
	v_readlane_b32 s73, v254, 54
	v_readlane_b32 s74, v254, 55
	v_readlane_b32 s75, v254, 56
	v_readlane_b32 s76, v254, 57
	v_readlane_b32 s77, v254, 58
	v_readlane_b32 s78, v254, 59
	v_readlane_b32 s79, v254, 60
	v_readlane_b32 s80, v254, 61
	v_readlane_b32 s81, v254, 62
	v_readlane_b32 s82, v254, 63
	v_readlane_b32 s83, v255, 0
	s_waitcnt vmcnt(0)
; __device__ __forceinline__ unsigned pk2(float lo, float hi) { unsigned r; asm("v_cvt_pk_bf16_f32 %0, %1, %2" : "=v"(r) : "v"(lo), "v"(hi)); return r; }
; #define PG8_WAIT_V(n) asm volatile("s_waitcnt vmcnt(" #n ")" ::: "memory")
; #define PG8_BAR __builtin_amdgcn_s_barrier()
; template <class Epi, class S_t>
; __device__ __forceinline__ void gemm_phase(LAS unsigned char* lds, int lda, int ldb, const S_t& S, const Epi& E) {
;     ...
;     PG8_WAIT_V(0);
;     if (wr == 0) PG8_BAR;
;     __device__ __forceinline__ void operator()(const f32x4 (&acc)[2][2][4][2], const Unit& u, int wr, int wc, int fr, int fq) const {
;     ...
; #pragma unroll
;         for (int ai = 0; ai < 2; ++ai)
; #pragma unroll
;             for (int m = 0; m < 4; ++m) { bf16_t* rowp = O + (size_t)(row0 + ai * HALF + m * 16) * PW + col0;
; #pragma unroll
;                 for (int bj = 0; bj < 2; ++bj) { const f32x4 v0 = acc[ai][bj][m][0] * sv[bj][0], v1 = acc[ai][bj][m][1] * sv[bj][1];
;                     u32x4 w; w.x = pk2(v0[0], v0[1]); w.y = pk2(v0[2], v0[3]); w.z = pk2(v1[0], v1[1]); w.w = pk2(v1[2], v1[3]);
;                     *(u32x4*)(rowp + bj * HALF) = w; } }
	v_pk_mul_f32 v[126:127], v[126:127], v[142:143]
	v_pk_mul_f32 v[124:125], v[124:125], v[140:141]
	v_pk_mul_f32 v[122:123], v[122:123], v[138:139]
	v_pk_mul_f32 v[120:121], v[120:121], v[136:137]
	v_pk_mul_f32 v[94:95], v[94:95], v[134:135]
	v_pk_mul_f32 v[92:93], v[92:93], v[132:133]
	v_pk_mul_f32 v[90:91], v[90:91], v[130:131]
	v_pk_mul_f32 v[88:89], v[88:89], v[128:129]
	v_pk_mul_f32 v[180:181], v[74:75], v[138:139]
	v_pk_mul_f32 v[182:183], v[72:73], v[136:137]
	v_cvt_pk_bf16_f32 v72, v124, v125
	v_cvt_pk_bf16_f32 v73, v126, v127
	v_cvt_pk_bf16_f32 v74, v120, v121
	v_cvt_pk_bf16_f32 v75, v122, v123
	v_pk_mul_f32 v[106:107], v[106:107], v[134:135]
	v_pk_mul_f32 v[104:105], v[104:105], v[132:133]
	v_pk_mul_f32 v[98:99], v[98:99], v[130:131]
	v_pk_mul_f32 v[96:97], v[96:97], v[128:129]
	v_pk_mul_f32 v[118:119], v[118:119], v[142:143]
	v_pk_mul_f32 v[116:117], v[116:117], v[140:141]
	v_pk_mul_f32 v[114:115], v[114:115], v[138:139]
	v_pk_mul_f32 v[112:113], v[112:113], v[136:137]
	v_pk_mul_f32 v[110:111], v[110:111], v[142:143]
	v_pk_mul_f32 v[108:109], v[108:109], v[140:141]
	v_pk_mul_f32 v[102:103], v[102:103], v[138:139]
	v_pk_mul_f32 v[100:101], v[100:101], v[136:137]
	v_pk_mul_f32 v[166:167], v[86:87], v[134:135]
	v_pk_mul_f32 v[170:171], v[84:85], v[132:133]
	v_pk_mul_f32 v[172:173], v[82:83], v[130:131]
	v_pk_mul_f32 v[174:175], v[80:81], v[128:129]
	v_pk_mul_f32 v[176:177], v[78:79], v[142:143]
	v_pk_mul_f32 v[178:179], v[76:77], v[140:141]
	v_cvt_pk_bf16_f32 v76, v104, v105
	v_cvt_pk_bf16_f32 v77, v106, v107
	v_cvt_pk_bf16_f32 v78, v96, v97
	v_cvt_pk_bf16_f32 v79, v98, v99
	v_cvt_pk_bf16_f32 v80, v116, v117
	v_cvt_pk_bf16_f32 v81, v118, v119
	v_cvt_pk_bf16_f32 v82, v112, v113
	v_cvt_pk_bf16_f32 v83, v114, v115
	v_cvt_pk_bf16_f32 v84, v92, v93
	v_cvt_pk_bf16_f32 v85, v94, v95
	v_cvt_pk_bf16_f32 v86, v88, v89
	v_cvt_pk_bf16_f32 v87, v90, v91
	v_cvt_pk_bf16_f32 v88, v108, v109
	v_cvt_pk_bf16_f32 v89, v110, v111
	v_cvt_pk_bf16_f32 v90, v100, v101
	v_cvt_pk_bf16_f32 v91, v102, v103
	v_cvt_pk_bf16_f32 v92, v170, v171
	v_cvt_pk_bf16_f32 v93, v166, v167
	v_cvt_pk_bf16_f32 v94, v174, v175
	v_cvt_pk_bf16_f32 v95, v172, v173
	global_store_dwordx4 v[154:155], v[72:75], off
	global_store_dwordx4 v[154:155], v[76:79], off offset:256
	global_store_dwordx4 v[168:169], v[80:83], off
	global_store_dwordx4 v[168:169], v[84:87], off offset:256
	global_store_dwordx4 v[158:159], v[88:91], off
	global_store_dwordx4 v[158:159], v[92:95], off offset:256
	v_cvt_pk_bf16_f32 v72, v178, v179
	v_cvt_pk_bf16_f32 v73, v176, v177
	v_cvt_pk_bf16_f32 v74, v182, v183
	v_cvt_pk_bf16_f32 v75, v180, v181
	global_store_dwordx4 v[156:157], v[72:75], off
	v_pk_mul_f32 v[70:71], v[70:71], v[134:135]
	v_pk_mul_f32 v[68:69], v[68:69], v[132:133]
	v_pk_mul_f32 v[72:73], v[66:67], v[130:131]
	v_pk_mul_f32 v[66:67], v[64:65], v[128:129]
	v_cvt_pk_bf16_f32 v64, v68, v69
	v_cvt_pk_bf16_f32 v65, v70, v71
	v_pk_mul_f32 v[60:61], v[60:61], v[140:141]
	v_cvt_pk_bf16_f32 v66, v66, v67
	v_cvt_pk_bf16_f32 v67, v72, v73
	global_store_dwordx4 v[156:157], v[64:67], off offset:256
	v_pk_mul_f32 v[62:63], v[62:63], v[142:143]
	v_pk_mul_f32 v[54:55], v[54:55], v[134:135]
	v_lshl_add_u64 v[64:65], v[154:155], 0, s[0:1]
	s_mov_b32 s0, 0x40000
	v_pk_mul_f32 v[66:67], v[58:59], v[138:139]
	v_pk_mul_f32 v[58:59], v[56:57], v[136:137]
	v_cvt_pk_bf16_f32 v56, v60, v61
	v_add_co_u32_e32 v60, vcc, s0, v154
	v_cvt_pk_bf16_f32 v57, v62, v63
	v_cvt_pk_bf16_f32 v58, v58, v59
	v_cvt_pk_bf16_f32 v59, v66, v67
	v_pk_mul_f32 v[52:53], v[52:53], v[132:133]
	s_nop 0
	v_addc_co_u32_e32 v61, vcc, 0, v155, vcc
	global_store_dwordx4 v[60:61], v[56:59], off
	s_mov_b64 s[0:1], 0x48000
	v_pk_mul_f32 v[48:49], v[48:49], v[140:141]
	v_pk_mul_f32 v[56:57], v[46:47], v[130:131]
	v_pk_mul_f32 v[46:47], v[44:45], v[128:129]
	v_cvt_pk_bf16_f32 v44, v52, v53
	v_cvt_pk_bf16_f32 v45, v54, v55
	v_pk_mul_f32 v[38:39], v[38:39], v[134:135]
	v_cvt_pk_bf16_f32 v46, v46, v47
	v_cvt_pk_bf16_f32 v47, v56, v57
	global_store_dwordx4 v[64:65], v[44:47], off offset:256
	v_pk_mul_f32 v[36:37], v[36:37], v[132:133]
	v_pk_mul_f32 v[32:33], v[32:33], v[140:141]
	v_lshl_add_u64 v[44:45], v[154:155], 0, s[0:1]
	v_pk_mul_f32 v[46:47], v[50:51], v[142:143]
	s_mov_b32 s0, 0x48000
	v_pk_mul_f32 v[50:51], v[42:43], v[138:139]
	v_pk_mul_f32 v[42:43], v[40:41], v[136:137]
	v_cvt_pk_bf16_f32 v41, v46, v47
	v_add_co_u32_e32 v46, vcc, s0, v154
	v_cvt_pk_bf16_f32 v40, v48, v49
	v_cvt_pk_bf16_f32 v42, v42, v43
	v_cvt_pk_bf16_f32 v43, v50, v51
	s_mov_b64 s[0:1], 0x50000
	s_nop 0
	v_addc_co_u32_e32 v47, vcc, 0, v155, vcc
	global_store_dwordx4 v[46:47], v[40:43], off
	v_pk_mul_f32 v[22:23], v[22:23], v[134:135]
	v_pk_mul_f32 v[20:21], v[20:21], v[132:133]
	v_pk_mul_f32 v[40:41], v[30:31], v[130:131]
	v_pk_mul_f32 v[30:31], v[28:29], v[128:129]
	v_cvt_pk_bf16_f32 v28, v36, v37
	v_cvt_pk_bf16_f32 v29, v38, v39
	v_pk_mul_f32 v[16:17], v[16:17], v[140:141]
	v_cvt_pk_bf16_f32 v30, v30, v31
	v_cvt_pk_bf16_f32 v31, v40, v41
	global_store_dwordx4 v[44:45], v[28:31], off offset:256
	v_pk_mul_f32 v[6:7], v[6:7], v[134:135]
	v_pk_mul_f32 v[4:5], v[4:5], v[132:133]
	v_lshl_add_u64 v[28:29], v[154:155], 0, s[0:1]
	v_pk_mul_f32 v[30:31], v[34:35], v[142:143]
	s_mov_b32 s0, 0x50000
	v_pk_mul_f32 v[34:35], v[26:27], v[138:139]
	v_pk_mul_f32 v[26:27], v[24:25], v[136:137]
	v_cvt_pk_bf16_f32 v25, v30, v31
	v_add_co_u32_e32 v30, vcc, s0, v154
	v_cvt_pk_bf16_f32 v24, v32, v33
	v_cvt_pk_bf16_f32 v26, v26, v27
	v_cvt_pk_bf16_f32 v27, v34, v35
	s_mov_b64 s[0:1], 0x58000
	s_nop 0
	v_addc_co_u32_e32 v31, vcc, 0, v155, vcc
	global_store_dwordx4 v[30:31], v[24:27], off
	s_nop 1
	v_pk_mul_f32 v[24:25], v[14:15], v[130:131]
	v_pk_mul_f32 v[14:15], v[12:13], v[128:129]
	v_cvt_pk_bf16_f32 v12, v20, v21
	v_cvt_pk_bf16_f32 v13, v22, v23
	s_nop 0
	v_cvt_pk_bf16_f32 v14, v14, v15
	v_cvt_pk_bf16_f32 v15, v24, v25
	global_store_dwordx4 v[28:29], v[12:15], off offset:256
	s_nop 1
	v_lshl_add_u64 v[12:13], v[154:155], 0, s[0:1]
	v_pk_mul_f32 v[14:15], v[18:19], v[142:143]
	s_mov_b32 s0, 0x58000
	v_pk_mul_f32 v[18:19], v[10:11], v[138:139]
	v_pk_mul_f32 v[10:11], v[8:9], v[136:137]
	v_cvt_pk_bf16_f32 v9, v14, v15
	v_add_co_u32_e32 v14, vcc, s0, v154
	v_cvt_pk_bf16_f32 v8, v16, v17
	v_cvt_pk_bf16_f32 v10, v10, v11
	v_cvt_pk_bf16_f32 v11, v18, v19
	s_nop 1
	v_addc_co_u32_e32 v15, vcc, 0, v155, vcc
	global_store_dwordx4 v[14:15], v[8:11], off
	s_and_b64 vcc, exec, s[6:7]
	s_nop 0
	v_pk_mul_f32 v[8:9], v[2:3], v[130:131]
	v_pk_mul_f32 v[2:3], v[0:1], v[128:129]
	v_cvt_pk_bf16_f32 v0, v4, v5
	v_cvt_pk_bf16_f32 v1, v6, v7
	s_nop 0
	v_cvt_pk_bf16_f32 v2, v2, v3
	v_cvt_pk_bf16_f32 v3, v8, v9
	global_store_dwordx4 v[12:13], v[0:3], off offset:256
	s_cbranch_vccz .LBB0_532
	s_waitcnt vmcnt(0)
	s_cmpk_gt_u32 s4, 0xff
	s_cbranch_scc1 .LBB0_539
	s_barrier

; #define PG8_STAGE(bufoff, gbase, voff) do { _Pragma("unroll") for (int _i = 0; _i < 2; ++_i) \
;         __builtin_amdgcn_global_load_lds((const unsigned*)((const char*)(gbase) + (voff)[_i]), (LAS unsigned*)(lds + (bufoff) + ldsw + _i * 8192), 16, 0, 0); } while (0)
; #define PG8_LDA(dst, b, h) do { _Pragma("unroll") for (int m = 0; m < 4; ++m) _Pragma("unroll") for (int k = 0; k < 2; ++k) dst[m][k] = *(const LAS bf16x8*)(lds + PG8_SA(b, h) + aoff + m * 2048 + k * 1024); } while (0)
; #define PG8_LDB(dst, b, h) do { _Pragma("unroll") for (int n = 0; n < 2; ++n) _Pragma("unroll") for (int k = 0; k < 2; ++k) dst[n][k] = *(const LAS bf16x8*)(lds + PG8_SB(b, h) + boff + n * 2048 + k * 1024); } while (0)
; #define PG8_MMA(ai, bj, At, Bt) do { __builtin_amdgcn_s_setprio(1); _Pragma("unroll") for (int m = 0; m < 4; ++m) _Pragma("unroll") for (int n = 0; n < 2; ++n) _Pragma("unroll") for (int k = 0; k < 2; ++k) \
;         acc[ai][bj][m][n] = __builtin_amdgcn_mfma_f32_16x16x32_bf16(Bt[n][k], At[m][k], acc[ai][bj][m][n], 0, 0, 0); __builtin_amdgcn_s_setprio(0); } while (0)
; #define PG8_WAIT_L(n) asm volatile("s_waitcnt lgkmcnt(" #n ")" ::: "memory")
; #define PG8_BAR __builtin_amdgcn_s_barrier()
; template <class Epi, class S_t>
; __device__ __forceinline__ void gemm_phase(LAS unsigned char* lds, int lda, int ldb, const S_t& S, const Epi& E) {
;     ...
;         const bool has_next = S.next(ui + 1, nxt);
;         const char* nA = has_next ? nxt.A : cA; const char* nB = has_next ? nxt.B : cB;
;         const int nt = cur.nt;
;         for (int t = 0; t < nt; t += 2) {
;             const bool last = (t == nt - 2);
;             const char* a1 = cA + (size_t)(t + 1) * kstep;
;             const char* a2 = last ? nA : cA + (size_t)(t + 2) * kstep; const char* b2 = last ? nB : cB + (size_t)(t + 2) * kstep;
;             const char* a3 = a2 + kstep; const char* b3 = b2 + kstep;
;             PG8_LDB(B0, 0, 0); PG8_SCHED; PG8_LDA(At, 0, 0); PG8_STAGE(PG8_SA(1, 1), a1 + hstepA, voffA);
;             PG8_WAIT_L(8); PG8_BAR; PG8_WAIT_L(0); PG8_MMA(0, 0, At, B0); PG8_BAR; PG8_SCHED;
;             PG8_LDB(B1, 0, 1); PG8_STAGE(PG8_SB(0, 0), b2, voffB);
;             PG8_BAR; PG8_WAIT_L(0); PG8_MMA(0, 1, At, B1); PG8_BAR;
;             PG8_LDA(At, 0, 1); PG8_STAGE(PG8_SA(0, 0), a2, voffA);
;             PG8_BAR; PG8_WAIT_L(0); PG8_MMA(1, 0, At, B0); PG8_BAR; PG8_SCHED;
.LBB0_547:
	s_add_u32 s15, s60, s0
	s_addc_u32 s19, s61, 0
	s_add_u32 s1, s15, 0x100
	s_addc_u32 s33, s19, 0
	s_and_b64 s[70:71], s[68:69], exec
	s_cselect_b32 s75, s57, s33
	s_cselect_b32 s74, s56, s1
	s_add_u32 s0, s62, s0
	s_addc_u32 s1, s63, 0
	s_add_u32 s33, s0, 0x100
	s_addc_u32 s43, s1, 0
	s_and_b64 s[0:1], s[68:69], exec
	s_cselect_b32 s79, s59, s43
	s_cselect_b32 s78, s58, s33
	s_add_u32 s82, s15, 0x80080
	s_addc_u32 s83, s19, 0
	s_add_i32 vcc_hi, s88, s64
	s_add_i32 m0, s53, 0xc000
	s_add_i32 s65, s53, 0xe000
	s_add_i32 s33, vcc_hi, 0x2000
	s_add_u32 s72, s78, 0x10000
	s_addc_u32 s73, s79, 0
	s_add_i32 vcc_lo, s89, s64
	s_add_i32 s43, vcc_lo, 0x2000
	s_add_i32 s90, 0, 0x18000
	ds_read_b128 v[32:35], v226
	ds_read_b128 v[36:39], v226 offset:1024
	ds_read_b128 v[48:51], v226 offset:2048
	ds_read_b128 v[52:55], v226 offset:3072
	s_add_u32 s70, s74, 0x80000
	s_addc_u32 s71, s75, 0
	s_add_i32 s19, s90, s64
	s_add_i32 s91, 0, 0x1c000
	s_add_i32 s15, s19, 0x2000
	s_add_u32 s68, s78, 0x10080
	s_addc_u32 s69, s79, 0
	s_add_i32 s1, s91, s64
	s_add_i32 s0, s1, 0x2000
	ds_read_b128 v[56:59], v227
	ds_read_b128 v[64:67], v227 offset:1024
	ds_read_b128 v[68:71], v227 offset:2048
	ds_read_b128 v[76:79], v227 offset:3072
	ds_read_b128 v[96:99], v227 offset:4096
	ds_read_b128 v[116:119], v227 offset:5120
	ds_read_b128 v[136:139], v227 offset:6144
	ds_read_b128 v[156:159], v227 offset:7168
	global_load_lds_dwordx4 v186, s[82:83]
	s_mov_b32 m0, s65
	s_nop 0
	global_load_lds_dwordx4 v190, s[82:83]
	s_waitcnt lgkmcnt(8)
	s_barrier
	s_waitcnt lgkmcnt(0)
	s_setprio 1
	v_mfma_f32_16x16x32_bf16 v[172:175], v[32:35], v[56:59], v[172:175]
	v_mfma_f32_16x16x32_bf16 v[168:171], v[48:51], v[56:59], v[168:171]
	v_mfma_f32_16x16x32_bf16 v[152:155], v[32:35], v[68:71], v[152:155]
	v_mfma_f32_16x16x32_bf16 v[148:151], v[48:51], v[68:71], v[148:151]
	v_mfma_f32_16x16x32_bf16 v[132:135], v[32:35], v[96:99], v[132:135]
	v_mfma_f32_16x16x32_bf16 v[128:131], v[48:51], v[96:99], v[128:131]
	v_mfma_f32_16x16x32_bf16 v[112:115], v[32:35], v[136:139], v[112:115]
	v_mfma_f32_16x16x32_bf16 v[108:111], v[48:51], v[136:139], v[108:111]
	v_mfma_f32_16x16x32_bf16 v[172:175], v[36:39], v[64:67], v[172:175]
	v_mfma_f32_16x16x32_bf16 v[168:171], v[52:55], v[64:67], v[168:171]
	v_mfma_f32_16x16x32_bf16 v[152:155], v[36:39], v[76:79], v[152:155]
	v_mfma_f32_16x16x32_bf16 v[148:151], v[52:55], v[76:79], v[148:151]
	v_mfma_f32_16x16x32_bf16 v[132:135], v[36:39], v[116:119], v[132:135]
	v_mfma_f32_16x16x32_bf16 v[128:131], v[52:55], v[116:119], v[128:131]
	v_mfma_f32_16x16x32_bf16 v[112:115], v[36:39], v[156:159], v[112:115]
	v_mfma_f32_16x16x32_bf16 v[108:111], v[52:55], v[156:159], v[108:111]
	s_setprio 0
	s_barrier
	s_mov_b32 m0, vcc_hi
	s_add_u32 s100, s78, s12
	s_addc_u32 s101, s79, s13
	ds_read_b128 v[176:179], v228
	ds_read_b128 v[180:183], v228 offset:1024
	ds_read_b128 v[196:199], v228 offset:2048
	ds_read_b128 v[200:203], v228 offset:3072
	global_load_lds_dwordx4 v188, s[78:79]
	s_mov_b32 m0, s33
	s_nop 0
	global_load_lds_dwordx4 v192, s[78:79]
	s_barrier
	s_waitcnt lgkmcnt(0)
	s_setprio 1
	v_mfma_f32_16x16x32_bf16 v[160:163], v[176:179], v[56:59], v[160:163]
	v_mfma_f32_16x16x32_bf16 v[56:59], v[196:199], v[56:59], v[164:167]
	v_mfma_f32_16x16x32_bf16 v[160:163], v[180:183], v[64:67], v[160:163]
	v_mfma_f32_16x16x32_bf16 v[56:59], v[200:203], v[64:67], v[56:59]
	v_mfma_f32_16x16x32_bf16 v[64:67], v[176:179], v[68:71], v[140:143]
	v_mfma_f32_16x16x32_bf16 v[68:71], v[196:199], v[68:71], v[144:147]
	v_mfma_f32_16x16x32_bf16 v[100:103], v[176:179], v[136:139], v[100:103]
	v_mfma_f32_16x16x32_bf16 v[104:107], v[196:199], v[136:139], v[104:107]
	v_mfma_f32_16x16x32_bf16 v[64:67], v[180:183], v[76:79], v[64:67]
	v_mfma_f32_16x16x32_bf16 v[68:71], v[200:203], v[76:79], v[68:71]
	v_mfma_f32_16x16x32_bf16 v[76:79], v[176:179], v[96:99], v[120:123]
	v_mfma_f32_16x16x32_bf16 v[96:99], v[196:199], v[96:99], v[124:127]
	v_mfma_f32_16x16x32_bf16 v[100:103], v[180:183], v[156:159], v[100:103]
	v_mfma_f32_16x16x32_bf16 v[104:107], v[200:203], v[156:159], v[104:107]
	v_mfma_f32_16x16x32_bf16 v[76:79], v[180:183], v[116:119], v[76:79]
	v_mfma_f32_16x16x32_bf16 v[96:99], v[200:203], v[116:119], v[96:99]
	s_setprio 0
	s_mov_b32 m0, s53
	s_add_u32 s98, s74, s12
	s_addc_u32 s99, s75, s13
	s_barrier
	ds_read_b128 v[116:119], v227 offset:16384
	ds_read_b128 v[120:123], v227 offset:17408
	ds_read_b128 v[124:127], v227 offset:18432
	ds_read_b128 v[136:139], v227 offset:19456
	ds_read_b128 v[140:143], v227 offset:20480
	ds_read_b128 v[144:147], v227 offset:21504
	ds_read_b128 v[156:159], v227 offset:22528
	ds_read_b128 v[164:167], v227 offset:23552
	global_load_lds_dwordx4 v186, s[74:75]
	s_mov_b32 m0, s95
	s_nop 0
	global_load_lds_dwordx4 v190, s[74:75]
	s_barrier
	s_waitcnt lgkmcnt(0)
	s_setprio 1
	v_mfma_f32_16x16x32_bf16 v[92:95], v[32:35], v[116:119], v[92:95]
	v_mfma_f32_16x16x32_bf16 v[88:91], v[48:51], v[116:119], v[88:91]
	v_mfma_f32_16x16x32_bf16 v[72:75], v[32:35], v[124:127], v[72:75]
	v_mfma_f32_16x16x32_bf16 v[60:63], v[48:51], v[124:127], v[60:63]
	v_mfma_f32_16x16x32_bf16 v[28:31], v[32:35], v[140:143], v[28:31]
	v_mfma_f32_16x16x32_bf16 v[24:27], v[48:51], v[140:143], v[24:27]
	v_mfma_f32_16x16x32_bf16 v[12:15], v[32:35], v[156:159], v[12:15]
	v_mfma_f32_16x16x32_bf16 v[8:11], v[48:51], v[156:159], v[8:11]
	v_mfma_f32_16x16x32_bf16 v[92:95], v[36:39], v[120:123], v[92:95]
	v_mfma_f32_16x16x32_bf16 v[88:91], v[52:55], v[120:123], v[88:91]
	v_mfma_f32_16x16x32_bf16 v[72:75], v[36:39], v[136:139], v[72:75]
	v_mfma_f32_16x16x32_bf16 v[60:63], v[52:55], v[136:139], v[60:63]
	v_mfma_f32_16x16x32_bf16 v[28:31], v[36:39], v[144:147], v[28:31]
	v_mfma_f32_16x16x32_bf16 v[24:27], v[52:55], v[144:147], v[24:27]
	v_mfma_f32_16x16x32_bf16 v[12:15], v[36:39], v[164:167], v[12:15]
	v_mfma_f32_16x16x32_bf16 v[8:11], v[52:55], v[164:167], v[8:11]
	s_setprio 0
	s_barrier
; #define PG8_STAGE(bufoff, gbase, voff) do { _Pragma("unroll") for (int _i = 0; _i < 2; ++_i) \
;         __builtin_amdgcn_global_load_lds((const unsigned*)((const char*)(gbase) + (voff)[_i]), (LAS unsigned*)(lds + (bufoff) + ldsw + _i * 8192), 16, 0, 0); } while (0)
; #define PG8_LDA(dst, b, h) do { _Pragma("unroll") for (int m = 0; m < 4; ++m) _Pragma("unroll") for (int k = 0; k < 2; ++k) dst[m][k] = *(const LAS bf16x8*)(lds + PG8_SA(b, h) + aoff + m * 2048 + k * 1024); } while (0)
; #define PG8_LDB(dst, b, h) do { _Pragma("unroll") for (int n = 0; n < 2; ++n) _Pragma("unroll") for (int k = 0; k < 2; ++k) dst[n][k] = *(const LAS bf16x8*)(lds + PG8_SB(b, h) + boff + n * 2048 + k * 1024); } while (0)
; #define PG8_MMA(ai, bj, At, Bt) do { __builtin_amdgcn_s_setprio(1); _Pragma("unroll") for (int m = 0; m < 4; ++m) _Pragma("unroll") for (int n = 0; n < 2; ++n) _Pragma("unroll") for (int k = 0; k < 2; ++k) \
;         acc[ai][bj][m][n] = __builtin_amdgcn_mfma_f32_16x16x32_bf16(Bt[n][k], At[m][k], acc[ai][bj][m][n], 0, 0, 0); __builtin_amdgcn_s_setprio(0); } while (0)
; #define PG8_WAIT_V(n) asm volatile("s_waitcnt vmcnt(" #n ")" ::: "memory")
; #define PG8_WAIT_L(n) asm volatile("s_waitcnt lgkmcnt(" #n ")" ::: "memory")
; #define PG8_BAR __builtin_amdgcn_s_barrier()
; #define PG8_SCHED __builtin_amdgcn_sched_barrier(0)
; template <class Epi, class S_t>
; __device__ __forceinline__ void gemm_phase(LAS unsigned char* lds, int lda, int ldb, const S_t& S, const Epi& E) {
;     ...
;             PG8_STAGE(PG8_SB(0, 1), b2 + hstepB, voffB);
;             PG8_WAIT_V(6); PG8_BAR; PG8_MMA(1, 1, At, B1); PG8_BAR;
;             PG8_LDB(B0, 1, 0); PG8_SCHED; PG8_LDA(At, 1, 0); PG8_STAGE(PG8_SA(0, 1), a2 + hstepA, voffA);
;             PG8_WAIT_L(8); PG8_BAR; PG8_WAIT_L(0); PG8_MMA(0, 0, At, B0); PG8_BAR; PG8_SCHED;
;             PG8_LDB(B1, 1, 1); PG8_STAGE(PG8_SB(1, 0), b3, voffB);
;             PG8_BAR; PG8_WAIT_L(0); PG8_MMA(0, 1, At, B1); PG8_BAR;
;             PG8_LDA(At, 1, 1); PG8_STAGE(PG8_SA(1, 0), a3, voffA);
	s_mov_b32 m0, vcc_lo
	global_load_lds_dwordx4 v188, s[72:73]
	s_mov_b32 m0, s43
	s_nop 0
	global_load_lds_dwordx4 v192, s[72:73]
	s_waitcnt vmcnt(6)
	s_barrier
	s_setprio 1
	v_mfma_f32_16x16x32_bf16 v[40:43], v[176:179], v[124:127], v[40:43]
	v_mfma_f32_16x16x32_bf16 v[44:47], v[196:199], v[124:127], v[44:47]
	v_mfma_f32_16x16x32_bf16 v[16:19], v[176:179], v[140:143], v[16:19]
	v_mfma_f32_16x16x32_bf16 v[20:23], v[196:199], v[140:143], v[20:23]
	v_mfma_f32_16x16x32_bf16 v[0:3], v[176:179], v[156:159], v[0:3]
	v_mfma_f32_16x16x32_bf16 v[4:7], v[196:199], v[156:159], v[4:7]
	v_mfma_f32_16x16x32_bf16 v[32:35], v[176:179], v[116:119], v[80:83]
	v_mfma_f32_16x16x32_bf16 v[36:39], v[196:199], v[116:119], v[84:87]
	v_mfma_f32_16x16x32_bf16 v[40:43], v[180:183], v[136:139], v[40:43]
	v_mfma_f32_16x16x32_bf16 v[44:47], v[200:203], v[136:139], v[44:47]
	v_mfma_f32_16x16x32_bf16 v[16:19], v[180:183], v[144:147], v[16:19]
	v_mfma_f32_16x16x32_bf16 v[20:23], v[200:203], v[144:147], v[20:23]
	v_mfma_f32_16x16x32_bf16 v[0:3], v[180:183], v[164:167], v[0:3]
	v_mfma_f32_16x16x32_bf16 v[4:7], v[200:203], v[164:167], v[4:7]
	v_mfma_f32_16x16x32_bf16 v[32:35], v[180:183], v[120:123], v[32:35]
	v_mfma_f32_16x16x32_bf16 v[36:39], v[200:203], v[120:123], v[36:39]
	s_setprio 0
	v_add_u32_e32 v84, s90, v219
	s_barrier
	ds_read_b128 v[48:51], v84
	ds_read_b128 v[52:55], v84 offset:1024
	ds_read_b128 v[80:83], v84 offset:2048
	ds_read_b128 v[84:87], v84 offset:3072
	s_mov_b32 m0, s96
	ds_read_b128 v[116:119], v227 offset:32768
	ds_read_b128 v[120:123], v227 offset:33792
	ds_read_b128 v[124:127], v227 offset:34816
	ds_read_b128 v[136:139], v227 offset:35840
	ds_read_b128 v[156:159], v227 offset:36864
	ds_read_b128 v[176:179], v227 offset:37888
	ds_read_b128 v[180:183], v227 offset:38912
	ds_read_b128 v[196:199], v227 offset:39936
	global_load_lds_dwordx4 v186, s[70:71]
	s_mov_b32 m0, s97
	s_nop 0
	global_load_lds_dwordx4 v190, s[70:71]
	s_waitcnt lgkmcnt(8)
	s_barrier
	s_waitcnt lgkmcnt(0)
	s_setprio 1
	v_mfma_f32_16x16x32_bf16 v[140:143], v[48:51], v[116:119], v[172:175]
	v_mfma_f32_16x16x32_bf16 v[172:175], v[52:55], v[120:123], v[140:143]
	v_mfma_f32_16x16x32_bf16 v[140:143], v[80:83], v[116:119], v[168:171]
	v_mfma_f32_16x16x32_bf16 v[168:171], v[84:87], v[120:123], v[140:143]
	v_mfma_f32_16x16x32_bf16 v[140:143], v[48:51], v[124:127], v[152:155]
	v_mfma_f32_16x16x32_bf16 v[152:155], v[52:55], v[136:139], v[140:143]
	v_mfma_f32_16x16x32_bf16 v[140:143], v[80:83], v[124:127], v[148:151]
	v_mfma_f32_16x16x32_bf16 v[132:135], v[48:51], v[156:159], v[132:135]
	v_mfma_f32_16x16x32_bf16 v[128:131], v[80:83], v[156:159], v[128:131]
	v_mfma_f32_16x16x32_bf16 v[112:115], v[48:51], v[180:183], v[112:115]
	v_mfma_f32_16x16x32_bf16 v[108:111], v[80:83], v[180:183], v[108:111]
	v_mfma_f32_16x16x32_bf16 v[148:151], v[84:87], v[136:139], v[140:143]
	v_mfma_f32_16x16x32_bf16 v[132:135], v[52:55], v[176:179], v[132:135]
	v_mfma_f32_16x16x32_bf16 v[128:131], v[84:87], v[176:179], v[128:131]
	v_mfma_f32_16x16x32_bf16 v[112:115], v[52:55], v[196:199], v[112:115]
	v_mfma_f32_16x16x32_bf16 v[108:111], v[84:87], v[196:199], v[108:111]
	s_setprio 0
	s_barrier
	v_add_u32_e32 v140, s91, v219
	s_mov_b32 m0, s19
	ds_read_b128 v[200:203], v140
	ds_read_b128 v[204:207], v140 offset:1024
	ds_read_b128 v[222:225], v140 offset:2048
	ds_read_b128 v[234:237], v140 offset:3072
	global_load_lds_dwordx4 v188, s[100:101]
	s_mov_b32 m0, s15
	s_nop 0
	global_load_lds_dwordx4 v192, s[100:101]
	s_barrier
	s_waitcnt lgkmcnt(0)
	s_setprio 1
	v_mfma_f32_16x16x32_bf16 v[56:59], v[222:225], v[116:119], v[56:59]
	v_mfma_f32_16x16x32_bf16 v[140:143], v[200:203], v[116:119], v[160:163]
	v_mfma_f32_16x16x32_bf16 v[164:167], v[234:237], v[120:123], v[56:59]
	v_mfma_f32_16x16x32_bf16 v[56:59], v[200:203], v[124:127], v[64:67]
	v_mfma_f32_16x16x32_bf16 v[160:163], v[204:207], v[120:123], v[140:143]
	v_mfma_f32_16x16x32_bf16 v[140:143], v[204:207], v[136:139], v[56:59]
	v_mfma_f32_16x16x32_bf16 v[56:59], v[222:225], v[124:127], v[68:71]
	v_mfma_f32_16x16x32_bf16 v[144:147], v[234:237], v[136:139], v[56:59]
	v_mfma_f32_16x16x32_bf16 v[56:59], v[200:203], v[156:159], v[76:79]
	v_mfma_f32_16x16x32_bf16 v[120:123], v[204:207], v[176:179], v[56:59]
	v_mfma_f32_16x16x32_bf16 v[56:59], v[222:225], v[156:159], v[96:99]
	v_mfma_f32_16x16x32_bf16 v[124:127], v[234:237], v[176:179], v[56:59]
	v_mfma_f32_16x16x32_bf16 v[56:59], v[200:203], v[180:183], v[100:103]
	v_mfma_f32_16x16x32_bf16 v[100:103], v[204:207], v[196:199], v[56:59]
	v_mfma_f32_16x16x32_bf16 v[56:59], v[222:225], v[180:183], v[104:107]
	v_mfma_f32_16x16x32_bf16 v[104:107], v[234:237], v[196:199], v[56:59]
	s_setprio 0
	s_mov_b32 m0, s16
	s_barrier
	s_nop 2
	ds_read_b128 v[56:59], v227 offset:49152
	ds_read_b128 v[64:67], v227 offset:50176
	ds_read_b128 v[68:71], v227 offset:51200
	ds_read_b128 v[76:79], v227 offset:52224
	ds_read_b128 v[96:99], v227 offset:53248
	ds_read_b128 v[116:119], v227 offset:54272
	ds_read_b128 v[136:139], v227 offset:55296
	ds_read_b128 v[156:159], v227 offset:56320
	global_load_lds_dwordx4 v186, s[98:99]
	s_mov_b32 m0, s17
	s_nop 0
	global_load_lds_dwordx4 v190, s[98:99]
	s_barrier
; #define PG8_STAGE(bufoff, gbase, voff) do { _Pragma("unroll") for (int _i = 0; _i < 2; ++_i) \
;         __builtin_amdgcn_global_load_lds((const unsigned*)((const char*)(gbase) + (voff)[_i]), (LAS unsigned*)(lds + (bufoff) + ldsw + _i * 8192), 16, 0, 0); } while (0)
; #define PG8_LDA(dst, b, h) do { _Pragma("unroll") for (int m = 0; m < 4; ++m) _Pragma("unroll") for (int k = 0; k < 2; ++k) dst[m][k] = *(const LAS bf16x8*)(lds + PG8_SA(b, h) + aoff + m * 2048 + k * 1024); } while (0)
; #define PG8_MMA(ai, bj, At, Bt) do { __builtin_amdgcn_s_setprio(1); _Pragma("unroll") for (int m = 0; m < 4; ++m) _Pragma("unroll") for (int n = 0; n < 2; ++n) _Pragma("unroll") for (int k = 0; k < 2; ++k) \
;         acc[ai][bj][m][n] = __builtin_amdgcn_mfma_f32_16x16x32_bf16(Bt[n][k], At[m][k], acc[ai][bj][m][n], 0, 0, 0); __builtin_amdgcn_s_setprio(0); } while (0)
; #define PG8_WAIT_V(n) asm volatile("s_waitcnt vmcnt(" #n ")" ::: "memory")
; #define PG8_WAIT_L(n) asm volatile("s_waitcnt lgkmcnt(" #n ")" ::: "memory")
; #define PG8_BAR __builtin_amdgcn_s_barrier()
; #define PG8_SCHED __builtin_amdgcn_sched_barrier(0)
; template <class Epi, class S_t>
; __device__ __forceinline__ void gemm_phase(LAS unsigned char* lds, int lda, int ldb, const S_t& S, const Epi& E) {
;     ...
;             PG8_LDA(At, 1, 1); PG8_STAGE(PG8_SA(1, 0), a3, voffA);
;             PG8_BAR; PG8_WAIT_L(0); PG8_MMA(1, 0, At, B0); PG8_BAR; PG8_SCHED;
;             PG8_STAGE(PG8_SB(1, 1), b3 + hstepB, voffB);
;             PG8_WAIT_V(6); PG8_BAR; PG8_MMA(1, 1, At, B1); PG8_BAR;
;     __device__ __forceinline__ void operator()(const f32x4 (&acc)[2][2][4][2], const Unit& u, int wr, int wc, int fr, int fq) const {
;         const int row0 = u.pm * BM + wr * 64 + fr, ch0 = u.pn * HALF + wc * 32 + 8 * fq;
;         float br[8], bi[8], sp[8];
; #pragma unroll
;         for (int q = 0; q < 2; ++q) { const f32x4 a = *(const f32x4*)(brg + ch0 + 4 * q), b = *(const f32x4*)(big + ch0 + 4 * q), c = *(const f32x4*)(spl + ch0 + 4 * q);
; #pragma unroll
;             for (int j = 0; j < 4; ++j) { br[4 * q + j] = a[j]; bi[4 * q + j] = b[j]; sp[4 * q + j] = c[j]; } }
;         u32x4 xraw[2][4];
; #pragma unroll
;         for (int ai = 0; ai < 2; ++ai)
; #pragma unroll
;             for (int m = 0; m < 4; ++m) xraw[ai][m] = *(const u32x4*)(XC + (size_t)(row0 + ai * HALF + m * 16) * LW + ch0);
	s_waitcnt lgkmcnt(0)
	s_setprio 1
	v_mfma_f32_16x16x32_bf16 v[92:95], v[48:51], v[56:59], v[92:95]
	v_mfma_f32_16x16x32_bf16 v[88:91], v[80:83], v[56:59], v[88:91]
	v_mfma_f32_16x16x32_bf16 v[72:75], v[48:51], v[68:71], v[72:75]
	v_mfma_f32_16x16x32_bf16 v[60:63], v[80:83], v[68:71], v[60:63]
	v_mfma_f32_16x16x32_bf16 v[28:31], v[48:51], v[96:99], v[28:31]
	v_mfma_f32_16x16x32_bf16 v[24:27], v[80:83], v[96:99], v[24:27]
	v_mfma_f32_16x16x32_bf16 v[12:15], v[48:51], v[136:139], v[12:15]
	v_mfma_f32_16x16x32_bf16 v[8:11], v[80:83], v[136:139], v[8:11]
	v_mfma_f32_16x16x32_bf16 v[92:95], v[52:55], v[64:67], v[92:95]
	v_mfma_f32_16x16x32_bf16 v[88:91], v[84:87], v[64:67], v[88:91]
	v_mfma_f32_16x16x32_bf16 v[72:75], v[52:55], v[76:79], v[72:75]
	v_mfma_f32_16x16x32_bf16 v[60:63], v[84:87], v[76:79], v[60:63]
	v_mfma_f32_16x16x32_bf16 v[28:31], v[52:55], v[116:119], v[28:31]
	v_mfma_f32_16x16x32_bf16 v[24:27], v[84:87], v[116:119], v[24:27]
	v_mfma_f32_16x16x32_bf16 v[12:15], v[52:55], v[156:159], v[12:15]
	v_mfma_f32_16x16x32_bf16 v[8:11], v[84:87], v[156:159], v[8:11]
	s_setprio 0
	s_barrier
	s_mov_b32 m0, s1
	global_load_lds_dwordx4 v188, s[68:69]
	s_mov_b32 m0, s0
	s_nop 0
	global_load_lds_dwordx4 v192, s[68:69]
	s_waitcnt vmcnt(6)
	s_barrier
	s_setprio 1
	v_mfma_f32_16x16x32_bf16 v[32:35], v[200:203], v[56:59], v[32:35]
	v_mfma_f32_16x16x32_bf16 v[80:83], v[204:207], v[64:67], v[32:35]
	v_mfma_f32_16x16x32_bf16 v[32:35], v[222:225], v[56:59], v[36:39]
	v_mfma_f32_16x16x32_bf16 v[84:87], v[234:237], v[64:67], v[32:35]
	v_mfma_f32_16x16x32_bf16 v[32:35], v[200:203], v[68:71], v[40:43]
	v_mfma_f32_16x16x32_bf16 v[40:43], v[204:207], v[76:79], v[32:35]
	v_mfma_f32_16x16x32_bf16 v[32:35], v[222:225], v[68:71], v[44:47]
	v_mfma_f32_16x16x32_bf16 v[16:19], v[200:203], v[96:99], v[16:19]
	v_mfma_f32_16x16x32_bf16 v[20:23], v[222:225], v[96:99], v[20:23]
	v_mfma_f32_16x16x32_bf16 v[0:3], v[200:203], v[136:139], v[0:3]
	v_mfma_f32_16x16x32_bf16 v[4:7], v[222:225], v[136:139], v[4:7]
	v_mfma_f32_16x16x32_bf16 v[44:47], v[234:237], v[76:79], v[32:35]
	v_mfma_f32_16x16x32_bf16 v[16:19], v[204:207], v[116:119], v[16:19]
	v_mfma_f32_16x16x32_bf16 v[20:23], v[234:237], v[116:119], v[20:23]
	v_mfma_f32_16x16x32_bf16 v[0:3], v[204:207], v[156:159], v[0:3]
	v_mfma_f32_16x16x32_bf16 v[4:7], v[234:237], v[156:159], v[4:7]
	s_setprio 0
	s_movk_i32 s0, 0x100
	s_andn2_b64 vcc, exec, s[66:67]
	s_mov_b64 s[68:69], -1
	s_mov_b64 s[66:67], 0
	s_barrier
	s_cbranch_vccz .LBB0_547
	v_lshl_or_b32 v196, s42, 7, v221
	v_readlane_b32 s68, v254, 49
	v_ashrrev_i32_e32 v197, 31, v196
	v_readlane_b32 s76, v254, 57
	v_readlane_b32 s77, v254, 58
	v_lshlrev_b64 v[32:33], 2, v[196:197]
	v_readlane_b32 s80, v254, 61
	v_readlane_b32 s81, v254, 62
	s_mov_b64 s[24:25], s[76:77]
	s_mov_b64 s[28:29], s[80:81]
	v_lshl_add_u64 v[34:35], s[24:25], 0, v[32:33]
	v_lshl_add_u64 v[48:49], s[28:29], 0, v[32:33]
	v_lshl_add_u64 v[50:51], s[10:11], 0, v[32:33]
	global_load_dwordx4 v[56:59], v[34:35], off offset:16
	global_load_dwordx4 v[68:71], v[34:35], off
	global_load_dwordx4 v[36:39], v[48:49], off offset:16
	s_nop 0
	global_load_dwordx4 v[32:35], v[48:49], off
	global_load_dwordx4 v[52:55], v[50:51], off offset:16
	global_load_dwordx4 v[64:67], v[50:51], off
	v_lshl_add_u32 v224, s5, 8, v215
	v_or_b32_e32 v222, 16, v224
	v_ashrrev_i32_e32 v225, 31, v224
	v_ashrrev_i32_e32 v223, 31, v222
	v_lshl_add_u64 v[48:49], v[196:197], 1, s[8:9]
	v_lshlrev_b64 v[50:51], 12, v[224:225]
	v_lshlrev_b64 v[76:77], 12, v[222:223]
	v_or_b32_e32 v208, 32, v224
	v_or_b32_e32 v206, 48, v224
	v_lshl_add_u64 v[50:51], v[48:49], 0, v[50:51]
	v_lshl_add_u64 v[76:77], v[48:49], 0, v[76:77]
	v_ashrrev_i32_e32 v209, 31, v208
	v_ashrrev_i32_e32 v207, 31, v206
	global_load_dwordx4 v[180:183], v[50:51], off
	global_load_dwordx4 v[176:179], v[76:77], off
	v_lshlrev_b64 v[50:51], 12, v[208:209]
	v_lshlrev_b64 v[76:77], 12, v[206:207]
	v_add_u32_e32 v204, 0x80, v224
	v_add_u32_e32 v202, 0x90, v224
	v_lshl_add_u64 v[50:51], v[48:49], 0, v[50:51]
	v_lshl_add_u64 v[76:77], v[48:49], 0, v[76:77]
	v_ashrrev_i32_e32 v205, 31, v204
	v_ashrrev_i32_e32 v203, 31, v202
	global_load_dwordx4 v[156:159], v[50:51], off
	global_load_dwordx4 v[136:139], v[76:77], off
	v_lshlrev_b64 v[50:51], 12, v[204:205]
	v_lshlrev_b64 v[76:77], 12, v[202:203]
	v_add_u32_e32 v200, 0xa0, v224
	v_add_u32_e32 v198, 0xb0, v224
	v_lshl_add_u64 v[50:51], v[48:49], 0, v[50:51]
	v_lshl_add_u64 v[76:77], v[48:49], 0, v[76:77]
	v_ashrrev_i32_e32 v201, 31, v200
	v_ashrrev_i32_e32 v199, 31, v198
	global_load_dwordx4 v[116:119], v[50:51], off
	global_load_dwordx4 v[96:99], v[76:77], off
	v_lshlrev_b64 v[50:51], 12, v[200:201]
	v_lshlrev_b64 v[76:77], 12, v[198:199]
	v_lshl_add_u64 v[50:51], v[48:49], 0, v[50:51]
	v_lshl_add_u64 v[48:49], v[48:49], 0, v[76:77]
	global_load_dwordx4 v[76:79], v[50:51], off
	s_nop 0
	global_load_dwordx4 v[48:51], v[48:49], off
	v_readlane_b32 s69, v254, 50
	v_readlane_b32 s70, v254, 51
	v_readlane_b32 s71, v254, 52
	v_readlane_b32 s72, v254, 53
	v_readlane_b32 s73, v254, 54
	v_readlane_b32 s74, v254, 55
	v_readlane_b32 s75, v254, 56
	v_readlane_b32 s78, v254, 59
	v_readlane_b32 s79, v254, 60
	v_readlane_b32 s82, v254, 63
	v_readlane_b32 s83, v255, 0
	s_waitcnt vmcnt(8)
; __device__ __forceinline__ float sigmoidf_(float x) { return __builtin_amdgcn_rcpf(1.0f + __expf(-x)); }
;     __device__ __forceinline__ void operator()(const f32x4 (&acc)[2][2][4][2], const Unit& u, int wr, int wc, int fr, int fq) const {
;     ...
; #pragma unroll
;         for (int ai = 0; ai < 2; ++ai)
; #pragma unroll
;             for (int m = 0; m < 4; ++m) { const size_t off = (size_t)(row0 + ai * HALF + m * 16) * LW + ch0;
;                 float xc[8]; unpack8(xraw[ai][m], xc);
;                 float la[8], uu[8];
; #pragma unroll
;                 for (int n = 0; n < 2; ++n)
; #pragma unroll
;                     for (int j = 0; j < 4; ++j) { const int e = 4 * n + j;
;                         const float r = sigmoidf_(acc[ai][0][m][n][j] + br[e]), ig = sigmoidf_(acc[ai][1][m][n][j] + bi[e]);
;                         const float l = -8.0f * r * sp[e]; la[e] = l;
;                         const float x2 = 2.0f * l;
;                         const float om = x2 > -0.03125f ? -x2 * (1.0f + x2 * (0.5f + x2 * (0.16666667f + x2 * 0.041666668f))) : 1.0f - __expf(x2);
;                         uu[e] = __builtin_amdgcn_sqrtf(om) * (ig * xc[e]); }
	s_mov_b32 s68, 0xbfb8aa3b
	s_mov_b32 s69, 0xbfb8aa3b
	s_mov_b32 s70, 0x3fb8aa3b
	s_mov_b32 s71, 0x3fb8aa3b
	s_mov_b32 s72, 1.0
	s_mov_b32 s73, 1.0
	s_mov_b32 s74, 0x3d2aaaab
	s_mov_b32 s75, 0x3d2aaaab
	s_mov_b32 s76, 0.5
	s_mov_b32 s77, 0.5
	v_mov_b32_e32 v222, v229
	v_mov_b32_e32 v223, v229
	v_mul_f32_e32 v64, 0xc1000000, v64
	v_mul_f32_e32 v65, 0xc1000000, v65
	v_mul_f32_e32 v66, 0xc1000000, v66
	v_mul_f32_e32 v67, 0xc1000000, v67
	v_mul_f32_e32 v52, 0xc1000000, v52
	v_mul_f32_e32 v53, 0xc1000000, v53
	v_mul_f32_e32 v54, 0xc1000000, v54
	v_mul_f32_e32 v55, 0xc1000000, v55
	v_lshlrev_b32_e32 v225, 13, v224
	v_lshl_add_u32 v225, v196, 2, v225
	v_pk_add_f32 v[172:173], v[172:173], v[68:69]
	v_pk_add_f32 v[160:161], v[160:161], v[32:33]
	v_pk_add_f32 v[174:175], v[174:175], v[70:71]
	v_pk_add_f32 v[162:163], v[162:163], v[34:35]
	v_pk_add_f32 v[168:169], v[168:169], v[56:57]
	v_pk_add_f32 v[164:165], v[164:165], v[36:37]
	v_pk_add_f32 v[170:171], v[170:171], v[58:59]
	v_pk_add_f32 v[166:167], v[166:167], v[38:39]
	v_pk_mul_f32 v[172:173], v[172:173], s[68:69]
	v_pk_mul_f32 v[160:161], v[160:161], s[68:69]
	v_pk_mul_f32 v[174:175], v[174:175], s[68:69]
	v_pk_mul_f32 v[162:163], v[162:163], s[68:69]
	v_pk_mul_f32 v[168:169], v[168:169], s[68:69]
	v_pk_mul_f32 v[164:165], v[164:165], s[68:69]
	v_pk_mul_f32 v[170:171], v[170:171], s[68:69]
	v_pk_mul_f32 v[166:167], v[166:167], s[68:69]
	v_exp_f32_e32 v172, v172
	v_exp_f32_e32 v173, v173
	v_exp_f32_e32 v174, v174
	v_exp_f32_e32 v175, v175
	v_exp_f32_e32 v168, v168
	v_exp_f32_e32 v169, v169
	v_exp_f32_e32 v170, v170
	v_exp_f32_e32 v171, v171
	v_exp_f32_e32 v160, v160
	v_exp_f32_e32 v161, v161
	v_exp_f32_e32 v162, v162
	v_exp_f32_e32 v163, v163
	v_exp_f32_e32 v164, v164
	v_exp_f32_e32 v165, v165
	v_exp_f32_e32 v166, v166
	v_exp_f32_e32 v167, v167
	v_pk_add_f32 v[172:173], v[172:173], s[72:73]
	v_pk_add_f32 v[160:161], v[160:161], s[72:73]
	v_pk_add_f32 v[174:175], v[174:175], s[72:73]
	v_pk_add_f32 v[162:163], v[162:163], s[72:73]
	v_pk_add_f32 v[168:169], v[168:169], s[72:73]
	v_pk_add_f32 v[164:165], v[164:165], s[72:73]
	v_pk_add_f32 v[170:171], v[170:171], s[72:73]
	v_pk_add_f32 v[166:167], v[166:167], s[72:73]
	v_rcp_f32_e32 v172, v172
	v_rcp_f32_e32 v173, v173
	v_rcp_f32_e32 v174, v174
	v_rcp_f32_e32 v175, v175
	v_rcp_f32_e32 v168, v168
	v_rcp_f32_e32 v169, v169
	v_rcp_f32_e32 v170, v170
	v_rcp_f32_e32 v171, v171
	v_rcp_f32_e32 v160, v160
	v_rcp_f32_e32 v161, v161
	v_rcp_f32_e32 v162, v162
	v_rcp_f32_e32 v163, v163
	v_rcp_f32_e32 v164, v164
	v_rcp_f32_e32 v165, v165
	v_rcp_f32_e32 v166, v166
	v_rcp_f32_e32 v167, v167
	s_waitcnt vmcnt(7)
	v_lshlrev_b32_e32 v230, 16, v180
	v_and_b32_e32 v231, 0xffff0000, v180
	v_lshlrev_b32_e32 v234, 16, v181
	v_and_b32_e32 v235, 0xffff0000, v181
	v_lshlrev_b32_e32 v236, 16, v182
	v_and_b32_e32 v237, 0xffff0000, v182
	v_lshlrev_b32_e32 v238, 16, v183
	v_and_b32_e32 v239, 0xffff0000, v183
	v_pk_mul_f32 v[172:173], v[64:65], v[172:173]
	v_pk_mul_f32 v[174:175], v[66:67], v[174:175]
	v_pk_mul_f32 v[168:169], v[52:53], v[168:169]
	v_pk_mul_f32 v[170:171], v[54:55], v[170:171]
	v_pk_mul_f32 v[160:161], v[160:161], v[230:231]
	v_pk_mul_f32 v[162:163], v[162:163], v[234:235]
	v_pk_mul_f32 v[164:165], v[164:165], v[236:237]
	v_pk_mul_f32 v[166:167], v[166:167], v[238:239]
	v_pk_add_f32 v[198:199], v[172:173], v[172:173]
	v_pk_add_f32 v[200:201], v[174:175], v[174:175]
	v_pk_mul_f32 v[206:207], v[198:199], s[70:71]
	v_pk_mul_f32 v[208:209], v[200:201], s[70:71]
	v_pk_fma_f32 v[202:203], v[198:199], s[74:75], v[222:223]
	v_pk_fma_f32 v[204:205], v[200:201], s[74:75], v[222:223]
	v_exp_f32_e32 v206, v206
	v_exp_f32_e32 v207, v207
	v_exp_f32_e32 v208, v208
	v_exp_f32_e32 v209, v209
	v_pk_fma_f32 v[202:203], v[198:199], v[202:203], s[76:77]
	v_pk_fma_f32 v[204:205], v[200:201], v[204:205], s[76:77]
	v_pk_fma_f32 v[202:203], v[198:199], v[202:203], s[72:73]
	v_pk_fma_f32 v[204:205], v[200:201], v[204:205], s[72:73]
	v_pk_mul_f32 v[202:203], v[202:203], v[198:199] neg_lo:[0,1] neg_hi:[0,1]
	v_pk_mul_f32 v[204:205], v[204:205], v[200:201] neg_lo:[0,1] neg_hi:[0,1]
	v_pk_add_f32 v[206:207], s[72:73], v[206:207] neg_lo:[0,1] neg_hi:[0,1]
	v_pk_add_f32 v[208:209], s[72:73], v[208:209] neg_lo:[0,1] neg_hi:[0,1]
	v_cmp_lt_f32_e64 s[78:79], s4, v198
	v_cmp_lt_f32_e64 s[80:81], s4, v199
	v_cmp_lt_f32_e64 s[82:83], s4, v200
	v_cmp_lt_f32_e64 s[24:25], s4, v201
	v_cndmask_b32_e64 v202, v206, v202, s[78:79]
	v_cndmask_b32_e64 v203, v207, v203, s[80:81]
	v_cndmask_b32_e64 v204, v208, v204, s[82:83]
	v_cndmask_b32_e64 v205, v209, v205, s[24:25]
	v_sqrt_f32_e32 v202, v202
	v_sqrt_f32_e32 v203, v203
	v_sqrt_f32_e32 v204, v204
	v_sqrt_f32_e32 v205, v205
	v_pk_mul_f32 v[160:161], v[160:161], v[202:203]
	v_pk_mul_f32 v[162:163], v[162:163], v[204:205]
	v_pk_add_f32 v[198:199], v[168:169], v[168:169]
	v_pk_add_f32 v[200:201], v[170:171], v[170:171]
	v_pk_mul_f32 v[206:207], v[198:199], s[70:71]
	v_pk_mul_f32 v[208:209], v[200:201], s[70:71]
	v_pk_fma_f32 v[202:203], v[198:199], s[74:75], v[222:223]
	v_pk_fma_f32 v[204:205], v[200:201], s[74:75], v[222:223]
	v_exp_f32_e32 v206, v206
	v_exp_f32_e32 v207, v207
	v_exp_f32_e32 v208, v208
	v_exp_f32_e32 v209, v209
	v_pk_fma_f32 v[202:203], v[198:199], v[202:203], s[76:77]
	v_pk_fma_f32 v[204:205], v[200:201], v[204:205], s[76:77]
	v_pk_fma_f32 v[202:203], v[198:199], v[202:203], s[72:73]
	v_pk_fma_f32 v[204:205], v[200:201], v[204:205], s[72:73]
	v_pk_mul_f32 v[202:203], v[202:203], v[198:199] neg_lo:[0,1] neg_hi:[0,1]
	v_pk_mul_f32 v[204:205], v[204:205], v[200:201] neg_lo:[0,1] neg_hi:[0,1]
	v_pk_add_f32 v[206:207], s[72:73], v[206:207] neg_lo:[0,1] neg_hi:[0,1]
; __device__ __forceinline__ unsigned pk2(float lo, float hi) { unsigned r; asm("v_cvt_pk_bf16_f32 %0, %1, %2" : "=v"(r) : "v"(lo), "v"(hi)); return r; }
; __device__ __forceinline__ float sigmoidf_(float x) { return __builtin_amdgcn_rcpf(1.0f + __expf(-x)); }
;     __device__ __forceinline__ void operator()(const f32x4 (&acc)[2][2][4][2], const Unit& u, int wr, int wc, int fr, int fq) const {
;     ...
;             for (int m = 0; m < 4; ++m) { const size_t off = (size_t)(row0 + ai * HALF + m * 16) * LW + ch0;
;                 float xc[8]; unpack8(xraw[ai][m], xc);
;                 float la[8], uu[8];
; #pragma unroll
;                 for (int n = 0; n < 2; ++n)
; #pragma unroll
;                     for (int j = 0; j < 4; ++j) { const int e = 4 * n + j;
;                         const float r = sigmoidf_(acc[ai][0][m][n][j] + br[e]), ig = sigmoidf_(acc[ai][1][m][n][j] + bi[e]);
;                         const float l = -8.0f * r * sp[e]; la[e] = l;
;                         const float x2 = 2.0f * l;
;                         const float om = x2 > -0.03125f ? -x2 * (1.0f + x2 * (0.5f + x2 * (0.16666667f + x2 * 0.041666668f))) : 1.0f - __expf(x2);
;                         uu[e] = __builtin_amdgcn_sqrtf(om) * (ig * xc[e]); }
;                 u32x4 w0, w1; w0.x = pk2(la[0], uu[0]); w0.y = pk2(la[1], uu[1]); w0.z = pk2(la[2], uu[2]); w0.w = pk2(la[3], uu[3]);
;                 w1.x = pk2(la[4], uu[4]); w1.y = pk2(la[5], uu[5]); w1.z = pk2(la[6], uu[6]); w1.w = pk2(la[7], uu[7]);
;                 *(u32x4*)(LU + off) = w0; *(u32x4*)(LU + off + 4) = w1; }
	v_pk_add_f32 v[208:209], s[72:73], v[208:209] neg_lo:[0,1] neg_hi:[0,1]
	v_cmp_lt_f32_e64 s[78:79], s4, v198
	v_cmp_lt_f32_e64 s[80:81], s4, v199
	v_cmp_lt_f32_e64 s[82:83], s4, v200
	v_cmp_lt_f32_e64 s[24:25], s4, v201
	v_cndmask_b32_e64 v202, v206, v202, s[78:79]
	v_cndmask_b32_e64 v203, v207, v203, s[80:81]
	v_cndmask_b32_e64 v204, v208, v204, s[82:83]
	v_cndmask_b32_e64 v205, v209, v205, s[24:25]
	v_sqrt_f32_e32 v202, v202
	v_sqrt_f32_e32 v203, v203
	v_sqrt_f32_e32 v204, v204
	v_sqrt_f32_e32 v205, v205
	v_pk_mul_f32 v[164:165], v[164:165], v[202:203]
	v_pk_mul_f32 v[166:167], v[166:167], v[204:205]
	v_cvt_pk_bf16_f32 v160, v172, v160
	v_cvt_pk_bf16_f32 v161, v173, v161
	v_cvt_pk_bf16_f32 v162, v174, v162
	v_cvt_pk_bf16_f32 v163, v175, v163
	v_cvt_pk_bf16_f32 v164, v168, v164
	v_cvt_pk_bf16_f32 v165, v169, v165
	v_cvt_pk_bf16_f32 v166, v170, v166
	v_cvt_pk_bf16_f32 v167, v171, v167
	v_mov_b32_e32 v197, v225
	global_store_dwordx4 v197, v[160:163], s[44:45]
	global_store_dwordx4 v197, v[164:167], s[44:45] offset:16
	v_pk_add_f32 v[152:153], v[152:153], v[68:69]
	v_pk_add_f32 v[140:141], v[140:141], v[32:33]
	v_pk_add_f32 v[154:155], v[154:155], v[70:71]
	v_pk_add_f32 v[142:143], v[142:143], v[34:35]
	v_pk_add_f32 v[148:149], v[148:149], v[56:57]
	v_pk_add_f32 v[144:145], v[144:145], v[36:37]
	v_pk_add_f32 v[150:151], v[150:151], v[58:59]
	v_pk_add_f32 v[146:147], v[146:147], v[38:39]
	v_pk_mul_f32 v[152:153], v[152:153], s[68:69]
	v_pk_mul_f32 v[140:141], v[140:141], s[68:69]
	v_pk_mul_f32 v[154:155], v[154:155], s[68:69]
	v_pk_mul_f32 v[142:143], v[142:143], s[68:69]
	v_pk_mul_f32 v[148:149], v[148:149], s[68:69]
	v_pk_mul_f32 v[144:145], v[144:145], s[68:69]
	v_pk_mul_f32 v[150:151], v[150:151], s[68:69]
	v_pk_mul_f32 v[146:147], v[146:147], s[68:69]
	v_exp_f32_e32 v152, v152
	v_exp_f32_e32 v153, v153
	v_exp_f32_e32 v154, v154
	v_exp_f32_e32 v155, v155
	v_exp_f32_e32 v148, v148
	v_exp_f32_e32 v149, v149
	v_exp_f32_e32 v150, v150
	v_exp_f32_e32 v151, v151
	v_exp_f32_e32 v140, v140
	v_exp_f32_e32 v141, v141
	v_exp_f32_e32 v142, v142
	v_exp_f32_e32 v143, v143
	v_exp_f32_e32 v144, v144
	v_exp_f32_e32 v145, v145
	v_exp_f32_e32 v146, v146
	v_exp_f32_e32 v147, v147
	v_pk_add_f32 v[152:153], v[152:153], s[72:73]
	v_pk_add_f32 v[140:141], v[140:141], s[72:73]
	v_pk_add_f32 v[154:155], v[154:155], s[72:73]
	v_pk_add_f32 v[142:143], v[142:143], s[72:73]
	v_pk_add_f32 v[148:149], v[148:149], s[72:73]
	v_pk_add_f32 v[144:145], v[144:145], s[72:73]
	v_pk_add_f32 v[150:151], v[150:151], s[72:73]
	v_pk_add_f32 v[146:147], v[146:147], s[72:73]
	v_rcp_f32_e32 v152, v152
	v_rcp_f32_e32 v153, v153
	v_rcp_f32_e32 v154, v154
	v_rcp_f32_e32 v155, v155
	v_rcp_f32_e32 v148, v148
	v_rcp_f32_e32 v149, v149
	v_rcp_f32_e32 v150, v150
	v_rcp_f32_e32 v151, v151
	v_rcp_f32_e32 v140, v140
	v_rcp_f32_e32 v141, v141
	v_rcp_f32_e32 v142, v142
	v_rcp_f32_e32 v143, v143
	v_rcp_f32_e32 v144, v144
	v_rcp_f32_e32 v145, v145
	v_rcp_f32_e32 v146, v146
	v_rcp_f32_e32 v147, v147
	s_waitcnt vmcnt(8)
	v_lshlrev_b32_e32 v230, 16, v176
	v_and_b32_e32 v231, 0xffff0000, v176
	v_lshlrev_b32_e32 v234, 16, v177
	v_and_b32_e32 v235, 0xffff0000, v177
	v_lshlrev_b32_e32 v236, 16, v178
	v_and_b32_e32 v237, 0xffff0000, v178
	v_lshlrev_b32_e32 v238, 16, v179
	v_and_b32_e32 v239, 0xffff0000, v179
	v_pk_mul_f32 v[152:153], v[64:65], v[152:153]
	v_pk_mul_f32 v[154:155], v[66:67], v[154:155]
	v_pk_mul_f32 v[148:149], v[52:53], v[148:149]
	v_pk_mul_f32 v[150:151], v[54:55], v[150:151]
	v_pk_mul_f32 v[140:141], v[140:141], v[230:231]
	v_pk_mul_f32 v[142:143], v[142:143], v[234:235]
	v_pk_mul_f32 v[144:145], v[144:145], v[236:237]
	v_pk_mul_f32 v[146:147], v[146:147], v[238:239]
	v_pk_add_f32 v[198:199], v[152:153], v[152:153]
	v_pk_add_f32 v[200:201], v[154:155], v[154:155]
	v_pk_mul_f32 v[206:207], v[198:199], s[70:71]
	v_pk_mul_f32 v[208:209], v[200:201], s[70:71]
	v_pk_fma_f32 v[202:203], v[198:199], s[74:75], v[222:223]
	v_pk_fma_f32 v[204:205], v[200:201], s[74:75], v[222:223]
	v_exp_f32_e32 v206, v206
	v_exp_f32_e32 v207, v207
	v_exp_f32_e32 v208, v208
	v_exp_f32_e32 v209, v209
	v_pk_fma_f32 v[202:203], v[198:199], v[202:203], s[76:77]
	v_pk_fma_f32 v[204:205], v[200:201], v[204:205], s[76:77]
	v_pk_fma_f32 v[202:203], v[198:199], v[202:203], s[72:73]
	v_pk_fma_f32 v[204:205], v[200:201], v[204:205], s[72:73]
	v_pk_mul_f32 v[202:203], v[202:203], v[198:199] neg_lo:[0,1] neg_hi:[0,1]
	v_pk_mul_f32 v[204:205], v[204:205], v[200:201] neg_lo:[0,1] neg_hi:[0,1]
	v_pk_add_f32 v[206:207], s[72:73], v[206:207] neg_lo:[0,1] neg_hi:[0,1]
	v_pk_add_f32 v[208:209], s[72:73], v[208:209] neg_lo:[0,1] neg_hi:[0,1]
	v_cmp_lt_f32_e64 s[78:79], s4, v198
	v_cmp_lt_f32_e64 s[80:81], s4, v199
	v_cmp_lt_f32_e64 s[82:83], s4, v200
	v_cmp_lt_f32_e64 s[24:25], s4, v201
	v_cndmask_b32_e64 v202, v206, v202, s[78:79]
	v_cndmask_b32_e64 v203, v207, v203, s[80:81]
	v_cndmask_b32_e64 v204, v208, v204, s[82:83]
	v_cndmask_b32_e64 v205, v209, v205, s[24:25]
	v_sqrt_f32_e32 v202, v202
	v_sqrt_f32_e32 v203, v203
	v_sqrt_f32_e32 v204, v204
	v_sqrt_f32_e32 v205, v205
	v_pk_mul_f32 v[140:141], v[140:141], v[202:203]
	v_pk_mul_f32 v[142:143], v[142:143], v[204:205]
	v_pk_add_f32 v[198:199], v[148:149], v[148:149]
	v_pk_add_f32 v[200:201], v[150:151], v[150:151]
	v_pk_mul_f32 v[206:207], v[198:199], s[70:71]
	v_pk_mul_f32 v[208:209], v[200:201], s[70:71]
	v_pk_fma_f32 v[202:203], v[198:199], s[74:75], v[222:223]
	v_pk_fma_f32 v[204:205], v[200:201], s[74:75], v[222:223]
	v_exp_f32_e32 v206, v206
	v_exp_f32_e32 v207, v207
	v_exp_f32_e32 v208, v208
	v_exp_f32_e32 v209, v209
	v_pk_fma_f32 v[202:203], v[198:199], v[202:203], s[76:77]
; __device__ __forceinline__ unsigned pk2(float lo, float hi) { unsigned r; asm("v_cvt_pk_bf16_f32 %0, %1, %2" : "=v"(r) : "v"(lo), "v"(hi)); return r; }
; __device__ __forceinline__ float sigmoidf_(float x) { return __builtin_amdgcn_rcpf(1.0f + __expf(-x)); }
;     __device__ __forceinline__ void operator()(const f32x4 (&acc)[2][2][4][2], const Unit& u, int wr, int wc, int fr, int fq) const {
;     ...
;             for (int m = 0; m < 4; ++m) { const size_t off = (size_t)(row0 + ai * HALF + m * 16) * LW + ch0;
;                 float xc[8]; unpack8(xraw[ai][m], xc);
;                 float la[8], uu[8];
; #pragma unroll
;                 for (int n = 0; n < 2; ++n)
; #pragma unroll
;                     for (int j = 0; j < 4; ++j) { const int e = 4 * n + j;
;                         const float r = sigmoidf_(acc[ai][0][m][n][j] + br[e]), ig = sigmoidf_(acc[ai][1][m][n][j] + bi[e]);
;                         const float l = -8.0f * r * sp[e]; la[e] = l;
;                         const float x2 = 2.0f * l;
;                         const float om = x2 > -0.03125f ? -x2 * (1.0f + x2 * (0.5f + x2 * (0.16666667f + x2 * 0.041666668f))) : 1.0f - __expf(x2);
;                         uu[e] = __builtin_amdgcn_sqrtf(om) * (ig * xc[e]); }
;                 u32x4 w0, w1; w0.x = pk2(la[0], uu[0]); w0.y = pk2(la[1], uu[1]); w0.z = pk2(la[2], uu[2]); w0.w = pk2(la[3], uu[3]);
;                 w1.x = pk2(la[4], uu[4]); w1.y = pk2(la[5], uu[5]); w1.z = pk2(la[6], uu[6]); w1.w = pk2(la[7], uu[7]);
;                 *(u32x4*)(LU + off) = w0; *(u32x4*)(LU + off + 4) = w1; }
	v_pk_fma_f32 v[204:205], v[200:201], v[204:205], s[76:77]
	v_pk_fma_f32 v[202:203], v[198:199], v[202:203], s[72:73]
	v_pk_fma_f32 v[204:205], v[200:201], v[204:205], s[72:73]
	v_pk_mul_f32 v[202:203], v[202:203], v[198:199] neg_lo:[0,1] neg_hi:[0,1]
	v_pk_mul_f32 v[204:205], v[204:205], v[200:201] neg_lo:[0,1] neg_hi:[0,1]
	v_pk_add_f32 v[206:207], s[72:73], v[206:207] neg_lo:[0,1] neg_hi:[0,1]
	v_pk_add_f32 v[208:209], s[72:73], v[208:209] neg_lo:[0,1] neg_hi:[0,1]
	v_cmp_lt_f32_e64 s[78:79], s4, v198
	v_cmp_lt_f32_e64 s[80:81], s4, v199
	v_cmp_lt_f32_e64 s[82:83], s4, v200
	v_cmp_lt_f32_e64 s[24:25], s4, v201
	v_cndmask_b32_e64 v202, v206, v202, s[78:79]
	v_cndmask_b32_e64 v203, v207, v203, s[80:81]
	v_cndmask_b32_e64 v204, v208, v204, s[82:83]
	v_cndmask_b32_e64 v205, v209, v205, s[24:25]
	v_sqrt_f32_e32 v202, v202
	v_sqrt_f32_e32 v203, v203
	v_sqrt_f32_e32 v204, v204
	v_sqrt_f32_e32 v205, v205
	v_pk_mul_f32 v[144:145], v[144:145], v[202:203]
	v_pk_mul_f32 v[146:147], v[146:147], v[204:205]
	v_cvt_pk_bf16_f32 v140, v152, v140
	v_cvt_pk_bf16_f32 v141, v153, v141
	v_cvt_pk_bf16_f32 v142, v154, v142
	v_cvt_pk_bf16_f32 v143, v155, v143
	v_cvt_pk_bf16_f32 v144, v148, v144
	v_cvt_pk_bf16_f32 v145, v149, v145
	v_cvt_pk_bf16_f32 v146, v150, v146
	v_cvt_pk_bf16_f32 v147, v151, v147
	v_add_u32_e32 v197, 0x20000, v225
	global_store_dwordx4 v197, v[140:143], s[44:45]
	global_store_dwordx4 v197, v[144:147], s[44:45] offset:16
	v_pk_add_f32 v[132:133], v[132:133], v[68:69]
	v_pk_add_f32 v[120:121], v[120:121], v[32:33]
	v_pk_add_f32 v[134:135], v[134:135], v[70:71]
	v_pk_add_f32 v[122:123], v[122:123], v[34:35]
	v_pk_add_f32 v[128:129], v[128:129], v[56:57]
	v_pk_add_f32 v[124:125], v[124:125], v[36:37]
	v_pk_add_f32 v[130:131], v[130:131], v[58:59]
	v_pk_add_f32 v[126:127], v[126:127], v[38:39]
	v_pk_mul_f32 v[132:133], v[132:133], s[68:69]
	v_pk_mul_f32 v[120:121], v[120:121], s[68:69]
	v_pk_mul_f32 v[134:135], v[134:135], s[68:69]
	v_pk_mul_f32 v[122:123], v[122:123], s[68:69]
	v_pk_mul_f32 v[128:129], v[128:129], s[68:69]
	v_pk_mul_f32 v[124:125], v[124:125], s[68:69]
	v_pk_mul_f32 v[130:131], v[130:131], s[68:69]
	v_pk_mul_f32 v[126:127], v[126:127], s[68:69]
	v_exp_f32_e32 v132, v132
	v_exp_f32_e32 v133, v133
	v_exp_f32_e32 v134, v134
	v_exp_f32_e32 v135, v135
	v_exp_f32_e32 v128, v128
	v_exp_f32_e32 v129, v129
	v_exp_f32_e32 v130, v130
	v_exp_f32_e32 v131, v131
	v_exp_f32_e32 v120, v120
	v_exp_f32_e32 v121, v121
	v_exp_f32_e32 v122, v122
	v_exp_f32_e32 v123, v123
	v_exp_f32_e32 v124, v124
	v_exp_f32_e32 v125, v125
	v_exp_f32_e32 v126, v126
	v_exp_f32_e32 v127, v127
	v_pk_add_f32 v[132:133], v[132:133], s[72:73]
	v_pk_add_f32 v[120:121], v[120:121], s[72:73]
	v_pk_add_f32 v[134:135], v[134:135], s[72:73]
	v_pk_add_f32 v[122:123], v[122:123], s[72:73]
	v_pk_add_f32 v[128:129], v[128:129], s[72:73]
	v_pk_add_f32 v[124:125], v[124:125], s[72:73]
	v_pk_add_f32 v[130:131], v[130:131], s[72:73]
	v_pk_add_f32 v[126:127], v[126:127], s[72:73]
	v_rcp_f32_e32 v132, v132
	v_rcp_f32_e32 v133, v133
	v_rcp_f32_e32 v134, v134
	v_rcp_f32_e32 v135, v135
	v_rcp_f32_e32 v128, v128
	v_rcp_f32_e32 v129, v129
	v_rcp_f32_e32 v130, v130
	v_rcp_f32_e32 v131, v131
	v_rcp_f32_e32 v120, v120
	v_rcp_f32_e32 v121, v121
	v_rcp_f32_e32 v122, v122
	v_rcp_f32_e32 v123, v123
	v_rcp_f32_e32 v124, v124
	v_rcp_f32_e32 v125, v125
	v_rcp_f32_e32 v126, v126
	v_rcp_f32_e32 v127, v127
	s_waitcnt vmcnt(9)
	v_lshlrev_b32_e32 v230, 16, v156
	v_and_b32_e32 v231, 0xffff0000, v156
	v_lshlrev_b32_e32 v234, 16, v157
	v_and_b32_e32 v235, 0xffff0000, v157
	v_lshlrev_b32_e32 v236, 16, v158
	v_and_b32_e32 v237, 0xffff0000, v158
	v_lshlrev_b32_e32 v238, 16, v159
	v_and_b32_e32 v239, 0xffff0000, v159
	v_pk_mul_f32 v[132:133], v[64:65], v[132:133]
	v_pk_mul_f32 v[134:135], v[66:67], v[134:135]
	v_pk_mul_f32 v[128:129], v[52:53], v[128:129]
	v_pk_mul_f32 v[130:131], v[54:55], v[130:131]
	v_pk_mul_f32 v[120:121], v[120:121], v[230:231]
	v_pk_mul_f32 v[122:123], v[122:123], v[234:235]
	v_pk_mul_f32 v[124:125], v[124:125], v[236:237]
	v_pk_mul_f32 v[126:127], v[126:127], v[238:239]
	v_pk_add_f32 v[198:199], v[132:133], v[132:133]
	v_pk_add_f32 v[200:201], v[134:135], v[134:135]
	v_pk_mul_f32 v[206:207], v[198:199], s[70:71]
	v_pk_mul_f32 v[208:209], v[200:201], s[70:71]
	v_pk_fma_f32 v[202:203], v[198:199], s[74:75], v[222:223]
	v_pk_fma_f32 v[204:205], v[200:201], s[74:75], v[222:223]
	v_exp_f32_e32 v206, v206
	v_exp_f32_e32 v207, v207
	v_exp_f32_e32 v208, v208
	v_exp_f32_e32 v209, v209
	v_pk_fma_f32 v[202:203], v[198:199], v[202:203], s[76:77]
	v_pk_fma_f32 v[204:205], v[200:201], v[204:205], s[76:77]
	v_pk_fma_f32 v[202:203], v[198:199], v[202:203], s[72:73]
	v_pk_fma_f32 v[204:205], v[200:201], v[204:205], s[72:73]
	v_pk_mul_f32 v[202:203], v[202:203], v[198:199] neg_lo:[0,1] neg_hi:[0,1]
	v_pk_mul_f32 v[204:205], v[204:205], v[200:201] neg_lo:[0,1] neg_hi:[0,1]
	v_pk_add_f32 v[206:207], s[72:73], v[206:207] neg_lo:[0,1] neg_hi:[0,1]
	v_pk_add_f32 v[208:209], s[72:73], v[208:209] neg_lo:[0,1] neg_hi:[0,1]
	v_cmp_lt_f32_e64 s[78:79], s4, v198
	v_cmp_lt_f32_e64 s[80:81], s4, v199
	v_cmp_lt_f32_e64 s[82:83], s4, v200
	v_cmp_lt_f32_e64 s[24:25], s4, v201
	v_cndmask_b32_e64 v202, v206, v202, s[78:79]
	v_cndmask_b32_e64 v203, v207, v203, s[80:81]
	v_cndmask_b32_e64 v204, v208, v204, s[82:83]
	v_cndmask_b32_e64 v205, v209, v205, s[24:25]
	v_sqrt_f32_e32 v202, v202
	v_sqrt_f32_e32 v203, v203
	v_sqrt_f32_e32 v204, v204
	v_sqrt_f32_e32 v205, v205
	v_pk_mul_f32 v[120:121], v[120:121], v[202:203]
	v_pk_mul_f32 v[122:123], v[122:123], v[204:205]
	v_pk_add_f32 v[198:199], v[128:129], v[128:129]
; __device__ __forceinline__ unsigned pk2(float lo, float hi) { unsigned r; asm("v_cvt_pk_bf16_f32 %0, %1, %2" : "=v"(r) : "v"(lo), "v"(hi)); return r; }
; __device__ __forceinline__ float sigmoidf_(float x) { return __builtin_amdgcn_rcpf(1.0f + __expf(-x)); }
;     __device__ __forceinline__ void operator()(const f32x4 (&acc)[2][2][4][2], const Unit& u, int wr, int wc, int fr, int fq) const {
;     ...
;             for (int m = 0; m < 4; ++m) { const size_t off = (size_t)(row0 + ai * HALF + m * 16) * LW + ch0;
;                 float xc[8]; unpack8(xraw[ai][m], xc);
;                 float la[8], uu[8];
; #pragma unroll
;                 for (int n = 0; n < 2; ++n)
; #pragma unroll
;                     for (int j = 0; j < 4; ++j) { const int e = 4 * n + j;
;                         const float r = sigmoidf_(acc[ai][0][m][n][j] + br[e]), ig = sigmoidf_(acc[ai][1][m][n][j] + bi[e]);
;                         const float l = -8.0f * r * sp[e]; la[e] = l;
;                         const float x2 = 2.0f * l;
;                         const float om = x2 > -0.03125f ? -x2 * (1.0f + x2 * (0.5f + x2 * (0.16666667f + x2 * 0.041666668f))) : 1.0f - __expf(x2);
;                         uu[e] = __builtin_amdgcn_sqrtf(om) * (ig * xc[e]); }
;                 u32x4 w0, w1; w0.x = pk2(la[0], uu[0]); w0.y = pk2(la[1], uu[1]); w0.z = pk2(la[2], uu[2]); w0.w = pk2(la[3], uu[3]);
;                 w1.x = pk2(la[4], uu[4]); w1.y = pk2(la[5], uu[5]); w1.z = pk2(la[6], uu[6]); w1.w = pk2(la[7], uu[7]);
;                 *(u32x4*)(LU + off) = w0; *(u32x4*)(LU + off + 4) = w1; }
	v_pk_add_f32 v[200:201], v[130:131], v[130:131]
	v_pk_mul_f32 v[206:207], v[198:199], s[70:71]
	v_pk_mul_f32 v[208:209], v[200:201], s[70:71]
	v_pk_fma_f32 v[202:203], v[198:199], s[74:75], v[222:223]
	v_pk_fma_f32 v[204:205], v[200:201], s[74:75], v[222:223]
	v_exp_f32_e32 v206, v206
	v_exp_f32_e32 v207, v207
	v_exp_f32_e32 v208, v208
	v_exp_f32_e32 v209, v209
	v_pk_fma_f32 v[202:203], v[198:199], v[202:203], s[76:77]
	v_pk_fma_f32 v[204:205], v[200:201], v[204:205], s[76:77]
	v_pk_fma_f32 v[202:203], v[198:199], v[202:203], s[72:73]
	v_pk_fma_f32 v[204:205], v[200:201], v[204:205], s[72:73]
	v_pk_mul_f32 v[202:203], v[202:203], v[198:199] neg_lo:[0,1] neg_hi:[0,1]
	v_pk_mul_f32 v[204:205], v[204:205], v[200:201] neg_lo:[0,1] neg_hi:[0,1]
	v_pk_add_f32 v[206:207], s[72:73], v[206:207] neg_lo:[0,1] neg_hi:[0,1]
	v_pk_add_f32 v[208:209], s[72:73], v[208:209] neg_lo:[0,1] neg_hi:[0,1]
	v_cmp_lt_f32_e64 s[78:79], s4, v198
	v_cmp_lt_f32_e64 s[80:81], s4, v199
	v_cmp_lt_f32_e64 s[82:83], s4, v200
	v_cmp_lt_f32_e64 s[24:25], s4, v201
	v_cndmask_b32_e64 v202, v206, v202, s[78:79]
	v_cndmask_b32_e64 v203, v207, v203, s[80:81]
	v_cndmask_b32_e64 v204, v208, v204, s[82:83]
	v_cndmask_b32_e64 v205, v209, v205, s[24:25]
	v_sqrt_f32_e32 v202, v202
	v_sqrt_f32_e32 v203, v203
	v_sqrt_f32_e32 v204, v204
	v_sqrt_f32_e32 v205, v205
	v_pk_mul_f32 v[124:125], v[124:125], v[202:203]
	v_pk_mul_f32 v[126:127], v[126:127], v[204:205]
	v_cvt_pk_bf16_f32 v120, v132, v120
	v_cvt_pk_bf16_f32 v121, v133, v121
	v_cvt_pk_bf16_f32 v122, v134, v122
	v_cvt_pk_bf16_f32 v123, v135, v123
	v_cvt_pk_bf16_f32 v124, v128, v124
	v_cvt_pk_bf16_f32 v125, v129, v125
	v_cvt_pk_bf16_f32 v126, v130, v126
	v_cvt_pk_bf16_f32 v127, v131, v127
	v_add_u32_e32 v197, 0x40000, v225
	global_store_dwordx4 v197, v[120:123], s[44:45]
	global_store_dwordx4 v197, v[124:127], s[44:45] offset:16
	v_pk_add_f32 v[112:113], v[112:113], v[68:69]
	v_pk_add_f32 v[100:101], v[100:101], v[32:33]
	v_pk_add_f32 v[114:115], v[114:115], v[70:71]
	v_pk_add_f32 v[102:103], v[102:103], v[34:35]
	v_pk_add_f32 v[108:109], v[108:109], v[56:57]
	v_pk_add_f32 v[104:105], v[104:105], v[36:37]
	v_pk_add_f32 v[110:111], v[110:111], v[58:59]
	v_pk_add_f32 v[106:107], v[106:107], v[38:39]
	v_pk_mul_f32 v[112:113], v[112:113], s[68:69]
	v_pk_mul_f32 v[100:101], v[100:101], s[68:69]
	v_pk_mul_f32 v[114:115], v[114:115], s[68:69]
	v_pk_mul_f32 v[102:103], v[102:103], s[68:69]
	v_pk_mul_f32 v[108:109], v[108:109], s[68:69]
	v_pk_mul_f32 v[104:105], v[104:105], s[68:69]
	v_pk_mul_f32 v[110:111], v[110:111], s[68:69]
	v_pk_mul_f32 v[106:107], v[106:107], s[68:69]
	v_exp_f32_e32 v112, v112
	v_exp_f32_e32 v113, v113
	v_exp_f32_e32 v114, v114
	v_exp_f32_e32 v115, v115
	v_exp_f32_e32 v108, v108
	v_exp_f32_e32 v109, v109
	v_exp_f32_e32 v110, v110
	v_exp_f32_e32 v111, v111
	v_exp_f32_e32 v100, v100
	v_exp_f32_e32 v101, v101
	v_exp_f32_e32 v102, v102
	v_exp_f32_e32 v103, v103
	v_exp_f32_e32 v104, v104
	v_exp_f32_e32 v105, v105
	v_exp_f32_e32 v106, v106
	v_exp_f32_e32 v107, v107
	v_pk_add_f32 v[112:113], v[112:113], s[72:73]
	v_pk_add_f32 v[100:101], v[100:101], s[72:73]
	v_pk_add_f32 v[114:115], v[114:115], s[72:73]
	v_pk_add_f32 v[102:103], v[102:103], s[72:73]
	v_pk_add_f32 v[108:109], v[108:109], s[72:73]
	v_pk_add_f32 v[104:105], v[104:105], s[72:73]
	v_pk_add_f32 v[110:111], v[110:111], s[72:73]
	v_pk_add_f32 v[106:107], v[106:107], s[72:73]
	v_rcp_f32_e32 v112, v112
	v_rcp_f32_e32 v113, v113
	v_rcp_f32_e32 v114, v114
	v_rcp_f32_e32 v115, v115
	v_rcp_f32_e32 v108, v108
	v_rcp_f32_e32 v109, v109
	v_rcp_f32_e32 v110, v110
	v_rcp_f32_e32 v111, v111
	v_rcp_f32_e32 v100, v100
	v_rcp_f32_e32 v101, v101
	v_rcp_f32_e32 v102, v102
	v_rcp_f32_e32 v103, v103
	v_rcp_f32_e32 v104, v104
	v_rcp_f32_e32 v105, v105
	v_rcp_f32_e32 v106, v106
	v_rcp_f32_e32 v107, v107
	s_waitcnt vmcnt(10)
	v_lshlrev_b32_e32 v230, 16, v136
	v_and_b32_e32 v231, 0xffff0000, v136
	v_lshlrev_b32_e32 v234, 16, v137
	v_and_b32_e32 v235, 0xffff0000, v137
	v_lshlrev_b32_e32 v236, 16, v138
	v_and_b32_e32 v237, 0xffff0000, v138
	v_lshlrev_b32_e32 v238, 16, v139
	v_and_b32_e32 v239, 0xffff0000, v139
	v_pk_mul_f32 v[112:113], v[64:65], v[112:113]
	v_pk_mul_f32 v[114:115], v[66:67], v[114:115]
	v_pk_mul_f32 v[108:109], v[52:53], v[108:109]
	v_pk_mul_f32 v[110:111], v[54:55], v[110:111]
	v_pk_mul_f32 v[100:101], v[100:101], v[230:231]
	v_pk_mul_f32 v[102:103], v[102:103], v[234:235]
	v_pk_mul_f32 v[104:105], v[104:105], v[236:237]
	v_pk_mul_f32 v[106:107], v[106:107], v[238:239]
	v_pk_add_f32 v[198:199], v[112:113], v[112:113]
	v_pk_add_f32 v[200:201], v[114:115], v[114:115]
	v_pk_mul_f32 v[206:207], v[198:199], s[70:71]
	v_pk_mul_f32 v[208:209], v[200:201], s[70:71]
	v_pk_fma_f32 v[202:203], v[198:199], s[74:75], v[222:223]
	v_pk_fma_f32 v[204:205], v[200:201], s[74:75], v[222:223]
	v_exp_f32_e32 v206, v206
	v_exp_f32_e32 v207, v207
	v_exp_f32_e32 v208, v208
	v_exp_f32_e32 v209, v209
	v_pk_fma_f32 v[202:203], v[198:199], v[202:203], s[76:77]
	v_pk_fma_f32 v[204:205], v[200:201], v[204:205], s[76:77]
	v_pk_fma_f32 v[202:203], v[198:199], v[202:203], s[72:73]
	v_pk_fma_f32 v[204:205], v[200:201], v[204:205], s[72:73]
	v_pk_mul_f32 v[202:203], v[202:203], v[198:199] neg_lo:[0,1] neg_hi:[0,1]
	v_pk_mul_f32 v[204:205], v[204:205], v[200:201] neg_lo:[0,1] neg_hi:[0,1]
	v_pk_add_f32 v[206:207], s[72:73], v[206:207] neg_lo:[0,1] neg_hi:[0,1]
	v_pk_add_f32 v[208:209], s[72:73], v[208:209] neg_lo:[0,1] neg_hi:[0,1]
	v_cmp_lt_f32_e64 s[78:79], s4, v198
	v_cmp_lt_f32_e64 s[80:81], s4, v199
	v_cmp_lt_f32_e64 s[82:83], s4, v200
	v_cmp_lt_f32_e64 s[24:25], s4, v201
	v_cndmask_b32_e64 v202, v206, v202, s[78:79]
; __device__ __forceinline__ unsigned pk2(float lo, float hi) { unsigned r; asm("v_cvt_pk_bf16_f32 %0, %1, %2" : "=v"(r) : "v"(lo), "v"(hi)); return r; }
; __device__ __forceinline__ float sigmoidf_(float x) { return __builtin_amdgcn_rcpf(1.0f + __expf(-x)); }
;     __device__ __forceinline__ void operator()(const f32x4 (&acc)[2][2][4][2], const Unit& u, int wr, int wc, int fr, int fq) const {
;     ...
;             for (int m = 0; m < 4; ++m) { const size_t off = (size_t)(row0 + ai * HALF + m * 16) * LW + ch0;
;                 float xc[8]; unpack8(xraw[ai][m], xc);
;                 float la[8], uu[8];
; #pragma unroll
;                 for (int n = 0; n < 2; ++n)
; #pragma unroll
;                     for (int j = 0; j < 4; ++j) { const int e = 4 * n + j;
;                         const float r = sigmoidf_(acc[ai][0][m][n][j] + br[e]), ig = sigmoidf_(acc[ai][1][m][n][j] + bi[e]);
;                         const float l = -8.0f * r * sp[e]; la[e] = l;
;                         const float x2 = 2.0f * l;
;                         const float om = x2 > -0.03125f ? -x2 * (1.0f + x2 * (0.5f + x2 * (0.16666667f + x2 * 0.041666668f))) : 1.0f - __expf(x2);
;                         uu[e] = __builtin_amdgcn_sqrtf(om) * (ig * xc[e]); }
;                 u32x4 w0, w1; w0.x = pk2(la[0], uu[0]); w0.y = pk2(la[1], uu[1]); w0.z = pk2(la[2], uu[2]); w0.w = pk2(la[3], uu[3]);
;                 w1.x = pk2(la[4], uu[4]); w1.y = pk2(la[5], uu[5]); w1.z = pk2(la[6], uu[6]); w1.w = pk2(la[7], uu[7]);
;                 *(u32x4*)(LU + off) = w0; *(u32x4*)(LU + off + 4) = w1; }
	v_cndmask_b32_e64 v203, v207, v203, s[80:81]
	v_cndmask_b32_e64 v204, v208, v204, s[82:83]
	v_cndmask_b32_e64 v205, v209, v205, s[24:25]
	v_sqrt_f32_e32 v202, v202
	v_sqrt_f32_e32 v203, v203
	v_sqrt_f32_e32 v204, v204
	v_sqrt_f32_e32 v205, v205
	v_pk_mul_f32 v[100:101], v[100:101], v[202:203]
	v_pk_mul_f32 v[102:103], v[102:103], v[204:205]
	v_pk_add_f32 v[198:199], v[108:109], v[108:109]
	v_pk_add_f32 v[200:201], v[110:111], v[110:111]
	v_pk_mul_f32 v[206:207], v[198:199], s[70:71]
	v_pk_mul_f32 v[208:209], v[200:201], s[70:71]
	v_pk_fma_f32 v[202:203], v[198:199], s[74:75], v[222:223]
	v_pk_fma_f32 v[204:205], v[200:201], s[74:75], v[222:223]
	v_exp_f32_e32 v206, v206
	v_exp_f32_e32 v207, v207
	v_exp_f32_e32 v208, v208
	v_exp_f32_e32 v209, v209
	v_pk_fma_f32 v[202:203], v[198:199], v[202:203], s[76:77]
	v_pk_fma_f32 v[204:205], v[200:201], v[204:205], s[76:77]
	v_pk_fma_f32 v[202:203], v[198:199], v[202:203], s[72:73]
	v_pk_fma_f32 v[204:205], v[200:201], v[204:205], s[72:73]
	v_pk_mul_f32 v[202:203], v[202:203], v[198:199] neg_lo:[0,1] neg_hi:[0,1]
	v_pk_mul_f32 v[204:205], v[204:205], v[200:201] neg_lo:[0,1] neg_hi:[0,1]
	v_pk_add_f32 v[206:207], s[72:73], v[206:207] neg_lo:[0,1] neg_hi:[0,1]
	v_pk_add_f32 v[208:209], s[72:73], v[208:209] neg_lo:[0,1] neg_hi:[0,1]
	v_cmp_lt_f32_e64 s[78:79], s4, v198
	v_cmp_lt_f32_e64 s[80:81], s4, v199
	v_cmp_lt_f32_e64 s[82:83], s4, v200
	v_cmp_lt_f32_e64 s[24:25], s4, v201
	v_cndmask_b32_e64 v202, v206, v202, s[78:79]
	v_cndmask_b32_e64 v203, v207, v203, s[80:81]
	v_cndmask_b32_e64 v204, v208, v204, s[82:83]
	v_cndmask_b32_e64 v205, v209, v205, s[24:25]
	v_sqrt_f32_e32 v202, v202
	v_sqrt_f32_e32 v203, v203
	v_sqrt_f32_e32 v204, v204
	v_sqrt_f32_e32 v205, v205
	v_pk_mul_f32 v[104:105], v[104:105], v[202:203]
	v_pk_mul_f32 v[106:107], v[106:107], v[204:205]
	v_cvt_pk_bf16_f32 v100, v112, v100
	v_cvt_pk_bf16_f32 v101, v113, v101
	v_cvt_pk_bf16_f32 v102, v114, v102
	v_cvt_pk_bf16_f32 v103, v115, v103
	v_cvt_pk_bf16_f32 v104, v108, v104
	v_cvt_pk_bf16_f32 v105, v109, v105
	v_cvt_pk_bf16_f32 v106, v110, v106
	v_cvt_pk_bf16_f32 v107, v111, v107
	v_add_u32_e32 v197, 0x60000, v225
	global_store_dwordx4 v197, v[100:103], s[44:45]
	global_store_dwordx4 v197, v[104:107], s[44:45] offset:16
	v_pk_add_f32 v[92:93], v[92:93], v[68:69]
	v_pk_add_f32 v[80:81], v[80:81], v[32:33]
	v_pk_add_f32 v[94:95], v[94:95], v[70:71]
	v_pk_add_f32 v[82:83], v[82:83], v[34:35]
	v_pk_add_f32 v[88:89], v[88:89], v[56:57]
	v_pk_add_f32 v[84:85], v[84:85], v[36:37]
	v_pk_add_f32 v[90:91], v[90:91], v[58:59]
	v_pk_add_f32 v[86:87], v[86:87], v[38:39]
	v_pk_mul_f32 v[92:93], v[92:93], s[68:69]
	v_pk_mul_f32 v[80:81], v[80:81], s[68:69]
	v_pk_mul_f32 v[94:95], v[94:95], s[68:69]
	v_pk_mul_f32 v[82:83], v[82:83], s[68:69]
	v_pk_mul_f32 v[88:89], v[88:89], s[68:69]
	v_pk_mul_f32 v[84:85], v[84:85], s[68:69]
	v_pk_mul_f32 v[90:91], v[90:91], s[68:69]
	v_pk_mul_f32 v[86:87], v[86:87], s[68:69]
	v_exp_f32_e32 v92, v92
	v_exp_f32_e32 v93, v93
	v_exp_f32_e32 v94, v94
	v_exp_f32_e32 v95, v95
	v_exp_f32_e32 v88, v88
	v_exp_f32_e32 v89, v89
	v_exp_f32_e32 v90, v90
	v_exp_f32_e32 v91, v91
	v_exp_f32_e32 v80, v80
	v_exp_f32_e32 v81, v81
	v_exp_f32_e32 v82, v82
	v_exp_f32_e32 v83, v83
	v_exp_f32_e32 v84, v84
	v_exp_f32_e32 v85, v85
	v_exp_f32_e32 v86, v86
	v_exp_f32_e32 v87, v87
	v_pk_add_f32 v[92:93], v[92:93], s[72:73]
	v_pk_add_f32 v[80:81], v[80:81], s[72:73]
	v_pk_add_f32 v[94:95], v[94:95], s[72:73]
	v_pk_add_f32 v[82:83], v[82:83], s[72:73]
	v_pk_add_f32 v[88:89], v[88:89], s[72:73]
	v_pk_add_f32 v[84:85], v[84:85], s[72:73]
	v_pk_add_f32 v[90:91], v[90:91], s[72:73]
	v_pk_add_f32 v[86:87], v[86:87], s[72:73]
	v_rcp_f32_e32 v92, v92
	v_rcp_f32_e32 v93, v93
	v_rcp_f32_e32 v94, v94
	v_rcp_f32_e32 v95, v95
	v_rcp_f32_e32 v88, v88
	v_rcp_f32_e32 v89, v89
	v_rcp_f32_e32 v90, v90
	v_rcp_f32_e32 v91, v91
	v_rcp_f32_e32 v80, v80
	v_rcp_f32_e32 v81, v81
	v_rcp_f32_e32 v82, v82
	v_rcp_f32_e32 v83, v83
	v_rcp_f32_e32 v84, v84
	v_rcp_f32_e32 v85, v85
	v_rcp_f32_e32 v86, v86
	v_rcp_f32_e32 v87, v87
	s_waitcnt vmcnt(11)
	v_lshlrev_b32_e32 v230, 16, v116
	v_and_b32_e32 v231, 0xffff0000, v116
	v_lshlrev_b32_e32 v234, 16, v117
	v_and_b32_e32 v235, 0xffff0000, v117
	v_lshlrev_b32_e32 v236, 16, v118
	v_and_b32_e32 v237, 0xffff0000, v118
	v_lshlrev_b32_e32 v238, 16, v119
	v_and_b32_e32 v239, 0xffff0000, v119
	v_pk_mul_f32 v[92:93], v[64:65], v[92:93]
	v_pk_mul_f32 v[94:95], v[66:67], v[94:95]
	v_pk_mul_f32 v[88:89], v[52:53], v[88:89]
	v_pk_mul_f32 v[90:91], v[54:55], v[90:91]
	v_pk_mul_f32 v[80:81], v[80:81], v[230:231]
	v_pk_mul_f32 v[82:83], v[82:83], v[234:235]
	v_pk_mul_f32 v[84:85], v[84:85], v[236:237]
	v_pk_mul_f32 v[86:87], v[86:87], v[238:239]
	v_pk_add_f32 v[198:199], v[92:93], v[92:93]
	v_pk_add_f32 v[200:201], v[94:95], v[94:95]
	v_pk_mul_f32 v[206:207], v[198:199], s[70:71]
	v_pk_mul_f32 v[208:209], v[200:201], s[70:71]
	v_pk_fma_f32 v[202:203], v[198:199], s[74:75], v[222:223]
	v_pk_fma_f32 v[204:205], v[200:201], s[74:75], v[222:223]
	v_exp_f32_e32 v206, v206
	v_exp_f32_e32 v207, v207
	v_exp_f32_e32 v208, v208
	v_exp_f32_e32 v209, v209
	v_pk_fma_f32 v[202:203], v[198:199], v[202:203], s[76:77]
	v_pk_fma_f32 v[204:205], v[200:201], v[204:205], s[76:77]
	v_pk_fma_f32 v[202:203], v[198:199], v[202:203], s[72:73]
	v_pk_fma_f32 v[204:205], v[200:201], v[204:205], s[72:73]
	v_pk_mul_f32 v[202:203], v[202:203], v[198:199] neg_lo:[0,1] neg_hi:[0,1]
	v_pk_mul_f32 v[204:205], v[204:205], v[200:201] neg_lo:[0,1] neg_hi:[0,1]
	v_pk_add_f32 v[206:207], s[72:73], v[206:207] neg_lo:[0,1] neg_hi:[0,1]
	v_pk_add_f32 v[208:209], s[72:73], v[208:209] neg_lo:[0,1] neg_hi:[0,1]
; __device__ __forceinline__ unsigned pk2(float lo, float hi) { unsigned r; asm("v_cvt_pk_bf16_f32 %0, %1, %2" : "=v"(r) : "v"(lo), "v"(hi)); return r; }
; __device__ __forceinline__ float sigmoidf_(float x) { return __builtin_amdgcn_rcpf(1.0f + __expf(-x)); }
;     __device__ __forceinline__ void operator()(const f32x4 (&acc)[2][2][4][2], const Unit& u, int wr, int wc, int fr, int fq) const {
;     ...
;             for (int m = 0; m < 4; ++m) { const size_t off = (size_t)(row0 + ai * HALF + m * 16) * LW + ch0;
;                 float xc[8]; unpack8(xraw[ai][m], xc);
;                 float la[8], uu[8];
; #pragma unroll
;                 for (int n = 0; n < 2; ++n)
; #pragma unroll
;                     for (int j = 0; j < 4; ++j) { const int e = 4 * n + j;
;                         const float r = sigmoidf_(acc[ai][0][m][n][j] + br[e]), ig = sigmoidf_(acc[ai][1][m][n][j] + bi[e]);
;                         const float l = -8.0f * r * sp[e]; la[e] = l;
;                         const float x2 = 2.0f * l;
;                         const float om = x2 > -0.03125f ? -x2 * (1.0f + x2 * (0.5f + x2 * (0.16666667f + x2 * 0.041666668f))) : 1.0f - __expf(x2);
;                         uu[e] = __builtin_amdgcn_sqrtf(om) * (ig * xc[e]); }
;                 u32x4 w0, w1; w0.x = pk2(la[0], uu[0]); w0.y = pk2(la[1], uu[1]); w0.z = pk2(la[2], uu[2]); w0.w = pk2(la[3], uu[3]);
;                 w1.x = pk2(la[4], uu[4]); w1.y = pk2(la[5], uu[5]); w1.z = pk2(la[6], uu[6]); w1.w = pk2(la[7], uu[7]);
;                 *(u32x4*)(LU + off) = w0; *(u32x4*)(LU + off + 4) = w1; }
	v_cmp_lt_f32_e64 s[78:79], s4, v198
	v_cmp_lt_f32_e64 s[80:81], s4, v199
	v_cmp_lt_f32_e64 s[82:83], s4, v200
	v_cmp_lt_f32_e64 s[24:25], s4, v201
	v_cndmask_b32_e64 v202, v206, v202, s[78:79]
	v_cndmask_b32_e64 v203, v207, v203, s[80:81]
	v_cndmask_b32_e64 v204, v208, v204, s[82:83]
	v_cndmask_b32_e64 v205, v209, v205, s[24:25]
	v_sqrt_f32_e32 v202, v202
	v_sqrt_f32_e32 v203, v203
	v_sqrt_f32_e32 v204, v204
	v_sqrt_f32_e32 v205, v205
	v_pk_mul_f32 v[80:81], v[80:81], v[202:203]
	v_pk_mul_f32 v[82:83], v[82:83], v[204:205]
	v_pk_add_f32 v[198:199], v[88:89], v[88:89]
	v_pk_add_f32 v[200:201], v[90:91], v[90:91]
	v_pk_mul_f32 v[206:207], v[198:199], s[70:71]
	v_pk_mul_f32 v[208:209], v[200:201], s[70:71]
	v_pk_fma_f32 v[202:203], v[198:199], s[74:75], v[222:223]
	v_pk_fma_f32 v[204:205], v[200:201], s[74:75], v[222:223]
	v_exp_f32_e32 v206, v206
	v_exp_f32_e32 v207, v207
	v_exp_f32_e32 v208, v208
	v_exp_f32_e32 v209, v209
	v_pk_fma_f32 v[202:203], v[198:199], v[202:203], s[76:77]
	v_pk_fma_f32 v[204:205], v[200:201], v[204:205], s[76:77]
	v_pk_fma_f32 v[202:203], v[198:199], v[202:203], s[72:73]
	v_pk_fma_f32 v[204:205], v[200:201], v[204:205], s[72:73]
	v_pk_mul_f32 v[202:203], v[202:203], v[198:199] neg_lo:[0,1] neg_hi:[0,1]
	v_pk_mul_f32 v[204:205], v[204:205], v[200:201] neg_lo:[0,1] neg_hi:[0,1]
	v_pk_add_f32 v[206:207], s[72:73], v[206:207] neg_lo:[0,1] neg_hi:[0,1]
	v_pk_add_f32 v[208:209], s[72:73], v[208:209] neg_lo:[0,1] neg_hi:[0,1]
	v_cmp_lt_f32_e64 s[78:79], s4, v198
	v_cmp_lt_f32_e64 s[80:81], s4, v199
	v_cmp_lt_f32_e64 s[82:83], s4, v200
	v_cmp_lt_f32_e64 s[24:25], s4, v201
	v_cndmask_b32_e64 v202, v206, v202, s[78:79]
	v_cndmask_b32_e64 v203, v207, v203, s[80:81]
	v_cndmask_b32_e64 v204, v208, v204, s[82:83]
	v_cndmask_b32_e64 v205, v209, v205, s[24:25]
	v_sqrt_f32_e32 v202, v202
	v_sqrt_f32_e32 v203, v203
	v_sqrt_f32_e32 v204, v204
	v_sqrt_f32_e32 v205, v205
	v_pk_mul_f32 v[84:85], v[84:85], v[202:203]
	v_pk_mul_f32 v[86:87], v[86:87], v[204:205]
	v_cvt_pk_bf16_f32 v80, v92, v80
	v_cvt_pk_bf16_f32 v81, v93, v81
	v_cvt_pk_bf16_f32 v82, v94, v82
	v_cvt_pk_bf16_f32 v83, v95, v83
	v_cvt_pk_bf16_f32 v84, v88, v84
	v_cvt_pk_bf16_f32 v85, v89, v85
	v_cvt_pk_bf16_f32 v86, v90, v86
	v_cvt_pk_bf16_f32 v87, v91, v87
	v_add_u32_e32 v197, 0x100000, v225
	global_store_dwordx4 v197, v[80:83], s[44:45]
	global_store_dwordx4 v197, v[84:87], s[44:45] offset:16
	v_pk_add_f32 v[72:73], v[72:73], v[68:69]
	v_pk_add_f32 v[40:41], v[40:41], v[32:33]
	v_pk_add_f32 v[74:75], v[74:75], v[70:71]
	v_pk_add_f32 v[42:43], v[42:43], v[34:35]
	v_pk_add_f32 v[60:61], v[60:61], v[56:57]
	v_pk_add_f32 v[44:45], v[44:45], v[36:37]
	v_pk_add_f32 v[62:63], v[62:63], v[58:59]
	v_pk_add_f32 v[46:47], v[46:47], v[38:39]
	v_pk_mul_f32 v[72:73], v[72:73], s[68:69]
	v_pk_mul_f32 v[40:41], v[40:41], s[68:69]
	v_pk_mul_f32 v[74:75], v[74:75], s[68:69]
	v_pk_mul_f32 v[42:43], v[42:43], s[68:69]
	v_pk_mul_f32 v[60:61], v[60:61], s[68:69]
	v_pk_mul_f32 v[44:45], v[44:45], s[68:69]
	v_pk_mul_f32 v[62:63], v[62:63], s[68:69]
	v_pk_mul_f32 v[46:47], v[46:47], s[68:69]
	v_exp_f32_e32 v72, v72
	v_exp_f32_e32 v73, v73
	v_exp_f32_e32 v74, v74
	v_exp_f32_e32 v75, v75
	v_exp_f32_e32 v60, v60
	v_exp_f32_e32 v61, v61
	v_exp_f32_e32 v62, v62
	v_exp_f32_e32 v63, v63
	v_exp_f32_e32 v40, v40
	v_exp_f32_e32 v41, v41
	v_exp_f32_e32 v42, v42
	v_exp_f32_e32 v43, v43
	v_exp_f32_e32 v44, v44
	v_exp_f32_e32 v45, v45
	v_exp_f32_e32 v46, v46
	v_exp_f32_e32 v47, v47
	v_pk_add_f32 v[72:73], v[72:73], s[72:73]
	v_pk_add_f32 v[40:41], v[40:41], s[72:73]
	v_pk_add_f32 v[74:75], v[74:75], s[72:73]
	v_pk_add_f32 v[42:43], v[42:43], s[72:73]
	v_pk_add_f32 v[60:61], v[60:61], s[72:73]
	v_pk_add_f32 v[44:45], v[44:45], s[72:73]
	v_pk_add_f32 v[62:63], v[62:63], s[72:73]
	v_pk_add_f32 v[46:47], v[46:47], s[72:73]
	v_rcp_f32_e32 v72, v72
	v_rcp_f32_e32 v73, v73
	v_rcp_f32_e32 v74, v74
	v_rcp_f32_e32 v75, v75
	v_rcp_f32_e32 v60, v60
	v_rcp_f32_e32 v61, v61
	v_rcp_f32_e32 v62, v62
	v_rcp_f32_e32 v63, v63
	v_rcp_f32_e32 v40, v40
	v_rcp_f32_e32 v41, v41
	v_rcp_f32_e32 v42, v42
	v_rcp_f32_e32 v43, v43
	v_rcp_f32_e32 v44, v44
	v_rcp_f32_e32 v45, v45
	v_rcp_f32_e32 v46, v46
	v_rcp_f32_e32 v47, v47
	s_waitcnt vmcnt(12)
	v_lshlrev_b32_e32 v230, 16, v96
	v_and_b32_e32 v231, 0xffff0000, v96
	v_lshlrev_b32_e32 v234, 16, v97
	v_and_b32_e32 v235, 0xffff0000, v97
	v_lshlrev_b32_e32 v236, 16, v98
	v_and_b32_e32 v237, 0xffff0000, v98
	v_lshlrev_b32_e32 v238, 16, v99
	v_and_b32_e32 v239, 0xffff0000, v99
	v_pk_mul_f32 v[72:73], v[64:65], v[72:73]
	v_pk_mul_f32 v[74:75], v[66:67], v[74:75]
	v_pk_mul_f32 v[60:61], v[52:53], v[60:61]
	v_pk_mul_f32 v[62:63], v[54:55], v[62:63]
	v_pk_mul_f32 v[40:41], v[40:41], v[230:231]
	v_pk_mul_f32 v[42:43], v[42:43], v[234:235]
	v_pk_mul_f32 v[44:45], v[44:45], v[236:237]
	v_pk_mul_f32 v[46:47], v[46:47], v[238:239]
	v_pk_add_f32 v[198:199], v[72:73], v[72:73]
	v_pk_add_f32 v[200:201], v[74:75], v[74:75]
	v_pk_mul_f32 v[206:207], v[198:199], s[70:71]
	v_pk_mul_f32 v[208:209], v[200:201], s[70:71]
	v_pk_fma_f32 v[202:203], v[198:199], s[74:75], v[222:223]
	v_pk_fma_f32 v[204:205], v[200:201], s[74:75], v[222:223]
	v_exp_f32_e32 v206, v206
	v_exp_f32_e32 v207, v207
	v_exp_f32_e32 v208, v208
	v_exp_f32_e32 v209, v209
	v_pk_fma_f32 v[202:203], v[198:199], v[202:203], s[76:77]
	v_pk_fma_f32 v[204:205], v[200:201], v[204:205], s[76:77]
	v_pk_fma_f32 v[202:203], v[198:199], v[202:203], s[72:73]
	v_pk_fma_f32 v[204:205], v[200:201], v[204:205], s[72:73]
	v_pk_mul_f32 v[202:203], v[202:203], v[198:199] neg_lo:[0,1] neg_hi:[0,1]
	v_pk_mul_f32 v[204:205], v[204:205], v[200:201] neg_lo:[0,1] neg_hi:[0,1]
; __device__ __forceinline__ unsigned pk2(float lo, float hi) { unsigned r; asm("v_cvt_pk_bf16_f32 %0, %1, %2" : "=v"(r) : "v"(lo), "v"(hi)); return r; }
; __device__ __forceinline__ float sigmoidf_(float x) { return __builtin_amdgcn_rcpf(1.0f + __expf(-x)); }
;     __device__ __forceinline__ void operator()(const f32x4 (&acc)[2][2][4][2], const Unit& u, int wr, int wc, int fr, int fq) const {
;     ...
;             for (int m = 0; m < 4; ++m) { const size_t off = (size_t)(row0 + ai * HALF + m * 16) * LW + ch0;
;                 float xc[8]; unpack8(xraw[ai][m], xc);
;                 float la[8], uu[8];
; #pragma unroll
;                 for (int n = 0; n < 2; ++n)
; #pragma unroll
;                     for (int j = 0; j < 4; ++j) { const int e = 4 * n + j;
;                         const float r = sigmoidf_(acc[ai][0][m][n][j] + br[e]), ig = sigmoidf_(acc[ai][1][m][n][j] + bi[e]);
;                         const float l = -8.0f * r * sp[e]; la[e] = l;
;                         const float x2 = 2.0f * l;
;                         const float om = x2 > -0.03125f ? -x2 * (1.0f + x2 * (0.5f + x2 * (0.16666667f + x2 * 0.041666668f))) : 1.0f - __expf(x2);
;                         uu[e] = __builtin_amdgcn_sqrtf(om) * (ig * xc[e]); }
;                 u32x4 w0, w1; w0.x = pk2(la[0], uu[0]); w0.y = pk2(la[1], uu[1]); w0.z = pk2(la[2], uu[2]); w0.w = pk2(la[3], uu[3]);
;                 w1.x = pk2(la[4], uu[4]); w1.y = pk2(la[5], uu[5]); w1.z = pk2(la[6], uu[6]); w1.w = pk2(la[7], uu[7]);
;                 *(u32x4*)(LU + off) = w0; *(u32x4*)(LU + off + 4) = w1; }
	v_pk_add_f32 v[206:207], s[72:73], v[206:207] neg_lo:[0,1] neg_hi:[0,1]
	v_pk_add_f32 v[208:209], s[72:73], v[208:209] neg_lo:[0,1] neg_hi:[0,1]
	v_cmp_lt_f32_e64 s[78:79], s4, v198
	v_cmp_lt_f32_e64 s[80:81], s4, v199
	v_cmp_lt_f32_e64 s[82:83], s4, v200
	v_cmp_lt_f32_e64 s[24:25], s4, v201
	v_cndmask_b32_e64 v202, v206, v202, s[78:79]
	v_cndmask_b32_e64 v203, v207, v203, s[80:81]
	v_cndmask_b32_e64 v204, v208, v204, s[82:83]
	v_cndmask_b32_e64 v205, v209, v205, s[24:25]
	v_sqrt_f32_e32 v202, v202
	v_sqrt_f32_e32 v203, v203
	v_sqrt_f32_e32 v204, v204
	v_sqrt_f32_e32 v205, v205
	v_pk_mul_f32 v[40:41], v[40:41], v[202:203]
	v_pk_mul_f32 v[42:43], v[42:43], v[204:205]
	v_pk_add_f32 v[198:199], v[60:61], v[60:61]
	v_pk_add_f32 v[200:201], v[62:63], v[62:63]
	v_pk_mul_f32 v[206:207], v[198:199], s[70:71]
	v_pk_mul_f32 v[208:209], v[200:201], s[70:71]
	v_pk_fma_f32 v[202:203], v[198:199], s[74:75], v[222:223]
	v_pk_fma_f32 v[204:205], v[200:201], s[74:75], v[222:223]
	v_exp_f32_e32 v206, v206
	v_exp_f32_e32 v207, v207
	v_exp_f32_e32 v208, v208
	v_exp_f32_e32 v209, v209
	v_pk_fma_f32 v[202:203], v[198:199], v[202:203], s[76:77]
	v_pk_fma_f32 v[204:205], v[200:201], v[204:205], s[76:77]
	v_pk_fma_f32 v[202:203], v[198:199], v[202:203], s[72:73]
	v_pk_fma_f32 v[204:205], v[200:201], v[204:205], s[72:73]
	v_pk_mul_f32 v[202:203], v[202:203], v[198:199] neg_lo:[0,1] neg_hi:[0,1]
	v_pk_mul_f32 v[204:205], v[204:205], v[200:201] neg_lo:[0,1] neg_hi:[0,1]
	v_pk_add_f32 v[206:207], s[72:73], v[206:207] neg_lo:[0,1] neg_hi:[0,1]
	v_pk_add_f32 v[208:209], s[72:73], v[208:209] neg_lo:[0,1] neg_hi:[0,1]
	v_cmp_lt_f32_e64 s[78:79], s4, v198
	v_cmp_lt_f32_e64 s[80:81], s4, v199
	v_cmp_lt_f32_e64 s[82:83], s4, v200
	v_cmp_lt_f32_e64 s[24:25], s4, v201
	v_cndmask_b32_e64 v202, v206, v202, s[78:79]
	v_cndmask_b32_e64 v203, v207, v203, s[80:81]
	v_cndmask_b32_e64 v204, v208, v204, s[82:83]
	v_cndmask_b32_e64 v205, v209, v205, s[24:25]
	v_sqrt_f32_e32 v202, v202
	v_sqrt_f32_e32 v203, v203
	v_sqrt_f32_e32 v204, v204
	v_sqrt_f32_e32 v205, v205
	v_pk_mul_f32 v[44:45], v[44:45], v[202:203]
	v_pk_mul_f32 v[46:47], v[46:47], v[204:205]
	v_cvt_pk_bf16_f32 v40, v72, v40
	v_cvt_pk_bf16_f32 v41, v73, v41
	v_cvt_pk_bf16_f32 v42, v74, v42
	v_cvt_pk_bf16_f32 v43, v75, v43
	v_cvt_pk_bf16_f32 v44, v60, v44
	v_cvt_pk_bf16_f32 v45, v61, v45
	v_cvt_pk_bf16_f32 v46, v62, v46
	v_cvt_pk_bf16_f32 v47, v63, v47
	v_add_u32_e32 v197, 0x120000, v225
	global_store_dwordx4 v197, v[40:43], s[44:45]
	global_store_dwordx4 v197, v[44:47], s[44:45] offset:16
	v_pk_add_f32 v[28:29], v[28:29], v[68:69]
	v_pk_add_f32 v[16:17], v[16:17], v[32:33]
	v_pk_add_f32 v[30:31], v[30:31], v[70:71]
	v_pk_add_f32 v[18:19], v[18:19], v[34:35]
	v_pk_add_f32 v[24:25], v[24:25], v[56:57]
	v_pk_add_f32 v[20:21], v[20:21], v[36:37]
	v_pk_add_f32 v[26:27], v[26:27], v[58:59]
	v_pk_add_f32 v[22:23], v[22:23], v[38:39]
	v_pk_mul_f32 v[28:29], v[28:29], s[68:69]
	v_pk_mul_f32 v[16:17], v[16:17], s[68:69]
	v_pk_mul_f32 v[30:31], v[30:31], s[68:69]
	v_pk_mul_f32 v[18:19], v[18:19], s[68:69]
	v_pk_mul_f32 v[24:25], v[24:25], s[68:69]
	v_pk_mul_f32 v[20:21], v[20:21], s[68:69]
	v_pk_mul_f32 v[26:27], v[26:27], s[68:69]
	v_pk_mul_f32 v[22:23], v[22:23], s[68:69]
	v_exp_f32_e32 v28, v28
	v_exp_f32_e32 v29, v29
	v_exp_f32_e32 v30, v30
	v_exp_f32_e32 v31, v31
	v_exp_f32_e32 v24, v24
	v_exp_f32_e32 v25, v25
	v_exp_f32_e32 v26, v26
	v_exp_f32_e32 v27, v27
	v_exp_f32_e32 v16, v16
	v_exp_f32_e32 v17, v17
	v_exp_f32_e32 v18, v18
	v_exp_f32_e32 v19, v19
	v_exp_f32_e32 v20, v20
	v_exp_f32_e32 v21, v21
	v_exp_f32_e32 v22, v22
	v_exp_f32_e32 v23, v23
	v_pk_add_f32 v[28:29], v[28:29], s[72:73]
	v_pk_add_f32 v[16:17], v[16:17], s[72:73]
	v_pk_add_f32 v[30:31], v[30:31], s[72:73]
	v_pk_add_f32 v[18:19], v[18:19], s[72:73]
	v_pk_add_f32 v[24:25], v[24:25], s[72:73]
	v_pk_add_f32 v[20:21], v[20:21], s[72:73]
	v_pk_add_f32 v[26:27], v[26:27], s[72:73]
	v_pk_add_f32 v[22:23], v[22:23], s[72:73]
	v_rcp_f32_e32 v28, v28
	v_rcp_f32_e32 v29, v29
	v_rcp_f32_e32 v30, v30
	v_rcp_f32_e32 v31, v31
	v_rcp_f32_e32 v24, v24
	v_rcp_f32_e32 v25, v25
	v_rcp_f32_e32 v26, v26
	v_rcp_f32_e32 v27, v27
	v_rcp_f32_e32 v16, v16
	v_rcp_f32_e32 v17, v17
	v_rcp_f32_e32 v18, v18
	v_rcp_f32_e32 v19, v19
	v_rcp_f32_e32 v20, v20
	v_rcp_f32_e32 v21, v21
	v_rcp_f32_e32 v22, v22
	v_rcp_f32_e32 v23, v23
	s_waitcnt vmcnt(13)
; __device__ __forceinline__ unsigned pk2(float lo, float hi) { unsigned r; asm("v_cvt_pk_bf16_f32 %0, %1, %2" : "=v"(r) : "v"(lo), "v"(hi)); return r; }
; __device__ __forceinline__ float sigmoidf_(float x) { return __builtin_amdgcn_rcpf(1.0f + __expf(-x)); }
;     __device__ __forceinline__ void operator()(const f32x4 (&acc)[2][2][4][2], const Unit& u, int wr, int wc, int fr, int fq) const {
;     ...
;             for (int m = 0; m < 4; ++m) { const size_t off = (size_t)(row0 + ai * HALF + m * 16) * LW + ch0;
;                 float xc[8]; unpack8(xraw[ai][m], xc);
;                 float la[8], uu[8];
; #pragma unroll
;                 for (int n = 0; n < 2; ++n)
; #pragma unroll
;                     for (int j = 0; j < 4; ++j) { const int e = 4 * n + j;
;                         const float r = sigmoidf_(acc[ai][0][m][n][j] + br[e]), ig = sigmoidf_(acc[ai][1][m][n][j] + bi[e]);
;                         const float l = -8.0f * r * sp[e]; la[e] = l;
;                         const float x2 = 2.0f * l;
;                         const float om = x2 > -0.03125f ? -x2 * (1.0f + x2 * (0.5f + x2 * (0.16666667f + x2 * 0.041666668f))) : 1.0f - __expf(x2);
;                         uu[e] = __builtin_amdgcn_sqrtf(om) * (ig * xc[e]); }
;                 u32x4 w0, w1; w0.x = pk2(la[0], uu[0]); w0.y = pk2(la[1], uu[1]); w0.z = pk2(la[2], uu[2]); w0.w = pk2(la[3], uu[3]);
;                 w1.x = pk2(la[4], uu[4]); w1.y = pk2(la[5], uu[5]); w1.z = pk2(la[6], uu[6]); w1.w = pk2(la[7], uu[7]);
;                 *(u32x4*)(LU + off) = w0; *(u32x4*)(LU + off + 4) = w1; }
	v_lshlrev_b32_e32 v230, 16, v76
	v_and_b32_e32 v231, 0xffff0000, v76
	v_lshlrev_b32_e32 v234, 16, v77
	v_and_b32_e32 v235, 0xffff0000, v77
	v_lshlrev_b32_e32 v236, 16, v78
	v_and_b32_e32 v237, 0xffff0000, v78
	v_lshlrev_b32_e32 v238, 16, v79
	v_and_b32_e32 v239, 0xffff0000, v79
	v_pk_mul_f32 v[28:29], v[64:65], v[28:29]
	v_pk_mul_f32 v[30:31], v[66:67], v[30:31]
	v_pk_mul_f32 v[24:25], v[52:53], v[24:25]
	v_pk_mul_f32 v[26:27], v[54:55], v[26:27]
	v_pk_mul_f32 v[16:17], v[16:17], v[230:231]
	v_pk_mul_f32 v[18:19], v[18:19], v[234:235]
	v_pk_mul_f32 v[20:21], v[20:21], v[236:237]
	v_pk_mul_f32 v[22:23], v[22:23], v[238:239]
	v_pk_add_f32 v[198:199], v[28:29], v[28:29]
	v_pk_add_f32 v[200:201], v[30:31], v[30:31]
	v_pk_mul_f32 v[206:207], v[198:199], s[70:71]
	v_pk_mul_f32 v[208:209], v[200:201], s[70:71]
	v_pk_fma_f32 v[202:203], v[198:199], s[74:75], v[222:223]
	v_pk_fma_f32 v[204:205], v[200:201], s[74:75], v[222:223]
	v_exp_f32_e32 v206, v206
	v_exp_f32_e32 v207, v207
	v_exp_f32_e32 v208, v208
	v_exp_f32_e32 v209, v209
	v_pk_fma_f32 v[202:203], v[198:199], v[202:203], s[76:77]
	v_pk_fma_f32 v[204:205], v[200:201], v[204:205], s[76:77]
	v_pk_fma_f32 v[202:203], v[198:199], v[202:203], s[72:73]
	v_pk_fma_f32 v[204:205], v[200:201], v[204:205], s[72:73]
	v_pk_mul_f32 v[202:203], v[202:203], v[198:199] neg_lo:[0,1] neg_hi:[0,1]
	v_pk_mul_f32 v[204:205], v[204:205], v[200:201] neg_lo:[0,1] neg_hi:[0,1]
	v_pk_add_f32 v[206:207], s[72:73], v[206:207] neg_lo:[0,1] neg_hi:[0,1]
	v_pk_add_f32 v[208:209], s[72:73], v[208:209] neg_lo:[0,1] neg_hi:[0,1]
	v_cmp_lt_f32_e64 s[78:79], s4, v198
	v_cmp_lt_f32_e64 s[80:81], s4, v199
	v_cmp_lt_f32_e64 s[82:83], s4, v200
	v_cmp_lt_f32_e64 s[24:25], s4, v201
	v_cndmask_b32_e64 v202, v206, v202, s[78:79]
	v_cndmask_b32_e64 v203, v207, v203, s[80:81]
	v_cndmask_b32_e64 v204, v208, v204, s[82:83]
	v_cndmask_b32_e64 v205, v209, v205, s[24:25]
	v_sqrt_f32_e32 v202, v202
	v_sqrt_f32_e32 v203, v203
	v_sqrt_f32_e32 v204, v204
	v_sqrt_f32_e32 v205, v205
	v_pk_mul_f32 v[16:17], v[16:17], v[202:203]
	v_pk_mul_f32 v[18:19], v[18:19], v[204:205]
	v_pk_add_f32 v[198:199], v[24:25], v[24:25]
	v_pk_add_f32 v[200:201], v[26:27], v[26:27]
	v_pk_mul_f32 v[206:207], v[198:199], s[70:71]
	v_pk_mul_f32 v[208:209], v[200:201], s[70:71]
	v_pk_fma_f32 v[202:203], v[198:199], s[74:75], v[222:223]
	v_pk_fma_f32 v[204:205], v[200:201], s[74:75], v[222:223]
	v_exp_f32_e32 v206, v206
	v_exp_f32_e32 v207, v207
	v_exp_f32_e32 v208, v208
	v_exp_f32_e32 v209, v209
	v_pk_fma_f32 v[202:203], v[198:199], v[202:203], s[76:77]
	v_pk_fma_f32 v[204:205], v[200:201], v[204:205], s[76:77]
	v_pk_fma_f32 v[202:203], v[198:199], v[202:203], s[72:73]
	v_pk_fma_f32 v[204:205], v[200:201], v[204:205], s[72:73]
	v_pk_mul_f32 v[202:203], v[202:203], v[198:199] neg_lo:[0,1] neg_hi:[0,1]
	v_pk_mul_f32 v[204:205], v[204:205], v[200:201] neg_lo:[0,1] neg_hi:[0,1]
	v_pk_add_f32 v[206:207], s[72:73], v[206:207] neg_lo:[0,1] neg_hi:[0,1]
	v_pk_add_f32 v[208:209], s[72:73], v[208:209] neg_lo:[0,1] neg_hi:[0,1]
	v_cmp_lt_f32_e64 s[78:79], s4, v198
	v_cmp_lt_f32_e64 s[80:81], s4, v199
	v_cmp_lt_f32_e64 s[82:83], s4, v200
	v_cmp_lt_f32_e64 s[24:25], s4, v201
	v_cndmask_b32_e64 v202, v206, v202, s[78:79]
	v_cndmask_b32_e64 v203, v207, v203, s[80:81]
	v_cndmask_b32_e64 v204, v208, v204, s[82:83]
	v_cndmask_b32_e64 v205, v209, v205, s[24:25]
	v_sqrt_f32_e32 v202, v202
	v_sqrt_f32_e32 v203, v203
	v_sqrt_f32_e32 v204, v204
	v_sqrt_f32_e32 v205, v205
	v_pk_mul_f32 v[20:21], v[20:21], v[202:203]
	v_pk_mul_f32 v[22:23], v[22:23], v[204:205]
	v_cvt_pk_bf16_f32 v16, v28, v16
	v_cvt_pk_bf16_f32 v17, v29, v17
	v_cvt_pk_bf16_f32 v18, v30, v18
	v_cvt_pk_bf16_f32 v19, v31, v19
	v_cvt_pk_bf16_f32 v20, v24, v20
	v_cvt_pk_bf16_f32 v21, v25, v21
	v_cvt_pk_bf16_f32 v22, v26, v22
	v_cvt_pk_bf16_f32 v23, v27, v23
	v_add_u32_e32 v197, 0x140000, v225
	global_store_dwordx4 v197, v[16:19], s[44:45]
	global_store_dwordx4 v197, v[20:23], s[44:45] offset:16
	v_pk_add_f32 v[12:13], v[12:13], v[68:69]
	v_pk_add_f32 v[0:1], v[0:1], v[32:33]
	v_pk_add_f32 v[14:15], v[14:15], v[70:71]
	v_pk_add_f32 v[2:3], v[2:3], v[34:35]
	v_pk_add_f32 v[8:9], v[8:9], v[56:57]
	v_pk_add_f32 v[4:5], v[4:5], v[36:37]
	v_pk_add_f32 v[10:11], v[10:11], v[58:59]
	v_pk_add_f32 v[6:7], v[6:7], v[38:39]
	v_pk_mul_f32 v[12:13], v[12:13], s[68:69]
	v_pk_mul_f32 v[0:1], v[0:1], s[68:69]
	v_pk_mul_f32 v[14:15], v[14:15], s[68:69]
	v_pk_mul_f32 v[2:3], v[2:3], s[68:69]
	v_pk_mul_f32 v[8:9], v[8:9], s[68:69]
	v_pk_mul_f32 v[4:5], v[4:5], s[68:69]
	v_pk_mul_f32 v[10:11], v[10:11], s[68:69]
	v_pk_mul_f32 v[6:7], v[6:7], s[68:69]
	v_exp_f32_e32 v12, v12
	v_exp_f32_e32 v13, v13
	v_exp_f32_e32 v14, v14
	v_exp_f32_e32 v15, v15
	v_exp_f32_e32 v8, v8
	v_exp_f32_e32 v9, v9
	v_exp_f32_e32 v10, v10
	v_exp_f32_e32 v11, v11
	v_exp_f32_e32 v0, v0
	v_exp_f32_e32 v1, v1
	v_exp_f32_e32 v2, v2
	v_exp_f32_e32 v3, v3
	v_exp_f32_e32 v4, v4
	v_exp_f32_e32 v5, v5
	v_exp_f32_e32 v6, v6
	v_exp_f32_e32 v7, v7
	v_pk_add_f32 v[12:13], v[12:13], s[72:73]
	v_pk_add_f32 v[0:1], v[0:1], s[72:73]
	v_pk_add_f32 v[14:15], v[14:15], s[72:73]
	v_pk_add_f32 v[2:3], v[2:3], s[72:73]
	v_pk_add_f32 v[8:9], v[8:9], s[72:73]
	v_pk_add_f32 v[4:5], v[4:5], s[72:73]
	v_pk_add_f32 v[10:11], v[10:11], s[72:73]
	v_pk_add_f32 v[6:7], v[6:7], s[72:73]
	v_rcp_f32_e32 v12, v12
	v_rcp_f32_e32 v13, v13
	v_rcp_f32_e32 v14, v14
	v_rcp_f32_e32 v15, v15
	v_rcp_f32_e32 v8, v8
	v_rcp_f32_e32 v9, v9
	v_rcp_f32_e32 v10, v10
	v_rcp_f32_e32 v11, v11
	v_rcp_f32_e32 v0, v0
	v_rcp_f32_e32 v1, v1
	v_rcp_f32_e32 v2, v2
	v_rcp_f32_e32 v3, v3
	v_rcp_f32_e32 v4, v4
	v_rcp_f32_e32 v5, v5
	v_rcp_f32_e32 v6, v6
	v_rcp_f32_e32 v7, v7
	s_waitcnt vmcnt(14)
; __device__ __forceinline__ unsigned pk2(float lo, float hi) { unsigned r; asm("v_cvt_pk_bf16_f32 %0, %1, %2" : "=v"(r) : "v"(lo), "v"(hi)); return r; }
; __device__ __forceinline__ float sigmoidf_(float x) { return __builtin_amdgcn_rcpf(1.0f + __expf(-x)); }
; template <class Epi, class S_t>
; __device__ __forceinline__ void gemm_phase(LAS unsigned char* lds, int lda, int ldb, const S_t& S, const Epi& E) {
;     ...
;         E(acc, cur, wr, wc, fr, fq);
;         if (!has_next) break;
;     __device__ __forceinline__ void operator()(const f32x4 (&acc)[2][2][4][2], const Unit& u, int wr, int wc, int fr, int fq) const {
;     ...
;             for (int m = 0; m < 4; ++m) { const size_t off = (size_t)(row0 + ai * HALF + m * 16) * LW + ch0;
;                 float xc[8]; unpack8(xraw[ai][m], xc);
;                 float la[8], uu[8];
; #pragma unroll
;                 for (int n = 0; n < 2; ++n)
; #pragma unroll
;                     for (int j = 0; j < 4; ++j) { const int e = 4 * n + j;
;                         const float r = sigmoidf_(acc[ai][0][m][n][j] + br[e]), ig = sigmoidf_(acc[ai][1][m][n][j] + bi[e]);
;                         const float l = -8.0f * r * sp[e]; la[e] = l;
;                         const float x2 = 2.0f * l;
;                         const float om = x2 > -0.03125f ? -x2 * (1.0f + x2 * (0.5f + x2 * (0.16666667f + x2 * 0.041666668f))) : 1.0f - __expf(x2);
;                         uu[e] = __builtin_amdgcn_sqrtf(om) * (ig * xc[e]); }
;                 u32x4 w0, w1; w0.x = pk2(la[0], uu[0]); w0.y = pk2(la[1], uu[1]); w0.z = pk2(la[2], uu[2]); w0.w = pk2(la[3], uu[3]);
;                 w1.x = pk2(la[4], uu[4]); w1.y = pk2(la[5], uu[5]); w1.z = pk2(la[6], uu[6]); w1.w = pk2(la[7], uu[7]);
;                 *(u32x4*)(LU + off) = w0; *(u32x4*)(LU + off + 4) = w1; }
	v_lshlrev_b32_e32 v230, 16, v48
	v_and_b32_e32 v231, 0xffff0000, v48
	v_lshlrev_b32_e32 v234, 16, v49
	v_and_b32_e32 v235, 0xffff0000, v49
	v_lshlrev_b32_e32 v236, 16, v50
	v_and_b32_e32 v237, 0xffff0000, v50
	v_lshlrev_b32_e32 v238, 16, v51
	v_and_b32_e32 v239, 0xffff0000, v51
	v_pk_mul_f32 v[12:13], v[64:65], v[12:13]
	v_pk_mul_f32 v[14:15], v[66:67], v[14:15]
	v_pk_mul_f32 v[8:9], v[52:53], v[8:9]
	v_pk_mul_f32 v[10:11], v[54:55], v[10:11]
	v_pk_mul_f32 v[0:1], v[0:1], v[230:231]
	v_pk_mul_f32 v[2:3], v[2:3], v[234:235]
	v_pk_mul_f32 v[4:5], v[4:5], v[236:237]
	v_pk_mul_f32 v[6:7], v[6:7], v[238:239]
	v_pk_add_f32 v[198:199], v[12:13], v[12:13]
	v_pk_add_f32 v[200:201], v[14:15], v[14:15]
	v_pk_mul_f32 v[206:207], v[198:199], s[70:71]
	v_pk_mul_f32 v[208:209], v[200:201], s[70:71]
	v_pk_fma_f32 v[202:203], v[198:199], s[74:75], v[222:223]
	v_pk_fma_f32 v[204:205], v[200:201], s[74:75], v[222:223]
	v_exp_f32_e32 v206, v206
	v_exp_f32_e32 v207, v207
	v_exp_f32_e32 v208, v208
	v_exp_f32_e32 v209, v209
	v_pk_fma_f32 v[202:203], v[198:199], v[202:203], s[76:77]
	v_pk_fma_f32 v[204:205], v[200:201], v[204:205], s[76:77]
	v_pk_fma_f32 v[202:203], v[198:199], v[202:203], s[72:73]
	v_pk_fma_f32 v[204:205], v[200:201], v[204:205], s[72:73]
	v_pk_mul_f32 v[202:203], v[202:203], v[198:199] neg_lo:[0,1] neg_hi:[0,1]
	v_pk_mul_f32 v[204:205], v[204:205], v[200:201] neg_lo:[0,1] neg_hi:[0,1]
	v_pk_add_f32 v[206:207], s[72:73], v[206:207] neg_lo:[0,1] neg_hi:[0,1]
	v_pk_add_f32 v[208:209], s[72:73], v[208:209] neg_lo:[0,1] neg_hi:[0,1]
	v_cmp_lt_f32_e64 s[78:79], s4, v198
	v_cmp_lt_f32_e64 s[80:81], s4, v199
	v_cmp_lt_f32_e64 s[82:83], s4, v200
	v_cmp_lt_f32_e64 s[24:25], s4, v201
	v_cndmask_b32_e64 v202, v206, v202, s[78:79]
	v_cndmask_b32_e64 v203, v207, v203, s[80:81]
	v_cndmask_b32_e64 v204, v208, v204, s[82:83]
	v_cndmask_b32_e64 v205, v209, v205, s[24:25]
	v_sqrt_f32_e32 v202, v202
	v_sqrt_f32_e32 v203, v203
	v_sqrt_f32_e32 v204, v204
	v_sqrt_f32_e32 v205, v205
	v_pk_mul_f32 v[0:1], v[0:1], v[202:203]
	v_pk_mul_f32 v[2:3], v[2:3], v[204:205]
	v_pk_add_f32 v[198:199], v[8:9], v[8:9]
	v_pk_add_f32 v[200:201], v[10:11], v[10:11]
	v_pk_mul_f32 v[206:207], v[198:199], s[70:71]
	v_pk_mul_f32 v[208:209], v[200:201], s[70:71]
	v_pk_fma_f32 v[202:203], v[198:199], s[74:75], v[222:223]
	v_pk_fma_f32 v[204:205], v[200:201], s[74:75], v[222:223]
	v_exp_f32_e32 v206, v206
	v_exp_f32_e32 v207, v207
	v_exp_f32_e32 v208, v208
	v_exp_f32_e32 v209, v209
	v_pk_fma_f32 v[202:203], v[198:199], v[202:203], s[76:77]
	v_pk_fma_f32 v[204:205], v[200:201], v[204:205], s[76:77]
	v_pk_fma_f32 v[202:203], v[198:199], v[202:203], s[72:73]
	v_pk_fma_f32 v[204:205], v[200:201], v[204:205], s[72:73]
	v_pk_mul_f32 v[202:203], v[202:203], v[198:199] neg_lo:[0,1] neg_hi:[0,1]
	v_pk_mul_f32 v[204:205], v[204:205], v[200:201] neg_lo:[0,1] neg_hi:[0,1]
	v_pk_add_f32 v[206:207], s[72:73], v[206:207] neg_lo:[0,1] neg_hi:[0,1]
	v_pk_add_f32 v[208:209], s[72:73], v[208:209] neg_lo:[0,1] neg_hi:[0,1]
	v_cmp_lt_f32_e64 s[78:79], s4, v198
	v_cmp_lt_f32_e64 s[80:81], s4, v199
	v_cmp_lt_f32_e64 s[82:83], s4, v200
	v_cmp_lt_f32_e64 s[24:25], s4, v201
	v_cndmask_b32_e64 v202, v206, v202, s[78:79]
	v_cndmask_b32_e64 v203, v207, v203, s[80:81]
	v_cndmask_b32_e64 v204, v208, v204, s[82:83]
	v_cndmask_b32_e64 v205, v209, v205, s[24:25]
	v_sqrt_f32_e32 v202, v202
	v_sqrt_f32_e32 v203, v203
	v_sqrt_f32_e32 v204, v204
	v_sqrt_f32_e32 v205, v205
	v_pk_mul_f32 v[4:5], v[4:5], v[202:203]
	v_pk_mul_f32 v[6:7], v[6:7], v[204:205]
	v_cvt_pk_bf16_f32 v0, v12, v0
	v_cvt_pk_bf16_f32 v1, v13, v1
	v_cvt_pk_bf16_f32 v2, v14, v2
	v_cvt_pk_bf16_f32 v3, v15, v3
	v_cvt_pk_bf16_f32 v4, v8, v4
	v_cvt_pk_bf16_f32 v5, v9, v5
	v_cvt_pk_bf16_f32 v6, v10, v6
	v_cvt_pk_bf16_f32 v7, v11, v7
	s_and_b64 vcc, exec, s[6:7]
	s_mov_b32 s42, s14
	s_mov_b32 s5, s18
	s_mov_b64 s[62:63], s[58:59]
	s_mov_b64 s[60:61], s[56:57]
	v_add_u32_e32 v197, 0x160000, v225
	global_store_dwordx4 v197, v[0:3], s[44:45]
	global_store_dwordx4 v197, v[4:7], s[44:45] offset:16
	s_cbranch_vccnz .LBB0_804
	s_branch .LBB0_544

; #define PG8_STAGE(bufoff, gbase, voff) do { _Pragma("unroll") for (int _i = 0; _i < 2; ++_i) \
;         __builtin_amdgcn_global_load_lds((const unsigned*)((const char*)(gbase) + (voff)[_i]), (LAS unsigned*)(lds + (bufoff) + ldsw + _i * 8192), 16, 0, 0); } while (0)
; #define PG8_LDA(dst, b, h) do { _Pragma("unroll") for (int m = 0; m < 4; ++m) _Pragma("unroll") for (int k = 0; k < 2; ++k) dst[m][k] = *(const LAS bf16x8*)(lds + PG8_SA(b, h) + aoff + m * 2048 + k * 1024); } while (0)
; #define PG8_LDB(dst, b, h) do { _Pragma("unroll") for (int n = 0; n < 2; ++n) _Pragma("unroll") for (int k = 0; k < 2; ++k) dst[n][k] = *(const LAS bf16x8*)(lds + PG8_SB(b, h) + boff + n * 2048 + k * 1024); } while (0)
; #define PG8_MMA(ai, bj, At, Bt) do { __builtin_amdgcn_s_setprio(1); _Pragma("unroll") for (int m = 0; m < 4; ++m) _Pragma("unroll") for (int n = 0; n < 2; ++n) _Pragma("unroll") for (int k = 0; k < 2; ++k) \
;         acc[ai][bj][m][n] = __builtin_amdgcn_mfma_f32_16x16x32_bf16(Bt[n][k], At[m][k], acc[ai][bj][m][n], 0, 0, 0); __builtin_amdgcn_s_setprio(0); } while (0)
; #define PG8_WAIT_V(n) asm volatile("s_waitcnt vmcnt(" #n ")" ::: "memory")
; #define PG8_WAIT_L(n) asm volatile("s_waitcnt lgkmcnt(" #n ")" ::: "memory")
; #define PG8_BAR __builtin_amdgcn_s_barrier()
; #define PG8_SCHED __builtin_amdgcn_sched_barrier(0)
; template <class Epi, class S_t>
; __device__ __forceinline__ void gemm_phase(LAS unsigned char* lds, int lda, int ldb, const S_t& S, const Epi& E) {
;     ...
;             PG8_LDB(B0, 0, 0); PG8_SCHED; PG8_LDA(At, 0, 0); PG8_STAGE(PG8_SA(1, 1), a1 + hstepA, voffA);
;             PG8_WAIT_L(8); PG8_BAR; PG8_WAIT_L(0); PG8_MMA(0, 0, At, B0); PG8_BAR; PG8_SCHED;
;             PG8_LDB(B1, 0, 1); PG8_STAGE(PG8_SB(0, 0), b2, voffB);
;             PG8_BAR; PG8_WAIT_L(0); PG8_MMA(0, 1, At, B1); PG8_BAR;
;             PG8_LDA(At, 0, 1); PG8_STAGE(PG8_SA(0, 0), a2, voffA);
;             PG8_BAR; PG8_WAIT_L(0); PG8_MMA(1, 0, At, B0); PG8_BAR; PG8_SCHED;
;             PG8_STAGE(PG8_SB(0, 1), b2 + hstepB, voffB);
;             PG8_WAIT_V(6); PG8_BAR; PG8_MMA(1, 1, At, B1); PG8_BAR;
.LBB0_945:
	ds_read_b128 v[140:143], v149
	ds_read_b128 v[152:155], v149 offset:1024
	ds_read_b128 v[156:159], v149 offset:2048
	ds_read_b128 v[160:163], v149 offset:3072
	s_add_u32 s33, s60, 0xfffc0080
	s_addc_u32 s52, s61, -1
	s_cmp_eq_u32 s43, 12
	s_cselect_b32 s67, s59, s52
	s_cselect_b32 s66, s58, s33
	s_cselect_b32 s63, s57, s1
	s_cselect_b32 s62, s56, s0
	s_add_i32 m0, s16, 0xc000
	ds_read_b128 v[164:167], v150
	ds_read_b128 v[168:171], v150 offset:1024
	ds_read_b128 v[172:175], v150 offset:2048
	ds_read_b128 v[176:179], v150 offset:3072
	ds_read_b128 v[180:183], v150 offset:4096
	ds_read_b128 v[186:189], v150 offset:5120
	ds_read_b128 v[190:193], v150 offset:6144
	ds_read_b128 v[194:197], v150 offset:7168
	global_load_lds_dwordx4 v136, s[60:61]
	s_add_i32 m0, s16, 0xe000
	s_nop 0
	global_load_lds_dwordx4 v138, s[60:61]
	s_waitcnt lgkmcnt(8)
	s_barrier
	s_waitcnt lgkmcnt(0)
	s_setprio 1
	v_mfma_f32_16x16x32_bf16 v[124:127], v[140:143], v[164:167], v[124:127]
	v_mfma_f32_16x16x32_bf16 v[120:123], v[156:159], v[164:167], v[120:123]
	v_mfma_f32_16x16x32_bf16 v[116:119], v[140:143], v[172:175], v[116:119]
	v_mfma_f32_16x16x32_bf16 v[108:111], v[156:159], v[172:175], v[108:111]
	v_mfma_f32_16x16x32_bf16 v[96:99], v[140:143], v[180:183], v[96:99]
	v_mfma_f32_16x16x32_bf16 v[88:91], v[156:159], v[180:183], v[88:91]
	v_mfma_f32_16x16x32_bf16 v[80:83], v[140:143], v[190:193], v[80:83]
	v_mfma_f32_16x16x32_bf16 v[72:75], v[156:159], v[190:193], v[72:75]
	v_mfma_f32_16x16x32_bf16 v[124:127], v[152:155], v[168:171], v[124:127]
	v_mfma_f32_16x16x32_bf16 v[120:123], v[160:163], v[168:171], v[120:123]
	v_mfma_f32_16x16x32_bf16 v[116:119], v[152:155], v[176:179], v[116:119]
	v_mfma_f32_16x16x32_bf16 v[108:111], v[160:163], v[176:179], v[108:111]
	v_mfma_f32_16x16x32_bf16 v[96:99], v[152:155], v[186:189], v[96:99]
	v_mfma_f32_16x16x32_bf16 v[88:91], v[160:163], v[186:189], v[88:91]
	v_mfma_f32_16x16x32_bf16 v[80:83], v[152:155], v[194:197], v[80:83]
	v_mfma_f32_16x16x32_bf16 v[72:75], v[160:163], v[194:197], v[72:75]
	s_setprio 0
	s_barrier
	s_add_i32 s33, s88, s5
	s_add_u32 s98, s62, s10
	s_addc_u32 s99, s63, s11
	s_mov_b32 m0, s33
	ds_read_b128 v[198:201], v151
	ds_read_b128 v[202:205], v151 offset:1024
	ds_read_b128 v[206:209], v151 offset:2048
	ds_read_b128 v[222:225], v151 offset:3072
	global_load_lds_dwordx4 v130, s[62:63]
	s_add_i32 m0, s33, 0x2000
	s_nop 0
	global_load_lds_dwordx4 v134, s[62:63]
	s_barrier
	s_waitcnt lgkmcnt(0)
	s_setprio 1
	v_mfma_f32_16x16x32_bf16 v[112:115], v[198:201], v[164:167], v[112:115]
	v_mfma_f32_16x16x32_bf16 v[104:107], v[206:209], v[164:167], v[104:107]
	v_mfma_f32_16x16x32_bf16 v[100:103], v[198:201], v[172:175], v[100:103]
	v_mfma_f32_16x16x32_bf16 v[92:95], v[206:209], v[172:175], v[92:95]
	v_mfma_f32_16x16x32_bf16 v[84:87], v[198:201], v[180:183], v[84:87]
	v_mfma_f32_16x16x32_bf16 v[76:79], v[206:209], v[180:183], v[76:79]
	v_mfma_f32_16x16x32_bf16 v[68:71], v[198:201], v[190:193], v[68:71]
	v_mfma_f32_16x16x32_bf16 v[64:67], v[206:209], v[190:193], v[64:67]
	v_mfma_f32_16x16x32_bf16 v[112:115], v[202:205], v[168:171], v[112:115]
	v_mfma_f32_16x16x32_bf16 v[104:107], v[222:225], v[168:171], v[104:107]
	v_mfma_f32_16x16x32_bf16 v[100:103], v[202:205], v[176:179], v[100:103]
	v_mfma_f32_16x16x32_bf16 v[92:95], v[222:225], v[176:179], v[92:95]
	v_mfma_f32_16x16x32_bf16 v[84:87], v[202:205], v[186:189], v[84:87]
	v_mfma_f32_16x16x32_bf16 v[76:79], v[222:225], v[186:189], v[76:79]
	v_mfma_f32_16x16x32_bf16 v[68:71], v[202:205], v[194:197], v[68:71]
	v_mfma_f32_16x16x32_bf16 v[64:67], v[222:225], v[194:197], v[64:67]
	s_setprio 0
	s_mov_b32 m0, s16
	s_add_u32 s100, s66, s10
	s_addc_u32 s101, s67, s11
	s_barrier
	ds_read_b128 v[164:167], v150 offset:16384
	ds_read_b128 v[168:171], v150 offset:17408
	ds_read_b128 v[172:175], v150 offset:18432
	ds_read_b128 v[176:179], v150 offset:19456
	ds_read_b128 v[180:183], v150 offset:20480
	ds_read_b128 v[186:189], v150 offset:21504
	ds_read_b128 v[190:193], v150 offset:22528
	ds_read_b128 v[194:197], v150 offset:23552
	global_load_lds_dwordx4 v128, s[66:67]
	s_mov_b32 m0, s17
	s_nop 0
	global_load_lds_dwordx4 v132, s[66:67]
	s_barrier
	s_waitcnt lgkmcnt(0)
	s_setprio 1
	v_mfma_f32_16x16x32_bf16 v[60:63], v[140:143], v[164:167], v[60:63]
	v_mfma_f32_16x16x32_bf16 v[56:59], v[156:159], v[164:167], v[56:59]
	v_mfma_f32_16x16x32_bf16 v[48:51], v[140:143], v[172:175], v[48:51]
	v_mfma_f32_16x16x32_bf16 v[40:43], v[156:159], v[172:175], v[40:43]
	v_mfma_f32_16x16x32_bf16 v[32:35], v[140:143], v[180:183], v[32:35]
	v_mfma_f32_16x16x32_bf16 v[24:27], v[156:159], v[180:183], v[24:27]
	v_mfma_f32_16x16x32_bf16 v[16:19], v[140:143], v[190:193], v[16:19]
	v_mfma_f32_16x16x32_bf16 v[8:11], v[156:159], v[190:193], v[8:11]
	v_mfma_f32_16x16x32_bf16 v[60:63], v[152:155], v[168:171], v[60:63]
	v_mfma_f32_16x16x32_bf16 v[56:59], v[160:163], v[168:171], v[56:59]
	v_mfma_f32_16x16x32_bf16 v[48:51], v[152:155], v[176:179], v[48:51]
	v_mfma_f32_16x16x32_bf16 v[40:43], v[160:163], v[176:179], v[40:43]
	v_mfma_f32_16x16x32_bf16 v[32:35], v[152:155], v[186:189], v[32:35]
	v_mfma_f32_16x16x32_bf16 v[24:27], v[160:163], v[186:189], v[24:27]
	v_mfma_f32_16x16x32_bf16 v[16:19], v[152:155], v[194:197], v[16:19]
	v_mfma_f32_16x16x32_bf16 v[8:11], v[160:163], v[194:197], v[8:11]
	s_setprio 0
	s_barrier
	s_add_u32 s52, s62, 0x40000
	s_addc_u32 s53, s63, 0
	s_add_i32 s33, s89, s5
	s_mov_b32 m0, s33
	s_nop 0
	global_load_lds_dwordx4 v130, s[52:53]
	s_add_i32 m0, s33, 0x2000
	s_nop 0
	global_load_lds_dwordx4 v134, s[52:53]
	s_waitcnt vmcnt(6)
	s_barrier
; #define PG8_STAGE(bufoff, gbase, voff) do { _Pragma("unroll") for (int _i = 0; _i < 2; ++_i) \
;         __builtin_amdgcn_global_load_lds((const unsigned*)((const char*)(gbase) + (voff)[_i]), (LAS unsigned*)(lds + (bufoff) + ldsw + _i * 8192), 16, 0, 0); } while (0)
; #define PG8_LDA(dst, b, h) do { _Pragma("unroll") for (int m = 0; m < 4; ++m) _Pragma("unroll") for (int k = 0; k < 2; ++k) dst[m][k] = *(const LAS bf16x8*)(lds + PG8_SA(b, h) + aoff + m * 2048 + k * 1024); } while (0)
; #define PG8_LDB(dst, b, h) do { _Pragma("unroll") for (int n = 0; n < 2; ++n) _Pragma("unroll") for (int k = 0; k < 2; ++k) dst[n][k] = *(const LAS bf16x8*)(lds + PG8_SB(b, h) + boff + n * 2048 + k * 1024); } while (0)
; #define PG8_WAIT_V(n) asm volatile("s_waitcnt vmcnt(" #n ")" ::: "memory")
; #define PG8_WAIT_L(n) asm volatile("s_waitcnt lgkmcnt(" #n ")" ::: "memory")
; #define PG8_BAR __builtin_amdgcn_s_barrier()
; #define PG8_SCHED __builtin_amdgcn_sched_barrier(0)
; template <class Epi, class S_t>
; __device__ __forceinline__ void gemm_phase(LAS unsigned char* lds, int lda, int ldb, const S_t& S, const Epi& E) {
;     ...
;             PG8_LDB(B0, 0, 0); PG8_SCHED; PG8_LDA(At, 0, 0); PG8_STAGE(PG8_SA(1, 1), a1 + hstepA, voffA);
;             PG8_WAIT_L(8); PG8_BAR; PG8_WAIT_L(0); PG8_MMA(0, 0, At, B0); PG8_BAR; PG8_SCHED;
;             PG8_LDB(B1, 0, 1); PG8_STAGE(PG8_SB(0, 0), b2, voffB);
;             PG8_BAR; PG8_WAIT_L(0); PG8_MMA(0, 1, At, B1); PG8_BAR;
;             PG8_LDA(At, 0, 1); PG8_STAGE(PG8_SA(0, 0), a2, voffA);
;             PG8_BAR; PG8_WAIT_L(0); PG8_MMA(1, 0, At, B0); PG8_BAR; PG8_SCHED;
;             PG8_STAGE(PG8_SB(0, 1), b2 + hstepB, voffB);
;             PG8_WAIT_V(6); PG8_BAR; PG8_MMA(1, 1, At, B1); PG8_BAR;
;             PG8_LDB(B0, 1, 0); PG8_SCHED; PG8_LDA(At, 1, 0); PG8_STAGE(PG8_SA(0, 1), a2 + hstepA, voffA);
;             PG8_WAIT_L(8); PG8_BAR; PG8_WAIT_L(0); PG8_MMA(0, 0, At, B0); PG8_BAR; PG8_SCHED;
;             PG8_LDB(B1, 1, 1); PG8_STAGE(PG8_SB(1, 0), b3, voffB);
;             PG8_BAR; PG8_WAIT_L(0); PG8_MMA(0, 1, At, B1); PG8_BAR;
;             PG8_LDA(At, 1, 1); PG8_STAGE(PG8_SA(1, 0), a3, voffA);
;             PG8_BAR; PG8_WAIT_L(0); PG8_MMA(1, 0, At, B0); PG8_BAR; PG8_SCHED;
;             PG8_STAGE(PG8_SB(1, 1), b3 + hstepB, voffB);
;             PG8_WAIT_V(6); PG8_BAR; PG8_MMA(1, 1, At, B1); PG8_BAR;
	s_setprio 1
	v_mfma_f32_16x16x32_bf16 v[52:55], v[198:201], v[164:167], v[52:55]
	v_mfma_f32_16x16x32_bf16 v[44:47], v[206:209], v[164:167], v[44:47]
	v_mfma_f32_16x16x32_bf16 v[36:39], v[198:201], v[172:175], v[36:39]
	v_mfma_f32_16x16x32_bf16 v[28:31], v[206:209], v[172:175], v[28:31]
	v_mfma_f32_16x16x32_bf16 v[20:23], v[198:201], v[180:183], v[20:23]
	v_mfma_f32_16x16x32_bf16 v[12:15], v[206:209], v[180:183], v[12:15]
	v_mfma_f32_16x16x32_bf16 v[4:7], v[198:201], v[190:193], v[4:7]
	v_mfma_f32_16x16x32_bf16 v[0:3], v[206:209], v[190:193], v[0:3]
	v_mfma_f32_16x16x32_bf16 v[52:55], v[202:205], v[168:171], v[52:55]
	v_mfma_f32_16x16x32_bf16 v[44:47], v[222:225], v[168:171], v[44:47]
	v_mfma_f32_16x16x32_bf16 v[36:39], v[202:205], v[176:179], v[36:39]
	v_mfma_f32_16x16x32_bf16 v[28:31], v[222:225], v[176:179], v[28:31]
	v_mfma_f32_16x16x32_bf16 v[20:23], v[202:205], v[186:189], v[20:23]
	v_mfma_f32_16x16x32_bf16 v[12:15], v[222:225], v[186:189], v[12:15]
	v_mfma_f32_16x16x32_bf16 v[4:7], v[202:205], v[194:197], v[4:7]
	v_mfma_f32_16x16x32_bf16 v[0:3], v[222:225], v[194:197], v[0:3]
	s_setprio 0
	v_add_u32_e32 v160, s90, v147
	s_barrier
	ds_read_b128 v[140:143], v160
	ds_read_b128 v[152:155], v160 offset:1024
	ds_read_b128 v[156:159], v160 offset:2048
	ds_read_b128 v[160:163], v160 offset:3072
	s_add_u32 s52, s66, 0x40000
	s_addc_u32 s53, s67, 0
	s_mov_b32 m0, s20
	ds_read_b128 v[164:167], v150 offset:32768
	ds_read_b128 v[168:171], v150 offset:33792
	ds_read_b128 v[172:175], v150 offset:34816
	ds_read_b128 v[176:179], v150 offset:35840
	ds_read_b128 v[180:183], v150 offset:36864
	ds_read_b128 v[186:189], v150 offset:37888
	ds_read_b128 v[190:193], v150 offset:38912
	ds_read_b128 v[194:197], v150 offset:39936
	global_load_lds_dwordx4 v128, s[52:53]
	s_mov_b32 m0, s21
	s_nop 0
	global_load_lds_dwordx4 v132, s[52:53]
	s_waitcnt lgkmcnt(8)
	s_barrier
	s_waitcnt lgkmcnt(0)
	s_setprio 1
	v_mfma_f32_16x16x32_bf16 v[124:127], v[140:143], v[164:167], v[124:127]
	v_mfma_f32_16x16x32_bf16 v[120:123], v[156:159], v[164:167], v[120:123]
	v_mfma_f32_16x16x32_bf16 v[116:119], v[140:143], v[172:175], v[116:119]
	v_mfma_f32_16x16x32_bf16 v[108:111], v[156:159], v[172:175], v[108:111]
	v_mfma_f32_16x16x32_bf16 v[96:99], v[140:143], v[180:183], v[96:99]
	v_mfma_f32_16x16x32_bf16 v[88:91], v[156:159], v[180:183], v[88:91]
	v_mfma_f32_16x16x32_bf16 v[80:83], v[140:143], v[190:193], v[80:83]
	v_mfma_f32_16x16x32_bf16 v[72:75], v[156:159], v[190:193], v[72:75]
	v_mfma_f32_16x16x32_bf16 v[124:127], v[152:155], v[168:171], v[124:127]
	v_mfma_f32_16x16x32_bf16 v[120:123], v[160:163], v[168:171], v[120:123]
	v_mfma_f32_16x16x32_bf16 v[116:119], v[152:155], v[176:179], v[116:119]
	v_mfma_f32_16x16x32_bf16 v[108:111], v[160:163], v[176:179], v[108:111]
	v_mfma_f32_16x16x32_bf16 v[96:99], v[152:155], v[186:189], v[96:99]
	v_mfma_f32_16x16x32_bf16 v[88:91], v[160:163], v[186:189], v[88:91]
	v_mfma_f32_16x16x32_bf16 v[80:83], v[152:155], v[194:197], v[80:83]
	v_mfma_f32_16x16x32_bf16 v[72:75], v[160:163], v[194:197], v[72:75]
	s_setprio 0
	s_barrier
	s_add_i32 s33, s90, s5
	v_add_u32_e32 v185, s91, v147
	s_mov_b32 m0, s33
	ds_read_b128 v[198:201], v185
	ds_read_b128 v[202:205], v185 offset:1024
	ds_read_b128 v[206:209], v185 offset:2048
	ds_read_b128 v[222:225], v185 offset:3072
	global_load_lds_dwordx4 v130, s[98:99]
	s_add_i32 m0, s33, 0x2000
	s_nop 0
	global_load_lds_dwordx4 v134, s[98:99]
	s_barrier
	s_waitcnt lgkmcnt(0)
	s_setprio 1
	v_mfma_f32_16x16x32_bf16 v[112:115], v[198:201], v[164:167], v[112:115]
	v_mfma_f32_16x16x32_bf16 v[104:107], v[206:209], v[164:167], v[104:107]
	v_mfma_f32_16x16x32_bf16 v[100:103], v[198:201], v[172:175], v[100:103]
	v_mfma_f32_16x16x32_bf16 v[92:95], v[206:209], v[172:175], v[92:95]
	v_mfma_f32_16x16x32_bf16 v[84:87], v[198:201], v[180:183], v[84:87]
	v_mfma_f32_16x16x32_bf16 v[76:79], v[206:209], v[180:183], v[76:79]
	v_mfma_f32_16x16x32_bf16 v[68:71], v[198:201], v[190:193], v[68:71]
	v_mfma_f32_16x16x32_bf16 v[64:67], v[206:209], v[190:193], v[64:67]
	v_mfma_f32_16x16x32_bf16 v[112:115], v[202:205], v[168:171], v[112:115]
	v_mfma_f32_16x16x32_bf16 v[104:107], v[222:225], v[168:171], v[104:107]
	v_mfma_f32_16x16x32_bf16 v[100:103], v[202:205], v[176:179], v[100:103]
	v_mfma_f32_16x16x32_bf16 v[92:95], v[222:225], v[176:179], v[92:95]
	v_mfma_f32_16x16x32_bf16 v[84:87], v[202:205], v[186:189], v[84:87]
	v_mfma_f32_16x16x32_bf16 v[76:79], v[222:225], v[186:189], v[76:79]
	v_mfma_f32_16x16x32_bf16 v[68:71], v[202:205], v[194:197], v[68:71]
	v_mfma_f32_16x16x32_bf16 v[64:67], v[222:225], v[194:197], v[64:67]
	s_setprio 0
	s_mov_b32 m0, s35
	s_barrier
	ds_read_b128 v[164:167], v150 offset:49152
	ds_read_b128 v[168:171], v150 offset:50176
	ds_read_b128 v[172:175], v150 offset:51200
	ds_read_b128 v[176:179], v150 offset:52224
	ds_read_b128 v[180:183], v150 offset:53248
	ds_read_b128 v[186:189], v150 offset:54272
	ds_read_b128 v[190:193], v150 offset:55296
	ds_read_b128 v[194:197], v150 offset:56320
	global_load_lds_dwordx4 v128, s[100:101]
	s_mov_b32 m0, s64
	s_nop 0
	global_load_lds_dwordx4 v132, s[100:101]
	s_barrier
; #define PG8_STAGE(bufoff, gbase, voff) do { _Pragma("unroll") for (int _i = 0; _i < 2; ++_i) \
;         __builtin_amdgcn_global_load_lds((const unsigned*)((const char*)(gbase) + (voff)[_i]), (LAS unsigned*)(lds + (bufoff) + ldsw + _i * 8192), 16, 0, 0); } while (0)
; #define PG8_LDA(dst, b, h) do { _Pragma("unroll") for (int m = 0; m < 4; ++m) _Pragma("unroll") for (int k = 0; k < 2; ++k) dst[m][k] = *(const LAS bf16x8*)(lds + PG8_SA(b, h) + aoff + m * 2048 + k * 1024); } while (0)
; #define PG8_LDB(dst, b, h) do { _Pragma("unroll") for (int n = 0; n < 2; ++n) _Pragma("unroll") for (int k = 0; k < 2; ++k) dst[n][k] = *(const LAS bf16x8*)(lds + PG8_SB(b, h) + boff + n * 2048 + k * 1024); } while (0)
; #define PG8_MMA(ai, bj, At, Bt) do { __builtin_amdgcn_s_setprio(1); _Pragma("unroll") for (int m = 0; m < 4; ++m) _Pragma("unroll") for (int n = 0; n < 2; ++n) _Pragma("unroll") for (int k = 0; k < 2; ++k) \
;         acc[ai][bj][m][n] = __builtin_amdgcn_mfma_f32_16x16x32_bf16(Bt[n][k], At[m][k], acc[ai][bj][m][n], 0, 0, 0); __builtin_amdgcn_s_setprio(0); } while (0)
; template <class Epi, class S_t>
; __device__ __forceinline__ void gemm_phase(LAS unsigned char* lds, int lda, int ldb, const S_t& S, const Epi& E) {
;     ...
;             PG8_WAIT_V(6); PG8_BAR; PG8_MMA(1, 1, At, B1); PG8_BAR;
;             PG8_LDB(B0, 1, 0); PG8_SCHED; PG8_LDA(At, 1, 0); PG8_STAGE(PG8_SA(0, 1), a2 + hstepA, voffA);
;             PG8_WAIT_L(8); PG8_BAR; PG8_WAIT_L(0); PG8_MMA(0, 0, At, B0); PG8_BAR; PG8_SCHED;
;             PG8_LDB(B1, 1, 1); PG8_STAGE(PG8_SB(1, 0), b3, voffB);
;             PG8_BAR; PG8_WAIT_L(0); PG8_MMA(0, 1, At, B1); PG8_BAR;
;             PG8_LDA(At, 1, 1); PG8_STAGE(PG8_SA(1, 0), a3, voffA);
;             PG8_BAR; PG8_WAIT_L(0); PG8_MMA(1, 0, At, B0); PG8_BAR; PG8_SCHED;
;             PG8_STAGE(PG8_SB(1, 1), b3 + hstepB, voffB);
;             PG8_WAIT_V(6); PG8_BAR; PG8_MMA(1, 1, At, B1); PG8_BAR;
;     __device__ __forceinline__ void operator()(const f32x4 (&acc)[2][2][4][2], const Unit& u, int wr, int wc, int fr, int fq) const {
;     ...
;                 for (int bj = 0; bj < 2; ++bj) { const int row = row0 + ai * HALF + m * 16, col = col0 + bj * HALF;
;                     gr[m][bj] = *(const u32x4*)(Z + (size_t)row * INW + gcol0 + col);
;                     if (ADD) orw[m][bj] = *(const u32x4*)(MG + (size_t)row * DM + col); }
	s_waitcnt lgkmcnt(0)
	s_setprio 1
	v_mfma_f32_16x16x32_bf16 v[60:63], v[140:143], v[164:167], v[60:63]
	v_mfma_f32_16x16x32_bf16 v[56:59], v[156:159], v[164:167], v[56:59]
	v_mfma_f32_16x16x32_bf16 v[48:51], v[140:143], v[172:175], v[48:51]
	v_mfma_f32_16x16x32_bf16 v[40:43], v[156:159], v[172:175], v[40:43]
	v_mfma_f32_16x16x32_bf16 v[32:35], v[140:143], v[180:183], v[32:35]
	v_mfma_f32_16x16x32_bf16 v[24:27], v[156:159], v[180:183], v[24:27]
	v_mfma_f32_16x16x32_bf16 v[16:19], v[140:143], v[190:193], v[16:19]
	v_mfma_f32_16x16x32_bf16 v[8:11], v[156:159], v[190:193], v[8:11]
	v_mfma_f32_16x16x32_bf16 v[60:63], v[152:155], v[168:171], v[60:63]
	v_mfma_f32_16x16x32_bf16 v[56:59], v[160:163], v[168:171], v[56:59]
	v_mfma_f32_16x16x32_bf16 v[48:51], v[152:155], v[176:179], v[48:51]
	v_mfma_f32_16x16x32_bf16 v[40:43], v[160:163], v[176:179], v[40:43]
	v_mfma_f32_16x16x32_bf16 v[32:35], v[152:155], v[186:189], v[32:35]
	v_mfma_f32_16x16x32_bf16 v[24:27], v[160:163], v[186:189], v[24:27]
	v_mfma_f32_16x16x32_bf16 v[16:19], v[152:155], v[194:197], v[16:19]
	v_mfma_f32_16x16x32_bf16 v[8:11], v[160:163], v[194:197], v[8:11]
	s_setprio 0
	s_barrier
	s_add_u32 s52, s62, 0x40080
	s_addc_u32 s53, s63, 0
	s_add_i32 s33, s91, s5
	s_mov_b32 m0, s33
	s_nop 0
	global_load_lds_dwordx4 v130, s[52:53]
	s_add_i32 m0, s33, 0x2000
	s_nop 0
	global_load_lds_dwordx4 v134, s[52:53]
	s_waitcnt vmcnt(6)
	s_barrier
	s_setprio 1
	v_mfma_f32_16x16x32_bf16 v[52:55], v[198:201], v[164:167], v[52:55]
	v_mfma_f32_16x16x32_bf16 v[44:47], v[206:209], v[164:167], v[44:47]
	v_mfma_f32_16x16x32_bf16 v[36:39], v[198:201], v[172:175], v[36:39]
	v_mfma_f32_16x16x32_bf16 v[28:31], v[206:209], v[172:175], v[28:31]
	v_mfma_f32_16x16x32_bf16 v[20:23], v[198:201], v[180:183], v[20:23]
	v_mfma_f32_16x16x32_bf16 v[12:15], v[206:209], v[180:183], v[12:15]
	v_mfma_f32_16x16x32_bf16 v[4:7], v[198:201], v[190:193], v[4:7]
	v_mfma_f32_16x16x32_bf16 v[0:3], v[206:209], v[190:193], v[0:3]
	v_mfma_f32_16x16x32_bf16 v[52:55], v[202:205], v[168:171], v[52:55]
	v_mfma_f32_16x16x32_bf16 v[44:47], v[222:225], v[168:171], v[44:47]
	v_mfma_f32_16x16x32_bf16 v[36:39], v[202:205], v[176:179], v[36:39]
	v_mfma_f32_16x16x32_bf16 v[28:31], v[222:225], v[176:179], v[28:31]
	v_mfma_f32_16x16x32_bf16 v[20:23], v[202:205], v[186:189], v[20:23]
	v_mfma_f32_16x16x32_bf16 v[12:15], v[222:225], v[186:189], v[12:15]
	v_mfma_f32_16x16x32_bf16 v[4:7], v[202:205], v[194:197], v[4:7]
	v_mfma_f32_16x16x32_bf16 v[0:3], v[222:225], v[194:197], v[0:3]
	s_setprio 0
	s_add_i32 s43, s43, 2
	s_add_u32 s60, s60, 0x100
	s_addc_u32 s61, s61, 0
	s_add_u32 s0, s0, 0x100
	s_addc_u32 s1, s1, 0
	s_cmp_gt_u32 s43, 13
	s_barrier
	s_cbranch_scc0 .LBB0_945
	v_lshl_or_b32 v140, s42, 8, v148
	v_lshl_add_u32 v142, s8, 8, v146
	v_ashrrev_i32_e32 v141, 31, v140
	v_mov_b64_e32 v[144:145], s[46:47]
	v_mad_i64_i32 v[152:153], s[0:1], v142, s69, v[144:145]
	v_lshlrev_b64 v[140:141], 1, v[140:141]
	v_or_b32_e32 v168, 16, v142
	v_lshl_add_u64 v[156:157], v[152:153], 0, v[140:141]
	v_mad_i64_i32 v[160:161], s[0:1], v168, s69, v[144:145]
	global_load_dwordx4 v[152:155], v[156:157], off
	s_nop 0
	global_load_dwordx4 v[156:159], v[156:157], off offset:256
	v_lshl_add_u64 v[164:165], v[160:161], 0, v[140:141]
	global_load_dwordx4 v[160:163], v[164:165], off
	v_or_b32_e32 v186, 32, v142
	global_load_dwordx4 v[164:167], v[164:165], off offset:256
	v_or_b32_e32 v188, 48, v142
	v_ashrrev_i32_e32 v143, 31, v142
	v_mad_i64_i32 v[170:171], s[0:1], v186, s69, v[144:145]
	v_mad_i64_i32 v[172:173], s[0:1], v188, s69, v[144:145]
	v_ashrrev_i32_e32 v169, 31, v168
	v_lshlrev_b64 v[174:175], 12, v[142:143]
	v_lshl_add_u64 v[176:177], v[170:171], 0, v[140:141]
	v_lshl_add_u64 v[180:181], v[172:173], 0, v[140:141]
	v_lshl_add_u64 v[190:191], s[44:45], 0, v[174:175]
	v_lshlrev_b64 v[192:193], 12, v[168:169]
	global_load_dwordx4 v[168:171], v[176:177], off
	global_load_dwordx4 v[172:175], v[176:177], off offset:256
	s_nop 0
	global_load_dwordx4 v[176:179], v[180:181], off
	s_nop 0
	global_load_dwordx4 v[180:183], v[180:181], off offset:256
	v_lshl_add_u64 v[190:191], v[190:191], 0, v[140:141]
	v_ashrrev_i32_e32 v187, 31, v186
	v_ashrrev_i32_e32 v189, 31, v188
	s_cmpk_lt_i32 s70, 0x3e8
	s_waitcnt vmcnt(0)
; __device__ __forceinline__ u32x4 pack8(const float (&f)[8]) { u32x4 w; w.x = pk2(f[0], f[1]); w.y = pk2(f[2], f[3]); w.z = pk2(f[4], f[5]); w.w = pk2(f[6], f[7]); return w; }
;     __device__ __forceinline__ void operator()(const f32x4 (&acc)[2][2][4][2], const Unit& u, int wr, int wc, int fr, int fq) const {
;     ...
;             for (int m = 0; m < 4; ++m)
; #pragma unroll
;                 for (int bj = 0; bj < 2; ++bj) { const int row = row0 + ai * HALF + m * 16, col = col0 + bj * HALF;
;                     float g[8], o[8]; unpack8(gr[m][bj], g);
;                     if (ADD) unpack8(orw[m][bj], o);
; #pragma unroll
;                     for (int n = 0; n < 2; ++n)
; #pragma unroll
;                         for (int j = 0; j < 4; ++j) { const int e = 4 * n + j; o[e] = ADD ? o[e] + g[e] * acc[ai][bj][m][n][j] : g[e] * acc[ai][bj][m][n][j]; }
;                     *(u32x4*)(MG + (size_t)row * DM + col) = pack8(o); }
	v_lshlrev_b32_e32 v143, 16, v152
	v_and_b32_e32 v152, 0xffff0000, v152
	v_lshlrev_b32_e32 v185, 16, v153
	v_and_b32_e32 v153, 0xffff0000, v153
	v_lshlrev_b32_e32 v194, 16, v154
	v_and_b32_e32 v154, 0xffff0000, v154
	v_lshlrev_b32_e32 v195, 16, v155
	v_and_b32_e32 v155, 0xffff0000, v155
	v_lshlrev_b32_e32 v196, 16, v156
	v_and_b32_e32 v156, 0xffff0000, v156
	v_lshlrev_b32_e32 v197, 16, v157
	v_and_b32_e32 v157, 0xffff0000, v157
	v_lshlrev_b32_e32 v198, 16, v158
	v_and_b32_e32 v158, 0xffff0000, v158
	v_lshlrev_b32_e32 v199, 16, v159
	v_and_b32_e32 v159, 0xffff0000, v159
	v_lshlrev_b32_e32 v200, 16, v160
	v_and_b32_e32 v160, 0xffff0000, v160
	v_lshlrev_b32_e32 v201, 16, v161
	v_lshlrev_b32_e32 v202, 16, v162
	v_and_b32_e32 v162, 0xffff0000, v162
	v_mul_f32_e32 v124, v124, v143
	v_mul_f32_e32 v125, v125, v152
	v_mul_f32_e32 v126, v126, v185
	v_mul_f32_e32 v127, v127, v153
	v_mul_f32_e32 v120, v120, v194
	v_mul_f32_e32 v121, v121, v154
	v_mul_f32_e32 v122, v122, v195
	v_mul_f32_e32 v123, v123, v155
	v_mul_f32_e32 v112, v112, v196
	v_mul_f32_e32 v113, v113, v156
	v_mul_f32_e32 v114, v114, v197
	v_mul_f32_e32 v115, v115, v157
	v_mul_f32_e32 v143, v104, v198
	v_mul_f32_e32 v152, v105, v158
	v_mul_f32_e32 v153, v106, v199
	v_mul_f32_e32 v154, v107, v159
	v_cvt_pk_bf16_f32 v104, v124, v125
	v_cvt_pk_bf16_f32 v105, v126, v127
	v_cvt_pk_bf16_f32 v106, v120, v121
	v_cvt_pk_bf16_f32 v107, v122, v123
	v_and_b32_e32 v161, 0xffff0000, v161
	v_cvt_pk_bf16_f32 v112, v112, v113
	v_cvt_pk_bf16_f32 v113, v114, v115
	v_cvt_pk_bf16_f32 v114, v143, v152
	v_cvt_pk_bf16_f32 v115, v153, v154
	global_store_dwordx4 v[190:191], v[104:107], off
	global_store_dwordx4 v[190:191], v[112:115], off offset:256
	v_mul_f32_e32 v108, v108, v202
	v_mul_f32_e32 v104, v116, v200
	v_mul_f32_e32 v105, v117, v160
	v_mul_f32_e32 v106, v118, v201
	v_mul_f32_e32 v109, v109, v162
	v_lshlrev_b32_e32 v203, 16, v163
	v_and_b32_e32 v163, 0xffff0000, v163
	v_mul_f32_e32 v107, v119, v161
	v_cvt_pk_bf16_f32 v104, v104, v105
	v_cvt_pk_bf16_f32 v105, v106, v107
	v_cvt_pk_bf16_f32 v106, v108, v109
	v_lshl_add_u64 v[108:109], s[44:45], 0, v[192:193]
	v_mul_f32_e32 v110, v110, v203
	v_mul_f32_e32 v111, v111, v163
	v_cvt_pk_bf16_f32 v107, v110, v111
	v_lshl_add_u64 v[108:109], v[108:109], 0, v[140:141]
	global_store_dwordx4 v[108:109], v[104:107], off
	v_lshlrev_b32_e32 v110, 16, v166
	v_and_b32_e32 v111, 0xffff0000, v166
	v_lshlrev_b32_e32 v104, 16, v164
	v_and_b32_e32 v105, 0xffff0000, v164
	v_lshlrev_b32_e32 v106, 16, v165
	v_and_b32_e32 v107, 0xffff0000, v165
	v_and_b32_e32 v113, 0xffff0000, v167
	v_lshlrev_b32_e32 v112, 16, v167
	v_mul_f32_e32 v100, v100, v104
	v_mul_f32_e32 v101, v101, v105
	v_mul_f32_e32 v102, v102, v106
	v_mul_f32_e32 v103, v103, v107
	v_mul_f32_e32 v104, v92, v110
	v_mul_f32_e32 v105, v93, v111
	v_mul_f32_e32 v95, v95, v113
	v_cvt_pk_bf16_f32 v92, v100, v101
	v_cvt_pk_bf16_f32 v93, v102, v103
	v_mul_f32_e32 v106, v94, v112
	v_cvt_pk_bf16_f32 v94, v104, v105
	v_cvt_pk_bf16_f32 v95, v106, v95
	global_store_dwordx4 v[108:109], v[92:95], off offset:256
	v_and_b32_e32 v105, 0xffff0000, v171
	v_lshlrev_b32_e32 v100, 16, v169
	v_lshlrev_b64 v[92:93], 12, v[186:187]
	v_lshlrev_b32_e32 v94, 16, v168
	v_and_b32_e32 v95, 0xffff0000, v168
	v_and_b32_e32 v101, 0xffff0000, v169
	v_lshlrev_b32_e32 v102, 16, v170
	v_and_b32_e32 v103, 0xffff0000, v170
	v_lshlrev_b32_e32 v104, 16, v171
	v_mul_f32_e32 v91, v91, v105
	v_lshl_add_u64 v[92:93], s[44:45], 0, v[92:93]
	v_mul_f32_e32 v94, v96, v94
	v_mul_f32_e32 v95, v97, v95
	v_mul_f32_e32 v96, v98, v100
	v_mul_f32_e32 v97, v99, v101
	v_mul_f32_e32 v98, v88, v102
	v_mul_f32_e32 v99, v89, v103
	v_mul_f32_e32 v100, v90, v104
	v_cvt_pk_bf16_f32 v88, v94, v95
	v_cvt_pk_bf16_f32 v89, v96, v97
	v_cvt_pk_bf16_f32 v90, v98, v99
	v_cvt_pk_bf16_f32 v91, v100, v91
	v_lshl_add_u64 v[92:93], v[92:93], 0, v[140:141]
	global_store_dwordx4 v[92:93], v[88:91], off
	v_lshlrev_b32_e32 v94, 16, v174
	v_and_b32_e32 v95, 0xffff0000, v174
	v_lshlrev_b32_e32 v88, 16, v172
	v_and_b32_e32 v89, 0xffff0000, v172
	v_lshlrev_b32_e32 v90, 16, v173
	v_and_b32_e32 v91, 0xffff0000, v173
	v_and_b32_e32 v97, 0xffff0000, v175
	v_lshlrev_b32_e32 v96, 16, v175
	v_mul_f32_e32 v84, v84, v88
	v_mul_f32_e32 v85, v85, v89
	v_mul_f32_e32 v86, v86, v90
	v_mul_f32_e32 v87, v87, v91
	v_mul_f32_e32 v88, v76, v94
	v_mul_f32_e32 v89, v77, v95
	v_mul_f32_e32 v79, v79, v97
	v_cvt_pk_bf16_f32 v76, v84, v85
	v_cvt_pk_bf16_f32 v77, v86, v87
	v_mul_f32_e32 v90, v78, v96
	v_cvt_pk_bf16_f32 v78, v88, v89
	v_cvt_pk_bf16_f32 v79, v90, v79
	global_store_dwordx4 v[92:93], v[76:79], off offset:256
	v_and_b32_e32 v89, 0xffff0000, v179
	v_lshlrev_b32_e32 v84, 16, v177
	v_lshlrev_b64 v[76:77], 12, v[188:189]
	v_lshlrev_b32_e32 v78, 16, v176
	v_and_b32_e32 v79, 0xffff0000, v176
	v_and_b32_e32 v85, 0xffff0000, v177
	v_lshlrev_b32_e32 v86, 16, v178
	v_and_b32_e32 v87, 0xffff0000, v178
	v_lshlrev_b32_e32 v88, 16, v179
	v_mul_f32_e32 v75, v75, v89
	v_lshl_add_u64 v[76:77], s[44:45], 0, v[76:77]
	v_mul_f32_e32 v78, v80, v78
	v_mul_f32_e32 v79, v81, v79
	v_mul_f32_e32 v80, v82, v84
	v_mul_f32_e32 v81, v83, v85
	v_mul_f32_e32 v82, v72, v86
	v_mul_f32_e32 v83, v73, v87
	v_mul_f32_e32 v84, v74, v88
	v_cvt_pk_bf16_f32 v72, v78, v79
	v_cvt_pk_bf16_f32 v73, v80, v81
	v_cvt_pk_bf16_f32 v74, v82, v83
	v_cvt_pk_bf16_f32 v75, v84, v75
	v_lshl_add_u64 v[76:77], v[76:77], 0, v[140:141]
	global_store_dwordx4 v[76:77], v[72:75], off
	v_lshlrev_b32_e32 v78, 16, v182
	v_and_b32_e32 v79, 0xffff0000, v182
	v_lshlrev_b32_e32 v72, 16, v180
	v_and_b32_e32 v73, 0xffff0000, v180
	v_lshlrev_b32_e32 v74, 16, v181
	v_and_b32_e32 v75, 0xffff0000, v181
; __device__ __forceinline__ u32x4 pack8(const float (&f)[8]) { u32x4 w; w.x = pk2(f[0], f[1]); w.y = pk2(f[2], f[3]); w.z = pk2(f[4], f[5]); w.w = pk2(f[6], f[7]); return w; }
;     __device__ __forceinline__ void operator()(const f32x4 (&acc)[2][2][4][2], const Unit& u, int wr, int wc, int fr, int fq) const {
;     ...
;             u32x4 gr[4][2], orw[4][2];
;             asm volatile("" ::: "memory");
; #pragma unroll
;             for (int m = 0; m < 4; ++m)
; #pragma unroll
;                 for (int bj = 0; bj < 2; ++bj) { const int row = row0 + ai * HALF + m * 16, col = col0 + bj * HALF;
;                     gr[m][bj] = *(const u32x4*)(Z + (size_t)row * INW + gcol0 + col);
;                     if (ADD) orw[m][bj] = *(const u32x4*)(MG + (size_t)row * DM + col); }
;     ...
;             for (int m = 0; m < 4; ++m)
; #pragma unroll
;                 for (int bj = 0; bj < 2; ++bj) { const int row = row0 + ai * HALF + m * 16, col = col0 + bj * HALF;
;                     float g[8], o[8]; unpack8(gr[m][bj], g);
;                     if (ADD) unpack8(orw[m][bj], o);
; #pragma unroll
;                     for (int n = 0; n < 2; ++n)
; #pragma unroll
;                         for (int j = 0; j < 4; ++j) { const int e = 4 * n + j; o[e] = ADD ? o[e] + g[e] * acc[ai][bj][m][n][j] : g[e] * acc[ai][bj][m][n][j]; }
;                     *(u32x4*)(MG + (size_t)row * DM + col) = pack8(o); }
	v_and_b32_e32 v81, 0xffff0000, v183
	v_lshlrev_b32_e32 v80, 16, v183
	v_mul_f32_e32 v68, v68, v72
	v_mul_f32_e32 v69, v69, v73
	v_mul_f32_e32 v70, v70, v74
	v_mul_f32_e32 v71, v71, v75
	v_mul_f32_e32 v72, v64, v78
	v_mul_f32_e32 v73, v65, v79
	v_mul_f32_e32 v67, v67, v81
	v_cvt_pk_bf16_f32 v64, v68, v69
	v_cvt_pk_bf16_f32 v65, v70, v71
	v_add_u32_e32 v96, 0x80, v142
	v_mul_f32_e32 v74, v66, v80
	v_cvt_pk_bf16_f32 v66, v72, v73
	v_cvt_pk_bf16_f32 v67, v74, v67
	global_store_dwordx4 v[76:77], v[64:67], off offset:256
	v_add_u32_e32 v98, 0x90, v142
	v_mad_i64_i32 v[72:73], s[0:1], v98, s69, v[144:145]
	v_mad_i64_i32 v[64:65], s[0:1], v96, s69, v[144:145]
	v_lshl_add_u64 v[68:69], v[64:65], 0, v[140:141]
	global_load_dwordx4 v[64:67], v[68:69], off
	s_nop 0
	global_load_dwordx4 v[68:71], v[68:69], off offset:256
	v_lshl_add_u64 v[76:77], v[72:73], 0, v[140:141]
	global_load_dwordx4 v[72:75], v[76:77], off
	v_add_u32_e32 v100, 0xa0, v142
	global_load_dwordx4 v[76:79], v[76:77], off offset:256
	v_mad_i64_i32 v[80:81], s[0:1], v100, s69, v[144:145]
	v_lshl_add_u64 v[84:85], v[80:81], 0, v[140:141]
	global_load_dwordx4 v[80:83], v[84:85], off
	s_nop 0
	global_load_dwordx4 v[84:87], v[84:85], off offset:256
	v_add_u32_e32 v102, 0xb0, v142
	v_mad_i64_i32 v[88:89], s[0:1], v102, s69, v[144:145]
	v_lshl_add_u64 v[92:93], v[88:89], 0, v[140:141]
	global_load_dwordx4 v[88:91], v[92:93], off
	s_nop 0
	global_load_dwordx4 v[92:95], v[92:93], off offset:256
	v_ashrrev_i32_e32 v97, 31, v96
	v_lshlrev_b64 v[96:97], 12, v[96:97]
	v_ashrrev_i32_e32 v99, 31, v98
	v_ashrrev_i32_e32 v101, 31, v100
	v_ashrrev_i32_e32 v103, 31, v102
	s_waitcnt vmcnt(0)
; __device__ __forceinline__ u32x4 pack8(const float (&f)[8]) { u32x4 w; w.x = pk2(f[0], f[1]); w.y = pk2(f[2], f[3]); w.z = pk2(f[4], f[5]); w.w = pk2(f[6], f[7]); return w; }
;     __device__ __forceinline__ void operator()(const f32x4 (&acc)[2][2][4][2], const Unit& u, int wr, int wc, int fr, int fq) const {
;     ...
;             for (int m = 0; m < 4; ++m)
; #pragma unroll
;                 for (int bj = 0; bj < 2; ++bj) { const int row = row0 + ai * HALF + m * 16, col = col0 + bj * HALF;
;                     float g[8], o[8]; unpack8(gr[m][bj], g);
;                     if (ADD) unpack8(orw[m][bj], o);
; #pragma unroll
;                     for (int n = 0; n < 2; ++n)
; #pragma unroll
;                         for (int j = 0; j < 4; ++j) { const int e = 4 * n + j; o[e] = ADD ? o[e] + g[e] * acc[ai][bj][m][n][j] : g[e] * acc[ai][bj][m][n][j]; }
;                     *(u32x4*)(MG + (size_t)row * DM + col) = pack8(o); }
;         }
;         if (!ADD && u.tag >= 1000) {
;             asm volatile("s_waitcnt vmcnt(0)" ::: "memory");
;             __builtin_amdgcn_fence(__ATOMIC_RELEASE, "agent");
;             asm volatile("s_waitcnt vmcnt(0)" ::: "memory");
;             if ((threadIdx.x & 63) == 0) __hip_atomic_fetch_add(flags + P7_FLAG(u.tag - 1000), 1u, __ATOMIC_RELAXED, __HIP_MEMORY_SCOPE_AGENT);
;         }
	v_lshlrev_b32_e32 v104, 16, v64
	v_and_b32_e32 v64, 0xffff0000, v64
	v_lshlrev_b32_e32 v105, 16, v65
	v_and_b32_e32 v65, 0xffff0000, v65
	v_lshlrev_b32_e32 v106, 16, v66
	v_and_b32_e32 v66, 0xffff0000, v66
	v_lshlrev_b32_e32 v107, 16, v67
	v_and_b32_e32 v67, 0xffff0000, v67
	v_mul_f32_e32 v60, v60, v104
	v_mul_f32_e32 v61, v61, v64
	v_mul_f32_e32 v63, v63, v65
	v_mul_f32_e32 v64, v56, v106
	v_mul_f32_e32 v65, v57, v66
	v_mul_f32_e32 v59, v59, v67
	v_cvt_pk_bf16_f32 v56, v60, v61
	v_lshl_add_u64 v[60:61], s[44:45], 0, v[96:97]
	v_mul_f32_e32 v62, v62, v105
	v_mul_f32_e32 v66, v58, v107
	v_cvt_pk_bf16_f32 v57, v62, v63
	v_cvt_pk_bf16_f32 v58, v64, v65
	v_cvt_pk_bf16_f32 v59, v66, v59
	v_lshl_add_u64 v[60:61], v[60:61], 0, v[140:141]
	v_and_b32_e32 v65, 0xffff0000, v71
	global_store_dwordx4 v[60:61], v[56:59], off
	v_lshlrev_b32_e32 v62, 16, v70
	v_and_b32_e32 v63, 0xffff0000, v70
	v_lshlrev_b32_e32 v56, 16, v68
	v_and_b32_e32 v57, 0xffff0000, v68
	v_lshlrev_b32_e32 v58, 16, v69
	v_and_b32_e32 v59, 0xffff0000, v69
	v_lshlrev_b32_e32 v64, 16, v71
	v_mul_f32_e32 v47, v47, v65
	v_mul_f32_e32 v52, v52, v56
	v_mul_f32_e32 v53, v53, v57
	v_mul_f32_e32 v54, v54, v58
	v_mul_f32_e32 v55, v55, v59
	v_mul_f32_e32 v56, v44, v62
	v_mul_f32_e32 v57, v45, v63
	v_mul_f32_e32 v58, v46, v64
	v_cvt_pk_bf16_f32 v44, v52, v53
	v_cvt_pk_bf16_f32 v45, v54, v55
	v_cvt_pk_bf16_f32 v47, v58, v47
	v_cvt_pk_bf16_f32 v46, v56, v57
	global_store_dwordx4 v[60:61], v[44:47], off offset:256
	v_and_b32_e32 v53, 0xffff0000, v73
	v_and_b32_e32 v57, 0xffff0000, v75
	v_lshlrev_b64 v[44:45], 12, v[98:99]
	v_and_b32_e32 v47, 0xffff0000, v72
	v_lshlrev_b32_e32 v46, 16, v72
	v_lshlrev_b32_e32 v52, 16, v73
	v_lshlrev_b32_e32 v54, 16, v74
	v_and_b32_e32 v55, 0xffff0000, v74
	v_lshlrev_b32_e32 v56, 16, v75
	v_mul_f32_e32 v47, v49, v47
	v_mul_f32_e32 v49, v51, v53
	v_mul_f32_e32 v43, v43, v57
	v_lshl_add_u64 v[44:45], s[44:45], 0, v[44:45]
	v_mul_f32_e32 v46, v48, v46
	v_mul_f32_e32 v48, v50, v52
	v_mul_f32_e32 v50, v40, v54
	v_mul_f32_e32 v51, v41, v55
	v_mul_f32_e32 v52, v42, v56
	v_cvt_pk_bf16_f32 v40, v46, v47
	v_cvt_pk_bf16_f32 v41, v48, v49
	v_cvt_pk_bf16_f32 v42, v50, v51
	v_cvt_pk_bf16_f32 v43, v52, v43
	v_lshl_add_u64 v[44:45], v[44:45], 0, v[140:141]
	v_and_b32_e32 v49, 0xffff0000, v79
	global_store_dwordx4 v[44:45], v[40:43], off
	v_lshlrev_b32_e32 v46, 16, v78
	v_and_b32_e32 v47, 0xffff0000, v78
	v_lshlrev_b32_e32 v40, 16, v76
	v_and_b32_e32 v41, 0xffff0000, v76
	v_lshlrev_b32_e32 v42, 16, v77
	v_and_b32_e32 v43, 0xffff0000, v77
	v_lshlrev_b32_e32 v48, 16, v79
	v_mul_f32_e32 v31, v31, v49
	v_mul_f32_e32 v36, v36, v40
	v_mul_f32_e32 v37, v37, v41
	v_mul_f32_e32 v38, v38, v42
	v_mul_f32_e32 v39, v39, v43
	v_mul_f32_e32 v40, v28, v46
	v_mul_f32_e32 v41, v29, v47
	v_mul_f32_e32 v42, v30, v48
	v_cvt_pk_bf16_f32 v28, v36, v37
	v_cvt_pk_bf16_f32 v29, v38, v39
	v_cvt_pk_bf16_f32 v31, v42, v31
	v_cvt_pk_bf16_f32 v30, v40, v41
	global_store_dwordx4 v[44:45], v[28:31], off offset:256
	v_and_b32_e32 v37, 0xffff0000, v81
	v_and_b32_e32 v41, 0xffff0000, v83
	v_lshlrev_b64 v[28:29], 12, v[100:101]
	v_and_b32_e32 v31, 0xffff0000, v80
	v_lshlrev_b32_e32 v30, 16, v80
	v_lshlrev_b32_e32 v36, 16, v81
	v_lshlrev_b32_e32 v38, 16, v82
	v_and_b32_e32 v39, 0xffff0000, v82
	v_lshlrev_b32_e32 v40, 16, v83
	v_mul_f32_e32 v31, v33, v31
	v_mul_f32_e32 v33, v35, v37
	v_mul_f32_e32 v27, v27, v41
	v_lshl_add_u64 v[28:29], s[44:45], 0, v[28:29]
	v_mul_f32_e32 v30, v32, v30
	v_mul_f32_e32 v32, v34, v36
	v_mul_f32_e32 v34, v24, v38
	v_mul_f32_e32 v35, v25, v39
	v_mul_f32_e32 v36, v26, v40
	v_cvt_pk_bf16_f32 v24, v30, v31
	v_cvt_pk_bf16_f32 v25, v32, v33
	v_cvt_pk_bf16_f32 v26, v34, v35
	v_cvt_pk_bf16_f32 v27, v36, v27
	v_lshl_add_u64 v[28:29], v[28:29], 0, v[140:141]
	v_and_b32_e32 v33, 0xffff0000, v87
	global_store_dwordx4 v[28:29], v[24:27], off
	v_lshlrev_b32_e32 v30, 16, v86
	v_and_b32_e32 v31, 0xffff0000, v86
	v_lshlrev_b32_e32 v24, 16, v84
	v_and_b32_e32 v25, 0xffff0000, v84
	v_lshlrev_b32_e32 v26, 16, v85
	v_and_b32_e32 v27, 0xffff0000, v85
	v_lshlrev_b32_e32 v32, 16, v87
	v_mul_f32_e32 v15, v15, v33
	v_mul_f32_e32 v20, v20, v24
	v_mul_f32_e32 v21, v21, v25
	v_mul_f32_e32 v22, v22, v26
	v_mul_f32_e32 v23, v23, v27
	v_mul_f32_e32 v24, v12, v30
	v_mul_f32_e32 v25, v13, v31
	v_mul_f32_e32 v26, v14, v32
	v_cvt_pk_bf16_f32 v12, v20, v21
	v_cvt_pk_bf16_f32 v13, v22, v23
	v_cvt_pk_bf16_f32 v15, v26, v15
	v_cvt_pk_bf16_f32 v14, v24, v25
	global_store_dwordx4 v[28:29], v[12:15], off offset:256
	v_and_b32_e32 v21, 0xffff0000, v89
	v_and_b32_e32 v25, 0xffff0000, v91
	v_lshlrev_b64 v[12:13], 12, v[102:103]
	v_and_b32_e32 v15, 0xffff0000, v88
	v_lshlrev_b32_e32 v14, 16, v88
	v_lshlrev_b32_e32 v20, 16, v89
	v_lshlrev_b32_e32 v22, 16, v90
	v_and_b32_e32 v23, 0xffff0000, v90
	v_lshlrev_b32_e32 v24, 16, v91
	v_mul_f32_e32 v15, v17, v15
	v_mul_f32_e32 v17, v19, v21
	v_mul_f32_e32 v11, v11, v25
	v_lshl_add_u64 v[12:13], s[44:45], 0, v[12:13]
	v_mul_f32_e32 v14, v16, v14
	v_mul_f32_e32 v16, v18, v20
	v_mul_f32_e32 v18, v8, v22
	v_mul_f32_e32 v19, v9, v23
	v_mul_f32_e32 v20, v10, v24
	v_cvt_pk_bf16_f32 v8, v14, v15
	v_cvt_pk_bf16_f32 v9, v16, v17
	v_cvt_pk_bf16_f32 v10, v18, v19
	v_cvt_pk_bf16_f32 v11, v20, v11
	v_lshl_add_u64 v[12:13], v[12:13], 0, v[140:141]
	v_and_b32_e32 v17, 0xffff0000, v95
	global_store_dwordx4 v[12:13], v[8:11], off
	v_lshlrev_b32_e32 v14, 16, v94
	v_and_b32_e32 v15, 0xffff0000, v94
	v_lshlrev_b32_e32 v8, 16, v92
	v_and_b32_e32 v9, 0xffff0000, v92
	v_lshlrev_b32_e32 v10, 16, v93
	v_and_b32_e32 v11, 0xffff0000, v93
	v_lshlrev_b32_e32 v16, 16, v95
	v_mul_f32_e32 v3, v3, v17
	v_mul_f32_e32 v4, v4, v8
	v_mul_f32_e32 v5, v5, v9
	v_mul_f32_e32 v6, v6, v10
	v_mul_f32_e32 v7, v7, v11
	v_mul_f32_e32 v8, v0, v14
	v_mul_f32_e32 v9, v1, v15
	v_mul_f32_e32 v10, v2, v16
	v_cvt_pk_bf16_f32 v0, v4, v5
	v_cvt_pk_bf16_f32 v1, v6, v7
	v_cvt_pk_bf16_f32 v2, v8, v9
	v_cvt_pk_bf16_f32 v3, v10, v3
	global_store_dwordx4 v[12:13], v[0:3], off offset:256
	s_branch .LBB0_941
	s_waitcnt vmcnt(0)
	buffer_wbl2 sc1
	s_waitcnt vmcnt(0) lgkmcnt(0)
	s_waitcnt vmcnt(0)
	s_and_saveexec_b64 s[0:1], s[6:7]
	s_cbranch_execz .LBB0_940
	s_mov_b64 s[52:53], exec
	v_mbcnt_lo_u32_b32 v0, s52, 0
	v_mbcnt_hi_u32_b32 v0, s53, v0
	v_cmp_eq_u32_e32 vcc, 0, v0
	s_and_b64 s[42:43], exec, vcc
	s_mov_b64 exec, s[42:43]
	s_cbranch_execz .LBB0_940
	s_lshl_b32 s8, s70, 6
	s_lshl_b64 s[42:43], s[8:9], 2
	v_readlane_b32 s56, v255, 1
	v_readlane_b32 s57, v255, 2
	s_add_u32 s8, s56, s42
	s_addc_u32 s33, s57, s43
	s_add_u32 s42, s8, 0xfffc4e00
	s_addc_u32 s43, s33, -1
	s_bcnt1_i32_b64 s8, s[52:53]
	v_mov_b32_e32 v0, s8
	global_atomic_add v131, v0, s[42:43]
	s_branch .LBB0_940

; #define PG8_STAGE(bufoff, gbase, voff) do { _Pragma("unroll") for (int _i = 0; _i < 2; ++_i) \
;         __builtin_amdgcn_global_load_lds((const unsigned*)((const char*)(gbase) + (voff)[_i]), (LAS unsigned*)(lds + (bufoff) + ldsw + _i * 8192), 16, 0, 0); } while (0)
; #define PG8_LDA(dst, b, h) do { _Pragma("unroll") for (int m = 0; m < 4; ++m) _Pragma("unroll") for (int k = 0; k < 2; ++k) dst[m][k] = *(const LAS bf16x8*)(lds + PG8_SA(b, h) + aoff + m * 2048 + k * 1024); } while (0)
; #define PG8_LDB(dst, b, h) do { _Pragma("unroll") for (int n = 0; n < 2; ++n) _Pragma("unroll") for (int k = 0; k < 2; ++k) dst[n][k] = *(const LAS bf16x8*)(lds + PG8_SB(b, h) + boff + n * 2048 + k * 1024); } while (0)
; #define PG8_WAIT_V(n) asm volatile("s_waitcnt vmcnt(" #n ")" ::: "memory")
; #define PG8_WAIT_L(n) asm volatile("s_waitcnt lgkmcnt(" #n ")" ::: "memory")
; #define PG8_BAR __builtin_amdgcn_s_barrier()
; #define PG8_SCHED __builtin_amdgcn_sched_barrier(0)
; template <class Epi, class S_t>
; __device__ __forceinline__ void gemm_phase(LAS unsigned char* lds, int lda, int ldb, const S_t& S, const Epi& E) {
;     ...
;             PG8_LDB(B0, 0, 0); PG8_SCHED; PG8_LDA(At, 0, 0); PG8_STAGE(PG8_SA(1, 1), a1 + hstepA, voffA);
;             PG8_WAIT_L(8); PG8_BAR; PG8_WAIT_L(0); PG8_MMA(0, 0, At, B0); PG8_BAR; PG8_SCHED;
;             PG8_LDB(B1, 0, 1); PG8_STAGE(PG8_SB(0, 0), b2, voffB);
;             PG8_BAR; PG8_WAIT_L(0); PG8_MMA(0, 1, At, B1); PG8_BAR;
;             PG8_LDA(At, 0, 1); PG8_STAGE(PG8_SA(0, 0), a2, voffA);
;             PG8_BAR; PG8_WAIT_L(0); PG8_MMA(1, 0, At, B0); PG8_BAR; PG8_SCHED;
;             PG8_STAGE(PG8_SB(0, 1), b2 + hstepB, voffB);
;             PG8_WAIT_V(6); PG8_BAR; PG8_MMA(1, 1, At, B1); PG8_BAR;
;             PG8_LDB(B0, 1, 0); PG8_SCHED; PG8_LDA(At, 1, 0); PG8_STAGE(PG8_SA(0, 1), a2 + hstepA, voffA);
;             PG8_WAIT_L(8); PG8_BAR; PG8_WAIT_L(0); PG8_MMA(0, 0, At, B0); PG8_BAR; PG8_SCHED;
;             PG8_LDB(B1, 1, 1); PG8_STAGE(PG8_SB(1, 0), b3, voffB);
;             PG8_BAR; PG8_WAIT_L(0); PG8_MMA(0, 1, At, B1); PG8_BAR;
;             PG8_LDA(At, 1, 1); PG8_STAGE(PG8_SA(1, 0), a3, voffA);
;             PG8_BAR; PG8_WAIT_L(0); PG8_MMA(1, 0, At, B0); PG8_BAR; PG8_SCHED;
;             PG8_STAGE(PG8_SB(1, 1), b3 + hstepB, voffB);
;             PG8_WAIT_V(6); PG8_BAR; PG8_MMA(1, 1, At, B1); PG8_BAR;
.LBB0_966:
	ds_read_b128 v[128:131], v169
	ds_read_b128 v[132:135], v169 offset:1024
	ds_read_b128 v[136:139], v169 offset:2048
	ds_read_b128 v[140:143], v169 offset:3072
	s_add_u32 s33, s56, 0xfff80080
	s_addc_u32 s58, s57, -1
	s_cmp_eq_u32 s43, 28
	s_cselect_b32 s61, s55, s58
	s_cselect_b32 s60, s54, s33
	s_cselect_b32 s59, s49, s1
	s_cselect_b32 s58, s48, s0
	s_add_i32 m0, s16, 0xc000
	ds_read_b128 v[156:159], v170
	ds_read_b128 v[160:163], v170 offset:1024
	ds_read_b128 v[172:175], v170 offset:2048
	ds_read_b128 v[176:179], v170 offset:3072
	ds_read_b128 v[180:183], v170 offset:4096
	ds_read_b128 v[186:189], v170 offset:5120
	ds_read_b128 v[190:193], v170 offset:6144
	ds_read_b128 v[194:197], v170 offset:7168
	global_load_lds_dwordx4 v152, s[56:57]
	s_add_i32 m0, s16, 0xe000
	s_nop 0
	global_load_lds_dwordx4 v154, s[56:57]
	s_waitcnt lgkmcnt(8)
	s_barrier
	s_waitcnt lgkmcnt(0)
	s_setprio 1
	v_mfma_f32_16x16x32_bf16 v[124:127], v[128:131], v[156:159], v[124:127]
	v_mfma_f32_16x16x32_bf16 v[120:123], v[136:139], v[156:159], v[120:123]
	v_mfma_f32_16x16x32_bf16 v[108:111], v[128:131], v[172:175], v[108:111]
	v_mfma_f32_16x16x32_bf16 v[104:107], v[136:139], v[172:175], v[104:107]
	v_mfma_f32_16x16x32_bf16 v[92:95], v[128:131], v[180:183], v[92:95]
	v_mfma_f32_16x16x32_bf16 v[88:91], v[136:139], v[180:183], v[88:91]
	v_mfma_f32_16x16x32_bf16 v[76:79], v[128:131], v[190:193], v[76:79]
	v_mfma_f32_16x16x32_bf16 v[72:75], v[136:139], v[190:193], v[72:75]
	v_mfma_f32_16x16x32_bf16 v[124:127], v[132:135], v[160:163], v[124:127]
	v_mfma_f32_16x16x32_bf16 v[120:123], v[140:143], v[160:163], v[120:123]
	v_mfma_f32_16x16x32_bf16 v[108:111], v[132:135], v[176:179], v[108:111]
	v_mfma_f32_16x16x32_bf16 v[104:107], v[140:143], v[176:179], v[104:107]
	v_mfma_f32_16x16x32_bf16 v[92:95], v[132:135], v[186:189], v[92:95]
	v_mfma_f32_16x16x32_bf16 v[88:91], v[140:143], v[186:189], v[88:91]
	v_mfma_f32_16x16x32_bf16 v[76:79], v[132:135], v[194:197], v[76:79]
	v_mfma_f32_16x16x32_bf16 v[72:75], v[140:143], v[194:197], v[72:75]
	s_setprio 0
	s_barrier
	s_add_i32 s33, s88, s5
	s_add_u32 s98, s58, s8
	s_addc_u32 s99, s59, s9
	s_mov_b32 m0, s33
	ds_read_b128 v[198:201], v171
	ds_read_b128 v[202:205], v171 offset:1024
	ds_read_b128 v[206:209], v171 offset:2048
	ds_read_b128 v[222:225], v171 offset:3072
	global_load_lds_dwordx4 v146, s[58:59]
	s_add_i32 m0, s33, 0x2000
	s_nop 0
	global_load_lds_dwordx4 v150, s[58:59]
	s_barrier
	s_waitcnt lgkmcnt(0)
	s_setprio 1
	v_mfma_f32_16x16x32_bf16 v[116:119], v[198:201], v[156:159], v[116:119]
	v_mfma_f32_16x16x32_bf16 v[112:115], v[206:209], v[156:159], v[112:115]
	v_mfma_f32_16x16x32_bf16 v[100:103], v[198:201], v[172:175], v[100:103]
	v_mfma_f32_16x16x32_bf16 v[96:99], v[206:209], v[172:175], v[96:99]
	v_mfma_f32_16x16x32_bf16 v[84:87], v[198:201], v[180:183], v[84:87]
	v_mfma_f32_16x16x32_bf16 v[80:83], v[206:209], v[180:183], v[80:83]
	v_mfma_f32_16x16x32_bf16 v[68:71], v[198:201], v[190:193], v[68:71]
	v_mfma_f32_16x16x32_bf16 v[64:67], v[206:209], v[190:193], v[64:67]
	v_mfma_f32_16x16x32_bf16 v[116:119], v[202:205], v[160:163], v[116:119]
	v_mfma_f32_16x16x32_bf16 v[112:115], v[222:225], v[160:163], v[112:115]
	v_mfma_f32_16x16x32_bf16 v[100:103], v[202:205], v[176:179], v[100:103]
	v_mfma_f32_16x16x32_bf16 v[96:99], v[222:225], v[176:179], v[96:99]
	v_mfma_f32_16x16x32_bf16 v[84:87], v[202:205], v[186:189], v[84:87]
	v_mfma_f32_16x16x32_bf16 v[80:83], v[222:225], v[186:189], v[80:83]
	v_mfma_f32_16x16x32_bf16 v[68:71], v[202:205], v[194:197], v[68:71]
	v_mfma_f32_16x16x32_bf16 v[64:67], v[222:225], v[194:197], v[64:67]
	s_setprio 0
	s_mov_b32 m0, s16
	s_add_u32 s100, s60, s8
	s_addc_u32 s101, s61, s9
	s_barrier
	ds_read_b128 v[156:159], v170 offset:16384
	ds_read_b128 v[160:163], v170 offset:17408
	ds_read_b128 v[172:175], v170 offset:18432
	ds_read_b128 v[176:179], v170 offset:19456
	ds_read_b128 v[180:183], v170 offset:20480
	ds_read_b128 v[186:189], v170 offset:21504
	ds_read_b128 v[190:193], v170 offset:22528
	ds_read_b128 v[194:197], v170 offset:23552
	global_load_lds_dwordx4 v144, s[60:61]
	s_mov_b32 m0, s17
	s_nop 0
	global_load_lds_dwordx4 v148, s[60:61]
	s_barrier
	s_waitcnt lgkmcnt(0)
	s_setprio 1
	v_mfma_f32_16x16x32_bf16 v[60:63], v[128:131], v[156:159], v[60:63]
	v_mfma_f32_16x16x32_bf16 v[56:59], v[136:139], v[156:159], v[56:59]
	v_mfma_f32_16x16x32_bf16 v[44:47], v[128:131], v[172:175], v[44:47]
	v_mfma_f32_16x16x32_bf16 v[40:43], v[136:139], v[172:175], v[40:43]
	v_mfma_f32_16x16x32_bf16 v[28:31], v[128:131], v[180:183], v[28:31]
	v_mfma_f32_16x16x32_bf16 v[24:27], v[136:139], v[180:183], v[24:27]
	v_mfma_f32_16x16x32_bf16 v[12:15], v[128:131], v[190:193], v[12:15]
	v_mfma_f32_16x16x32_bf16 v[8:11], v[136:139], v[190:193], v[8:11]
	v_mfma_f32_16x16x32_bf16 v[60:63], v[132:135], v[160:163], v[60:63]
	v_mfma_f32_16x16x32_bf16 v[56:59], v[140:143], v[160:163], v[56:59]
	v_mfma_f32_16x16x32_bf16 v[44:47], v[132:135], v[176:179], v[44:47]
	v_mfma_f32_16x16x32_bf16 v[40:43], v[140:143], v[176:179], v[40:43]
	v_mfma_f32_16x16x32_bf16 v[28:31], v[132:135], v[186:189], v[28:31]
	v_mfma_f32_16x16x32_bf16 v[24:27], v[140:143], v[186:189], v[24:27]
	v_mfma_f32_16x16x32_bf16 v[12:15], v[132:135], v[194:197], v[12:15]
	v_mfma_f32_16x16x32_bf16 v[8:11], v[140:143], v[194:197], v[8:11]
	s_setprio 0
	s_barrier
	s_add_u32 s64, s58, 0x80000
	s_addc_u32 s65, s59, 0
	s_add_i32 s33, s89, s5
	s_mov_b32 m0, s33
	s_nop 0
	global_load_lds_dwordx4 v146, s[64:65]
	s_add_i32 m0, s33, 0x2000
	s_nop 0
	global_load_lds_dwordx4 v150, s[64:65]
	s_waitcnt vmcnt(6)
	s_barrier
; #define PG8_STAGE(bufoff, gbase, voff) do { _Pragma("unroll") for (int _i = 0; _i < 2; ++_i) \
;         __builtin_amdgcn_global_load_lds((const unsigned*)((const char*)(gbase) + (voff)[_i]), (LAS unsigned*)(lds + (bufoff) + ldsw + _i * 8192), 16, 0, 0); } while (0)
; #define PG8_LDA(dst, b, h) do { _Pragma("unroll") for (int m = 0; m < 4; ++m) _Pragma("unroll") for (int k = 0; k < 2; ++k) dst[m][k] = *(const LAS bf16x8*)(lds + PG8_SA(b, h) + aoff + m * 2048 + k * 1024); } while (0)
; #define PG8_LDB(dst, b, h) do { _Pragma("unroll") for (int n = 0; n < 2; ++n) _Pragma("unroll") for (int k = 0; k < 2; ++k) dst[n][k] = *(const LAS bf16x8*)(lds + PG8_SB(b, h) + boff + n * 2048 + k * 1024); } while (0)
; #define PG8_MMA(ai, bj, At, Bt) do { __builtin_amdgcn_s_setprio(1); _Pragma("unroll") for (int m = 0; m < 4; ++m) _Pragma("unroll") for (int n = 0; n < 2; ++n) _Pragma("unroll") for (int k = 0; k < 2; ++k) \
;         acc[ai][bj][m][n] = __builtin_amdgcn_mfma_f32_16x16x32_bf16(Bt[n][k], At[m][k], acc[ai][bj][m][n], 0, 0, 0); __builtin_amdgcn_s_setprio(0); } while (0)
; #define PG8_WAIT_V(n) asm volatile("s_waitcnt vmcnt(" #n ")" ::: "memory")
; #define PG8_WAIT_L(n) asm volatile("s_waitcnt lgkmcnt(" #n ")" ::: "memory")
; #define PG8_BAR __builtin_amdgcn_s_barrier()
; #define PG8_SCHED __builtin_amdgcn_sched_barrier(0)
; template <class Epi, class S_t>
; __device__ __forceinline__ void gemm_phase(LAS unsigned char* lds, int lda, int ldb, const S_t& S, const Epi& E) {
;     ...
;             PG8_WAIT_V(6); PG8_BAR; PG8_MMA(1, 1, At, B1); PG8_BAR;
;             PG8_LDB(B0, 1, 0); PG8_SCHED; PG8_LDA(At, 1, 0); PG8_STAGE(PG8_SA(0, 1), a2 + hstepA, voffA);
;             PG8_WAIT_L(8); PG8_BAR; PG8_WAIT_L(0); PG8_MMA(0, 0, At, B0); PG8_BAR; PG8_SCHED;
;             PG8_LDB(B1, 1, 1); PG8_STAGE(PG8_SB(1, 0), b3, voffB);
;             PG8_BAR; PG8_WAIT_L(0); PG8_MMA(0, 1, At, B1); PG8_BAR;
	s_setprio 1
	v_mfma_f32_16x16x32_bf16 v[52:55], v[198:201], v[156:159], v[52:55]
	v_mfma_f32_16x16x32_bf16 v[48:51], v[206:209], v[156:159], v[48:51]
	v_mfma_f32_16x16x32_bf16 v[36:39], v[198:201], v[172:175], v[36:39]
	v_mfma_f32_16x16x32_bf16 v[32:35], v[206:209], v[172:175], v[32:35]
	v_mfma_f32_16x16x32_bf16 v[20:23], v[198:201], v[180:183], v[20:23]
	v_mfma_f32_16x16x32_bf16 v[16:19], v[206:209], v[180:183], v[16:19]
	v_mfma_f32_16x16x32_bf16 v[4:7], v[198:201], v[190:193], v[4:7]
	v_mfma_f32_16x16x32_bf16 v[0:3], v[206:209], v[190:193], v[0:3]
	v_mfma_f32_16x16x32_bf16 v[52:55], v[202:205], v[160:163], v[52:55]
	v_mfma_f32_16x16x32_bf16 v[48:51], v[222:225], v[160:163], v[48:51]
	v_mfma_f32_16x16x32_bf16 v[36:39], v[202:205], v[176:179], v[36:39]
	v_mfma_f32_16x16x32_bf16 v[32:35], v[222:225], v[176:179], v[32:35]
	v_mfma_f32_16x16x32_bf16 v[20:23], v[202:205], v[186:189], v[20:23]
	v_mfma_f32_16x16x32_bf16 v[16:19], v[222:225], v[186:189], v[16:19]
	v_mfma_f32_16x16x32_bf16 v[4:7], v[202:205], v[194:197], v[4:7]
	v_mfma_f32_16x16x32_bf16 v[0:3], v[222:225], v[194:197], v[0:3]
	s_setprio 0
	v_add_u32_e32 v140, s90, v167
	s_barrier
	ds_read_b128 v[128:131], v140
	ds_read_b128 v[132:135], v140 offset:1024
	ds_read_b128 v[136:139], v140 offset:2048
	ds_read_b128 v[140:143], v140 offset:3072
	s_add_u32 s60, s60, 0x80000
	s_addc_u32 s61, s61, 0
	s_mov_b32 m0, s20
	ds_read_b128 v[156:159], v170 offset:32768
	ds_read_b128 v[160:163], v170 offset:33792
	ds_read_b128 v[172:175], v170 offset:34816
	ds_read_b128 v[176:179], v170 offset:35840
	ds_read_b128 v[180:183], v170 offset:36864
	ds_read_b128 v[186:189], v170 offset:37888
	ds_read_b128 v[190:193], v170 offset:38912
	ds_read_b128 v[194:197], v170 offset:39936
	global_load_lds_dwordx4 v144, s[60:61]
	s_mov_b32 m0, s21
	s_nop 0
	global_load_lds_dwordx4 v148, s[60:61]
	s_waitcnt lgkmcnt(8)
	s_barrier
	s_waitcnt lgkmcnt(0)
	s_setprio 1
	v_mfma_f32_16x16x32_bf16 v[124:127], v[128:131], v[156:159], v[124:127]
	v_mfma_f32_16x16x32_bf16 v[120:123], v[136:139], v[156:159], v[120:123]
	v_mfma_f32_16x16x32_bf16 v[108:111], v[128:131], v[172:175], v[108:111]
	v_mfma_f32_16x16x32_bf16 v[104:107], v[136:139], v[172:175], v[104:107]
	v_mfma_f32_16x16x32_bf16 v[92:95], v[128:131], v[180:183], v[92:95]
	v_mfma_f32_16x16x32_bf16 v[88:91], v[136:139], v[180:183], v[88:91]
	v_mfma_f32_16x16x32_bf16 v[76:79], v[128:131], v[190:193], v[76:79]
	v_mfma_f32_16x16x32_bf16 v[72:75], v[136:139], v[190:193], v[72:75]
	v_mfma_f32_16x16x32_bf16 v[124:127], v[132:135], v[160:163], v[124:127]
	v_mfma_f32_16x16x32_bf16 v[120:123], v[140:143], v[160:163], v[120:123]
	v_mfma_f32_16x16x32_bf16 v[108:111], v[132:135], v[176:179], v[108:111]
	v_mfma_f32_16x16x32_bf16 v[104:107], v[140:143], v[176:179], v[104:107]
	v_mfma_f32_16x16x32_bf16 v[92:95], v[132:135], v[186:189], v[92:95]
	v_mfma_f32_16x16x32_bf16 v[88:91], v[140:143], v[186:189], v[88:91]
	v_mfma_f32_16x16x32_bf16 v[76:79], v[132:135], v[194:197], v[76:79]
	v_mfma_f32_16x16x32_bf16 v[72:75], v[140:143], v[194:197], v[72:75]
	s_setprio 0
	s_barrier
	s_add_i32 s33, s90, s5
	v_add_u32_e32 v185, s91, v167
	s_mov_b32 m0, s33
	ds_read_b128 v[198:201], v185
	ds_read_b128 v[202:205], v185 offset:1024
	ds_read_b128 v[206:209], v185 offset:2048
	ds_read_b128 v[222:225], v185 offset:3072
	global_load_lds_dwordx4 v146, s[98:99]
	s_add_i32 m0, s33, 0x2000
	s_nop 0
	global_load_lds_dwordx4 v150, s[98:99]
	s_barrier
; #define PG8_STAGE(bufoff, gbase, voff) do { _Pragma("unroll") for (int _i = 0; _i < 2; ++_i) \
;         __builtin_amdgcn_global_load_lds((const unsigned*)((const char*)(gbase) + (voff)[_i]), (LAS unsigned*)(lds + (bufoff) + ldsw + _i * 8192), 16, 0, 0); } while (0)
; #define PG8_LDA(dst, b, h) do { _Pragma("unroll") for (int m = 0; m < 4; ++m) _Pragma("unroll") for (int k = 0; k < 2; ++k) dst[m][k] = *(const LAS bf16x8*)(lds + PG8_SA(b, h) + aoff + m * 2048 + k * 1024); } while (0)
; #define PG8_MMA(ai, bj, At, Bt) do { __builtin_amdgcn_s_setprio(1); _Pragma("unroll") for (int m = 0; m < 4; ++m) _Pragma("unroll") for (int n = 0; n < 2; ++n) _Pragma("unroll") for (int k = 0; k < 2; ++k) \
;         acc[ai][bj][m][n] = __builtin_amdgcn_mfma_f32_16x16x32_bf16(Bt[n][k], At[m][k], acc[ai][bj][m][n], 0, 0, 0); __builtin_amdgcn_s_setprio(0); } while (0)
; #define PG8_WAIT_V(n) asm volatile("s_waitcnt vmcnt(" #n ")" ::: "memory")
; #define PG8_WAIT_L(n) asm volatile("s_waitcnt lgkmcnt(" #n ")" ::: "memory")
; #define PG8_BAR __builtin_amdgcn_s_barrier()
; #define PG8_SCHED __builtin_amdgcn_sched_barrier(0)
; template <class Epi, class S_t>
; __device__ __forceinline__ void gemm_phase(LAS unsigned char* lds, int lda, int ldb, const S_t& S, const Epi& E) {
;     ...
;             PG8_BAR; PG8_WAIT_L(0); PG8_MMA(0, 1, At, B1); PG8_BAR;
;             PG8_LDA(At, 1, 1); PG8_STAGE(PG8_SA(1, 0), a3, voffA);
;             PG8_BAR; PG8_WAIT_L(0); PG8_MMA(1, 0, At, B0); PG8_BAR; PG8_SCHED;
;             PG8_STAGE(PG8_SB(1, 1), b3 + hstepB, voffB);
;             PG8_WAIT_V(6); PG8_BAR; PG8_MMA(1, 1, At, B1); PG8_BAR;
;     __device__ __forceinline__ void operator()(const f32x4 (&acc)[2][2][4][2], const Unit& u, int wr, int wc, int fr, int fq) const {
;     ...
;         if (ADD && u.tag >= 2000) {
;             unsigned* f = flags + P7_FLAG(u.tag - 2000); unsigned sp = 0;
;             while ((unsigned)__builtin_amdgcn_readfirstlane(__hip_atomic_load(f, __ATOMIC_RELAXED, __HIP_MEMORY_SCOPE_AGENT)) < 8u) { __builtin_amdgcn_s_sleep(2); if (++sp > (1u << 20)) break; }
;             __builtin_amdgcn_fence(__ATOMIC_ACQUIRE, "agent");
;             asm volatile("s_waitcnt vmcnt(0)" ::: "memory");
	s_waitcnt lgkmcnt(0)
	s_setprio 1
	v_mfma_f32_16x16x32_bf16 v[116:119], v[198:201], v[156:159], v[116:119]
	v_mfma_f32_16x16x32_bf16 v[112:115], v[206:209], v[156:159], v[112:115]
	v_mfma_f32_16x16x32_bf16 v[100:103], v[198:201], v[172:175], v[100:103]
	v_mfma_f32_16x16x32_bf16 v[96:99], v[206:209], v[172:175], v[96:99]
	v_mfma_f32_16x16x32_bf16 v[84:87], v[198:201], v[180:183], v[84:87]
	v_mfma_f32_16x16x32_bf16 v[80:83], v[206:209], v[180:183], v[80:83]
	v_mfma_f32_16x16x32_bf16 v[68:71], v[198:201], v[190:193], v[68:71]
	v_mfma_f32_16x16x32_bf16 v[64:67], v[206:209], v[190:193], v[64:67]
	v_mfma_f32_16x16x32_bf16 v[116:119], v[202:205], v[160:163], v[116:119]
	v_mfma_f32_16x16x32_bf16 v[112:115], v[222:225], v[160:163], v[112:115]
	v_mfma_f32_16x16x32_bf16 v[100:103], v[202:205], v[176:179], v[100:103]
	v_mfma_f32_16x16x32_bf16 v[96:99], v[222:225], v[176:179], v[96:99]
	v_mfma_f32_16x16x32_bf16 v[84:87], v[202:205], v[186:189], v[84:87]
	v_mfma_f32_16x16x32_bf16 v[80:83], v[222:225], v[186:189], v[80:83]
	v_mfma_f32_16x16x32_bf16 v[68:71], v[202:205], v[194:197], v[68:71]
	v_mfma_f32_16x16x32_bf16 v[64:67], v[222:225], v[194:197], v[64:67]
	s_setprio 0
	s_mov_b32 m0, s35
	s_barrier
	ds_read_b128 v[156:159], v170 offset:49152
	ds_read_b128 v[160:163], v170 offset:50176
	ds_read_b128 v[172:175], v170 offset:51200
	ds_read_b128 v[176:179], v170 offset:52224
	ds_read_b128 v[180:183], v170 offset:53248
	ds_read_b128 v[186:189], v170 offset:54272
	ds_read_b128 v[190:193], v170 offset:55296
	ds_read_b128 v[194:197], v170 offset:56320
	global_load_lds_dwordx4 v144, s[100:101]
	s_mov_b32 m0, s47
	s_nop 0
	global_load_lds_dwordx4 v148, s[100:101]
	s_barrier
	s_waitcnt lgkmcnt(0)
	s_setprio 1
	v_mfma_f32_16x16x32_bf16 v[60:63], v[128:131], v[156:159], v[60:63]
	v_mfma_f32_16x16x32_bf16 v[56:59], v[136:139], v[156:159], v[56:59]
	v_mfma_f32_16x16x32_bf16 v[44:47], v[128:131], v[172:175], v[44:47]
	v_mfma_f32_16x16x32_bf16 v[40:43], v[136:139], v[172:175], v[40:43]
	v_mfma_f32_16x16x32_bf16 v[28:31], v[128:131], v[180:183], v[28:31]
	v_mfma_f32_16x16x32_bf16 v[24:27], v[136:139], v[180:183], v[24:27]
	v_mfma_f32_16x16x32_bf16 v[12:15], v[128:131], v[190:193], v[12:15]
	v_mfma_f32_16x16x32_bf16 v[8:11], v[136:139], v[190:193], v[8:11]
	v_mfma_f32_16x16x32_bf16 v[60:63], v[132:135], v[160:163], v[60:63]
	v_mfma_f32_16x16x32_bf16 v[56:59], v[140:143], v[160:163], v[56:59]
	v_mfma_f32_16x16x32_bf16 v[44:47], v[132:135], v[176:179], v[44:47]
	v_mfma_f32_16x16x32_bf16 v[40:43], v[140:143], v[176:179], v[40:43]
	v_mfma_f32_16x16x32_bf16 v[28:31], v[132:135], v[186:189], v[28:31]
	v_mfma_f32_16x16x32_bf16 v[24:27], v[140:143], v[186:189], v[24:27]
	v_mfma_f32_16x16x32_bf16 v[12:15], v[132:135], v[194:197], v[12:15]
	v_mfma_f32_16x16x32_bf16 v[8:11], v[140:143], v[194:197], v[8:11]
	s_setprio 0
	s_barrier
	s_add_u32 s58, s58, 0x80080
	s_addc_u32 s59, s59, 0
	s_add_i32 s33, s91, s5
	s_mov_b32 m0, s33
	s_nop 0
	global_load_lds_dwordx4 v146, s[58:59]
	s_add_i32 m0, s33, 0x2000
	s_nop 0
	global_load_lds_dwordx4 v150, s[58:59]
	s_waitcnt vmcnt(6)
	s_barrier
	s_setprio 1
	v_mfma_f32_16x16x32_bf16 v[52:55], v[198:201], v[156:159], v[52:55]
	v_mfma_f32_16x16x32_bf16 v[48:51], v[206:209], v[156:159], v[48:51]
	v_mfma_f32_16x16x32_bf16 v[36:39], v[198:201], v[172:175], v[36:39]
	v_mfma_f32_16x16x32_bf16 v[32:35], v[206:209], v[172:175], v[32:35]
	v_mfma_f32_16x16x32_bf16 v[20:23], v[198:201], v[180:183], v[20:23]
	v_mfma_f32_16x16x32_bf16 v[16:19], v[206:209], v[180:183], v[16:19]
	v_mfma_f32_16x16x32_bf16 v[4:7], v[198:201], v[190:193], v[4:7]
	v_mfma_f32_16x16x32_bf16 v[0:3], v[206:209], v[190:193], v[0:3]
	v_mfma_f32_16x16x32_bf16 v[52:55], v[202:205], v[160:163], v[52:55]
	v_mfma_f32_16x16x32_bf16 v[48:51], v[222:225], v[160:163], v[48:51]
	v_mfma_f32_16x16x32_bf16 v[36:39], v[202:205], v[176:179], v[36:39]
	v_mfma_f32_16x16x32_bf16 v[32:35], v[222:225], v[176:179], v[32:35]
	v_mfma_f32_16x16x32_bf16 v[20:23], v[202:205], v[186:189], v[20:23]
	v_mfma_f32_16x16x32_bf16 v[16:19], v[222:225], v[186:189], v[16:19]
	v_mfma_f32_16x16x32_bf16 v[4:7], v[202:205], v[194:197], v[4:7]
	v_mfma_f32_16x16x32_bf16 v[0:3], v[222:225], v[194:197], v[0:3]
	s_setprio 0
	s_add_i32 s43, s43, 2
	s_add_u32 s56, s56, 0x100
	s_addc_u32 s57, s57, 0
	s_add_u32 s0, s0, 0x100
	s_addc_u32 s1, s1, 0
	s_cmp_gt_u32 s43, 29
	s_barrier
	s_cbranch_scc0 .LBB0_966
	s_sub_i32 s98, s2, 32
	s_cmp_lt_u32 s98, 32
	s_cbranch_scc0 .Lp7x_nowait
	v_readlane_b32 s100, v255, 1
	v_readlane_b32 s101, v255, 2
	s_lshl_b32 s98, s98, 6
	s_addk_i32 s98, 0x1c00
	s_add_u32 s100, s100, s98
	s_addc_u32 s101, s101, 0

; #define PG8_STAGE(bufoff, gbase, voff) do { _Pragma("unroll") for (int _i = 0; _i < 2; ++_i) \
;         __builtin_amdgcn_global_load_lds((const unsigned*)((const char*)(gbase) + (voff)[_i]), (LAS unsigned*)(lds + (bufoff) + ldsw + _i * 8192), 16, 0, 0); } while (0)
; #define PG8_LDA(dst, b, h) do { _Pragma("unroll") for (int m = 0; m < 4; ++m) _Pragma("unroll") for (int k = 0; k < 2; ++k) dst[m][k] = *(const LAS bf16x8*)(lds + PG8_SA(b, h) + aoff + m * 2048 + k * 1024); } while (0)
; #define PG8_LDB(dst, b, h) do { _Pragma("unroll") for (int n = 0; n < 2; ++n) _Pragma("unroll") for (int k = 0; k < 2; ++k) dst[n][k] = *(const LAS bf16x8*)(lds + PG8_SB(b, h) + boff + n * 2048 + k * 1024); } while (0)
; #define PG8_WAIT_V(n) asm volatile("s_waitcnt vmcnt(" #n ")" ::: "memory")
; #define PG8_WAIT_L(n) asm volatile("s_waitcnt lgkmcnt(" #n ")" ::: "memory")
; #define PG8_BAR __builtin_amdgcn_s_barrier()
; #define PG8_SCHED __builtin_amdgcn_sched_barrier(0)
; template <class Epi, class S_t>
; __device__ __forceinline__ void gemm_phase(LAS unsigned char* lds, int lda, int ldb, const S_t& S, const Epi& E) {
;     ...
;             PG8_LDB(B0, 0, 0); PG8_SCHED; PG8_LDA(At, 0, 0); PG8_STAGE(PG8_SA(1, 1), a1 + hstepA, voffA);
;             PG8_WAIT_L(8); PG8_BAR; PG8_WAIT_L(0); PG8_MMA(0, 0, At, B0); PG8_BAR; PG8_SCHED;
;             PG8_LDB(B1, 0, 1); PG8_STAGE(PG8_SB(0, 0), b2, voffB);
;             PG8_BAR; PG8_WAIT_L(0); PG8_MMA(0, 1, At, B1); PG8_BAR;
;             PG8_LDA(At, 0, 1); PG8_STAGE(PG8_SA(0, 0), a2, voffA);
;             PG8_BAR; PG8_WAIT_L(0); PG8_MMA(1, 0, At, B0); PG8_BAR; PG8_SCHED;
;             PG8_STAGE(PG8_SB(0, 1), b2 + hstepB, voffB);
;             PG8_WAIT_V(6); PG8_BAR; PG8_MMA(1, 1, At, B1); PG8_BAR;
;             PG8_LDB(B0, 1, 0); PG8_SCHED; PG8_LDA(At, 1, 0); PG8_STAGE(PG8_SA(0, 1), a2 + hstepA, voffA);
;             PG8_WAIT_L(8); PG8_BAR; PG8_WAIT_L(0); PG8_MMA(0, 0, At, B0); PG8_BAR; PG8_SCHED;
;             PG8_LDB(B1, 1, 1); PG8_STAGE(PG8_SB(1, 0), b3, voffB);
;             PG8_BAR; PG8_WAIT_L(0); PG8_MMA(0, 1, At, B1); PG8_BAR;
;             PG8_LDA(At, 1, 1); PG8_STAGE(PG8_SA(1, 0), a3, voffA);
;             PG8_BAR; PG8_WAIT_L(0); PG8_MMA(1, 0, At, B0); PG8_BAR; PG8_SCHED;
;             PG8_STAGE(PG8_SB(1, 1), b3 + hstepB, voffB);
;             PG8_WAIT_V(6); PG8_BAR; PG8_MMA(1, 1, At, B1); PG8_BAR;
.LBB0_1051:
	ds_read_b128 v[150:153], v146
	ds_read_b128 v[154:157], v146 offset:1024
	ds_read_b128 v[158:161], v146 offset:2048
	ds_read_b128 v[162:165], v146 offset:3072
	s_add_i32 s70, s62, 2
	s_add_u32 s33, s60, 0xfff80080
	s_addc_u32 s63, s61, -1
	s_cmp_eq_u32 s0, s62
	s_cselect_b32 s62, s56, s1
	s_cselect_b32 s67, s59, s63
	s_cselect_b32 s66, s58, s33
	s_cselect_b32 s63, s57, s69
	s_add_i32 m0, s16, 0xc000
	ds_read_b128 v[166:169], v147
	ds_read_b128 v[170:173], v147 offset:1024
	ds_read_b128 v[174:177], v147 offset:2048
	ds_read_b128 v[178:181], v147 offset:3072
	ds_read_b128 v[186:189], v147 offset:4096
	ds_read_b128 v[190:193], v147 offset:5120
	ds_read_b128 v[194:197], v147 offset:6144
	ds_read_b128 v[198:201], v147 offset:7168
	global_load_lds_dwordx4 v136, s[60:61]
	s_add_i32 m0, s16, 0xe000
	s_nop 0
	global_load_lds_dwordx4 v138, s[60:61]
	s_waitcnt lgkmcnt(8)
	s_barrier
	s_waitcnt lgkmcnt(0)
	s_setprio 1
	v_mfma_f32_16x16x32_bf16 v[124:127], v[150:153], v[166:169], v[124:127]
	v_mfma_f32_16x16x32_bf16 v[120:123], v[158:161], v[166:169], v[120:123]
	v_mfma_f32_16x16x32_bf16 v[112:115], v[150:153], v[174:177], v[112:115]
	v_mfma_f32_16x16x32_bf16 v[104:107], v[158:161], v[174:177], v[104:107]
	v_mfma_f32_16x16x32_bf16 v[96:99], v[150:153], v[186:189], v[96:99]
	v_mfma_f32_16x16x32_bf16 v[88:91], v[158:161], v[186:189], v[88:91]
	v_mfma_f32_16x16x32_bf16 v[80:83], v[150:153], v[194:197], v[80:83]
	v_mfma_f32_16x16x32_bf16 v[72:75], v[158:161], v[194:197], v[72:75]
	v_mfma_f32_16x16x32_bf16 v[124:127], v[154:157], v[170:173], v[124:127]
	v_mfma_f32_16x16x32_bf16 v[120:123], v[162:165], v[170:173], v[120:123]
	v_mfma_f32_16x16x32_bf16 v[112:115], v[154:157], v[178:181], v[112:115]
	v_mfma_f32_16x16x32_bf16 v[104:107], v[162:165], v[178:181], v[104:107]
	v_mfma_f32_16x16x32_bf16 v[96:99], v[154:157], v[190:193], v[96:99]
	v_mfma_f32_16x16x32_bf16 v[88:91], v[162:165], v[190:193], v[88:91]
	v_mfma_f32_16x16x32_bf16 v[80:83], v[154:157], v[198:201], v[80:83]
	v_mfma_f32_16x16x32_bf16 v[72:75], v[162:165], v[198:201], v[72:75]
	s_setprio 0
	s_barrier
	s_add_i32 s33, s88, s5
	s_add_u32 s98, s62, s12
	s_addc_u32 s99, s63, s13
	s_mov_b32 m0, s33
	ds_read_b128 v[202:205], v148
	ds_read_b128 v[206:209], v148 offset:1024
	ds_read_b128 v[222:225], v148 offset:2048
	ds_read_b128 v[226:229], v148 offset:3072
	global_load_lds_dwordx4 v130, s[62:63]
	s_add_i32 m0, s33, 0x2000
	s_nop 0
	global_load_lds_dwordx4 v134, s[62:63]
	s_barrier
	s_waitcnt lgkmcnt(0)
	s_setprio 1
	v_mfma_f32_16x16x32_bf16 v[116:119], v[202:205], v[166:169], v[116:119]
	v_mfma_f32_16x16x32_bf16 v[108:111], v[222:225], v[166:169], v[108:111]
	v_mfma_f32_16x16x32_bf16 v[100:103], v[202:205], v[174:177], v[100:103]
	v_mfma_f32_16x16x32_bf16 v[92:95], v[222:225], v[174:177], v[92:95]
	v_mfma_f32_16x16x32_bf16 v[84:87], v[202:205], v[186:189], v[84:87]
	v_mfma_f32_16x16x32_bf16 v[76:79], v[222:225], v[186:189], v[76:79]
	v_mfma_f32_16x16x32_bf16 v[68:71], v[202:205], v[194:197], v[68:71]
	v_mfma_f32_16x16x32_bf16 v[64:67], v[222:225], v[194:197], v[64:67]
	v_mfma_f32_16x16x32_bf16 v[116:119], v[206:209], v[170:173], v[116:119]
	v_mfma_f32_16x16x32_bf16 v[108:111], v[226:229], v[170:173], v[108:111]
	v_mfma_f32_16x16x32_bf16 v[100:103], v[206:209], v[178:181], v[100:103]
	v_mfma_f32_16x16x32_bf16 v[92:95], v[226:229], v[178:181], v[92:95]
	v_mfma_f32_16x16x32_bf16 v[84:87], v[206:209], v[190:193], v[84:87]
	v_mfma_f32_16x16x32_bf16 v[76:79], v[226:229], v[190:193], v[76:79]
	v_mfma_f32_16x16x32_bf16 v[68:71], v[206:209], v[198:201], v[68:71]
	v_mfma_f32_16x16x32_bf16 v[64:67], v[226:229], v[198:201], v[64:67]
	s_setprio 0
	s_mov_b32 m0, s16
	s_add_u32 s100, s66, s12
	s_addc_u32 s101, s67, s13
	s_barrier
	ds_read_b128 v[166:169], v147 offset:16384
	ds_read_b128 v[170:173], v147 offset:17408
	ds_read_b128 v[174:177], v147 offset:18432
	ds_read_b128 v[178:181], v147 offset:19456
	ds_read_b128 v[186:189], v147 offset:20480
	ds_read_b128 v[190:193], v147 offset:21504
	ds_read_b128 v[194:197], v147 offset:22528
	ds_read_b128 v[198:201], v147 offset:23552
	global_load_lds_dwordx4 v128, s[66:67]
	s_mov_b32 m0, s17
	s_nop 0
	global_load_lds_dwordx4 v132, s[66:67]
	s_barrier
	s_waitcnt lgkmcnt(0)
	s_setprio 1
	v_mfma_f32_16x16x32_bf16 v[60:63], v[150:153], v[166:169], v[60:63]
	v_mfma_f32_16x16x32_bf16 v[56:59], v[158:161], v[166:169], v[56:59]
	v_mfma_f32_16x16x32_bf16 v[52:55], v[150:153], v[174:177], v[52:55]
	v_mfma_f32_16x16x32_bf16 v[44:47], v[158:161], v[174:177], v[44:47]
	v_mfma_f32_16x16x32_bf16 v[36:39], v[150:153], v[186:189], v[36:39]
	v_mfma_f32_16x16x32_bf16 v[28:31], v[158:161], v[186:189], v[28:31]
	v_mfma_f32_16x16x32_bf16 v[20:23], v[150:153], v[194:197], v[20:23]
	v_mfma_f32_16x16x32_bf16 v[12:15], v[158:161], v[194:197], v[12:15]
	v_mfma_f32_16x16x32_bf16 v[60:63], v[154:157], v[170:173], v[60:63]
	v_mfma_f32_16x16x32_bf16 v[56:59], v[162:165], v[170:173], v[56:59]
	v_mfma_f32_16x16x32_bf16 v[52:55], v[154:157], v[178:181], v[52:55]
	v_mfma_f32_16x16x32_bf16 v[44:47], v[162:165], v[178:181], v[44:47]
	v_mfma_f32_16x16x32_bf16 v[36:39], v[154:157], v[190:193], v[36:39]
	v_mfma_f32_16x16x32_bf16 v[28:31], v[162:165], v[190:193], v[28:31]
	v_mfma_f32_16x16x32_bf16 v[20:23], v[154:157], v[198:201], v[20:23]
	v_mfma_f32_16x16x32_bf16 v[12:15], v[162:165], v[198:201], v[12:15]
	s_setprio 0
	s_barrier
	s_add_u32 s72, s62, 0x80000
	s_addc_u32 s73, s63, 0
	s_add_i32 s33, s89, s5
	s_mov_b32 m0, s33
	s_nop 0
	global_load_lds_dwordx4 v130, s[72:73]
	s_add_i32 m0, s33, 0x2000
	s_nop 0
	global_load_lds_dwordx4 v134, s[72:73]
	s_waitcnt vmcnt(6)
	s_barrier
; #define PG8_STAGE(bufoff, gbase, voff) do { _Pragma("unroll") for (int _i = 0; _i < 2; ++_i) \
;         __builtin_amdgcn_global_load_lds((const unsigned*)((const char*)(gbase) + (voff)[_i]), (LAS unsigned*)(lds + (bufoff) + ldsw + _i * 8192), 16, 0, 0); } while (0)
; #define PG8_LDA(dst, b, h) do { _Pragma("unroll") for (int m = 0; m < 4; ++m) _Pragma("unroll") for (int k = 0; k < 2; ++k) dst[m][k] = *(const LAS bf16x8*)(lds + PG8_SA(b, h) + aoff + m * 2048 + k * 1024); } while (0)
; #define PG8_LDB(dst, b, h) do { _Pragma("unroll") for (int n = 0; n < 2; ++n) _Pragma("unroll") for (int k = 0; k < 2; ++k) dst[n][k] = *(const LAS bf16x8*)(lds + PG8_SB(b, h) + boff + n * 2048 + k * 1024); } while (0)
; #define PG8_MMA(ai, bj, At, Bt) do { __builtin_amdgcn_s_setprio(1); _Pragma("unroll") for (int m = 0; m < 4; ++m) _Pragma("unroll") for (int n = 0; n < 2; ++n) _Pragma("unroll") for (int k = 0; k < 2; ++k) \
;         acc[ai][bj][m][n] = __builtin_amdgcn_mfma_f32_16x16x32_bf16(Bt[n][k], At[m][k], acc[ai][bj][m][n], 0, 0, 0); __builtin_amdgcn_s_setprio(0); } while (0)
; #define PG8_WAIT_V(n) asm volatile("s_waitcnt vmcnt(" #n ")" ::: "memory")
; #define PG8_WAIT_L(n) asm volatile("s_waitcnt lgkmcnt(" #n ")" ::: "memory")
; #define PG8_BAR __builtin_amdgcn_s_barrier()
; #define PG8_SCHED __builtin_amdgcn_sched_barrier(0)
; template <class Epi, class S_t>
; __device__ __forceinline__ void gemm_phase(LAS unsigned char* lds, int lda, int ldb, const S_t& S, const Epi& E) {
;     ...
;             PG8_WAIT_V(6); PG8_BAR; PG8_MMA(1, 1, At, B1); PG8_BAR;
;             PG8_LDB(B0, 1, 0); PG8_SCHED; PG8_LDA(At, 1, 0); PG8_STAGE(PG8_SA(0, 1), a2 + hstepA, voffA);
;             PG8_WAIT_L(8); PG8_BAR; PG8_WAIT_L(0); PG8_MMA(0, 0, At, B0); PG8_BAR; PG8_SCHED;
;             PG8_LDB(B1, 1, 1); PG8_STAGE(PG8_SB(1, 0), b3, voffB);
;             PG8_BAR; PG8_WAIT_L(0); PG8_MMA(0, 1, At, B1); PG8_BAR;
;             PG8_LDA(At, 1, 1); PG8_STAGE(PG8_SA(1, 0), a3, voffA);
;             PG8_BAR; PG8_WAIT_L(0); PG8_MMA(1, 0, At, B0); PG8_BAR; PG8_SCHED;
	s_setprio 1
	v_mfma_f32_16x16x32_bf16 v[48:51], v[202:205], v[166:169], v[48:51]
	v_mfma_f32_16x16x32_bf16 v[40:43], v[222:225], v[166:169], v[40:43]
	v_mfma_f32_16x16x32_bf16 v[32:35], v[202:205], v[174:177], v[32:35]
	v_mfma_f32_16x16x32_bf16 v[24:27], v[222:225], v[174:177], v[24:27]
	v_mfma_f32_16x16x32_bf16 v[16:19], v[202:205], v[186:189], v[16:19]
	v_mfma_f32_16x16x32_bf16 v[8:11], v[222:225], v[186:189], v[8:11]
	v_mfma_f32_16x16x32_bf16 v[4:7], v[202:205], v[194:197], v[4:7]
	v_mfma_f32_16x16x32_bf16 v[0:3], v[222:225], v[194:197], v[0:3]
	v_mfma_f32_16x16x32_bf16 v[48:51], v[206:209], v[170:173], v[48:51]
	v_mfma_f32_16x16x32_bf16 v[40:43], v[226:229], v[170:173], v[40:43]
	v_mfma_f32_16x16x32_bf16 v[32:35], v[206:209], v[178:181], v[32:35]
	v_mfma_f32_16x16x32_bf16 v[24:27], v[226:229], v[178:181], v[24:27]
	v_mfma_f32_16x16x32_bf16 v[16:19], v[206:209], v[190:193], v[16:19]
	v_mfma_f32_16x16x32_bf16 v[8:11], v[226:229], v[190:193], v[8:11]
	v_mfma_f32_16x16x32_bf16 v[4:7], v[206:209], v[198:201], v[4:7]
	v_mfma_f32_16x16x32_bf16 v[0:3], v[226:229], v[198:201], v[0:3]
	s_setprio 0
	v_add_u32_e32 v149, s90, v143
	s_barrier
	ds_read_b128 v[150:153], v149
	ds_read_b128 v[154:157], v149 offset:1024
	ds_read_b128 v[158:161], v149 offset:2048
	ds_read_b128 v[162:165], v149 offset:3072
	s_add_u32 s66, s66, 0x80000
	s_addc_u32 s67, s67, 0
	s_mov_b32 m0, s20
	ds_read_b128 v[166:169], v147 offset:32768
	ds_read_b128 v[170:173], v147 offset:33792
	ds_read_b128 v[174:177], v147 offset:34816
	ds_read_b128 v[178:181], v147 offset:35840
	ds_read_b128 v[186:189], v147 offset:36864
	ds_read_b128 v[190:193], v147 offset:37888
	ds_read_b128 v[194:197], v147 offset:38912
	ds_read_b128 v[198:201], v147 offset:39936
	global_load_lds_dwordx4 v128, s[66:67]
	s_mov_b32 m0, s21
	s_nop 0
	global_load_lds_dwordx4 v132, s[66:67]
	s_waitcnt lgkmcnt(8)
	s_barrier
	s_waitcnt lgkmcnt(0)
	s_setprio 1
	v_mfma_f32_16x16x32_bf16 v[124:127], v[150:153], v[166:169], v[124:127]
	v_mfma_f32_16x16x32_bf16 v[120:123], v[158:161], v[166:169], v[120:123]
	v_mfma_f32_16x16x32_bf16 v[112:115], v[150:153], v[174:177], v[112:115]
	v_mfma_f32_16x16x32_bf16 v[104:107], v[158:161], v[174:177], v[104:107]
	v_mfma_f32_16x16x32_bf16 v[96:99], v[150:153], v[186:189], v[96:99]
	v_mfma_f32_16x16x32_bf16 v[88:91], v[158:161], v[186:189], v[88:91]
	v_mfma_f32_16x16x32_bf16 v[80:83], v[150:153], v[194:197], v[80:83]
	v_mfma_f32_16x16x32_bf16 v[72:75], v[158:161], v[194:197], v[72:75]
	v_mfma_f32_16x16x32_bf16 v[124:127], v[154:157], v[170:173], v[124:127]
	v_mfma_f32_16x16x32_bf16 v[120:123], v[162:165], v[170:173], v[120:123]
	v_mfma_f32_16x16x32_bf16 v[112:115], v[154:157], v[178:181], v[112:115]
	v_mfma_f32_16x16x32_bf16 v[104:107], v[162:165], v[178:181], v[104:107]
	v_mfma_f32_16x16x32_bf16 v[96:99], v[154:157], v[190:193], v[96:99]
	v_mfma_f32_16x16x32_bf16 v[88:91], v[162:165], v[190:193], v[88:91]
	v_mfma_f32_16x16x32_bf16 v[80:83], v[154:157], v[198:201], v[80:83]
	v_mfma_f32_16x16x32_bf16 v[72:75], v[162:165], v[198:201], v[72:75]
	s_setprio 0
	s_barrier
	s_add_i32 s33, s90, s5
	v_add_u32_e32 v149, s91, v143
	s_mov_b32 m0, s33
	ds_read_b128 v[202:205], v149
	ds_read_b128 v[206:209], v149 offset:1024
	ds_read_b128 v[222:225], v149 offset:2048
	ds_read_b128 v[226:229], v149 offset:3072
	global_load_lds_dwordx4 v130, s[98:99]
	s_add_i32 m0, s33, 0x2000
	s_nop 0
	global_load_lds_dwordx4 v134, s[98:99]
	s_barrier
	s_waitcnt lgkmcnt(0)
	s_setprio 1
	v_mfma_f32_16x16x32_bf16 v[116:119], v[202:205], v[166:169], v[116:119]
	v_mfma_f32_16x16x32_bf16 v[108:111], v[222:225], v[166:169], v[108:111]
	v_mfma_f32_16x16x32_bf16 v[100:103], v[202:205], v[174:177], v[100:103]
	v_mfma_f32_16x16x32_bf16 v[92:95], v[222:225], v[174:177], v[92:95]
	v_mfma_f32_16x16x32_bf16 v[84:87], v[202:205], v[186:189], v[84:87]
	v_mfma_f32_16x16x32_bf16 v[76:79], v[222:225], v[186:189], v[76:79]
	v_mfma_f32_16x16x32_bf16 v[68:71], v[202:205], v[194:197], v[68:71]
	v_mfma_f32_16x16x32_bf16 v[64:67], v[222:225], v[194:197], v[64:67]
	v_mfma_f32_16x16x32_bf16 v[116:119], v[206:209], v[170:173], v[116:119]
	v_mfma_f32_16x16x32_bf16 v[108:111], v[226:229], v[170:173], v[108:111]
	v_mfma_f32_16x16x32_bf16 v[100:103], v[206:209], v[178:181], v[100:103]
	v_mfma_f32_16x16x32_bf16 v[92:95], v[226:229], v[178:181], v[92:95]
	v_mfma_f32_16x16x32_bf16 v[84:87], v[206:209], v[190:193], v[84:87]
	v_mfma_f32_16x16x32_bf16 v[76:79], v[226:229], v[190:193], v[76:79]
	v_mfma_f32_16x16x32_bf16 v[68:71], v[206:209], v[198:201], v[68:71]
	v_mfma_f32_16x16x32_bf16 v[64:67], v[226:229], v[198:201], v[64:67]
	s_setprio 0
	s_mov_b32 m0, s35
	s_barrier
	ds_read_b128 v[166:169], v147 offset:49152
	ds_read_b128 v[170:173], v147 offset:50176
	ds_read_b128 v[174:177], v147 offset:51200
	ds_read_b128 v[178:181], v147 offset:52224
	ds_read_b128 v[186:189], v147 offset:53248
	ds_read_b128 v[190:193], v147 offset:54272
	ds_read_b128 v[194:197], v147 offset:55296
	ds_read_b128 v[198:201], v147 offset:56320
	global_load_lds_dwordx4 v128, s[100:101]
	s_mov_b32 m0, s52
	s_nop 0
	global_load_lds_dwordx4 v132, s[100:101]
	s_barrier
; #define PG8_STAGE(bufoff, gbase, voff) do { _Pragma("unroll") for (int _i = 0; _i < 2; ++_i) \
;         __builtin_amdgcn_global_load_lds((const unsigned*)((const char*)(gbase) + (voff)[_i]), (LAS unsigned*)(lds + (bufoff) + ldsw + _i * 8192), 16, 0, 0); } while (0)
; #define PG8_MMA(ai, bj, At, Bt) do { __builtin_amdgcn_s_setprio(1); _Pragma("unroll") for (int m = 0; m < 4; ++m) _Pragma("unroll") for (int n = 0; n < 2; ++n) _Pragma("unroll") for (int k = 0; k < 2; ++k) \
;         acc[ai][bj][m][n] = __builtin_amdgcn_mfma_f32_16x16x32_bf16(Bt[n][k], At[m][k], acc[ai][bj][m][n], 0, 0, 0); __builtin_amdgcn_s_setprio(0); } while (0)
; #define PG8_WAIT_V(n) asm volatile("s_waitcnt vmcnt(" #n ")" ::: "memory")
; #define PG8_WAIT_L(n) asm volatile("s_waitcnt lgkmcnt(" #n ")" ::: "memory")
; #define PG8_BAR __builtin_amdgcn_s_barrier()
; #define PG8_SCHED __builtin_amdgcn_sched_barrier(0)
; template <class Epi, class S_t>
; __device__ __forceinline__ void gemm_phase(LAS unsigned char* lds, int lda, int ldb, const S_t& S, const Epi& E) {
;     ...
;             PG8_BAR; PG8_WAIT_L(0); PG8_MMA(1, 0, At, B0); PG8_BAR; PG8_SCHED;
;             PG8_STAGE(PG8_SB(1, 1), b3 + hstepB, voffB);
;             PG8_WAIT_V(6); PG8_BAR; PG8_MMA(1, 1, At, B1); PG8_BAR;
;     __device__ __forceinline__ void operator()(const f32x4 (&acc)[2][2][4][2], const Unit& u, int wr, int wc, int fr, int fq) const {
;     ...
;             const int row0 = (u.pm - 32) * BM + wr * 64 + fr;
;             float* Op = Os + (size_t)(u.tag - 1) * (1024ull * DM);
; #pragma unroll
;             for (int ai = 0; ai < 2; ++ai)
; #pragma unroll
;                 for (int m = 0; m < 4; ++m) { float* rowp = Op + (size_t)(row0 + ai * HALF + m * 16) * DM + col0;
; #pragma unroll
;                     for (int bj = 0; bj < 2; ++bj)
; #pragma unroll
;                         for (int n = 0; n < 2; ++n) *(f32x4*)(rowp + bj * HALF + 4 * n) = acc[ai][bj][m][n]; }
	s_waitcnt lgkmcnt(0)
	s_setprio 1
	v_mfma_f32_16x16x32_bf16 v[60:63], v[150:153], v[166:169], v[60:63]
	v_mfma_f32_16x16x32_bf16 v[56:59], v[158:161], v[166:169], v[56:59]
	v_mfma_f32_16x16x32_bf16 v[52:55], v[150:153], v[174:177], v[52:55]
	v_mfma_f32_16x16x32_bf16 v[44:47], v[158:161], v[174:177], v[44:47]
	v_mfma_f32_16x16x32_bf16 v[36:39], v[150:153], v[186:189], v[36:39]
	v_mfma_f32_16x16x32_bf16 v[28:31], v[158:161], v[186:189], v[28:31]
	v_mfma_f32_16x16x32_bf16 v[20:23], v[150:153], v[194:197], v[20:23]
	v_mfma_f32_16x16x32_bf16 v[12:15], v[158:161], v[194:197], v[12:15]
	v_mfma_f32_16x16x32_bf16 v[60:63], v[154:157], v[170:173], v[60:63]
	v_mfma_f32_16x16x32_bf16 v[56:59], v[162:165], v[170:173], v[56:59]
	v_mfma_f32_16x16x32_bf16 v[52:55], v[154:157], v[178:181], v[52:55]
	v_mfma_f32_16x16x32_bf16 v[44:47], v[162:165], v[178:181], v[44:47]
	v_mfma_f32_16x16x32_bf16 v[36:39], v[154:157], v[190:193], v[36:39]
	v_mfma_f32_16x16x32_bf16 v[28:31], v[162:165], v[190:193], v[28:31]
	v_mfma_f32_16x16x32_bf16 v[20:23], v[154:157], v[198:201], v[20:23]
	v_mfma_f32_16x16x32_bf16 v[12:15], v[162:165], v[198:201], v[12:15]
	s_setprio 0
	s_barrier
	s_add_u32 s62, s62, 0x80080
	s_addc_u32 s63, s63, 0
	s_add_i32 s33, s91, s5
	s_mov_b32 m0, s33
	s_nop 0
	global_load_lds_dwordx4 v130, s[62:63]
	s_add_i32 m0, s33, 0x2000
	s_nop 0
	global_load_lds_dwordx4 v134, s[62:63]
	s_waitcnt vmcnt(6)
	s_barrier
	s_setprio 1
	v_mfma_f32_16x16x32_bf16 v[48:51], v[202:205], v[166:169], v[48:51]
	v_mfma_f32_16x16x32_bf16 v[40:43], v[222:225], v[166:169], v[40:43]
	v_mfma_f32_16x16x32_bf16 v[32:35], v[202:205], v[174:177], v[32:35]
	v_mfma_f32_16x16x32_bf16 v[24:27], v[222:225], v[174:177], v[24:27]
	v_mfma_f32_16x16x32_bf16 v[16:19], v[202:205], v[186:189], v[16:19]
	v_mfma_f32_16x16x32_bf16 v[8:11], v[222:225], v[186:189], v[8:11]
	v_mfma_f32_16x16x32_bf16 v[4:7], v[202:205], v[194:197], v[4:7]
	v_mfma_f32_16x16x32_bf16 v[0:3], v[222:225], v[194:197], v[0:3]
	v_mfma_f32_16x16x32_bf16 v[48:51], v[206:209], v[170:173], v[48:51]
	v_mfma_f32_16x16x32_bf16 v[40:43], v[226:229], v[170:173], v[40:43]
	v_mfma_f32_16x16x32_bf16 v[32:35], v[206:209], v[178:181], v[32:35]
	v_mfma_f32_16x16x32_bf16 v[24:27], v[226:229], v[178:181], v[24:27]
	v_mfma_f32_16x16x32_bf16 v[16:19], v[206:209], v[190:193], v[16:19]
	v_mfma_f32_16x16x32_bf16 v[8:11], v[226:229], v[190:193], v[8:11]
	v_mfma_f32_16x16x32_bf16 v[4:7], v[206:209], v[198:201], v[4:7]
	v_mfma_f32_16x16x32_bf16 v[0:3], v[226:229], v[198:201], v[0:3]
	s_setprio 0
	s_add_u32 s60, s60, 0x100
	s_addc_u32 s61, s61, 0
	s_add_u32 s1, s1, 0x100
	s_addc_u32 s69, s69, 0
	s_cmp_ge_u32 s70, s42
	s_mov_b32 s62, s70
	s_barrier
	s_cbranch_scc0 .LBB0_1051
	v_lshl_or_b32 v140, s43, 8, v145
	s_lshl_b32 s33, s8, 8
	s_cmp_lg_u32 s68, 0
	v_ashrrev_i32_e32 v141, 31, v140
	s_cbranch_scc0 .LBB0_1054
	s_add_i32 s8, s68, -1
	s_lshl_b64 s[0:1], s[8:9], 23
	v_add_u32_e32 v150, s33, v144
	s_add_u32 s0, s10, s0
	v_or_b32_e32 v156, 16, v150
	s_addc_u32 s1, s11, s1
	v_ashrrev_i32_e32 v151, 31, v150
	v_ashrrev_i32_e32 v157, 31, v156
	v_lshl_add_u64 v[152:153], v[140:141], 2, s[0:1]
	v_lshlrev_b64 v[154:155], 13, v[150:151]
	v_lshlrev_b64 v[156:157], 13, v[156:157]
	v_lshl_add_u64 v[154:155], v[152:153], 0, v[154:155]
	v_lshl_add_u64 v[156:157], v[152:153], 0, v[156:157]
	global_store_dwordx4 v[154:155], v[124:127], off
	global_store_dwordx4 v[154:155], v[120:123], off offset:16
	global_store_dwordx4 v[154:155], v[116:119], off offset:512
	global_store_dwordx4 v[154:155], v[108:111], off offset:528
	global_store_dwordx4 v[156:157], v[112:115], off
	global_store_dwordx4 v[156:157], v[104:107], off offset:16
	global_store_dwordx4 v[156:157], v[100:103], off offset:512
	global_store_dwordx4 v[156:157], v[92:95], off offset:528
	v_or_b32_e32 v156, 32, v150
	v_or_b32_e32 v150, 48, v150
	v_ashrrev_i32_e32 v157, 31, v156
	v_ashrrev_i32_e32 v151, 31, v150
	v_lshlrev_b64 v[156:157], 13, v[156:157]
	v_lshlrev_b64 v[150:151], 13, v[150:151]
	v_lshl_add_u64 v[156:157], v[152:153], 0, v[156:157]
	v_lshl_add_u64 v[150:151], v[152:153], 0, v[150:151]
	s_mov_b64 s[0:1], 0x100000
	global_store_dwordx4 v[156:157], v[96:99], off
	global_store_dwordx4 v[156:157], v[88:91], off offset:16
	global_store_dwordx4 v[156:157], v[84:87], off offset:512
	global_store_dwordx4 v[156:157], v[76:79], off offset:528
	global_store_dwordx4 v[150:151], v[80:83], off
	global_store_dwordx4 v[150:151], v[72:75], off offset:16
	global_store_dwordx4 v[150:151], v[68:71], off offset:512
	global_store_dwordx4 v[150:151], v[64:67], off offset:528
	v_lshl_add_u64 v[150:151], v[154:155], 0, s[0:1]
	s_mov_b32 s0, 0x100000
	v_add_co_u32_e32 v152, vcc, s0, v154
	s_mov_b64 s[0:1], 0x120000
	s_nop 0
	v_addc_co_u32_e32 v153, vcc, 0, v155, vcc
	global_store_dwordx4 v[152:153], v[60:63], off
	global_store_dwordx4 v[150:151], v[56:59], off offset:16
	global_store_dwordx4 v[150:151], v[48:51], off offset:512
	global_store_dwordx4 v[150:151], v[40:43], off offset:528
	v_lshl_add_u64 v[150:151], v[154:155], 0, s[0:1]
	s_mov_b32 s0, 0x120000
	v_add_co_u32_e32 v152, vcc, s0, v154
	s_mov_b64 s[0:1], 0x140000
	s_nop 0
	v_addc_co_u32_e32 v153, vcc, 0, v155, vcc
	global_store_dwordx4 v[152:153], v[52:55], off
	global_store_dwordx4 v[150:151], v[44:47], off offset:16
	global_store_dwordx4 v[150:151], v[32:35], off offset:512
	global_store_dwordx4 v[150:151], v[24:27], off offset:528
	v_lshl_add_u64 v[150:151], v[154:155], 0, s[0:1]
	s_mov_b32 s0, 0x140000
	v_add_co_u32_e32 v152, vcc, s0, v154
	s_mov_b64 s[0:1], 0x160000
	s_nop 0
	v_addc_co_u32_e32 v153, vcc, 0, v155, vcc
	global_store_dwordx4 v[152:153], v[36:39], off
	global_store_dwordx4 v[150:151], v[28:31], off offset:16
	global_store_dwordx4 v[150:151], v[16:19], off offset:512
	global_store_dwordx4 v[150:151], v[8:11], off offset:528
	v_add_co_u32_e32 v152, vcc, 0x160000, v154
	v_lshl_add_u64 v[150:151], v[154:155], 0, s[0:1]
	s_nop 0
	v_addc_co_u32_e32 v153, vcc, 0, v155, vcc
	global_store_dwordx4 v[152:153], v[20:23], off
	global_store_dwordx4 v[150:151], v[12:15], off offset:16
	global_store_dwordx4 v[150:151], v[4:7], off offset:512
	global_store_dwordx4 v[150:151], v[0:3], off offset:528
	s_cbranch_execnz .LBB0_1047
	s_branch .LBB0_1046

; #define PG8_STAGE(bufoff, gbase, voff) do { _Pragma("unroll") for (int _i = 0; _i < 2; ++_i) \
;         __builtin_amdgcn_global_load_lds((const unsigned*)((const char*)(gbase) + (voff)[_i]), (LAS unsigned*)(lds + (bufoff) + ldsw + _i * 8192), 16, 0, 0); } while (0)
; #define PG8_LDA(dst, b, h) do { _Pragma("unroll") for (int m = 0; m < 4; ++m) _Pragma("unroll") for (int k = 0; k < 2; ++k) dst[m][k] = *(const LAS bf16x8*)(lds + PG8_SA(b, h) + aoff + m * 2048 + k * 1024); } while (0)
; #define PG8_LDB(dst, b, h) do { _Pragma("unroll") for (int n = 0; n < 2; ++n) _Pragma("unroll") for (int k = 0; k < 2; ++k) dst[n][k] = *(const LAS bf16x8*)(lds + PG8_SB(b, h) + boff + n * 2048 + k * 1024); } while (0)
; #define PG8_WAIT_V(n) asm volatile("s_waitcnt vmcnt(" #n ")" ::: "memory")
; #define PG8_WAIT_L(n) asm volatile("s_waitcnt lgkmcnt(" #n ")" ::: "memory")
; #define PG8_BAR __builtin_amdgcn_s_barrier()
; #define PG8_SCHED __builtin_amdgcn_sched_barrier(0)
; template <class Epi, class S_t>
; __device__ __forceinline__ void gemm_phase(LAS unsigned char* lds, int lda, int ldb, const S_t& S, const Epi& E) {
;     ...
;             PG8_LDB(B0, 0, 0); PG8_SCHED; PG8_LDA(At, 0, 0); PG8_STAGE(PG8_SA(1, 1), a1 + hstepA, voffA);
;             PG8_WAIT_L(8); PG8_BAR; PG8_WAIT_L(0); PG8_MMA(0, 0, At, B0); PG8_BAR; PG8_SCHED;
;             PG8_LDB(B1, 0, 1); PG8_STAGE(PG8_SB(0, 0), b2, voffB);
;             PG8_BAR; PG8_WAIT_L(0); PG8_MMA(0, 1, At, B1); PG8_BAR;
;             PG8_LDA(At, 0, 1); PG8_STAGE(PG8_SA(0, 0), a2, voffA);
;             PG8_BAR; PG8_WAIT_L(0); PG8_MMA(1, 0, At, B0); PG8_BAR; PG8_SCHED;
;             PG8_STAGE(PG8_SB(0, 1), b2 + hstepB, voffB);
;             PG8_WAIT_V(6); PG8_BAR; PG8_MMA(1, 1, At, B1); PG8_BAR;
;             PG8_LDB(B0, 1, 0); PG8_SCHED; PG8_LDA(At, 1, 0); PG8_STAGE(PG8_SA(0, 1), a2 + hstepA, voffA);
;             PG8_WAIT_L(8); PG8_BAR; PG8_WAIT_L(0); PG8_MMA(0, 0, At, B0); PG8_BAR; PG8_SCHED;
;             PG8_LDB(B1, 1, 1); PG8_STAGE(PG8_SB(1, 0), b3, voffB);
;             PG8_BAR; PG8_WAIT_L(0); PG8_MMA(0, 1, At, B1); PG8_BAR;
;             PG8_LDA(At, 1, 1); PG8_STAGE(PG8_SA(1, 0), a3, voffA);
;             PG8_BAR; PG8_WAIT_L(0); PG8_MMA(1, 0, At, B0); PG8_BAR; PG8_SCHED;
;             PG8_STAGE(PG8_SB(1, 1), b3 + hstepB, voffB);
;             PG8_WAIT_V(6); PG8_BAR; PG8_MMA(1, 1, At, B1); PG8_BAR;
.LBB0_1200:
	ds_read_b128 v[128:131], v223
	ds_read_b128 v[132:135], v223 offset:1024
	ds_read_b128 v[136:139], v223 offset:2048
	ds_read_b128 v[140:143], v223 offset:3072
	s_add_u32 s33, s74, 0xfff80080
	s_addc_u32 s43, s75, -1
	s_cmp_eq_u32 s5, 28
	s_cselect_b32 s79, s69, s43
	s_cselect_b32 s78, s68, s33
	s_cselect_b32 s77, s71, s1
	s_cselect_b32 s76, s70, s0
	s_add_i32 m0, s7, 0xc000
	ds_read_b128 v[144:147], v246
	ds_read_b128 v[148:151], v246 offset:1024
	ds_read_b128 v[152:155], v246 offset:2048
	ds_read_b128 v[156:159], v246 offset:3072
	ds_read_b128 v[160:163], v246 offset:4096
	ds_read_b128 v[164:167], v246 offset:5120
	ds_read_b128 v[168:171], v246 offset:6144
	ds_read_b128 v[172:175], v246 offset:7168
	global_load_lds_dwordx4 v236, s[74:75]
	s_add_i32 m0, s7, 0xe000
	s_nop 0
	global_load_lds_dwordx4 v238, s[74:75]
	s_waitcnt lgkmcnt(8)
	s_barrier
	s_waitcnt lgkmcnt(0)
	s_setprio 1
	v_mfma_f32_16x16x32_bf16 v[124:127], v[128:131], v[144:147], v[124:127]
	v_mfma_f32_16x16x32_bf16 v[120:123], v[136:139], v[144:147], v[120:123]
	v_mfma_f32_16x16x32_bf16 v[116:119], v[128:131], v[152:155], v[116:119]
	v_mfma_f32_16x16x32_bf16 v[108:111], v[136:139], v[152:155], v[108:111]
	v_mfma_f32_16x16x32_bf16 v[100:103], v[128:131], v[160:163], v[100:103]
	v_mfma_f32_16x16x32_bf16 v[92:95], v[136:139], v[160:163], v[92:95]
	v_mfma_f32_16x16x32_bf16 v[84:87], v[128:131], v[168:171], v[84:87]
	v_mfma_f32_16x16x32_bf16 v[76:79], v[136:139], v[168:171], v[76:79]
	v_mfma_f32_16x16x32_bf16 v[124:127], v[132:135], v[148:151], v[124:127]
	v_mfma_f32_16x16x32_bf16 v[120:123], v[140:143], v[148:151], v[120:123]
	v_mfma_f32_16x16x32_bf16 v[116:119], v[132:135], v[156:159], v[116:119]
	v_mfma_f32_16x16x32_bf16 v[108:111], v[140:143], v[156:159], v[108:111]
	v_mfma_f32_16x16x32_bf16 v[100:103], v[132:135], v[164:167], v[100:103]
	v_mfma_f32_16x16x32_bf16 v[92:95], v[140:143], v[164:167], v[92:95]
	v_mfma_f32_16x16x32_bf16 v[84:87], v[132:135], v[172:175], v[84:87]
	v_mfma_f32_16x16x32_bf16 v[76:79], v[140:143], v[172:175], v[76:79]
	s_setprio 0
	s_barrier
	s_add_i32 s33, s88, s64
	s_add_u32 s98, s76, s38
	s_addc_u32 s99, s77, s39
	s_mov_b32 m0, s33
	ds_read_b128 v[176:179], v247
	ds_read_b128 v[180:183], v247 offset:1024
	ds_read_b128 v[184:187], v247 offset:2048
	ds_read_b128 v[188:191], v247 offset:3072
	global_load_lds_dwordx4 v228, s[76:77]
	s_add_i32 m0, s33, 0x2000
	s_nop 0
	global_load_lds_dwordx4 v224, s[76:77]
	s_barrier
	s_waitcnt lgkmcnt(0)
	s_setprio 1
	v_mfma_f32_16x16x32_bf16 v[112:115], v[176:179], v[144:147], v[112:115]
	v_mfma_f32_16x16x32_bf16 v[104:107], v[184:187], v[144:147], v[104:107]
	v_mfma_f32_16x16x32_bf16 v[96:99], v[176:179], v[152:155], v[96:99]
	v_mfma_f32_16x16x32_bf16 v[88:91], v[184:187], v[152:155], v[88:91]
	v_mfma_f32_16x16x32_bf16 v[80:83], v[176:179], v[160:163], v[80:83]
	v_mfma_f32_16x16x32_bf16 v[72:75], v[184:187], v[160:163], v[72:75]
	v_mfma_f32_16x16x32_bf16 v[68:71], v[176:179], v[168:171], v[68:71]
	v_mfma_f32_16x16x32_bf16 v[64:67], v[184:187], v[168:171], v[64:67]
	v_mfma_f32_16x16x32_bf16 v[112:115], v[180:183], v[148:151], v[112:115]
	v_mfma_f32_16x16x32_bf16 v[104:107], v[188:191], v[148:151], v[104:107]
	v_mfma_f32_16x16x32_bf16 v[96:99], v[180:183], v[156:159], v[96:99]
	v_mfma_f32_16x16x32_bf16 v[88:91], v[188:191], v[156:159], v[88:91]
	v_mfma_f32_16x16x32_bf16 v[80:83], v[180:183], v[164:167], v[80:83]
	v_mfma_f32_16x16x32_bf16 v[72:75], v[188:191], v[164:167], v[72:75]
	v_mfma_f32_16x16x32_bf16 v[68:71], v[180:183], v[172:175], v[68:71]
	v_mfma_f32_16x16x32_bf16 v[64:67], v[188:191], v[172:175], v[64:67]
	s_setprio 0
	s_mov_b32 m0, s7
	s_add_u32 s100, s78, s38
	s_addc_u32 s101, s79, s39
	s_barrier
	ds_read_b128 v[144:147], v246 offset:16384
	ds_read_b128 v[148:151], v246 offset:17408
	ds_read_b128 v[152:155], v246 offset:18432
	ds_read_b128 v[156:159], v246 offset:19456
	ds_read_b128 v[160:163], v246 offset:20480
	ds_read_b128 v[164:167], v246 offset:21504
	ds_read_b128 v[168:171], v246 offset:22528
	ds_read_b128 v[172:175], v246 offset:23552
	global_load_lds_dwordx4 v230, s[78:79]
	s_mov_b32 m0, s35
	s_nop 0
	global_load_lds_dwordx4 v226, s[78:79]
	s_barrier
	s_waitcnt lgkmcnt(0)
	s_setprio 1
	v_mfma_f32_16x16x32_bf16 v[60:63], v[128:131], v[144:147], v[60:63]
	v_mfma_f32_16x16x32_bf16 v[56:59], v[136:139], v[144:147], v[56:59]
	v_mfma_f32_16x16x32_bf16 v[52:55], v[128:131], v[152:155], v[52:55]
	v_mfma_f32_16x16x32_bf16 v[44:47], v[136:139], v[152:155], v[44:47]
	v_mfma_f32_16x16x32_bf16 v[36:39], v[128:131], v[160:163], v[36:39]
	v_mfma_f32_16x16x32_bf16 v[28:31], v[136:139], v[160:163], v[28:31]
	v_mfma_f32_16x16x32_bf16 v[20:23], v[128:131], v[168:171], v[20:23]
	v_mfma_f32_16x16x32_bf16 v[12:15], v[136:139], v[168:171], v[12:15]
	v_mfma_f32_16x16x32_bf16 v[60:63], v[132:135], v[148:151], v[60:63]
	v_mfma_f32_16x16x32_bf16 v[56:59], v[140:143], v[148:151], v[56:59]
	v_mfma_f32_16x16x32_bf16 v[52:55], v[132:135], v[156:159], v[52:55]
	v_mfma_f32_16x16x32_bf16 v[44:47], v[140:143], v[156:159], v[44:47]
	v_mfma_f32_16x16x32_bf16 v[36:39], v[132:135], v[164:167], v[36:39]
	v_mfma_f32_16x16x32_bf16 v[28:31], v[140:143], v[164:167], v[28:31]
	v_mfma_f32_16x16x32_bf16 v[20:23], v[132:135], v[172:175], v[20:23]
	v_mfma_f32_16x16x32_bf16 v[12:15], v[140:143], v[172:175], v[12:15]
	s_setprio 0
	s_barrier
	s_add_u32 s52, s76, 0x80000
	s_addc_u32 s53, s77, 0
	s_add_i32 s33, s89, s64
	s_mov_b32 m0, s33
	s_nop 0
	global_load_lds_dwordx4 v228, s[52:53]
	s_add_i32 m0, s33, 0x2000
	s_nop 0
	global_load_lds_dwordx4 v224, s[52:53]
	s_waitcnt vmcnt(6)
	s_barrier
; #define PG8_STAGE(bufoff, gbase, voff) do { _Pragma("unroll") for (int _i = 0; _i < 2; ++_i) \
;         __builtin_amdgcn_global_load_lds((const unsigned*)((const char*)(gbase) + (voff)[_i]), (LAS unsigned*)(lds + (bufoff) + ldsw + _i * 8192), 16, 0, 0); } while (0)
; #define PG8_LDA(dst, b, h) do { _Pragma("unroll") for (int m = 0; m < 4; ++m) _Pragma("unroll") for (int k = 0; k < 2; ++k) dst[m][k] = *(const LAS bf16x8*)(lds + PG8_SA(b, h) + aoff + m * 2048 + k * 1024); } while (0)
; #define PG8_LDB(dst, b, h) do { _Pragma("unroll") for (int n = 0; n < 2; ++n) _Pragma("unroll") for (int k = 0; k < 2; ++k) dst[n][k] = *(const LAS bf16x8*)(lds + PG8_SB(b, h) + boff + n * 2048 + k * 1024); } while (0)
; #define PG8_MMA(ai, bj, At, Bt) do { __builtin_amdgcn_s_setprio(1); _Pragma("unroll") for (int m = 0; m < 4; ++m) _Pragma("unroll") for (int n = 0; n < 2; ++n) _Pragma("unroll") for (int k = 0; k < 2; ++k) \
;         acc[ai][bj][m][n] = __builtin_amdgcn_mfma_f32_16x16x32_bf16(Bt[n][k], At[m][k], acc[ai][bj][m][n], 0, 0, 0); __builtin_amdgcn_s_setprio(0); } while (0)
; #define PG8_WAIT_V(n) asm volatile("s_waitcnt vmcnt(" #n ")" ::: "memory")
; #define PG8_WAIT_L(n) asm volatile("s_waitcnt lgkmcnt(" #n ")" ::: "memory")
; #define PG8_BAR __builtin_amdgcn_s_barrier()
; #define PG8_SCHED __builtin_amdgcn_sched_barrier(0)
; template <class Epi, class S_t>
; __device__ __forceinline__ void gemm_phase(LAS unsigned char* lds, int lda, int ldb, const S_t& S, const Epi& E) {
;     ...
;             PG8_WAIT_V(6); PG8_BAR; PG8_MMA(1, 1, At, B1); PG8_BAR;
;             PG8_LDB(B0, 1, 0); PG8_SCHED; PG8_LDA(At, 1, 0); PG8_STAGE(PG8_SA(0, 1), a2 + hstepA, voffA);
;             PG8_WAIT_L(8); PG8_BAR; PG8_WAIT_L(0); PG8_MMA(0, 0, At, B0); PG8_BAR; PG8_SCHED;
;             PG8_LDB(B1, 1, 1); PG8_STAGE(PG8_SB(1, 0), b3, voffB);
;             PG8_BAR; PG8_WAIT_L(0); PG8_MMA(0, 1, At, B1); PG8_BAR;
	s_setprio 1
	v_mfma_f32_16x16x32_bf16 v[48:51], v[176:179], v[144:147], v[48:51]
	v_mfma_f32_16x16x32_bf16 v[40:43], v[184:187], v[144:147], v[40:43]
	v_mfma_f32_16x16x32_bf16 v[32:35], v[176:179], v[152:155], v[32:35]
	v_mfma_f32_16x16x32_bf16 v[24:27], v[184:187], v[152:155], v[24:27]
	v_mfma_f32_16x16x32_bf16 v[16:19], v[176:179], v[160:163], v[16:19]
	v_mfma_f32_16x16x32_bf16 v[8:11], v[184:187], v[160:163], v[8:11]
	v_mfma_f32_16x16x32_bf16 v[4:7], v[176:179], v[168:171], v[4:7]
	v_mfma_f32_16x16x32_bf16 v[0:3], v[184:187], v[168:171], v[0:3]
	v_mfma_f32_16x16x32_bf16 v[48:51], v[180:183], v[148:151], v[48:51]
	v_mfma_f32_16x16x32_bf16 v[40:43], v[188:191], v[148:151], v[40:43]
	v_mfma_f32_16x16x32_bf16 v[32:35], v[180:183], v[156:159], v[32:35]
	v_mfma_f32_16x16x32_bf16 v[24:27], v[188:191], v[156:159], v[24:27]
	v_mfma_f32_16x16x32_bf16 v[16:19], v[180:183], v[164:167], v[16:19]
	v_mfma_f32_16x16x32_bf16 v[8:11], v[188:191], v[164:167], v[8:11]
	v_mfma_f32_16x16x32_bf16 v[4:7], v[180:183], v[172:175], v[4:7]
	v_mfma_f32_16x16x32_bf16 v[0:3], v[188:191], v[172:175], v[0:3]
	s_setprio 0
	v_add_u32_e32 v140, s90, v215
	s_barrier
	ds_read_b128 v[128:131], v140
	ds_read_b128 v[132:135], v140 offset:1024
	ds_read_b128 v[136:139], v140 offset:2048
	ds_read_b128 v[140:143], v140 offset:3072
	s_add_u32 s52, s78, 0x80000
	s_addc_u32 s53, s79, 0
	s_mov_b32 m0, s92
	ds_read_b128 v[144:147], v246 offset:32768
	ds_read_b128 v[148:151], v246 offset:33792
	ds_read_b128 v[152:155], v246 offset:34816
	ds_read_b128 v[156:159], v246 offset:35840
	ds_read_b128 v[160:163], v246 offset:36864
	ds_read_b128 v[164:167], v246 offset:37888
	ds_read_b128 v[168:171], v246 offset:38912
	ds_read_b128 v[172:175], v246 offset:39936
	global_load_lds_dwordx4 v230, s[52:53]
	s_mov_b32 m0, s50
	s_nop 0
	global_load_lds_dwordx4 v226, s[52:53]
	s_waitcnt lgkmcnt(8)
	s_barrier
	s_waitcnt lgkmcnt(0)
	s_setprio 1
	v_mfma_f32_16x16x32_bf16 v[124:127], v[128:131], v[144:147], v[124:127]
	v_mfma_f32_16x16x32_bf16 v[120:123], v[136:139], v[144:147], v[120:123]
	v_mfma_f32_16x16x32_bf16 v[116:119], v[128:131], v[152:155], v[116:119]
	v_mfma_f32_16x16x32_bf16 v[108:111], v[136:139], v[152:155], v[108:111]
	v_mfma_f32_16x16x32_bf16 v[100:103], v[128:131], v[160:163], v[100:103]
	v_mfma_f32_16x16x32_bf16 v[92:95], v[136:139], v[160:163], v[92:95]
	v_mfma_f32_16x16x32_bf16 v[84:87], v[128:131], v[168:171], v[84:87]
	v_mfma_f32_16x16x32_bf16 v[76:79], v[136:139], v[168:171], v[76:79]
	v_mfma_f32_16x16x32_bf16 v[124:127], v[132:135], v[148:151], v[124:127]
	v_mfma_f32_16x16x32_bf16 v[120:123], v[140:143], v[148:151], v[120:123]
	v_mfma_f32_16x16x32_bf16 v[116:119], v[132:135], v[156:159], v[116:119]
	v_mfma_f32_16x16x32_bf16 v[108:111], v[140:143], v[156:159], v[108:111]
	v_mfma_f32_16x16x32_bf16 v[100:103], v[132:135], v[164:167], v[100:103]
	v_mfma_f32_16x16x32_bf16 v[92:95], v[140:143], v[164:167], v[92:95]
	v_mfma_f32_16x16x32_bf16 v[84:87], v[132:135], v[172:175], v[84:87]
	v_mfma_f32_16x16x32_bf16 v[76:79], v[140:143], v[172:175], v[76:79]
	s_setprio 0
	s_barrier
	s_add_i32 s33, s90, s64
	v_add_u32_e32 v188, s91, v215
	s_mov_b32 m0, s33
	ds_read_b128 v[176:179], v188
	ds_read_b128 v[180:183], v188 offset:1024
	ds_read_b128 v[184:187], v188 offset:2048
	ds_read_b128 v[188:191], v188 offset:3072
	global_load_lds_dwordx4 v228, s[98:99]
	s_add_i32 m0, s33, 0x2000
	s_nop 0
	global_load_lds_dwordx4 v224, s[98:99]
	s_barrier
	s_waitcnt lgkmcnt(0)
	s_setprio 1
	v_mfma_f32_16x16x32_bf16 v[112:115], v[176:179], v[144:147], v[112:115]
	v_mfma_f32_16x16x32_bf16 v[104:107], v[184:187], v[144:147], v[104:107]
	v_mfma_f32_16x16x32_bf16 v[96:99], v[176:179], v[152:155], v[96:99]
	v_mfma_f32_16x16x32_bf16 v[88:91], v[184:187], v[152:155], v[88:91]
	v_mfma_f32_16x16x32_bf16 v[80:83], v[176:179], v[160:163], v[80:83]
	v_mfma_f32_16x16x32_bf16 v[72:75], v[184:187], v[160:163], v[72:75]
	v_mfma_f32_16x16x32_bf16 v[68:71], v[176:179], v[168:171], v[68:71]
	v_mfma_f32_16x16x32_bf16 v[64:67], v[184:187], v[168:171], v[64:67]
	v_mfma_f32_16x16x32_bf16 v[112:115], v[180:183], v[148:151], v[112:115]
	v_mfma_f32_16x16x32_bf16 v[104:107], v[188:191], v[148:151], v[104:107]
	v_mfma_f32_16x16x32_bf16 v[96:99], v[180:183], v[156:159], v[96:99]
	v_mfma_f32_16x16x32_bf16 v[88:91], v[188:191], v[156:159], v[88:91]
	v_mfma_f32_16x16x32_bf16 v[80:83], v[180:183], v[164:167], v[80:83]
	v_mfma_f32_16x16x32_bf16 v[72:75], v[188:191], v[164:167], v[72:75]
	v_mfma_f32_16x16x32_bf16 v[68:71], v[180:183], v[172:175], v[68:71]
	v_mfma_f32_16x16x32_bf16 v[64:67], v[188:191], v[172:175], v[64:67]
	s_setprio 0
	s_mov_b32 m0, s96
	s_barrier
	ds_read_b128 v[144:147], v246 offset:49152
	ds_read_b128 v[148:151], v246 offset:50176
	ds_read_b128 v[152:155], v246 offset:51200
	ds_read_b128 v[156:159], v246 offset:52224
	ds_read_b128 v[160:163], v246 offset:53248
	ds_read_b128 v[164:167], v246 offset:54272
	ds_read_b128 v[168:171], v246 offset:55296
	ds_read_b128 v[172:175], v246 offset:56320
	global_load_lds_dwordx4 v230, s[100:101]
	s_mov_b32 m0, s97
	s_nop 0
	global_load_lds_dwordx4 v226, s[100:101]
	s_barrier
; #define PG8_BAR __builtin_amdgcn_s_barrier()
; template <class Epi, class S_t>
; __device__ __forceinline__ void gemm_phase(LAS unsigned char* lds, int lda, int ldb, const S_t& S, const Epi& E) {
;     ...
;             PG8_BAR; PG8_WAIT_L(0); PG8_MMA(1, 0, At, B0); PG8_BAR; PG8_SCHED;
;             PG8_STAGE(PG8_SB(1, 1), b3 + hstepB, voffB);
;             PG8_WAIT_V(6); PG8_BAR; PG8_MMA(1, 1, At, B1); PG8_BAR;
;     __device__ __forceinline__ void operator()(const f32x4 (&acc)[2][2][4][2], const Unit& u, int wr, int wc, int fr, int fq) const {
;     ...
;         if (u.pm >= 32) {
; #pragma unroll
;             for (int ai = 0; ai < 2; ++ai)
; #pragma unroll
;                 for (int m = 0; m < 4; ++m) { bf16_t* rowp = UP + (size_t)(row0 + ai * HALF + m * 16) * (2 * DFF) + col0;
; #pragma unroll
;                     for (int bj = 0; bj < 2; ++bj) { const f32x4 v0 = acc[ai][bj][m][0], v1 = acc[ai][bj][m][1];
;                         u32x4 w; w.x = pk2(v0[0], v0[1]); w.y = pk2(v0[2], v0[3]); w.z = pk2(v1[0], v1[1]); w.w = pk2(v1[2], v1[3]);
;                         *(u32x4*)(rowp + bj * HALF) = w; } }
;             return;
;         }
;         const int j0 = u.pn * HALF + wc * 32 + 8 * fq;
;         u32x2 res0[8];
; #pragma unroll
;         for (int n = 0; n < 2; ++n) {
;             asm volatile("" ::: "memory");
;             const int jc = j0 + 4 * n;
;             const f32x4 wg0 = *(const f32x4*)(wconv + jc), wg1 = *(const f32x4*)(wconv + 2 * DFF + jc), wg2 = *(const f32x4*)(wconv + 4 * DFF + jc), bg = *(const f32x4*)(bconv + jc);
;             const f32x4 wv0 = *(const f32x4*)(wconv + DFF + jc), wv1 = *(const f32x4*)(wconv + 3 * DFF + jc), wv2 = *(const f32x4*)(wconv + 5 * DFF + jc), bv = *(const f32x4*)(bconv + DFF + jc);
; #pragma unroll
;             for (int ai = 0; ai < 2; ++ai)
; #pragma unroll
;                 for (int m = 0; m < 4; ++m) { const int row = row0 + ai * HALF + m * 16;
;                     const f32x4 g0 = acc[ai][0][m][n], v0 = acc[ai][1][m][n];
;                     f32x4 gp = (f32x4){0.f, 0.f, 0.f, 0.f}, vp = gp;
;                     if (m > 0) { gp = acc[ai][0][m > 0 ? m - 1 : 0][n]; vp = acc[ai][1][m > 0 ? m - 1 : 0][n]; }
;                     f32x4 f;
; #pragma unroll
;                     for (int j = 0; j < 4; ++j) {
;                         const float g1 = dpp_shr1(dpp_ror1(gp[j]), g0[j]), g2 = dpp_shr2(dpp_ror2(gp[j]), g0[j]);
	s_waitcnt lgkmcnt(0)
	s_setprio 1
	v_mfma_f32_16x16x32_bf16 v[60:63], v[128:131], v[144:147], v[60:63]
	v_mfma_f32_16x16x32_bf16 v[56:59], v[136:139], v[144:147], v[56:59]
	v_mfma_f32_16x16x32_bf16 v[52:55], v[128:131], v[152:155], v[52:55]
	v_mfma_f32_16x16x32_bf16 v[44:47], v[136:139], v[152:155], v[44:47]
	v_mfma_f32_16x16x32_bf16 v[36:39], v[128:131], v[160:163], v[36:39]
	v_mfma_f32_16x16x32_bf16 v[28:31], v[136:139], v[160:163], v[28:31]
	v_mfma_f32_16x16x32_bf16 v[20:23], v[128:131], v[168:171], v[20:23]
	v_mfma_f32_16x16x32_bf16 v[12:15], v[136:139], v[168:171], v[12:15]
	v_mfma_f32_16x16x32_bf16 v[60:63], v[132:135], v[148:151], v[60:63]
	v_mfma_f32_16x16x32_bf16 v[56:59], v[140:143], v[148:151], v[56:59]
	v_mfma_f32_16x16x32_bf16 v[52:55], v[132:135], v[156:159], v[52:55]
	v_mfma_f32_16x16x32_bf16 v[44:47], v[140:143], v[156:159], v[44:47]
	v_mfma_f32_16x16x32_bf16 v[36:39], v[132:135], v[164:167], v[36:39]
	v_mfma_f32_16x16x32_bf16 v[28:31], v[140:143], v[164:167], v[28:31]
	v_mfma_f32_16x16x32_bf16 v[20:23], v[132:135], v[172:175], v[20:23]
	v_mfma_f32_16x16x32_bf16 v[12:15], v[140:143], v[172:175], v[12:15]
	s_setprio 0
	s_barrier
	s_add_u32 s52, s76, 0x80080
	s_addc_u32 s53, s77, 0
	s_add_i32 s33, s91, s64
	s_mov_b32 m0, s33
	s_nop 0
	global_load_lds_dwordx4 v228, s[52:53]
	s_add_i32 m0, s33, 0x2000
	s_nop 0
	global_load_lds_dwordx4 v224, s[52:53]
	s_waitcnt vmcnt(6)
	s_barrier
	s_setprio 1
	v_mfma_f32_16x16x32_bf16 v[48:51], v[176:179], v[144:147], v[48:51]
	v_mfma_f32_16x16x32_bf16 v[40:43], v[184:187], v[144:147], v[40:43]
	v_mfma_f32_16x16x32_bf16 v[32:35], v[176:179], v[152:155], v[32:35]
	v_mfma_f32_16x16x32_bf16 v[24:27], v[184:187], v[152:155], v[24:27]
	v_mfma_f32_16x16x32_bf16 v[16:19], v[176:179], v[160:163], v[16:19]
	v_mfma_f32_16x16x32_bf16 v[8:11], v[184:187], v[160:163], v[8:11]
	v_mfma_f32_16x16x32_bf16 v[4:7], v[176:179], v[168:171], v[4:7]
	v_mfma_f32_16x16x32_bf16 v[0:3], v[184:187], v[168:171], v[0:3]
	v_mfma_f32_16x16x32_bf16 v[48:51], v[180:183], v[148:151], v[48:51]
	v_mfma_f32_16x16x32_bf16 v[40:43], v[188:191], v[148:151], v[40:43]
	v_mfma_f32_16x16x32_bf16 v[32:35], v[180:183], v[156:159], v[32:35]
	v_mfma_f32_16x16x32_bf16 v[24:27], v[188:191], v[156:159], v[24:27]
	v_mfma_f32_16x16x32_bf16 v[16:19], v[180:183], v[164:167], v[16:19]
	v_mfma_f32_16x16x32_bf16 v[8:11], v[188:191], v[164:167], v[8:11]
	v_mfma_f32_16x16x32_bf16 v[4:7], v[180:183], v[172:175], v[4:7]
	v_mfma_f32_16x16x32_bf16 v[0:3], v[188:191], v[172:175], v[0:3]
	s_setprio 0
	s_add_i32 s5, s5, 2
	s_add_u32 s74, s74, 0x100
	s_addc_u32 s75, s75, 0
	s_add_u32 s0, s0, 0x100
	s_addc_u32 s1, s1, 0
	s_cmp_gt_u32 s5, 29
	s_barrier
	s_cbranch_scc0 .LBB0_1200
	s_lshl_b32 s5, s72, 8
	s_add_i32 s5, s5, s95
	v_or_b32_e32 v248, s5, v232
	s_cmp_lt_i32 s72, 32
	v_lshl_or_b32 v240, s42, 8, v219
	s_cbranch_scc0 .LBB0_1215
	v_lshl_or_b32 v130, s42, 7, v219
	v_readlane_b32 s16, v254, 33
	v_readlane_b32 s17, v254, 34
	v_readlane_b32 s18, v254, 35
	v_readlane_b32 s19, v254, 36
	v_readlane_b32 s20, v254, 37
	v_readlane_b32 s21, v254, 38
	v_readlane_b32 s22, v254, 39
	v_readlane_b32 s23, v254, 40
	v_readlane_b32 s24, v254, 41
	v_readlane_b32 s25, v254, 42
	v_readlane_b32 s26, v254, 43
	v_readlane_b32 s27, v254, 44
	v_readlane_b32 s28, v254, 45
	v_readlane_b32 s29, v254, 46
	v_readlane_b32 s30, v254, 47
	v_readlane_b32 s31, v254, 48
	v_ashrrev_i32_e32 v131, 31, v130
	s_ashr_i32 s72, s5, 6
	v_lshlrev_b64 v[128:129], 2, v[130:131]
	s_lshl_b32 s72, s72, 2
	s_add_i32 s73, s72, 8
	v_readfirstlane_b32 s98, v212
	v_and_b32_e32 v249, 48, v212
	s_lshr_b32 s98, s98, 6
	s_lshl_b32 s98, s98, 10
	s_add_i32 s98, s98, 0x20840
	v_lshl_add_u32 v249, v249, 1, s98
	ds_read_b128 v[146:149], v249 offset:768
	ds_read_b128 v[178:181], v249 offset:784
	ds_read_b128 v[158:161], v249 offset:512
	ds_read_b128 v[190:193], v249 offset:528
	ds_read_b128 v[162:165], v249 offset:896
	ds_read_b128 v[194:197], v249 offset:912
	ds_read_b128 v[174:177], v249 offset:640
	ds_read_b128 v[206:209], v249 offset:656
	ds_read_b128 v[154:157], v249 offset:256
	ds_read_b128 v[186:189], v249 offset:272
	ds_read_b128 v[170:173], v249 offset:384
	ds_read_b128 v[202:205], v249 offset:400
	ds_read_b128 v[150:153], v249 offset:0
	ds_read_b128 v[182:185], v249 offset:16
	ds_read_b128 v[166:169], v249 offset:128
	ds_read_b128 v[198:201], v249 offset:144
	v_lshl_add_u64 v[242:243], v[130:131], 1, s[40:41]
	v_ashrrev_i32_e32 v241, 31, v240
	s_mov_b32 s98, 0xbdd2d3e8
	s_mov_b32 s99, 0xbdd2d3e8
	s_mov_b32 s100, 1.0
	s_mov_b32 s101, 1.0
	v_mov_b32_e32 v244, 0xc0135761
	v_mov_b32_e32 v245, 0xc0135761
	s_and_saveexec_b64 s[42:43], s[10:11]
	v_or_b32_e32 v144, s72, v232
	v_mov_b64_e32 v[128:129], s[80:81]
	v_mad_u64_u32 v[128:129], vcc, v144, s83, v[128:129]
	v_lshl_add_u64 v[128:129], v[240:241], 1, v[128:129]
	v_cvt_pk_bf16_f32 v132, v124, v125
	v_cvt_pk_bf16_f32 v133, v126, v127
	v_cvt_pk_bf16_f32 v134, v120, v121
	v_cvt_pk_bf16_f32 v135, v122, v123
	v_cvt_pk_bf16_f32 v136, v112, v113
	v_cvt_pk_bf16_f32 v137, v114, v115
	v_cvt_pk_bf16_f32 v138, v104, v105
	v_cvt_pk_bf16_f32 v139, v106, v107
	global_store_dwordx4 v[128:129], v[132:135], off
	global_store_dwordx4 v[128:129], v[136:139], off offset:256
	v_or_b32_e32 v144, s73, v232
	v_mov_b64_e32 v[130:131], s[80:81]
	v_mad_u64_u32 v[130:131], vcc, v144, s83, v[130:131]
	v_lshl_add_u64 v[130:131], v[240:241], 1, v[130:131]
	v_cvt_pk_bf16_f32 v140, v60, v61
	v_cvt_pk_bf16_f32 v141, v62, v63
	v_cvt_pk_bf16_f32 v142, v56, v57
	v_cvt_pk_bf16_f32 v143, v58, v59
	v_cvt_pk_bf16_f32 v250, v48, v49
	v_cvt_pk_bf16_f32 v251, v50, v51
	v_cvt_pk_bf16_f32 v252, v40, v41
	v_cvt_pk_bf16_f32 v253, v42, v43
	global_store_dwordx4 v[130:131], v[140:143], off
	global_store_dwordx4 v[130:131], v[250:253], off offset:256
	s_or_b64 exec, exec, s[42:43]
	s_and_saveexec_b64 s[42:43], s[12:13]
	v_add_u32_e32 v144, s72, v234
	v_mov_b64_e32 v[128:129], s[80:81]
	v_mad_u64_u32 v[128:129], vcc, v144, s83, v[128:129]
	v_lshl_add_u64 v[128:129], v[240:241], 1, v[128:129]
	v_cvt_pk_bf16_f32 v132, v84, v85
	v_cvt_pk_bf16_f32 v133, v86, v87
	v_cvt_pk_bf16_f32 v134, v76, v77
	v_cvt_pk_bf16_f32 v135, v78, v79
	v_cvt_pk_bf16_f32 v136, v68, v69
	v_cvt_pk_bf16_f32 v137, v70, v71
	v_cvt_pk_bf16_f32 v138, v64, v65
	v_cvt_pk_bf16_f32 v139, v66, v67
	global_store_dwordx4 v[128:129], v[132:135], off
	global_store_dwordx4 v[128:129], v[136:139], off offset:256
	s_or_b64 exec, exec, s[42:43]
	s_waitcnt lgkmcnt(0)
; __device__ __forceinline__ unsigned pk2(float lo, float hi) { unsigned r; asm("v_cvt_pk_bf16_f32 %0, %1, %2" : "=v"(r) : "v"(lo), "v"(hi)); return r; }
; __device__ __forceinline__ float gelu_tanh(float x) { const float y = 1.5957691216f * (x + 0.044715f * x * x * x); return x * __builtin_amdgcn_rcpf(1.0f + __expf(-y)); }
;     __device__ __forceinline__ void operator()(const f32x4 (&acc)[2][2][4][2], const Unit& u, int wr, int wc, int fr, int fq) const {
;     ...
;         for (int n = 0; n < 2; ++n) {
;             asm volatile("" ::: "memory");
;             const int jc = j0 + 4 * n;
;             const f32x4 wg0 = *(const f32x4*)(wconv + jc), wg1 = *(const f32x4*)(wconv + 2 * DFF + jc), wg2 = *(const f32x4*)(wconv + 4 * DFF + jc), bg = *(const f32x4*)(bconv + jc);
;             const f32x4 wv0 = *(const f32x4*)(wconv + DFF + jc), wv1 = *(const f32x4*)(wconv + 3 * DFF + jc), wv2 = *(const f32x4*)(wconv + 5 * DFF + jc), bv = *(const f32x4*)(bconv + DFF + jc);
; #pragma unroll
;             for (int ai = 0; ai < 2; ++ai)
; #pragma unroll
;                 for (int m = 0; m < 4; ++m) { const int row = row0 + ai * HALF + m * 16;
;                     const f32x4 g0 = acc[ai][0][m][n], v0 = acc[ai][1][m][n];
;                     f32x4 gp = (f32x4){0.f, 0.f, 0.f, 0.f}, vp = gp;
;                     if (m > 0) { gp = acc[ai][0][m > 0 ? m - 1 : 0][n]; vp = acc[ai][1][m > 0 ? m - 1 : 0][n]; }
;                     f32x4 f;
; #pragma unroll
;                     for (int j = 0; j < 4; ++j) {
;                         const float g1 = dpp_shr1(dpp_ror1(gp[j]), g0[j]), g2 = dpp_shr2(dpp_ror2(gp[j]), g0[j]);
;                         const float v1 = dpp_shr1(dpp_ror1(vp[j]), v0[j]), v2 = dpp_shr2(dpp_ror2(vp[j]), v0[j]);
;                         const float cg_ = bg[j] + g2 * wg0[j] + g1 * wg1[j] + g0[j] * wg2[j];
;                         const float cv_ = bv[j] + v2 * wv0[j] + v1 * wv1[j] + v0[j] * wv2[j];
;                         f[j] = gelu_tanh(cg_) * cv_; }
;                     u32x2 w; w.x = pk2(f[0], f[1]); w.y = pk2(f[2], f[3]);
;                     if (n == 0) res0[ai * 4 + m] = w;
;                     else if (m > 0 || fr >= 2) { u32x4 w4; w4.x = res0[ai * 4 + m].x; w4.y = res0[ai * 4 + m].y; w4.z = w.x; w4.w = w.y; *(u32x4*)(F + (size_t)row * DFF + j0) = w4; }
	s_nop 4
	v_pk_fma_f32 v[132:133], v[124:125], v[158:159], v[146:147]
	v_pk_fma_f32 v[136:137], v[112:113], v[174:175], v[162:163]
	v_pk_fma_f32 v[134:135], v[126:127], v[160:161], v[148:149]
	v_pk_fma_f32 v[138:139], v[114:115], v[176:177], v[164:165]
	v_fmac_f32_dpp v132, v124, v154 row_shr:1 row_mask:0xf bank_mask:0xf
	v_fmac_f32_dpp v133, v125, v155 row_shr:1 row_mask:0xf bank_mask:0xf
	v_fmac_f32_dpp v134, v126, v156 row_shr:1 row_mask:0xf bank_mask:0xf
	v_fmac_f32_dpp v135, v127, v157 row_shr:1 row_mask:0xf bank_mask:0xf
	v_fmac_f32_dpp v136, v112, v170 row_shr:1 row_mask:0xf bank_mask:0xf
	v_fmac_f32_dpp v137, v113, v171 row_shr:1 row_mask:0xf bank_mask:0xf
	v_fmac_f32_dpp v138, v114, v172 row_shr:1 row_mask:0xf bank_mask:0xf
	v_fmac_f32_dpp v139, v115, v173 row_shr:1 row_mask:0xf bank_mask:0xf
	v_fmac_f32_dpp v132, v124, v150 row_shr:2 row_mask:0xf bank_mask:0xf
	v_fmac_f32_dpp v133, v125, v151 row_shr:2 row_mask:0xf bank_mask:0xf
	v_fmac_f32_dpp v134, v126, v152 row_shr:2 row_mask:0xf bank_mask:0xf
	v_fmac_f32_dpp v135, v127, v153 row_shr:2 row_mask:0xf bank_mask:0xf
	v_fmac_f32_dpp v136, v112, v166 row_shr:2 row_mask:0xf bank_mask:0xf
	v_fmac_f32_dpp v137, v113, v167 row_shr:2 row_mask:0xf bank_mask:0xf
	v_fmac_f32_dpp v138, v114, v168 row_shr:2 row_mask:0xf bank_mask:0xf
	v_fmac_f32_dpp v139, v115, v169 row_shr:2 row_mask:0xf bank_mask:0xf
	v_pk_mul_f32 v[140:141], v[132:133], v[132:133]
	v_pk_mul_f32 v[142:143], v[134:135], v[134:135]
	v_pk_fma_f32 v[140:141], v[140:141], s[98:99], v[244:245]
	v_pk_fma_f32 v[142:143], v[142:143], s[98:99], v[244:245]
	v_pk_mul_f32 v[140:141], v[132:133], v[140:141]
	v_pk_mul_f32 v[142:143], v[134:135], v[142:143]
	v_exp_f32_e32 v140, v140
	v_exp_f32_e32 v141, v141
	v_exp_f32_e32 v142, v142
	v_exp_f32_e32 v143, v143
	v_pk_add_f32 v[140:141], v[140:141], s[100:101]
	v_pk_add_f32 v[142:143], v[142:143], s[100:101]
	v_rcp_f32_e32 v140, v140
	v_rcp_f32_e32 v141, v141
	v_rcp_f32_e32 v142, v142
	v_rcp_f32_e32 v143, v143
	v_pk_mul_f32 v[140:141], v[132:133], v[140:141]
	v_pk_mul_f32 v[142:143], v[134:135], v[142:143]
	v_pk_mul_f32 v[140:141], v[140:141], v[136:137]
	v_pk_mul_f32 v[142:143], v[142:143], v[138:139]
	v_cvt_pk_bf16_f32 v128, v140, v141
	v_cvt_pk_bf16_f32 v129, v142, v143
	v_pk_fma_f32 v[132:133], v[120:121], v[190:191], v[178:179]
	v_pk_fma_f32 v[136:137], v[104:105], v[206:207], v[194:195]
	v_pk_fma_f32 v[134:135], v[122:123], v[192:193], v[180:181]
	v_pk_fma_f32 v[138:139], v[106:107], v[208:209], v[196:197]
	v_fmac_f32_dpp v132, v120, v186 row_shr:1 row_mask:0xf bank_mask:0xf
	v_fmac_f32_dpp v133, v121, v187 row_shr:1 row_mask:0xf bank_mask:0xf
	v_fmac_f32_dpp v134, v122, v188 row_shr:1 row_mask:0xf bank_mask:0xf
	v_fmac_f32_dpp v135, v123, v189 row_shr:1 row_mask:0xf bank_mask:0xf
	v_fmac_f32_dpp v136, v104, v202 row_shr:1 row_mask:0xf bank_mask:0xf
	v_fmac_f32_dpp v137, v105, v203 row_shr:1 row_mask:0xf bank_mask:0xf
	v_fmac_f32_dpp v138, v106, v204 row_shr:1 row_mask:0xf bank_mask:0xf
	v_fmac_f32_dpp v139, v107, v205 row_shr:1 row_mask:0xf bank_mask:0xf
	v_fmac_f32_dpp v132, v120, v182 row_shr:2 row_mask:0xf bank_mask:0xf
	v_fmac_f32_dpp v133, v121, v183 row_shr:2 row_mask:0xf bank_mask:0xf
	v_fmac_f32_dpp v134, v122, v184 row_shr:2 row_mask:0xf bank_mask:0xf
	v_fmac_f32_dpp v135, v123, v185 row_shr:2 row_mask:0xf bank_mask:0xf
	v_fmac_f32_dpp v136, v104, v198 row_shr:2 row_mask:0xf bank_mask:0xf
	v_fmac_f32_dpp v137, v105, v199 row_shr:2 row_mask:0xf bank_mask:0xf
	v_fmac_f32_dpp v138, v106, v200 row_shr:2 row_mask:0xf bank_mask:0xf
	v_fmac_f32_dpp v139, v107, v201 row_shr:2 row_mask:0xf bank_mask:0xf
	v_pk_mul_f32 v[140:141], v[132:133], v[132:133]
	v_pk_mul_f32 v[142:143], v[134:135], v[134:135]
	v_pk_fma_f32 v[140:141], v[140:141], s[98:99], v[244:245]
	v_pk_fma_f32 v[142:143], v[142:143], s[98:99], v[244:245]
	v_pk_mul_f32 v[140:141], v[132:133], v[140:141]
	v_pk_mul_f32 v[142:143], v[134:135], v[142:143]
	v_exp_f32_e32 v140, v140
	v_exp_f32_e32 v141, v141
	v_exp_f32_e32 v142, v142
	v_exp_f32_e32 v143, v143
	v_pk_add_f32 v[140:141], v[140:141], s[100:101]
	v_pk_add_f32 v[142:143], v[142:143], s[100:101]
	v_rcp_f32_e32 v140, v140
	v_rcp_f32_e32 v141, v141
	v_rcp_f32_e32 v142, v142
	v_rcp_f32_e32 v143, v143
	v_pk_mul_f32 v[140:141], v[132:133], v[140:141]
	v_pk_mul_f32 v[142:143], v[134:135], v[142:143]
	v_pk_mul_f32 v[140:141], v[140:141], v[136:137]
	v_pk_mul_f32 v[142:143], v[142:143], v[138:139]
	v_cvt_pk_bf16_f32 v130, v140, v141
	v_cvt_pk_bf16_f32 v131, v142, v143
	s_and_saveexec_b64 s[42:43], s[8:9]
	v_mad_u64_u32 v[144:145], vcc, v248, s4, v[242:243]
	global_store_dwordx4 v[144:145], v[128:131], off nt
	s_or_b64 exec, exec, s[42:43]
	s_nop 4
	v_pk_fma_f32 v[132:133], v[116:117], v[158:159], v[146:147]
	v_pk_fma_f32 v[136:137], v[96:97], v[174:175], v[162:163]
	v_pk_fma_f32 v[134:135], v[118:119], v[160:161], v[148:149]
	v_pk_fma_f32 v[138:139], v[98:99], v[176:177], v[164:165]
	v_fmac_f32_dpp v132, v116, v154 row_shr:1 row_mask:0xf bank_mask:0xf
	v_fmac_f32_dpp v133, v117, v155 row_shr:1 row_mask:0xf bank_mask:0xf
	v_fmac_f32_dpp v134, v118, v156 row_shr:1 row_mask:0xf bank_mask:0xf
	v_fmac_f32_dpp v135, v119, v157 row_shr:1 row_mask:0xf bank_mask:0xf
	v_fmac_f32_dpp v136, v96, v170 row_shr:1 row_mask:0xf bank_mask:0xf
	v_fmac_f32_dpp v137, v97, v171 row_shr:1 row_mask:0xf bank_mask:0xf
	v_fmac_f32_dpp v138, v98, v172 row_shr:1 row_mask:0xf bank_mask:0xf
	v_fmac_f32_dpp v139, v99, v173 row_shr:1 row_mask:0xf bank_mask:0xf
	v_fmac_f32_dpp v132, v124, v154 row_shl:15 row_mask:0xf bank_mask:0xf
	v_fmac_f32_dpp v133, v125, v155 row_shl:15 row_mask:0xf bank_mask:0xf
; __device__ __forceinline__ unsigned pk2(float lo, float hi) { unsigned r; asm("v_cvt_pk_bf16_f32 %0, %1, %2" : "=v"(r) : "v"(lo), "v"(hi)); return r; }
; __device__ __forceinline__ float gelu_tanh(float x) { const float y = 1.5957691216f * (x + 0.044715f * x * x * x); return x * __builtin_amdgcn_rcpf(1.0f + __expf(-y)); }
; __device__ __forceinline__ float dpp_shr1(float old, float src) { return __int_as_float(__builtin_amdgcn_update_dpp(__float_as_int(old), __float_as_int(src), 0x111, 0xf, 0xf, false)); }
; __device__ __forceinline__ float dpp_shr2(float old, float src) { return __int_as_float(__builtin_amdgcn_update_dpp(__float_as_int(old), __float_as_int(src), 0x112, 0xf, 0xf, false)); }
; __device__ __forceinline__ float dpp_ror1(float src) { return __int_as_float(__builtin_amdgcn_update_dpp(0, __float_as_int(src), 0x121, 0xf, 0xf, false)); }
; __device__ __forceinline__ float dpp_ror2(float src) { return __int_as_float(__builtin_amdgcn_update_dpp(0, __float_as_int(src), 0x122, 0xf, 0xf, false)); }
;     __device__ __forceinline__ void operator()(const f32x4 (&acc)[2][2][4][2], const Unit& u, int wr, int wc, int fr, int fq) const {
;     ...
;                     for (int j = 0; j < 4; ++j) {
;                         const float g1 = dpp_shr1(dpp_ror1(gp[j]), g0[j]), g2 = dpp_shr2(dpp_ror2(gp[j]), g0[j]);
;                         const float v1 = dpp_shr1(dpp_ror1(vp[j]), v0[j]), v2 = dpp_shr2(dpp_ror2(vp[j]), v0[j]);
;                         const float cg_ = bg[j] + g2 * wg0[j] + g1 * wg1[j] + g0[j] * wg2[j];
;                         const float cv_ = bv[j] + v2 * wv0[j] + v1 * wv1[j] + v0[j] * wv2[j];
;                         f[j] = gelu_tanh(cg_) * cv_; }
;                     u32x2 w; w.x = pk2(f[0], f[1]); w.y = pk2(f[2], f[3]);
;                     if (n == 0) res0[ai * 4 + m] = w;
;                     else if (m > 0 || fr >= 2) { u32x4 w4; w4.x = res0[ai * 4 + m].x; w4.y = res0[ai * 4 + m].y; w4.z = w.x; w4.w = w.y; *(u32x4*)(F + (size_t)row * DFF + j0) = w4; }
	v_fmac_f32_dpp v134, v126, v156 row_shl:15 row_mask:0xf bank_mask:0xf
	v_fmac_f32_dpp v135, v127, v157 row_shl:15 row_mask:0xf bank_mask:0xf
	v_fmac_f32_dpp v136, v112, v170 row_shl:15 row_mask:0xf bank_mask:0xf
	v_fmac_f32_dpp v137, v113, v171 row_shl:15 row_mask:0xf bank_mask:0xf
	v_fmac_f32_dpp v138, v114, v172 row_shl:15 row_mask:0xf bank_mask:0xf
	v_fmac_f32_dpp v139, v115, v173 row_shl:15 row_mask:0xf bank_mask:0xf
	v_fmac_f32_dpp v132, v116, v150 row_shr:2 row_mask:0xf bank_mask:0xf
	v_fmac_f32_dpp v133, v117, v151 row_shr:2 row_mask:0xf bank_mask:0xf
	v_fmac_f32_dpp v134, v118, v152 row_shr:2 row_mask:0xf bank_mask:0xf
	v_fmac_f32_dpp v135, v119, v153 row_shr:2 row_mask:0xf bank_mask:0xf
	v_fmac_f32_dpp v136, v96, v166 row_shr:2 row_mask:0xf bank_mask:0xf
	v_fmac_f32_dpp v137, v97, v167 row_shr:2 row_mask:0xf bank_mask:0xf
	v_fmac_f32_dpp v138, v98, v168 row_shr:2 row_mask:0xf bank_mask:0xf
	v_fmac_f32_dpp v139, v99, v169 row_shr:2 row_mask:0xf bank_mask:0xf
	v_fmac_f32_dpp v132, v124, v150 row_shl:14 row_mask:0xf bank_mask:0xf
	v_fmac_f32_dpp v133, v125, v151 row_shl:14 row_mask:0xf bank_mask:0xf
	v_fmac_f32_dpp v134, v126, v152 row_shl:14 row_mask:0xf bank_mask:0xf
	v_fmac_f32_dpp v135, v127, v153 row_shl:14 row_mask:0xf bank_mask:0xf
	v_fmac_f32_dpp v136, v112, v166 row_shl:14 row_mask:0xf bank_mask:0xf
	v_fmac_f32_dpp v137, v113, v167 row_shl:14 row_mask:0xf bank_mask:0xf
	v_fmac_f32_dpp v138, v114, v168 row_shl:14 row_mask:0xf bank_mask:0xf
	v_fmac_f32_dpp v139, v115, v169 row_shl:14 row_mask:0xf bank_mask:0xf
	v_pk_mul_f32 v[140:141], v[132:133], v[132:133]
	v_pk_mul_f32 v[142:143], v[134:135], v[134:135]
	v_pk_fma_f32 v[140:141], v[140:141], s[98:99], v[244:245]
	v_pk_fma_f32 v[142:143], v[142:143], s[98:99], v[244:245]
	v_pk_mul_f32 v[140:141], v[132:133], v[140:141]
	v_pk_mul_f32 v[142:143], v[134:135], v[142:143]
	v_exp_f32_e32 v140, v140
	v_exp_f32_e32 v141, v141
	v_exp_f32_e32 v142, v142
	v_exp_f32_e32 v143, v143
	v_pk_add_f32 v[140:141], v[140:141], s[100:101]
	v_pk_add_f32 v[142:143], v[142:143], s[100:101]
	v_rcp_f32_e32 v140, v140
	v_rcp_f32_e32 v141, v141
	v_rcp_f32_e32 v142, v142
	v_rcp_f32_e32 v143, v143
	v_pk_mul_f32 v[140:141], v[132:133], v[140:141]
	v_pk_mul_f32 v[142:143], v[134:135], v[142:143]
	v_pk_mul_f32 v[140:141], v[140:141], v[136:137]
	v_pk_mul_f32 v[142:143], v[142:143], v[138:139]
	v_cvt_pk_bf16_f32 v250, v140, v141
	v_cvt_pk_bf16_f32 v251, v142, v143
	v_pk_fma_f32 v[132:133], v[108:109], v[190:191], v[178:179]
	v_pk_fma_f32 v[136:137], v[88:89], v[206:207], v[194:195]
	v_pk_fma_f32 v[134:135], v[110:111], v[192:193], v[180:181]
	v_pk_fma_f32 v[138:139], v[90:91], v[208:209], v[196:197]
	v_fmac_f32_dpp v132, v108, v186 row_shr:1 row_mask:0xf bank_mask:0xf
	v_fmac_f32_dpp v133, v109, v187 row_shr:1 row_mask:0xf bank_mask:0xf
	v_fmac_f32_dpp v134, v110, v188 row_shr:1 row_mask:0xf bank_mask:0xf
	v_fmac_f32_dpp v135, v111, v189 row_shr:1 row_mask:0xf bank_mask:0xf
	v_fmac_f32_dpp v136, v88, v202 row_shr:1 row_mask:0xf bank_mask:0xf
	v_fmac_f32_dpp v137, v89, v203 row_shr:1 row_mask:0xf bank_mask:0xf
	v_fmac_f32_dpp v138, v90, v204 row_shr:1 row_mask:0xf bank_mask:0xf
	v_fmac_f32_dpp v139, v91, v205 row_shr:1 row_mask:0xf bank_mask:0xf
	v_fmac_f32_dpp v132, v120, v186 row_shl:15 row_mask:0xf bank_mask:0xf
	v_fmac_f32_dpp v133, v121, v187 row_shl:15 row_mask:0xf bank_mask:0xf
	v_fmac_f32_dpp v134, v122, v188 row_shl:15 row_mask:0xf bank_mask:0xf
	v_fmac_f32_dpp v135, v123, v189 row_shl:15 row_mask:0xf bank_mask:0xf
	v_fmac_f32_dpp v136, v104, v202 row_shl:15 row_mask:0xf bank_mask:0xf
	v_fmac_f32_dpp v137, v105, v203 row_shl:15 row_mask:0xf bank_mask:0xf
	v_fmac_f32_dpp v138, v106, v204 row_shl:15 row_mask:0xf bank_mask:0xf
	v_fmac_f32_dpp v139, v107, v205 row_shl:15 row_mask:0xf bank_mask:0xf
	v_fmac_f32_dpp v132, v108, v182 row_shr:2 row_mask:0xf bank_mask:0xf
	v_fmac_f32_dpp v133, v109, v183 row_shr:2 row_mask:0xf bank_mask:0xf
	v_fmac_f32_dpp v134, v110, v184 row_shr:2 row_mask:0xf bank_mask:0xf
	v_fmac_f32_dpp v135, v111, v185 row_shr:2 row_mask:0xf bank_mask:0xf
	v_fmac_f32_dpp v136, v88, v198 row_shr:2 row_mask:0xf bank_mask:0xf
	v_fmac_f32_dpp v137, v89, v199 row_shr:2 row_mask:0xf bank_mask:0xf
	v_fmac_f32_dpp v138, v90, v200 row_shr:2 row_mask:0xf bank_mask:0xf
	v_fmac_f32_dpp v139, v91, v201 row_shr:2 row_mask:0xf bank_mask:0xf
	v_fmac_f32_dpp v132, v120, v182 row_shl:14 row_mask:0xf bank_mask:0xf
	v_fmac_f32_dpp v133, v121, v183 row_shl:14 row_mask:0xf bank_mask:0xf
	v_fmac_f32_dpp v134, v122, v184 row_shl:14 row_mask:0xf bank_mask:0xf
	v_fmac_f32_dpp v135, v123, v185 row_shl:14 row_mask:0xf bank_mask:0xf
	v_fmac_f32_dpp v136, v104, v198 row_shl:14 row_mask:0xf bank_mask:0xf
	v_fmac_f32_dpp v137, v105, v199 row_shl:14 row_mask:0xf bank_mask:0xf
	v_fmac_f32_dpp v138, v106, v200 row_shl:14 row_mask:0xf bank_mask:0xf
	v_fmac_f32_dpp v139, v107, v201 row_shl:14 row_mask:0xf bank_mask:0xf
	v_pk_mul_f32 v[140:141], v[132:133], v[132:133]
	v_pk_mul_f32 v[142:143], v[134:135], v[134:135]
	v_pk_fma_f32 v[140:141], v[140:141], s[98:99], v[244:245]
	v_pk_fma_f32 v[142:143], v[142:143], s[98:99], v[244:245]
	v_pk_mul_f32 v[140:141], v[132:133], v[140:141]
	v_pk_mul_f32 v[142:143], v[134:135], v[142:143]
	v_exp_f32_e32 v140, v140
	v_exp_f32_e32 v141, v141
	v_exp_f32_e32 v142, v142
	v_exp_f32_e32 v143, v143
	v_pk_add_f32 v[140:141], v[140:141], s[100:101]
	v_pk_add_f32 v[142:143], v[142:143], s[100:101]
	v_rcp_f32_e32 v140, v140
	v_rcp_f32_e32 v141, v141
	v_rcp_f32_e32 v142, v142
	v_rcp_f32_e32 v143, v143
	v_pk_mul_f32 v[140:141], v[132:133], v[140:141]
	v_pk_mul_f32 v[142:143], v[134:135], v[142:143]
; __device__ __forceinline__ unsigned pk2(float lo, float hi) { unsigned r; asm("v_cvt_pk_bf16_f32 %0, %1, %2" : "=v"(r) : "v"(lo), "v"(hi)); return r; }
; __device__ __forceinline__ float gelu_tanh(float x) { const float y = 1.5957691216f * (x + 0.044715f * x * x * x); return x * __builtin_amdgcn_rcpf(1.0f + __expf(-y)); }
; __device__ __forceinline__ float dpp_shr1(float old, float src) { return __int_as_float(__builtin_amdgcn_update_dpp(__float_as_int(old), __float_as_int(src), 0x111, 0xf, 0xf, false)); }
; __device__ __forceinline__ float dpp_shr2(float old, float src) { return __int_as_float(__builtin_amdgcn_update_dpp(__float_as_int(old), __float_as_int(src), 0x112, 0xf, 0xf, false)); }
; __device__ __forceinline__ float dpp_ror1(float src) { return __int_as_float(__builtin_amdgcn_update_dpp(0, __float_as_int(src), 0x121, 0xf, 0xf, false)); }
; __device__ __forceinline__ float dpp_ror2(float src) { return __int_as_float(__builtin_amdgcn_update_dpp(0, __float_as_int(src), 0x122, 0xf, 0xf, false)); }
;     __device__ __forceinline__ void operator()(const f32x4 (&acc)[2][2][4][2], const Unit& u, int wr, int wc, int fr, int fq) const {
;     ...
;                     for (int j = 0; j < 4; ++j) {
;                         const float g1 = dpp_shr1(dpp_ror1(gp[j]), g0[j]), g2 = dpp_shr2(dpp_ror2(gp[j]), g0[j]);
;                         const float v1 = dpp_shr1(dpp_ror1(vp[j]), v0[j]), v2 = dpp_shr2(dpp_ror2(vp[j]), v0[j]);
;                         const float cg_ = bg[j] + g2 * wg0[j] + g1 * wg1[j] + g0[j] * wg2[j];
;                         const float cv_ = bv[j] + v2 * wv0[j] + v1 * wv1[j] + v0[j] * wv2[j];
;                         f[j] = gelu_tanh(cg_) * cv_; }
;                     u32x2 w; w.x = pk2(f[0], f[1]); w.y = pk2(f[2], f[3]);
;                     if (n == 0) res0[ai * 4 + m] = w;
;                     else if (m > 0 || fr >= 2) { u32x4 w4; w4.x = res0[ai * 4 + m].x; w4.y = res0[ai * 4 + m].y; w4.z = w.x; w4.w = w.y; *(u32x4*)(F + (size_t)row * DFF + j0) = w4; }
	v_pk_mul_f32 v[140:141], v[140:141], v[136:137]
	v_pk_mul_f32 v[142:143], v[142:143], v[138:139]
	v_cvt_pk_bf16_f32 v252, v140, v141
	v_cvt_pk_bf16_f32 v253, v142, v143
	v_add_u32_e32 v144, 0x10, v248
	v_mad_u64_u32 v[144:145], vcc, v144, s4, v[242:243]
	global_store_dwordx4 v[144:145], v[250:253], off nt
	v_pk_fma_f32 v[132:133], v[100:101], v[158:159], v[146:147]
	v_pk_fma_f32 v[136:137], v[80:81], v[174:175], v[162:163]
	v_pk_fma_f32 v[134:135], v[102:103], v[160:161], v[148:149]
	v_pk_fma_f32 v[138:139], v[82:83], v[176:177], v[164:165]
	v_fmac_f32_dpp v132, v100, v154 row_shr:1 row_mask:0xf bank_mask:0xf
	v_fmac_f32_dpp v133, v101, v155 row_shr:1 row_mask:0xf bank_mask:0xf
	v_fmac_f32_dpp v134, v102, v156 row_shr:1 row_mask:0xf bank_mask:0xf
	v_fmac_f32_dpp v135, v103, v157 row_shr:1 row_mask:0xf bank_mask:0xf
	v_fmac_f32_dpp v136, v80, v170 row_shr:1 row_mask:0xf bank_mask:0xf
	v_fmac_f32_dpp v137, v81, v171 row_shr:1 row_mask:0xf bank_mask:0xf
	v_fmac_f32_dpp v138, v82, v172 row_shr:1 row_mask:0xf bank_mask:0xf
	v_fmac_f32_dpp v139, v83, v173 row_shr:1 row_mask:0xf bank_mask:0xf
	v_fmac_f32_dpp v132, v116, v154 row_shl:15 row_mask:0xf bank_mask:0xf
	v_fmac_f32_dpp v133, v117, v155 row_shl:15 row_mask:0xf bank_mask:0xf
	v_fmac_f32_dpp v134, v118, v156 row_shl:15 row_mask:0xf bank_mask:0xf
	v_fmac_f32_dpp v135, v119, v157 row_shl:15 row_mask:0xf bank_mask:0xf
	v_fmac_f32_dpp v136, v96, v170 row_shl:15 row_mask:0xf bank_mask:0xf
	v_fmac_f32_dpp v137, v97, v171 row_shl:15 row_mask:0xf bank_mask:0xf
	v_fmac_f32_dpp v138, v98, v172 row_shl:15 row_mask:0xf bank_mask:0xf
	v_fmac_f32_dpp v139, v99, v173 row_shl:15 row_mask:0xf bank_mask:0xf
	v_fmac_f32_dpp v132, v100, v150 row_shr:2 row_mask:0xf bank_mask:0xf
	v_fmac_f32_dpp v133, v101, v151 row_shr:2 row_mask:0xf bank_mask:0xf
	v_fmac_f32_dpp v134, v102, v152 row_shr:2 row_mask:0xf bank_mask:0xf
	v_fmac_f32_dpp v135, v103, v153 row_shr:2 row_mask:0xf bank_mask:0xf
	v_fmac_f32_dpp v136, v80, v166 row_shr:2 row_mask:0xf bank_mask:0xf
	v_fmac_f32_dpp v137, v81, v167 row_shr:2 row_mask:0xf bank_mask:0xf
	v_fmac_f32_dpp v138, v82, v168 row_shr:2 row_mask:0xf bank_mask:0xf
	v_fmac_f32_dpp v139, v83, v169 row_shr:2 row_mask:0xf bank_mask:0xf
	v_fmac_f32_dpp v132, v116, v150 row_shl:14 row_mask:0xf bank_mask:0xf
	v_fmac_f32_dpp v133, v117, v151 row_shl:14 row_mask:0xf bank_mask:0xf
	v_fmac_f32_dpp v134, v118, v152 row_shl:14 row_mask:0xf bank_mask:0xf
	v_fmac_f32_dpp v135, v119, v153 row_shl:14 row_mask:0xf bank_mask:0xf
	v_fmac_f32_dpp v136, v96, v166 row_shl:14 row_mask:0xf bank_mask:0xf
	v_fmac_f32_dpp v137, v97, v167 row_shl:14 row_mask:0xf bank_mask:0xf
	v_fmac_f32_dpp v138, v98, v168 row_shl:14 row_mask:0xf bank_mask:0xf
	v_fmac_f32_dpp v139, v99, v169 row_shl:14 row_mask:0xf bank_mask:0xf
	v_pk_mul_f32 v[140:141], v[132:133], v[132:133]
	v_pk_mul_f32 v[142:143], v[134:135], v[134:135]
	v_pk_fma_f32 v[140:141], v[140:141], s[98:99], v[244:245]
	v_pk_fma_f32 v[142:143], v[142:143], s[98:99], v[244:245]
	v_pk_mul_f32 v[140:141], v[132:133], v[140:141]
	v_pk_mul_f32 v[142:143], v[134:135], v[142:143]
	v_exp_f32_e32 v140, v140
	v_exp_f32_e32 v141, v141
	v_exp_f32_e32 v142, v142
	v_exp_f32_e32 v143, v143
	v_pk_add_f32 v[140:141], v[140:141], s[100:101]
	v_pk_add_f32 v[142:143], v[142:143], s[100:101]
	v_rcp_f32_e32 v140, v140
	v_rcp_f32_e32 v141, v141
	v_rcp_f32_e32 v142, v142
	v_rcp_f32_e32 v143, v143
	v_pk_mul_f32 v[140:141], v[132:133], v[140:141]
	v_pk_mul_f32 v[142:143], v[134:135], v[142:143]
	v_pk_mul_f32 v[140:141], v[140:141], v[136:137]
	v_pk_mul_f32 v[142:143], v[142:143], v[138:139]
	v_cvt_pk_bf16_f32 v128, v140, v141
	v_cvt_pk_bf16_f32 v129, v142, v143
	v_pk_fma_f32 v[132:133], v[92:93], v[190:191], v[178:179]
	v_pk_fma_f32 v[136:137], v[72:73], v[206:207], v[194:195]
	v_pk_fma_f32 v[134:135], v[94:95], v[192:193], v[180:181]
	v_pk_fma_f32 v[138:139], v[74:75], v[208:209], v[196:197]
	v_fmac_f32_dpp v132, v92, v186 row_shr:1 row_mask:0xf bank_mask:0xf
	v_fmac_f32_dpp v133, v93, v187 row_shr:1 row_mask:0xf bank_mask:0xf
	v_fmac_f32_dpp v134, v94, v188 row_shr:1 row_mask:0xf bank_mask:0xf
	v_fmac_f32_dpp v135, v95, v189 row_shr:1 row_mask:0xf bank_mask:0xf
	v_fmac_f32_dpp v136, v72, v202 row_shr:1 row_mask:0xf bank_mask:0xf
	v_fmac_f32_dpp v137, v73, v203 row_shr:1 row_mask:0xf bank_mask:0xf
	v_fmac_f32_dpp v138, v74, v204 row_shr:1 row_mask:0xf bank_mask:0xf
	v_fmac_f32_dpp v139, v75, v205 row_shr:1 row_mask:0xf bank_mask:0xf
	v_fmac_f32_dpp v132, v108, v186 row_shl:15 row_mask:0xf bank_mask:0xf
	v_fmac_f32_dpp v133, v109, v187 row_shl:15 row_mask:0xf bank_mask:0xf
	v_fmac_f32_dpp v134, v110, v188 row_shl:15 row_mask:0xf bank_mask:0xf
	v_fmac_f32_dpp v135, v111, v189 row_shl:15 row_mask:0xf bank_mask:0xf
	v_fmac_f32_dpp v136, v88, v202 row_shl:15 row_mask:0xf bank_mask:0xf
	v_fmac_f32_dpp v137, v89, v203 row_shl:15 row_mask:0xf bank_mask:0xf
	v_fmac_f32_dpp v138, v90, v204 row_shl:15 row_mask:0xf bank_mask:0xf
	v_fmac_f32_dpp v139, v91, v205 row_shl:15 row_mask:0xf bank_mask:0xf
	v_fmac_f32_dpp v132, v92, v182 row_shr:2 row_mask:0xf bank_mask:0xf
	v_fmac_f32_dpp v133, v93, v183 row_shr:2 row_mask:0xf bank_mask:0xf
	v_fmac_f32_dpp v134, v94, v184 row_shr:2 row_mask:0xf bank_mask:0xf
	v_fmac_f32_dpp v135, v95, v185 row_shr:2 row_mask:0xf bank_mask:0xf
	v_fmac_f32_dpp v136, v72, v198 row_shr:2 row_mask:0xf bank_mask:0xf
	v_fmac_f32_dpp v137, v73, v199 row_shr:2 row_mask:0xf bank_mask:0xf
	v_fmac_f32_dpp v138, v74, v200 row_shr:2 row_mask:0xf bank_mask:0xf
	v_fmac_f32_dpp v139, v75, v201 row_shr:2 row_mask:0xf bank_mask:0xf
	v_fmac_f32_dpp v132, v108, v182 row_shl:14 row_mask:0xf bank_mask:0xf
; __device__ __forceinline__ unsigned pk2(float lo, float hi) { unsigned r; asm("v_cvt_pk_bf16_f32 %0, %1, %2" : "=v"(r) : "v"(lo), "v"(hi)); return r; }
; __device__ __forceinline__ float gelu_tanh(float x) { const float y = 1.5957691216f * (x + 0.044715f * x * x * x); return x * __builtin_amdgcn_rcpf(1.0f + __expf(-y)); }
; __device__ __forceinline__ float dpp_shr1(float old, float src) { return __int_as_float(__builtin_amdgcn_update_dpp(__float_as_int(old), __float_as_int(src), 0x111, 0xf, 0xf, false)); }
; __device__ __forceinline__ float dpp_shr2(float old, float src) { return __int_as_float(__builtin_amdgcn_update_dpp(__float_as_int(old), __float_as_int(src), 0x112, 0xf, 0xf, false)); }
; __device__ __forceinline__ float dpp_ror1(float src) { return __int_as_float(__builtin_amdgcn_update_dpp(0, __float_as_int(src), 0x121, 0xf, 0xf, false)); }
; __device__ __forceinline__ float dpp_ror2(float src) { return __int_as_float(__builtin_amdgcn_update_dpp(0, __float_as_int(src), 0x122, 0xf, 0xf, false)); }
;     __device__ __forceinline__ void operator()(const f32x4 (&acc)[2][2][4][2], const Unit& u, int wr, int wc, int fr, int fq) const {
;     ...
;                     for (int j = 0; j < 4; ++j) {
;                         const float g1 = dpp_shr1(dpp_ror1(gp[j]), g0[j]), g2 = dpp_shr2(dpp_ror2(gp[j]), g0[j]);
;                         const float v1 = dpp_shr1(dpp_ror1(vp[j]), v0[j]), v2 = dpp_shr2(dpp_ror2(vp[j]), v0[j]);
;                         const float cg_ = bg[j] + g2 * wg0[j] + g1 * wg1[j] + g0[j] * wg2[j];
;                         const float cv_ = bv[j] + v2 * wv0[j] + v1 * wv1[j] + v0[j] * wv2[j];
;                         f[j] = gelu_tanh(cg_) * cv_; }
;                     u32x2 w; w.x = pk2(f[0], f[1]); w.y = pk2(f[2], f[3]);
;                     if (n == 0) res0[ai * 4 + m] = w;
;                     else if (m > 0 || fr >= 2) { u32x4 w4; w4.x = res0[ai * 4 + m].x; w4.y = res0[ai * 4 + m].y; w4.z = w.x; w4.w = w.y; *(u32x4*)(F + (size_t)row * DFF + j0) = w4; }
	v_fmac_f32_dpp v133, v109, v183 row_shl:14 row_mask:0xf bank_mask:0xf
	v_fmac_f32_dpp v134, v110, v184 row_shl:14 row_mask:0xf bank_mask:0xf
	v_fmac_f32_dpp v135, v111, v185 row_shl:14 row_mask:0xf bank_mask:0xf
	v_fmac_f32_dpp v136, v88, v198 row_shl:14 row_mask:0xf bank_mask:0xf
	v_fmac_f32_dpp v137, v89, v199 row_shl:14 row_mask:0xf bank_mask:0xf
	v_fmac_f32_dpp v138, v90, v200 row_shl:14 row_mask:0xf bank_mask:0xf
	v_fmac_f32_dpp v139, v91, v201 row_shl:14 row_mask:0xf bank_mask:0xf
	v_pk_mul_f32 v[140:141], v[132:133], v[132:133]
	v_pk_mul_f32 v[142:143], v[134:135], v[134:135]
	v_pk_fma_f32 v[140:141], v[140:141], s[98:99], v[244:245]
	v_pk_fma_f32 v[142:143], v[142:143], s[98:99], v[244:245]
	v_pk_mul_f32 v[140:141], v[132:133], v[140:141]
	v_pk_mul_f32 v[142:143], v[134:135], v[142:143]
	v_exp_f32_e32 v140, v140
	v_exp_f32_e32 v141, v141
	v_exp_f32_e32 v142, v142
	v_exp_f32_e32 v143, v143
	v_pk_add_f32 v[140:141], v[140:141], s[100:101]
	v_pk_add_f32 v[142:143], v[142:143], s[100:101]
	v_rcp_f32_e32 v140, v140
	v_rcp_f32_e32 v141, v141
	v_rcp_f32_e32 v142, v142
	v_rcp_f32_e32 v143, v143
	v_pk_mul_f32 v[140:141], v[132:133], v[140:141]
	v_pk_mul_f32 v[142:143], v[134:135], v[142:143]
	v_pk_mul_f32 v[140:141], v[140:141], v[136:137]
	v_pk_mul_f32 v[142:143], v[142:143], v[138:139]
	v_cvt_pk_bf16_f32 v130, v140, v141
	v_cvt_pk_bf16_f32 v131, v142, v143
	v_add_u32_e32 v144, 0x20, v248
	v_mad_u64_u32 v[144:145], vcc, v144, s4, v[242:243]
	global_store_dwordx4 v[144:145], v[128:131], off nt
	v_pk_fma_f32 v[132:133], v[84:85], v[158:159], v[146:147]
	v_pk_fma_f32 v[136:137], v[68:69], v[174:175], v[162:163]
	v_pk_fma_f32 v[134:135], v[86:87], v[160:161], v[148:149]
	v_pk_fma_f32 v[138:139], v[70:71], v[176:177], v[164:165]
	v_fmac_f32_dpp v132, v84, v154 row_shr:1 row_mask:0xf bank_mask:0xf
	v_fmac_f32_dpp v133, v85, v155 row_shr:1 row_mask:0xf bank_mask:0xf
	v_fmac_f32_dpp v134, v86, v156 row_shr:1 row_mask:0xf bank_mask:0xf
	v_fmac_f32_dpp v135, v87, v157 row_shr:1 row_mask:0xf bank_mask:0xf
	v_fmac_f32_dpp v136, v68, v170 row_shr:1 row_mask:0xf bank_mask:0xf
	v_fmac_f32_dpp v137, v69, v171 row_shr:1 row_mask:0xf bank_mask:0xf
	v_fmac_f32_dpp v138, v70, v172 row_shr:1 row_mask:0xf bank_mask:0xf
	v_fmac_f32_dpp v139, v71, v173 row_shr:1 row_mask:0xf bank_mask:0xf
	v_fmac_f32_dpp v132, v100, v154 row_shl:15 row_mask:0xf bank_mask:0xf
	v_fmac_f32_dpp v133, v101, v155 row_shl:15 row_mask:0xf bank_mask:0xf
	v_fmac_f32_dpp v134, v102, v156 row_shl:15 row_mask:0xf bank_mask:0xf
	v_fmac_f32_dpp v135, v103, v157 row_shl:15 row_mask:0xf bank_mask:0xf
	v_fmac_f32_dpp v136, v80, v170 row_shl:15 row_mask:0xf bank_mask:0xf
	v_fmac_f32_dpp v137, v81, v171 row_shl:15 row_mask:0xf bank_mask:0xf
	v_fmac_f32_dpp v138, v82, v172 row_shl:15 row_mask:0xf bank_mask:0xf
	v_fmac_f32_dpp v139, v83, v173 row_shl:15 row_mask:0xf bank_mask:0xf
	v_fmac_f32_dpp v132, v84, v150 row_shr:2 row_mask:0xf bank_mask:0xf
	v_fmac_f32_dpp v133, v85, v151 row_shr:2 row_mask:0xf bank_mask:0xf
	v_fmac_f32_dpp v134, v86, v152 row_shr:2 row_mask:0xf bank_mask:0xf
	v_fmac_f32_dpp v135, v87, v153 row_shr:2 row_mask:0xf bank_mask:0xf
	v_fmac_f32_dpp v136, v68, v166 row_shr:2 row_mask:0xf bank_mask:0xf
	v_fmac_f32_dpp v137, v69, v167 row_shr:2 row_mask:0xf bank_mask:0xf
	v_fmac_f32_dpp v138, v70, v168 row_shr:2 row_mask:0xf bank_mask:0xf
	v_fmac_f32_dpp v139, v71, v169 row_shr:2 row_mask:0xf bank_mask:0xf
	v_fmac_f32_dpp v132, v100, v150 row_shl:14 row_mask:0xf bank_mask:0xf
	v_fmac_f32_dpp v133, v101, v151 row_shl:14 row_mask:0xf bank_mask:0xf
	v_fmac_f32_dpp v134, v102, v152 row_shl:14 row_mask:0xf bank_mask:0xf
	v_fmac_f32_dpp v135, v103, v153 row_shl:14 row_mask:0xf bank_mask:0xf
	v_fmac_f32_dpp v136, v80, v166 row_shl:14 row_mask:0xf bank_mask:0xf
	v_fmac_f32_dpp v137, v81, v167 row_shl:14 row_mask:0xf bank_mask:0xf
	v_fmac_f32_dpp v138, v82, v168 row_shl:14 row_mask:0xf bank_mask:0xf
	v_fmac_f32_dpp v139, v83, v169 row_shl:14 row_mask:0xf bank_mask:0xf
	v_pk_mul_f32 v[140:141], v[132:133], v[132:133]
	v_pk_mul_f32 v[142:143], v[134:135], v[134:135]
	v_pk_fma_f32 v[140:141], v[140:141], s[98:99], v[244:245]
	v_pk_fma_f32 v[142:143], v[142:143], s[98:99], v[244:245]
	v_pk_mul_f32 v[140:141], v[132:133], v[140:141]
	v_pk_mul_f32 v[142:143], v[134:135], v[142:143]
	v_exp_f32_e32 v140, v140
	v_exp_f32_e32 v141, v141
	v_exp_f32_e32 v142, v142
	v_exp_f32_e32 v143, v143
	v_pk_add_f32 v[140:141], v[140:141], s[100:101]
	v_pk_add_f32 v[142:143], v[142:143], s[100:101]
	v_rcp_f32_e32 v140, v140
	v_rcp_f32_e32 v141, v141
	v_rcp_f32_e32 v142, v142
	v_rcp_f32_e32 v143, v143
	v_pk_mul_f32 v[140:141], v[132:133], v[140:141]
	v_pk_mul_f32 v[142:143], v[134:135], v[142:143]
	v_pk_mul_f32 v[140:141], v[140:141], v[136:137]
	v_pk_mul_f32 v[142:143], v[142:143], v[138:139]
	v_cvt_pk_bf16_f32 v250, v140, v141
	v_cvt_pk_bf16_f32 v251, v142, v143
	v_pk_fma_f32 v[132:133], v[76:77], v[190:191], v[178:179]
	v_pk_fma_f32 v[136:137], v[64:65], v[206:207], v[194:195]
	v_pk_fma_f32 v[134:135], v[78:79], v[192:193], v[180:181]
	v_pk_fma_f32 v[138:139], v[66:67], v[208:209], v[196:197]
	v_fmac_f32_dpp v132, v76, v186 row_shr:1 row_mask:0xf bank_mask:0xf
	v_fmac_f32_dpp v133, v77, v187 row_shr:1 row_mask:0xf bank_mask:0xf
	v_fmac_f32_dpp v134, v78, v188 row_shr:1 row_mask:0xf bank_mask:0xf
	v_fmac_f32_dpp v135, v79, v189 row_shr:1 row_mask:0xf bank_mask:0xf
	v_fmac_f32_dpp v136, v64, v202 row_shr:1 row_mask:0xf bank_mask:0xf
	v_fmac_f32_dpp v137, v65, v203 row_shr:1 row_mask:0xf bank_mask:0xf
	v_fmac_f32_dpp v138, v66, v204 row_shr:1 row_mask:0xf bank_mask:0xf
	v_fmac_f32_dpp v139, v67, v205 row_shr:1 row_mask:0xf bank_mask:0xf
; __device__ __forceinline__ unsigned pk2(float lo, float hi) { unsigned r; asm("v_cvt_pk_bf16_f32 %0, %1, %2" : "=v"(r) : "v"(lo), "v"(hi)); return r; }
; __device__ __forceinline__ float gelu_tanh(float x) { const float y = 1.5957691216f * (x + 0.044715f * x * x * x); return x * __builtin_amdgcn_rcpf(1.0f + __expf(-y)); }
; __device__ __forceinline__ float dpp_shr1(float old, float src) { return __int_as_float(__builtin_amdgcn_update_dpp(__float_as_int(old), __float_as_int(src), 0x111, 0xf, 0xf, false)); }
; __device__ __forceinline__ float dpp_shr2(float old, float src) { return __int_as_float(__builtin_amdgcn_update_dpp(__float_as_int(old), __float_as_int(src), 0x112, 0xf, 0xf, false)); }
; __device__ __forceinline__ float dpp_ror1(float src) { return __int_as_float(__builtin_amdgcn_update_dpp(0, __float_as_int(src), 0x121, 0xf, 0xf, false)); }
; __device__ __forceinline__ float dpp_ror2(float src) { return __int_as_float(__builtin_amdgcn_update_dpp(0, __float_as_int(src), 0x122, 0xf, 0xf, false)); }
;     __device__ __forceinline__ void operator()(const f32x4 (&acc)[2][2][4][2], const Unit& u, int wr, int wc, int fr, int fq) const {
;     ...
;                     for (int j = 0; j < 4; ++j) {
;                         const float g1 = dpp_shr1(dpp_ror1(gp[j]), g0[j]), g2 = dpp_shr2(dpp_ror2(gp[j]), g0[j]);
;                         const float v1 = dpp_shr1(dpp_ror1(vp[j]), v0[j]), v2 = dpp_shr2(dpp_ror2(vp[j]), v0[j]);
;                         const float cg_ = bg[j] + g2 * wg0[j] + g1 * wg1[j] + g0[j] * wg2[j];
;                         const float cv_ = bv[j] + v2 * wv0[j] + v1 * wv1[j] + v0[j] * wv2[j];
;                         f[j] = gelu_tanh(cg_) * cv_; }
;                     u32x2 w; w.x = pk2(f[0], f[1]); w.y = pk2(f[2], f[3]);
;                     if (n == 0) res0[ai * 4 + m] = w;
;                     else if (m > 0 || fr >= 2) { u32x4 w4; w4.x = res0[ai * 4 + m].x; w4.y = res0[ai * 4 + m].y; w4.z = w.x; w4.w = w.y; *(u32x4*)(F + (size_t)row * DFF + j0) = w4; }
	v_fmac_f32_dpp v132, v92, v186 row_shl:15 row_mask:0xf bank_mask:0xf
	v_fmac_f32_dpp v133, v93, v187 row_shl:15 row_mask:0xf bank_mask:0xf
	v_fmac_f32_dpp v134, v94, v188 row_shl:15 row_mask:0xf bank_mask:0xf
	v_fmac_f32_dpp v135, v95, v189 row_shl:15 row_mask:0xf bank_mask:0xf
	v_fmac_f32_dpp v136, v72, v202 row_shl:15 row_mask:0xf bank_mask:0xf
	v_fmac_f32_dpp v137, v73, v203 row_shl:15 row_mask:0xf bank_mask:0xf
	v_fmac_f32_dpp v138, v74, v204 row_shl:15 row_mask:0xf bank_mask:0xf
	v_fmac_f32_dpp v139, v75, v205 row_shl:15 row_mask:0xf bank_mask:0xf
	v_fmac_f32_dpp v132, v76, v182 row_shr:2 row_mask:0xf bank_mask:0xf
	v_fmac_f32_dpp v133, v77, v183 row_shr:2 row_mask:0xf bank_mask:0xf
	v_fmac_f32_dpp v134, v78, v184 row_shr:2 row_mask:0xf bank_mask:0xf
	v_fmac_f32_dpp v135, v79, v185 row_shr:2 row_mask:0xf bank_mask:0xf
	v_fmac_f32_dpp v136, v64, v198 row_shr:2 row_mask:0xf bank_mask:0xf
	v_fmac_f32_dpp v137, v65, v199 row_shr:2 row_mask:0xf bank_mask:0xf
	v_fmac_f32_dpp v138, v66, v200 row_shr:2 row_mask:0xf bank_mask:0xf
	v_fmac_f32_dpp v139, v67, v201 row_shr:2 row_mask:0xf bank_mask:0xf
	v_fmac_f32_dpp v132, v92, v182 row_shl:14 row_mask:0xf bank_mask:0xf
	v_fmac_f32_dpp v133, v93, v183 row_shl:14 row_mask:0xf bank_mask:0xf
	v_fmac_f32_dpp v134, v94, v184 row_shl:14 row_mask:0xf bank_mask:0xf
	v_fmac_f32_dpp v135, v95, v185 row_shl:14 row_mask:0xf bank_mask:0xf
	v_fmac_f32_dpp v136, v72, v198 row_shl:14 row_mask:0xf bank_mask:0xf
	v_fmac_f32_dpp v137, v73, v199 row_shl:14 row_mask:0xf bank_mask:0xf
	v_fmac_f32_dpp v138, v74, v200 row_shl:14 row_mask:0xf bank_mask:0xf
	v_fmac_f32_dpp v139, v75, v201 row_shl:14 row_mask:0xf bank_mask:0xf
	v_pk_mul_f32 v[140:141], v[132:133], v[132:133]
	v_pk_mul_f32 v[142:143], v[134:135], v[134:135]
	v_pk_fma_f32 v[140:141], v[140:141], s[98:99], v[244:245]
	v_pk_fma_f32 v[142:143], v[142:143], s[98:99], v[244:245]
	v_pk_mul_f32 v[140:141], v[132:133], v[140:141]
	v_pk_mul_f32 v[142:143], v[134:135], v[142:143]
	v_exp_f32_e32 v140, v140
	v_exp_f32_e32 v141, v141
	v_exp_f32_e32 v142, v142
	v_exp_f32_e32 v143, v143
	v_pk_add_f32 v[140:141], v[140:141], s[100:101]
	v_pk_add_f32 v[142:143], v[142:143], s[100:101]
	v_rcp_f32_e32 v140, v140
	v_rcp_f32_e32 v141, v141
	v_rcp_f32_e32 v142, v142
	v_rcp_f32_e32 v143, v143
	v_pk_mul_f32 v[140:141], v[132:133], v[140:141]
	v_pk_mul_f32 v[142:143], v[134:135], v[142:143]
	v_pk_mul_f32 v[140:141], v[140:141], v[136:137]
	v_pk_mul_f32 v[142:143], v[142:143], v[138:139]
	v_cvt_pk_bf16_f32 v252, v140, v141
	v_cvt_pk_bf16_f32 v253, v142, v143
	v_add_u32_e32 v144, 0x30, v248
	v_mad_u64_u32 v[144:145], vcc, v144, s4, v[242:243]
	global_store_dwordx4 v[144:145], v[250:253], off nt
	v_pk_fma_f32 v[132:133], v[60:61], v[158:159], v[146:147]
	v_pk_fma_f32 v[136:137], v[48:49], v[174:175], v[162:163]
	v_pk_fma_f32 v[134:135], v[62:63], v[160:161], v[148:149]
	v_pk_fma_f32 v[138:139], v[50:51], v[176:177], v[164:165]
	v_fmac_f32_dpp v132, v60, v154 row_shr:1 row_mask:0xf bank_mask:0xf
	v_fmac_f32_dpp v133, v61, v155 row_shr:1 row_mask:0xf bank_mask:0xf
	v_fmac_f32_dpp v134, v62, v156 row_shr:1 row_mask:0xf bank_mask:0xf
	v_fmac_f32_dpp v135, v63, v157 row_shr:1 row_mask:0xf bank_mask:0xf
	v_fmac_f32_dpp v136, v48, v170 row_shr:1 row_mask:0xf bank_mask:0xf
	v_fmac_f32_dpp v137, v49, v171 row_shr:1 row_mask:0xf bank_mask:0xf
	v_fmac_f32_dpp v138, v50, v172 row_shr:1 row_mask:0xf bank_mask:0xf
	v_fmac_f32_dpp v139, v51, v173 row_shr:1 row_mask:0xf bank_mask:0xf
	v_fmac_f32_dpp v132, v60, v150 row_shr:2 row_mask:0xf bank_mask:0xf
	v_fmac_f32_dpp v133, v61, v151 row_shr:2 row_mask:0xf bank_mask:0xf
	v_fmac_f32_dpp v134, v62, v152 row_shr:2 row_mask:0xf bank_mask:0xf
	v_fmac_f32_dpp v135, v63, v153 row_shr:2 row_mask:0xf bank_mask:0xf
	v_fmac_f32_dpp v136, v48, v166 row_shr:2 row_mask:0xf bank_mask:0xf
	v_fmac_f32_dpp v137, v49, v167 row_shr:2 row_mask:0xf bank_mask:0xf
	v_fmac_f32_dpp v138, v50, v168 row_shr:2 row_mask:0xf bank_mask:0xf
	v_fmac_f32_dpp v139, v51, v169 row_shr:2 row_mask:0xf bank_mask:0xf
	v_pk_mul_f32 v[140:141], v[132:133], v[132:133]
	v_pk_mul_f32 v[142:143], v[134:135], v[134:135]
	v_pk_fma_f32 v[140:141], v[140:141], s[98:99], v[244:245]
	v_pk_fma_f32 v[142:143], v[142:143], s[98:99], v[244:245]
	v_pk_mul_f32 v[140:141], v[132:133], v[140:141]
	v_pk_mul_f32 v[142:143], v[134:135], v[142:143]
	v_exp_f32_e32 v140, v140
	v_exp_f32_e32 v141, v141
	v_exp_f32_e32 v142, v142
	v_exp_f32_e32 v143, v143
	v_pk_add_f32 v[140:141], v[140:141], s[100:101]
	v_pk_add_f32 v[142:143], v[142:143], s[100:101]
	v_rcp_f32_e32 v140, v140
	v_rcp_f32_e32 v141, v141
	v_rcp_f32_e32 v142, v142
	v_rcp_f32_e32 v143, v143
	v_pk_mul_f32 v[140:141], v[132:133], v[140:141]
	v_pk_mul_f32 v[142:143], v[134:135], v[142:143]
	v_pk_mul_f32 v[140:141], v[140:141], v[136:137]
	v_pk_mul_f32 v[142:143], v[142:143], v[138:139]
	v_cvt_pk_bf16_f32 v128, v140, v141
	v_cvt_pk_bf16_f32 v129, v142, v143
	v_pk_fma_f32 v[132:133], v[56:57], v[190:191], v[178:179]
	v_pk_fma_f32 v[136:137], v[40:41], v[206:207], v[194:195]
	v_pk_fma_f32 v[134:135], v[58:59], v[192:193], v[180:181]
	v_pk_fma_f32 v[138:139], v[42:43], v[208:209], v[196:197]
	v_fmac_f32_dpp v132, v56, v186 row_shr:1 row_mask:0xf bank_mask:0xf
	v_fmac_f32_dpp v133, v57, v187 row_shr:1 row_mask:0xf bank_mask:0xf
	v_fmac_f32_dpp v134, v58, v188 row_shr:1 row_mask:0xf bank_mask:0xf
	v_fmac_f32_dpp v135, v59, v189 row_shr:1 row_mask:0xf bank_mask:0xf
	v_fmac_f32_dpp v136, v40, v202 row_shr:1 row_mask:0xf bank_mask:0xf
	v_fmac_f32_dpp v137, v41, v203 row_shr:1 row_mask:0xf bank_mask:0xf
	v_fmac_f32_dpp v138, v42, v204 row_shr:1 row_mask:0xf bank_mask:0xf
; __device__ __forceinline__ unsigned pk2(float lo, float hi) { unsigned r; asm("v_cvt_pk_bf16_f32 %0, %1, %2" : "=v"(r) : "v"(lo), "v"(hi)); return r; }
; __device__ __forceinline__ float gelu_tanh(float x) { const float y = 1.5957691216f * (x + 0.044715f * x * x * x); return x * __builtin_amdgcn_rcpf(1.0f + __expf(-y)); }
; __device__ __forceinline__ float dpp_shr1(float old, float src) { return __int_as_float(__builtin_amdgcn_update_dpp(__float_as_int(old), __float_as_int(src), 0x111, 0xf, 0xf, false)); }
; __device__ __forceinline__ float dpp_shr2(float old, float src) { return __int_as_float(__builtin_amdgcn_update_dpp(__float_as_int(old), __float_as_int(src), 0x112, 0xf, 0xf, false)); }
; __device__ __forceinline__ float dpp_ror1(float src) { return __int_as_float(__builtin_amdgcn_update_dpp(0, __float_as_int(src), 0x121, 0xf, 0xf, false)); }
; __device__ __forceinline__ float dpp_ror2(float src) { return __int_as_float(__builtin_amdgcn_update_dpp(0, __float_as_int(src), 0x122, 0xf, 0xf, false)); }
;     __device__ __forceinline__ void operator()(const f32x4 (&acc)[2][2][4][2], const Unit& u, int wr, int wc, int fr, int fq) const {
;     ...
;                     for (int j = 0; j < 4; ++j) {
;                         const float g1 = dpp_shr1(dpp_ror1(gp[j]), g0[j]), g2 = dpp_shr2(dpp_ror2(gp[j]), g0[j]);
;                         const float v1 = dpp_shr1(dpp_ror1(vp[j]), v0[j]), v2 = dpp_shr2(dpp_ror2(vp[j]), v0[j]);
;                         const float cg_ = bg[j] + g2 * wg0[j] + g1 * wg1[j] + g0[j] * wg2[j];
;                         const float cv_ = bv[j] + v2 * wv0[j] + v1 * wv1[j] + v0[j] * wv2[j];
;                         f[j] = gelu_tanh(cg_) * cv_; }
;                     u32x2 w; w.x = pk2(f[0], f[1]); w.y = pk2(f[2], f[3]);
;                     if (n == 0) res0[ai * 4 + m] = w;
;                     else if (m > 0 || fr >= 2) { u32x4 w4; w4.x = res0[ai * 4 + m].x; w4.y = res0[ai * 4 + m].y; w4.z = w.x; w4.w = w.y; *(u32x4*)(F + (size_t)row * DFF + j0) = w4; }
	v_fmac_f32_dpp v139, v43, v205 row_shr:1 row_mask:0xf bank_mask:0xf
	v_fmac_f32_dpp v132, v56, v182 row_shr:2 row_mask:0xf bank_mask:0xf
	v_fmac_f32_dpp v133, v57, v183 row_shr:2 row_mask:0xf bank_mask:0xf
	v_fmac_f32_dpp v134, v58, v184 row_shr:2 row_mask:0xf bank_mask:0xf
	v_fmac_f32_dpp v135, v59, v185 row_shr:2 row_mask:0xf bank_mask:0xf
	v_fmac_f32_dpp v136, v40, v198 row_shr:2 row_mask:0xf bank_mask:0xf
	v_fmac_f32_dpp v137, v41, v199 row_shr:2 row_mask:0xf bank_mask:0xf
	v_fmac_f32_dpp v138, v42, v200 row_shr:2 row_mask:0xf bank_mask:0xf
	v_fmac_f32_dpp v139, v43, v201 row_shr:2 row_mask:0xf bank_mask:0xf
	v_pk_mul_f32 v[140:141], v[132:133], v[132:133]
	v_pk_mul_f32 v[142:143], v[134:135], v[134:135]
	v_pk_fma_f32 v[140:141], v[140:141], s[98:99], v[244:245]
	v_pk_fma_f32 v[142:143], v[142:143], s[98:99], v[244:245]
	v_pk_mul_f32 v[140:141], v[132:133], v[140:141]
	v_pk_mul_f32 v[142:143], v[134:135], v[142:143]
	v_exp_f32_e32 v140, v140
	v_exp_f32_e32 v141, v141
	v_exp_f32_e32 v142, v142
	v_exp_f32_e32 v143, v143
	v_pk_add_f32 v[140:141], v[140:141], s[100:101]
	v_pk_add_f32 v[142:143], v[142:143], s[100:101]
	v_rcp_f32_e32 v140, v140
	v_rcp_f32_e32 v141, v141
	v_rcp_f32_e32 v142, v142
	v_rcp_f32_e32 v143, v143
	v_pk_mul_f32 v[140:141], v[132:133], v[140:141]
	v_pk_mul_f32 v[142:143], v[134:135], v[142:143]
	v_pk_mul_f32 v[140:141], v[140:141], v[136:137]
	v_pk_mul_f32 v[142:143], v[142:143], v[138:139]
	v_cvt_pk_bf16_f32 v130, v140, v141
	v_cvt_pk_bf16_f32 v131, v142, v143
	s_and_saveexec_b64 s[42:43], s[8:9]
	v_add_u32_e32 v144, 0x80, v248
	v_mad_u64_u32 v[144:145], vcc, v144, s4, v[242:243]
	global_store_dwordx4 v[144:145], v[128:131], off nt
	s_or_b64 exec, exec, s[42:43]
	s_nop 4
	v_pk_fma_f32 v[132:133], v[52:53], v[158:159], v[146:147]
	v_pk_fma_f32 v[136:137], v[32:33], v[174:175], v[162:163]
	v_pk_fma_f32 v[134:135], v[54:55], v[160:161], v[148:149]
	v_pk_fma_f32 v[138:139], v[34:35], v[176:177], v[164:165]
	v_fmac_f32_dpp v132, v52, v154 row_shr:1 row_mask:0xf bank_mask:0xf
	v_fmac_f32_dpp v133, v53, v155 row_shr:1 row_mask:0xf bank_mask:0xf
	v_fmac_f32_dpp v134, v54, v156 row_shr:1 row_mask:0xf bank_mask:0xf
	v_fmac_f32_dpp v135, v55, v157 row_shr:1 row_mask:0xf bank_mask:0xf
	v_fmac_f32_dpp v136, v32, v170 row_shr:1 row_mask:0xf bank_mask:0xf
	v_fmac_f32_dpp v137, v33, v171 row_shr:1 row_mask:0xf bank_mask:0xf
	v_fmac_f32_dpp v138, v34, v172 row_shr:1 row_mask:0xf bank_mask:0xf
	v_fmac_f32_dpp v139, v35, v173 row_shr:1 row_mask:0xf bank_mask:0xf
	v_fmac_f32_dpp v132, v60, v154 row_shl:15 row_mask:0xf bank_mask:0xf
	v_fmac_f32_dpp v133, v61, v155 row_shl:15 row_mask:0xf bank_mask:0xf
	v_fmac_f32_dpp v134, v62, v156 row_shl:15 row_mask:0xf bank_mask:0xf
	v_fmac_f32_dpp v135, v63, v157 row_shl:15 row_mask:0xf bank_mask:0xf
	v_fmac_f32_dpp v136, v48, v170 row_shl:15 row_mask:0xf bank_mask:0xf
	v_fmac_f32_dpp v137, v49, v171 row_shl:15 row_mask:0xf bank_mask:0xf
	v_fmac_f32_dpp v138, v50, v172 row_shl:15 row_mask:0xf bank_mask:0xf
	v_fmac_f32_dpp v139, v51, v173 row_shl:15 row_mask:0xf bank_mask:0xf
	v_fmac_f32_dpp v132, v52, v150 row_shr:2 row_mask:0xf bank_mask:0xf
	v_fmac_f32_dpp v133, v53, v151 row_shr:2 row_mask:0xf bank_mask:0xf
	v_fmac_f32_dpp v134, v54, v152 row_shr:2 row_mask:0xf bank_mask:0xf
	v_fmac_f32_dpp v135, v55, v153 row_shr:2 row_mask:0xf bank_mask:0xf
	v_fmac_f32_dpp v136, v32, v166 row_shr:2 row_mask:0xf bank_mask:0xf
	v_fmac_f32_dpp v137, v33, v167 row_shr:2 row_mask:0xf bank_mask:0xf
	v_fmac_f32_dpp v138, v34, v168 row_shr:2 row_mask:0xf bank_mask:0xf
	v_fmac_f32_dpp v139, v35, v169 row_shr:2 row_mask:0xf bank_mask:0xf
	v_fmac_f32_dpp v132, v60, v150 row_shl:14 row_mask:0xf bank_mask:0xf
	v_fmac_f32_dpp v133, v61, v151 row_shl:14 row_mask:0xf bank_mask:0xf
	v_fmac_f32_dpp v134, v62, v152 row_shl:14 row_mask:0xf bank_mask:0xf
	v_fmac_f32_dpp v135, v63, v153 row_shl:14 row_mask:0xf bank_mask:0xf
	v_fmac_f32_dpp v136, v48, v166 row_shl:14 row_mask:0xf bank_mask:0xf
	v_fmac_f32_dpp v137, v49, v167 row_shl:14 row_mask:0xf bank_mask:0xf
	v_fmac_f32_dpp v138, v50, v168 row_shl:14 row_mask:0xf bank_mask:0xf
	v_fmac_f32_dpp v139, v51, v169 row_shl:14 row_mask:0xf bank_mask:0xf
	v_pk_mul_f32 v[140:141], v[132:133], v[132:133]
	v_pk_mul_f32 v[142:143], v[134:135], v[134:135]
	v_pk_fma_f32 v[140:141], v[140:141], s[98:99], v[244:245]
	v_pk_fma_f32 v[142:143], v[142:143], s[98:99], v[244:245]
	v_pk_mul_f32 v[140:141], v[132:133], v[140:141]
	v_pk_mul_f32 v[142:143], v[134:135], v[142:143]
	v_exp_f32_e32 v140, v140
	v_exp_f32_e32 v141, v141
	v_exp_f32_e32 v142, v142
	v_exp_f32_e32 v143, v143
	v_pk_add_f32 v[140:141], v[140:141], s[100:101]
	v_pk_add_f32 v[142:143], v[142:143], s[100:101]
	v_rcp_f32_e32 v140, v140
	v_rcp_f32_e32 v141, v141
	v_rcp_f32_e32 v142, v142
	v_rcp_f32_e32 v143, v143
	v_pk_mul_f32 v[140:141], v[132:133], v[140:141]
	v_pk_mul_f32 v[142:143], v[134:135], v[142:143]
	v_pk_mul_f32 v[140:141], v[140:141], v[136:137]
	v_pk_mul_f32 v[142:143], v[142:143], v[138:139]
	v_cvt_pk_bf16_f32 v250, v140, v141
	v_cvt_pk_bf16_f32 v251, v142, v143
	v_pk_fma_f32 v[132:133], v[44:45], v[190:191], v[178:179]
	v_pk_fma_f32 v[136:137], v[24:25], v[206:207], v[194:195]
	v_pk_fma_f32 v[134:135], v[46:47], v[192:193], v[180:181]
	v_pk_fma_f32 v[138:139], v[26:27], v[208:209], v[196:197]
	v_fmac_f32_dpp v132, v44, v186 row_shr:1 row_mask:0xf bank_mask:0xf
	v_fmac_f32_dpp v133, v45, v187 row_shr:1 row_mask:0xf bank_mask:0xf
	v_fmac_f32_dpp v134, v46, v188 row_shr:1 row_mask:0xf bank_mask:0xf
	v_fmac_f32_dpp v135, v47, v189 row_shr:1 row_mask:0xf bank_mask:0xf
	v_fmac_f32_dpp v136, v24, v202 row_shr:1 row_mask:0xf bank_mask:0xf
; __device__ __forceinline__ unsigned pk2(float lo, float hi) { unsigned r; asm("v_cvt_pk_bf16_f32 %0, %1, %2" : "=v"(r) : "v"(lo), "v"(hi)); return r; }
; __device__ __forceinline__ float gelu_tanh(float x) { const float y = 1.5957691216f * (x + 0.044715f * x * x * x); return x * __builtin_amdgcn_rcpf(1.0f + __expf(-y)); }
; __device__ __forceinline__ float dpp_shr1(float old, float src) { return __int_as_float(__builtin_amdgcn_update_dpp(__float_as_int(old), __float_as_int(src), 0x111, 0xf, 0xf, false)); }
; __device__ __forceinline__ float dpp_shr2(float old, float src) { return __int_as_float(__builtin_amdgcn_update_dpp(__float_as_int(old), __float_as_int(src), 0x112, 0xf, 0xf, false)); }
; __device__ __forceinline__ float dpp_ror1(float src) { return __int_as_float(__builtin_amdgcn_update_dpp(0, __float_as_int(src), 0x121, 0xf, 0xf, false)); }
; __device__ __forceinline__ float dpp_ror2(float src) { return __int_as_float(__builtin_amdgcn_update_dpp(0, __float_as_int(src), 0x122, 0xf, 0xf, false)); }
;     __device__ __forceinline__ void operator()(const f32x4 (&acc)[2][2][4][2], const Unit& u, int wr, int wc, int fr, int fq) const {
;     ...
;                     for (int j = 0; j < 4; ++j) {
;                         const float g1 = dpp_shr1(dpp_ror1(gp[j]), g0[j]), g2 = dpp_shr2(dpp_ror2(gp[j]), g0[j]);
;                         const float v1 = dpp_shr1(dpp_ror1(vp[j]), v0[j]), v2 = dpp_shr2(dpp_ror2(vp[j]), v0[j]);
;                         const float cg_ = bg[j] + g2 * wg0[j] + g1 * wg1[j] + g0[j] * wg2[j];
;                         const float cv_ = bv[j] + v2 * wv0[j] + v1 * wv1[j] + v0[j] * wv2[j];
;                         f[j] = gelu_tanh(cg_) * cv_; }
;                     u32x2 w; w.x = pk2(f[0], f[1]); w.y = pk2(f[2], f[3]);
;                     if (n == 0) res0[ai * 4 + m] = w;
;                     else if (m > 0 || fr >= 2) { u32x4 w4; w4.x = res0[ai * 4 + m].x; w4.y = res0[ai * 4 + m].y; w4.z = w.x; w4.w = w.y; *(u32x4*)(F + (size_t)row * DFF + j0) = w4; }
	v_fmac_f32_dpp v137, v25, v203 row_shr:1 row_mask:0xf bank_mask:0xf
	v_fmac_f32_dpp v138, v26, v204 row_shr:1 row_mask:0xf bank_mask:0xf
	v_fmac_f32_dpp v139, v27, v205 row_shr:1 row_mask:0xf bank_mask:0xf
	v_fmac_f32_dpp v132, v56, v186 row_shl:15 row_mask:0xf bank_mask:0xf
	v_fmac_f32_dpp v133, v57, v187 row_shl:15 row_mask:0xf bank_mask:0xf
	v_fmac_f32_dpp v134, v58, v188 row_shl:15 row_mask:0xf bank_mask:0xf
	v_fmac_f32_dpp v135, v59, v189 row_shl:15 row_mask:0xf bank_mask:0xf
	v_fmac_f32_dpp v136, v40, v202 row_shl:15 row_mask:0xf bank_mask:0xf
	v_fmac_f32_dpp v137, v41, v203 row_shl:15 row_mask:0xf bank_mask:0xf
	v_fmac_f32_dpp v138, v42, v204 row_shl:15 row_mask:0xf bank_mask:0xf
	v_fmac_f32_dpp v139, v43, v205 row_shl:15 row_mask:0xf bank_mask:0xf
	v_fmac_f32_dpp v132, v44, v182 row_shr:2 row_mask:0xf bank_mask:0xf
	v_fmac_f32_dpp v133, v45, v183 row_shr:2 row_mask:0xf bank_mask:0xf
	v_fmac_f32_dpp v134, v46, v184 row_shr:2 row_mask:0xf bank_mask:0xf
	v_fmac_f32_dpp v135, v47, v185 row_shr:2 row_mask:0xf bank_mask:0xf
	v_fmac_f32_dpp v136, v24, v198 row_shr:2 row_mask:0xf bank_mask:0xf
	v_fmac_f32_dpp v137, v25, v199 row_shr:2 row_mask:0xf bank_mask:0xf
	v_fmac_f32_dpp v138, v26, v200 row_shr:2 row_mask:0xf bank_mask:0xf
	v_fmac_f32_dpp v139, v27, v201 row_shr:2 row_mask:0xf bank_mask:0xf
	v_fmac_f32_dpp v132, v56, v182 row_shl:14 row_mask:0xf bank_mask:0xf
	v_fmac_f32_dpp v133, v57, v183 row_shl:14 row_mask:0xf bank_mask:0xf
	v_fmac_f32_dpp v134, v58, v184 row_shl:14 row_mask:0xf bank_mask:0xf
	v_fmac_f32_dpp v135, v59, v185 row_shl:14 row_mask:0xf bank_mask:0xf
	v_fmac_f32_dpp v136, v40, v198 row_shl:14 row_mask:0xf bank_mask:0xf
	v_fmac_f32_dpp v137, v41, v199 row_shl:14 row_mask:0xf bank_mask:0xf
	v_fmac_f32_dpp v138, v42, v200 row_shl:14 row_mask:0xf bank_mask:0xf
	v_fmac_f32_dpp v139, v43, v201 row_shl:14 row_mask:0xf bank_mask:0xf
	v_pk_mul_f32 v[140:141], v[132:133], v[132:133]
	v_pk_mul_f32 v[142:143], v[134:135], v[134:135]
	v_pk_fma_f32 v[140:141], v[140:141], s[98:99], v[244:245]
	v_pk_fma_f32 v[142:143], v[142:143], s[98:99], v[244:245]
	v_pk_mul_f32 v[140:141], v[132:133], v[140:141]
	v_pk_mul_f32 v[142:143], v[134:135], v[142:143]
	v_exp_f32_e32 v140, v140
	v_exp_f32_e32 v141, v141
	v_exp_f32_e32 v142, v142
	v_exp_f32_e32 v143, v143
	v_pk_add_f32 v[140:141], v[140:141], s[100:101]
	v_pk_add_f32 v[142:143], v[142:143], s[100:101]
	v_rcp_f32_e32 v140, v140
	v_rcp_f32_e32 v141, v141
	v_rcp_f32_e32 v142, v142
	v_rcp_f32_e32 v143, v143
	v_pk_mul_f32 v[140:141], v[132:133], v[140:141]
	v_pk_mul_f32 v[142:143], v[134:135], v[142:143]
	v_pk_mul_f32 v[140:141], v[140:141], v[136:137]
	v_pk_mul_f32 v[142:143], v[142:143], v[138:139]
	v_cvt_pk_bf16_f32 v252, v140, v141
	v_cvt_pk_bf16_f32 v253, v142, v143
	v_add_u32_e32 v144, 0x90, v248
	v_mad_u64_u32 v[144:145], vcc, v144, s4, v[242:243]
	global_store_dwordx4 v[144:145], v[250:253], off nt
	v_pk_fma_f32 v[132:133], v[36:37], v[158:159], v[146:147]
	v_pk_fma_f32 v[136:137], v[16:17], v[174:175], v[162:163]
	v_pk_fma_f32 v[134:135], v[38:39], v[160:161], v[148:149]
	v_pk_fma_f32 v[138:139], v[18:19], v[176:177], v[164:165]
	v_fmac_f32_dpp v132, v36, v154 row_shr:1 row_mask:0xf bank_mask:0xf
	v_fmac_f32_dpp v133, v37, v155 row_shr:1 row_mask:0xf bank_mask:0xf
	v_fmac_f32_dpp v134, v38, v156 row_shr:1 row_mask:0xf bank_mask:0xf
	v_fmac_f32_dpp v135, v39, v157 row_shr:1 row_mask:0xf bank_mask:0xf
	v_fmac_f32_dpp v136, v16, v170 row_shr:1 row_mask:0xf bank_mask:0xf
	v_fmac_f32_dpp v137, v17, v171 row_shr:1 row_mask:0xf bank_mask:0xf
	v_fmac_f32_dpp v138, v18, v172 row_shr:1 row_mask:0xf bank_mask:0xf
	v_fmac_f32_dpp v139, v19, v173 row_shr:1 row_mask:0xf bank_mask:0xf
	v_fmac_f32_dpp v132, v52, v154 row_shl:15 row_mask:0xf bank_mask:0xf
	v_fmac_f32_dpp v133, v53, v155 row_shl:15 row_mask:0xf bank_mask:0xf
	v_fmac_f32_dpp v134, v54, v156 row_shl:15 row_mask:0xf bank_mask:0xf
	v_fmac_f32_dpp v135, v55, v157 row_shl:15 row_mask:0xf bank_mask:0xf
	v_fmac_f32_dpp v136, v32, v170 row_shl:15 row_mask:0xf bank_mask:0xf
	v_fmac_f32_dpp v137, v33, v171 row_shl:15 row_mask:0xf bank_mask:0xf
	v_fmac_f32_dpp v138, v34, v172 row_shl:15 row_mask:0xf bank_mask:0xf
	v_fmac_f32_dpp v139, v35, v173 row_shl:15 row_mask:0xf bank_mask:0xf
	v_fmac_f32_dpp v132, v36, v150 row_shr:2 row_mask:0xf bank_mask:0xf
	v_fmac_f32_dpp v133, v37, v151 row_shr:2 row_mask:0xf bank_mask:0xf
	v_fmac_f32_dpp v134, v38, v152 row_shr:2 row_mask:0xf bank_mask:0xf
	v_fmac_f32_dpp v135, v39, v153 row_shr:2 row_mask:0xf bank_mask:0xf
	v_fmac_f32_dpp v136, v16, v166 row_shr:2 row_mask:0xf bank_mask:0xf
	v_fmac_f32_dpp v137, v17, v167 row_shr:2 row_mask:0xf bank_mask:0xf
	v_fmac_f32_dpp v138, v18, v168 row_shr:2 row_mask:0xf bank_mask:0xf
	v_fmac_f32_dpp v139, v19, v169 row_shr:2 row_mask:0xf bank_mask:0xf
	v_fmac_f32_dpp v132, v52, v150 row_shl:14 row_mask:0xf bank_mask:0xf
	v_fmac_f32_dpp v133, v53, v151 row_shl:14 row_mask:0xf bank_mask:0xf
	v_fmac_f32_dpp v134, v54, v152 row_shl:14 row_mask:0xf bank_mask:0xf
	v_fmac_f32_dpp v135, v55, v153 row_shl:14 row_mask:0xf bank_mask:0xf
	v_fmac_f32_dpp v136, v32, v166 row_shl:14 row_mask:0xf bank_mask:0xf
	v_fmac_f32_dpp v137, v33, v167 row_shl:14 row_mask:0xf bank_mask:0xf
	v_fmac_f32_dpp v138, v34, v168 row_shl:14 row_mask:0xf bank_mask:0xf
	v_fmac_f32_dpp v139, v35, v169 row_shl:14 row_mask:0xf bank_mask:0xf
	v_pk_mul_f32 v[140:141], v[132:133], v[132:133]
	v_pk_mul_f32 v[142:143], v[134:135], v[134:135]
	v_pk_fma_f32 v[140:141], v[140:141], s[98:99], v[244:245]
	v_pk_fma_f32 v[142:143], v[142:143], s[98:99], v[244:245]
	v_pk_mul_f32 v[140:141], v[132:133], v[140:141]
; __device__ __forceinline__ unsigned pk2(float lo, float hi) { unsigned r; asm("v_cvt_pk_bf16_f32 %0, %1, %2" : "=v"(r) : "v"(lo), "v"(hi)); return r; }
; __device__ __forceinline__ float gelu_tanh(float x) { const float y = 1.5957691216f * (x + 0.044715f * x * x * x); return x * __builtin_amdgcn_rcpf(1.0f + __expf(-y)); }
; __device__ __forceinline__ float dpp_shr1(float old, float src) { return __int_as_float(__builtin_amdgcn_update_dpp(__float_as_int(old), __float_as_int(src), 0x111, 0xf, 0xf, false)); }
; __device__ __forceinline__ float dpp_shr2(float old, float src) { return __int_as_float(__builtin_amdgcn_update_dpp(__float_as_int(old), __float_as_int(src), 0x112, 0xf, 0xf, false)); }
; __device__ __forceinline__ float dpp_ror1(float src) { return __int_as_float(__builtin_amdgcn_update_dpp(0, __float_as_int(src), 0x121, 0xf, 0xf, false)); }
; __device__ __forceinline__ float dpp_ror2(float src) { return __int_as_float(__builtin_amdgcn_update_dpp(0, __float_as_int(src), 0x122, 0xf, 0xf, false)); }
;     __device__ __forceinline__ void operator()(const f32x4 (&acc)[2][2][4][2], const Unit& u, int wr, int wc, int fr, int fq) const {
;     ...
;                     for (int j = 0; j < 4; ++j) {
;                         const float g1 = dpp_shr1(dpp_ror1(gp[j]), g0[j]), g2 = dpp_shr2(dpp_ror2(gp[j]), g0[j]);
;                         const float v1 = dpp_shr1(dpp_ror1(vp[j]), v0[j]), v2 = dpp_shr2(dpp_ror2(vp[j]), v0[j]);
;                         const float cg_ = bg[j] + g2 * wg0[j] + g1 * wg1[j] + g0[j] * wg2[j];
;                         const float cv_ = bv[j] + v2 * wv0[j] + v1 * wv1[j] + v0[j] * wv2[j];
;                         f[j] = gelu_tanh(cg_) * cv_; }
;                     u32x2 w; w.x = pk2(f[0], f[1]); w.y = pk2(f[2], f[3]);
;                     if (n == 0) res0[ai * 4 + m] = w;
;                     else if (m > 0 || fr >= 2) { u32x4 w4; w4.x = res0[ai * 4 + m].x; w4.y = res0[ai * 4 + m].y; w4.z = w.x; w4.w = w.y; *(u32x4*)(F + (size_t)row * DFF + j0) = w4; }
	v_pk_mul_f32 v[142:143], v[134:135], v[142:143]
	v_exp_f32_e32 v140, v140
	v_exp_f32_e32 v141, v141
	v_exp_f32_e32 v142, v142
	v_exp_f32_e32 v143, v143
	v_pk_add_f32 v[140:141], v[140:141], s[100:101]
	v_pk_add_f32 v[142:143], v[142:143], s[100:101]
	v_rcp_f32_e32 v140, v140
	v_rcp_f32_e32 v141, v141
	v_rcp_f32_e32 v142, v142
	v_rcp_f32_e32 v143, v143
	v_pk_mul_f32 v[140:141], v[132:133], v[140:141]
	v_pk_mul_f32 v[142:143], v[134:135], v[142:143]
	v_pk_mul_f32 v[140:141], v[140:141], v[136:137]
	v_pk_mul_f32 v[142:143], v[142:143], v[138:139]
	v_cvt_pk_bf16_f32 v128, v140, v141
	v_cvt_pk_bf16_f32 v129, v142, v143
	v_pk_fma_f32 v[132:133], v[28:29], v[190:191], v[178:179]
	v_pk_fma_f32 v[136:137], v[8:9], v[206:207], v[194:195]
	v_pk_fma_f32 v[134:135], v[30:31], v[192:193], v[180:181]
	v_pk_fma_f32 v[138:139], v[10:11], v[208:209], v[196:197]
	v_fmac_f32_dpp v132, v28, v186 row_shr:1 row_mask:0xf bank_mask:0xf
	v_fmac_f32_dpp v133, v29, v187 row_shr:1 row_mask:0xf bank_mask:0xf
	v_fmac_f32_dpp v134, v30, v188 row_shr:1 row_mask:0xf bank_mask:0xf
	v_fmac_f32_dpp v135, v31, v189 row_shr:1 row_mask:0xf bank_mask:0xf
	v_fmac_f32_dpp v136, v8, v202 row_shr:1 row_mask:0xf bank_mask:0xf
	v_fmac_f32_dpp v137, v9, v203 row_shr:1 row_mask:0xf bank_mask:0xf
	v_fmac_f32_dpp v138, v10, v204 row_shr:1 row_mask:0xf bank_mask:0xf
	v_fmac_f32_dpp v139, v11, v205 row_shr:1 row_mask:0xf bank_mask:0xf
	v_fmac_f32_dpp v132, v44, v186 row_shl:15 row_mask:0xf bank_mask:0xf
	v_fmac_f32_dpp v133, v45, v187 row_shl:15 row_mask:0xf bank_mask:0xf
	v_fmac_f32_dpp v134, v46, v188 row_shl:15 row_mask:0xf bank_mask:0xf
	v_fmac_f32_dpp v135, v47, v189 row_shl:15 row_mask:0xf bank_mask:0xf
	v_fmac_f32_dpp v136, v24, v202 row_shl:15 row_mask:0xf bank_mask:0xf
	v_fmac_f32_dpp v137, v25, v203 row_shl:15 row_mask:0xf bank_mask:0xf
	v_fmac_f32_dpp v138, v26, v204 row_shl:15 row_mask:0xf bank_mask:0xf
	v_fmac_f32_dpp v139, v27, v205 row_shl:15 row_mask:0xf bank_mask:0xf
	v_fmac_f32_dpp v132, v28, v182 row_shr:2 row_mask:0xf bank_mask:0xf
	v_fmac_f32_dpp v133, v29, v183 row_shr:2 row_mask:0xf bank_mask:0xf
	v_fmac_f32_dpp v134, v30, v184 row_shr:2 row_mask:0xf bank_mask:0xf
	v_fmac_f32_dpp v135, v31, v185 row_shr:2 row_mask:0xf bank_mask:0xf
	v_fmac_f32_dpp v136, v8, v198 row_shr:2 row_mask:0xf bank_mask:0xf
	v_fmac_f32_dpp v137, v9, v199 row_shr:2 row_mask:0xf bank_mask:0xf
	v_fmac_f32_dpp v138, v10, v200 row_shr:2 row_mask:0xf bank_mask:0xf
	v_fmac_f32_dpp v139, v11, v201 row_shr:2 row_mask:0xf bank_mask:0xf
	v_fmac_f32_dpp v132, v44, v182 row_shl:14 row_mask:0xf bank_mask:0xf
	v_fmac_f32_dpp v133, v45, v183 row_shl:14 row_mask:0xf bank_mask:0xf
	v_fmac_f32_dpp v134, v46, v184 row_shl:14 row_mask:0xf bank_mask:0xf
	v_fmac_f32_dpp v135, v47, v185 row_shl:14 row_mask:0xf bank_mask:0xf
	v_fmac_f32_dpp v136, v24, v198 row_shl:14 row_mask:0xf bank_mask:0xf
	v_fmac_f32_dpp v137, v25, v199 row_shl:14 row_mask:0xf bank_mask:0xf
	v_fmac_f32_dpp v138, v26, v200 row_shl:14 row_mask:0xf bank_mask:0xf
	v_fmac_f32_dpp v139, v27, v201 row_shl:14 row_mask:0xf bank_mask:0xf
	v_pk_mul_f32 v[140:141], v[132:133], v[132:133]
	v_pk_mul_f32 v[142:143], v[134:135], v[134:135]
	v_pk_fma_f32 v[140:141], v[140:141], s[98:99], v[244:245]
	v_pk_fma_f32 v[142:143], v[142:143], s[98:99], v[244:245]
	v_pk_mul_f32 v[140:141], v[132:133], v[140:141]
	v_pk_mul_f32 v[142:143], v[134:135], v[142:143]
	v_exp_f32_e32 v140, v140
	v_exp_f32_e32 v141, v141
	v_exp_f32_e32 v142, v142
	v_exp_f32_e32 v143, v143
	v_pk_add_f32 v[140:141], v[140:141], s[100:101]
	v_pk_add_f32 v[142:143], v[142:143], s[100:101]
	v_rcp_f32_e32 v140, v140
	v_rcp_f32_e32 v141, v141
	v_rcp_f32_e32 v142, v142
	v_rcp_f32_e32 v143, v143
	v_pk_mul_f32 v[140:141], v[132:133], v[140:141]
	v_pk_mul_f32 v[142:143], v[134:135], v[142:143]
	v_pk_mul_f32 v[140:141], v[140:141], v[136:137]
	v_pk_mul_f32 v[142:143], v[142:143], v[138:139]
	v_cvt_pk_bf16_f32 v130, v140, v141
	v_cvt_pk_bf16_f32 v131, v142, v143
	v_add_u32_e32 v144, 0xa0, v248
	v_mad_u64_u32 v[144:145], vcc, v144, s4, v[242:243]
	global_store_dwordx4 v[144:145], v[128:131], off nt
	v_pk_fma_f32 v[132:133], v[20:21], v[158:159], v[146:147]
	v_pk_fma_f32 v[136:137], v[4:5], v[174:175], v[162:163]
	v_pk_fma_f32 v[134:135], v[22:23], v[160:161], v[148:149]
	v_pk_fma_f32 v[138:139], v[6:7], v[176:177], v[164:165]
	v_fmac_f32_dpp v132, v20, v154 row_shr:1 row_mask:0xf bank_mask:0xf
	v_fmac_f32_dpp v133, v21, v155 row_shr:1 row_mask:0xf bank_mask:0xf
	v_fmac_f32_dpp v134, v22, v156 row_shr:1 row_mask:0xf bank_mask:0xf
	v_fmac_f32_dpp v135, v23, v157 row_shr:1 row_mask:0xf bank_mask:0xf
	v_fmac_f32_dpp v136, v4, v170 row_shr:1 row_mask:0xf bank_mask:0xf
	v_fmac_f32_dpp v137, v5, v171 row_shr:1 row_mask:0xf bank_mask:0xf
	v_fmac_f32_dpp v138, v6, v172 row_shr:1 row_mask:0xf bank_mask:0xf
	v_fmac_f32_dpp v139, v7, v173 row_shr:1 row_mask:0xf bank_mask:0xf
	v_fmac_f32_dpp v132, v36, v154 row_shl:15 row_mask:0xf bank_mask:0xf
	v_fmac_f32_dpp v133, v37, v155 row_shl:15 row_mask:0xf bank_mask:0xf
	v_fmac_f32_dpp v134, v38, v156 row_shl:15 row_mask:0xf bank_mask:0xf
	v_fmac_f32_dpp v135, v39, v157 row_shl:15 row_mask:0xf bank_mask:0xf
	v_fmac_f32_dpp v136, v16, v170 row_shl:15 row_mask:0xf bank_mask:0xf
	v_fmac_f32_dpp v137, v17, v171 row_shl:15 row_mask:0xf bank_mask:0xf
	v_fmac_f32_dpp v138, v18, v172 row_shl:15 row_mask:0xf bank_mask:0xf
	v_fmac_f32_dpp v139, v19, v173 row_shl:15 row_mask:0xf bank_mask:0xf
	v_fmac_f32_dpp v132, v20, v150 row_shr:2 row_mask:0xf bank_mask:0xf
	v_fmac_f32_dpp v133, v21, v151 row_shr:2 row_mask:0xf bank_mask:0xf
	v_fmac_f32_dpp v134, v22, v152 row_shr:2 row_mask:0xf bank_mask:0xf
; __device__ __forceinline__ unsigned pk2(float lo, float hi) { unsigned r; asm("v_cvt_pk_bf16_f32 %0, %1, %2" : "=v"(r) : "v"(lo), "v"(hi)); return r; }
; __device__ __forceinline__ float gelu_tanh(float x) { const float y = 1.5957691216f * (x + 0.044715f * x * x * x); return x * __builtin_amdgcn_rcpf(1.0f + __expf(-y)); }
; __device__ __forceinline__ float dpp_shr1(float old, float src) { return __int_as_float(__builtin_amdgcn_update_dpp(__float_as_int(old), __float_as_int(src), 0x111, 0xf, 0xf, false)); }
; __device__ __forceinline__ float dpp_shr2(float old, float src) { return __int_as_float(__builtin_amdgcn_update_dpp(__float_as_int(old), __float_as_int(src), 0x112, 0xf, 0xf, false)); }
;     __device__ __forceinline__ void operator()(const f32x4 (&acc)[2][2][4][2], const Unit& u, int wr, int wc, int fr, int fq) const {
;     ...
;                     for (int j = 0; j < 4; ++j) {
;                         const float g1 = dpp_shr1(dpp_ror1(gp[j]), g0[j]), g2 = dpp_shr2(dpp_ror2(gp[j]), g0[j]);
;                         const float v1 = dpp_shr1(dpp_ror1(vp[j]), v0[j]), v2 = dpp_shr2(dpp_ror2(vp[j]), v0[j]);
;                         const float cg_ = bg[j] + g2 * wg0[j] + g1 * wg1[j] + g0[j] * wg2[j];
;                         const float cv_ = bv[j] + v2 * wv0[j] + v1 * wv1[j] + v0[j] * wv2[j];
;                         f[j] = gelu_tanh(cg_) * cv_; }
;                     u32x2 w; w.x = pk2(f[0], f[1]); w.y = pk2(f[2], f[3]);
;                     if (n == 0) res0[ai * 4 + m] = w;
;                     else if (m > 0 || fr >= 2) { u32x4 w4; w4.x = res0[ai * 4 + m].x; w4.y = res0[ai * 4 + m].y; w4.z = w.x; w4.w = w.y; *(u32x4*)(F + (size_t)row * DFF + j0) = w4; }
;                     if (n == 1 && ((m == 0 && fr < 2) || (m == 3 && fr >= 14))) { const int slot = m == 0 ? fr : fr - 12;
;                         const f32x4 ga = acc[ai][0][m][0], va = acc[ai][1][m][0];
;                         bf16_t* bp = UPB + ((size_t)(row >> 6) * 4 + slot) * (2 * DFF) + col0;
;                         u32x4 wg_, wv_; wg_.x = pk2(ga[0], ga[1]); wg_.y = pk2(ga[2], ga[3]); wg_.z = pk2(g0[0], g0[1]); wg_.w = pk2(g0[2], g0[3]);
;                         wv_.x = pk2(va[0], va[1]); wv_.y = pk2(va[2], va[3]); wv_.z = pk2(v0[0], v0[1]); wv_.w = pk2(v0[2], v0[3]);
;                         *(u32x4*)bp = wg_; *(u32x4*)(bp + HALF) = wv_; } }
	v_fmac_f32_dpp v135, v23, v153 row_shr:2 row_mask:0xf bank_mask:0xf
	v_fmac_f32_dpp v136, v4, v166 row_shr:2 row_mask:0xf bank_mask:0xf
	v_fmac_f32_dpp v137, v5, v167 row_shr:2 row_mask:0xf bank_mask:0xf
	v_fmac_f32_dpp v138, v6, v168 row_shr:2 row_mask:0xf bank_mask:0xf
	v_fmac_f32_dpp v139, v7, v169 row_shr:2 row_mask:0xf bank_mask:0xf
	v_fmac_f32_dpp v132, v36, v150 row_shl:14 row_mask:0xf bank_mask:0xf
	v_fmac_f32_dpp v133, v37, v151 row_shl:14 row_mask:0xf bank_mask:0xf
	v_fmac_f32_dpp v134, v38, v152 row_shl:14 row_mask:0xf bank_mask:0xf
	v_fmac_f32_dpp v135, v39, v153 row_shl:14 row_mask:0xf bank_mask:0xf
	v_fmac_f32_dpp v136, v16, v166 row_shl:14 row_mask:0xf bank_mask:0xf
	v_fmac_f32_dpp v137, v17, v167 row_shl:14 row_mask:0xf bank_mask:0xf
	v_fmac_f32_dpp v138, v18, v168 row_shl:14 row_mask:0xf bank_mask:0xf
	v_fmac_f32_dpp v139, v19, v169 row_shl:14 row_mask:0xf bank_mask:0xf
	v_pk_mul_f32 v[140:141], v[132:133], v[132:133]
	v_pk_mul_f32 v[142:143], v[134:135], v[134:135]
	v_pk_fma_f32 v[140:141], v[140:141], s[98:99], v[244:245]
	v_pk_fma_f32 v[142:143], v[142:143], s[98:99], v[244:245]
	v_pk_mul_f32 v[140:141], v[132:133], v[140:141]
	v_pk_mul_f32 v[142:143], v[134:135], v[142:143]
	v_exp_f32_e32 v140, v140
	v_exp_f32_e32 v141, v141
	v_exp_f32_e32 v142, v142
	v_exp_f32_e32 v143, v143
	v_pk_add_f32 v[140:141], v[140:141], s[100:101]
	v_pk_add_f32 v[142:143], v[142:143], s[100:101]
	v_rcp_f32_e32 v140, v140
	v_rcp_f32_e32 v141, v141
	v_rcp_f32_e32 v142, v142
	v_rcp_f32_e32 v143, v143
	v_pk_mul_f32 v[140:141], v[132:133], v[140:141]
	v_pk_mul_f32 v[142:143], v[134:135], v[142:143]
	v_pk_mul_f32 v[140:141], v[140:141], v[136:137]
	v_pk_mul_f32 v[142:143], v[142:143], v[138:139]
	v_cvt_pk_bf16_f32 v250, v140, v141
	v_cvt_pk_bf16_f32 v251, v142, v143
	v_pk_fma_f32 v[132:133], v[12:13], v[190:191], v[178:179]
	v_pk_fma_f32 v[136:137], v[0:1], v[206:207], v[194:195]
	v_pk_fma_f32 v[134:135], v[14:15], v[192:193], v[180:181]
	v_pk_fma_f32 v[138:139], v[2:3], v[208:209], v[196:197]
	v_fmac_f32_dpp v132, v12, v186 row_shr:1 row_mask:0xf bank_mask:0xf
	v_fmac_f32_dpp v133, v13, v187 row_shr:1 row_mask:0xf bank_mask:0xf
	v_fmac_f32_dpp v134, v14, v188 row_shr:1 row_mask:0xf bank_mask:0xf
	v_fmac_f32_dpp v135, v15, v189 row_shr:1 row_mask:0xf bank_mask:0xf
	v_fmac_f32_dpp v136, v0, v202 row_shr:1 row_mask:0xf bank_mask:0xf
	v_fmac_f32_dpp v137, v1, v203 row_shr:1 row_mask:0xf bank_mask:0xf
	v_fmac_f32_dpp v138, v2, v204 row_shr:1 row_mask:0xf bank_mask:0xf
	v_fmac_f32_dpp v139, v3, v205 row_shr:1 row_mask:0xf bank_mask:0xf
	v_fmac_f32_dpp v132, v28, v186 row_shl:15 row_mask:0xf bank_mask:0xf
	v_fmac_f32_dpp v133, v29, v187 row_shl:15 row_mask:0xf bank_mask:0xf
	v_fmac_f32_dpp v134, v30, v188 row_shl:15 row_mask:0xf bank_mask:0xf
	v_fmac_f32_dpp v135, v31, v189 row_shl:15 row_mask:0xf bank_mask:0xf
	v_fmac_f32_dpp v136, v8, v202 row_shl:15 row_mask:0xf bank_mask:0xf
	v_fmac_f32_dpp v137, v9, v203 row_shl:15 row_mask:0xf bank_mask:0xf
	v_fmac_f32_dpp v138, v10, v204 row_shl:15 row_mask:0xf bank_mask:0xf
	v_fmac_f32_dpp v139, v11, v205 row_shl:15 row_mask:0xf bank_mask:0xf
	v_fmac_f32_dpp v132, v12, v182 row_shr:2 row_mask:0xf bank_mask:0xf
	v_fmac_f32_dpp v133, v13, v183 row_shr:2 row_mask:0xf bank_mask:0xf
	v_fmac_f32_dpp v134, v14, v184 row_shr:2 row_mask:0xf bank_mask:0xf
	v_fmac_f32_dpp v135, v15, v185 row_shr:2 row_mask:0xf bank_mask:0xf
	v_fmac_f32_dpp v136, v0, v198 row_shr:2 row_mask:0xf bank_mask:0xf
	v_fmac_f32_dpp v137, v1, v199 row_shr:2 row_mask:0xf bank_mask:0xf
	v_fmac_f32_dpp v138, v2, v200 row_shr:2 row_mask:0xf bank_mask:0xf
	v_fmac_f32_dpp v139, v3, v201 row_shr:2 row_mask:0xf bank_mask:0xf
	v_fmac_f32_dpp v132, v28, v182 row_shl:14 row_mask:0xf bank_mask:0xf
	v_fmac_f32_dpp v133, v29, v183 row_shl:14 row_mask:0xf bank_mask:0xf
	v_fmac_f32_dpp v134, v30, v184 row_shl:14 row_mask:0xf bank_mask:0xf
	v_fmac_f32_dpp v135, v31, v185 row_shl:14 row_mask:0xf bank_mask:0xf
	v_fmac_f32_dpp v136, v8, v198 row_shl:14 row_mask:0xf bank_mask:0xf
	v_fmac_f32_dpp v137, v9, v199 row_shl:14 row_mask:0xf bank_mask:0xf
	v_fmac_f32_dpp v138, v10, v200 row_shl:14 row_mask:0xf bank_mask:0xf
	v_fmac_f32_dpp v139, v11, v201 row_shl:14 row_mask:0xf bank_mask:0xf
	v_pk_mul_f32 v[140:141], v[132:133], v[132:133]
	v_pk_mul_f32 v[142:143], v[134:135], v[134:135]
	v_pk_fma_f32 v[140:141], v[140:141], s[98:99], v[244:245]
	v_pk_fma_f32 v[142:143], v[142:143], s[98:99], v[244:245]
	v_pk_mul_f32 v[140:141], v[132:133], v[140:141]
	v_pk_mul_f32 v[142:143], v[134:135], v[142:143]
	v_exp_f32_e32 v140, v140
	v_exp_f32_e32 v141, v141
	v_exp_f32_e32 v142, v142
	v_exp_f32_e32 v143, v143
	v_pk_add_f32 v[140:141], v[140:141], s[100:101]
	v_pk_add_f32 v[142:143], v[142:143], s[100:101]
	v_rcp_f32_e32 v140, v140
	v_rcp_f32_e32 v141, v141
	v_rcp_f32_e32 v142, v142
	v_rcp_f32_e32 v143, v143
	v_pk_mul_f32 v[140:141], v[132:133], v[140:141]
	v_pk_mul_f32 v[142:143], v[134:135], v[142:143]
	v_pk_mul_f32 v[140:141], v[140:141], v[136:137]
	v_pk_mul_f32 v[142:143], v[142:143], v[138:139]
	v_cvt_pk_bf16_f32 v252, v140, v141
	v_cvt_pk_bf16_f32 v253, v142, v143
	v_add_u32_e32 v144, 0xb0, v248
	v_mad_u64_u32 v[144:145], vcc, v144, s4, v[242:243]
	global_store_dwordx4 v[144:145], v[250:253], off nt
	s_mov_b64 s[0:1], 0
	s_and_saveexec_b64 s[42:43], s[12:13]
	s_xor_b64 s[52:53], exec, s[42:43]
	s_cbranch_execz .LBB0_1214
	v_add_u32_e32 v144, s73, v234
	v_mov_b64_e32 v[132:133], s[80:81]
	v_mad_u64_u32 v[132:133], vcc, v144, s83, v[132:133]
	v_lshl_add_u64 v[132:133], v[240:241], 1, v[132:133]
	s_mov_b64 s[72:73], exec
	v_cvt_pk_bf16_f32 v134, v20, v21
	v_cvt_pk_bf16_f32 v135, v22, v23
	v_cvt_pk_bf16_f32 v136, v12, v13
	v_cvt_pk_bf16_f32 v137, v14, v15
	v_cvt_pk_bf16_f32 v128, v4, v5
	v_cvt_pk_bf16_f32 v129, v6, v7
	v_cvt_pk_bf16_f32 v130, v0, v1
	v_cvt_pk_bf16_f32 v131, v2, v3
	global_store_dwordx4 v[132:133], v[134:137], off

; #define PG8_STAGE(bufoff, gbase, voff) do { _Pragma("unroll") for (int _i = 0; _i < 2; ++_i) \
;         __builtin_amdgcn_global_load_lds((const unsigned*)((const char*)(gbase) + (voff)[_i]), (LAS unsigned*)(lds + (bufoff) + ldsw + _i * 8192), 16, 0, 0); } while (0)
; #define PG8_LDA(dst, b, h) do { _Pragma("unroll") for (int m = 0; m < 4; ++m) _Pragma("unroll") for (int k = 0; k < 2; ++k) dst[m][k] = *(const LAS bf16x8*)(lds + PG8_SA(b, h) + aoff + m * 2048 + k * 1024); } while (0)
; #define PG8_LDB(dst, b, h) do { _Pragma("unroll") for (int n = 0; n < 2; ++n) _Pragma("unroll") for (int k = 0; k < 2; ++k) dst[n][k] = *(const LAS bf16x8*)(lds + PG8_SB(b, h) + boff + n * 2048 + k * 1024); } while (0)
; #define PG8_MMA(ai, bj, At, Bt) do { __builtin_amdgcn_s_setprio(1); _Pragma("unroll") for (int m = 0; m < 4; ++m) _Pragma("unroll") for (int n = 0; n < 2; ++n) _Pragma("unroll") for (int k = 0; k < 2; ++k) \
;         acc[ai][bj][m][n] = __builtin_amdgcn_mfma_f32_16x16x32_bf16(Bt[n][k], At[m][k], acc[ai][bj][m][n], 0, 0, 0); __builtin_amdgcn_s_setprio(0); } while (0)
; #define PG8_BAR __builtin_amdgcn_s_barrier()
; template <class Epi, class S_t>
; __device__ __forceinline__ void gemm_phase(LAS unsigned char* lds, int lda, int ldb, const S_t& S, const Epi& E) {
;     ...
;             const char* a1 = cA + (size_t)(t + 1) * kstep;
;             const char* a2 = last ? nA : cA + (size_t)(t + 2) * kstep; const char* b2 = last ? nB : cB + (size_t)(t + 2) * kstep;
;             const char* a3 = a2 + kstep; const char* b3 = b2 + kstep;
;             PG8_LDB(B0, 0, 0); PG8_SCHED; PG8_LDA(At, 0, 0); PG8_STAGE(PG8_SA(1, 1), a1 + hstepA, voffA);
;             PG8_WAIT_L(8); PG8_BAR; PG8_WAIT_L(0); PG8_MMA(0, 0, At, B0); PG8_BAR; PG8_SCHED;
;             PG8_LDB(B1, 0, 1); PG8_STAGE(PG8_SB(0, 0), b2, voffB);
;             PG8_BAR; PG8_WAIT_L(0); PG8_MMA(0, 1, At, B1); PG8_BAR;
;             PG8_LDA(At, 0, 1); PG8_STAGE(PG8_SA(0, 0), a2, voffA);
;             PG8_BAR; PG8_WAIT_L(0); PG8_MMA(1, 0, At, B0); PG8_BAR; PG8_SCHED;
;             PG8_STAGE(PG8_SB(0, 1), b2 + hstepB, voffB);
;             PG8_WAIT_V(6); PG8_BAR; PG8_MMA(1, 1, At, B1); PG8_BAR;
;             PG8_LDB(B0, 1, 0); PG8_SCHED; PG8_LDA(At, 1, 0); PG8_STAGE(PG8_SA(0, 1), a2 + hstepA, voffA);
;             PG8_WAIT_L(8); PG8_BAR; PG8_WAIT_L(0); PG8_MMA(0, 0, At, B0); PG8_BAR; PG8_SCHED;
.LBB0_1383:
	ds_read_b128 v[150:153], v146
	ds_read_b128 v[154:157], v146 offset:1024
	ds_read_b128 v[158:161], v146 offset:2048
	ds_read_b128 v[162:165], v146 offset:3072
	s_add_i32 s71, s50, 2
	s_add_u32 s48, s46, 0x100
	s_addc_u32 s49, s47, 0
	s_cmp_eq_u32 s0, s50
	s_cselect_b32 s50, s40, s1
	s_cselect_b32 s53, s43, s49
	s_cselect_b32 s52, s42, s48
	s_cselect_b32 s51, s41, s70
	s_add_i32 m0, s20, 0xc000
	ds_read_b128 v[166:169], v147
	ds_read_b128 v[170:173], v147 offset:1024
	ds_read_b128 v[174:177], v147 offset:2048
	ds_read_b128 v[178:181], v147 offset:3072
	ds_read_b128 v[182:185], v147 offset:4096
	ds_read_b128 v[186:189], v147 offset:5120
	ds_read_b128 v[190:193], v147 offset:6144
	ds_read_b128 v[194:197], v147 offset:7168
	global_load_lds_dwordx4 v136, s[46:47]
	s_add_i32 m0, s20, 0xe000
	s_nop 0
	global_load_lds_dwordx4 v138, s[46:47]
	s_waitcnt lgkmcnt(8)
	s_barrier
	s_waitcnt lgkmcnt(0)
	s_setprio 1
	v_mfma_f32_16x16x32_bf16 v[124:127], v[150:153], v[166:169], v[124:127]
	v_mfma_f32_16x16x32_bf16 v[120:123], v[158:161], v[166:169], v[120:123]
	v_mfma_f32_16x16x32_bf16 v[112:115], v[150:153], v[174:177], v[112:115]
	v_mfma_f32_16x16x32_bf16 v[104:107], v[158:161], v[174:177], v[104:107]
	v_mfma_f32_16x16x32_bf16 v[96:99], v[150:153], v[182:185], v[96:99]
	v_mfma_f32_16x16x32_bf16 v[88:91], v[158:161], v[182:185], v[88:91]
	v_mfma_f32_16x16x32_bf16 v[80:83], v[150:153], v[190:193], v[80:83]
	v_mfma_f32_16x16x32_bf16 v[72:75], v[158:161], v[190:193], v[72:75]
	v_mfma_f32_16x16x32_bf16 v[124:127], v[154:157], v[170:173], v[124:127]
	v_mfma_f32_16x16x32_bf16 v[120:123], v[162:165], v[170:173], v[120:123]
	v_mfma_f32_16x16x32_bf16 v[112:115], v[154:157], v[178:181], v[112:115]
	v_mfma_f32_16x16x32_bf16 v[104:107], v[162:165], v[178:181], v[104:107]
	v_mfma_f32_16x16x32_bf16 v[96:99], v[154:157], v[186:189], v[96:99]
	v_mfma_f32_16x16x32_bf16 v[88:91], v[162:165], v[186:189], v[88:91]
	v_mfma_f32_16x16x32_bf16 v[80:83], v[154:157], v[194:197], v[80:83]
	v_mfma_f32_16x16x32_bf16 v[72:75], v[162:165], v[194:197], v[72:75]
	s_setprio 0
	s_barrier
	s_add_i32 s33, s88, s17
	s_add_u32 s98, s50, s4
	s_addc_u32 s99, s51, s5
	s_mov_b32 m0, s33
	ds_read_b128 v[198:201], v148
	ds_read_b128 v[202:205], v148 offset:1024
	ds_read_b128 v[206:209], v148 offset:2048
	ds_read_b128 v[224:227], v148 offset:3072
	global_load_lds_dwordx4 v130, s[50:51]
	s_add_i32 m0, s33, 0x2000
	s_nop 0
	global_load_lds_dwordx4 v134, s[50:51]
	s_barrier
	s_waitcnt lgkmcnt(0)
	s_setprio 1
	v_mfma_f32_16x16x32_bf16 v[116:119], v[198:201], v[166:169], v[116:119]
	v_mfma_f32_16x16x32_bf16 v[108:111], v[206:209], v[166:169], v[108:111]
	v_mfma_f32_16x16x32_bf16 v[100:103], v[198:201], v[174:177], v[100:103]
	v_mfma_f32_16x16x32_bf16 v[92:95], v[206:209], v[174:177], v[92:95]
	v_mfma_f32_16x16x32_bf16 v[84:87], v[198:201], v[182:185], v[84:87]
	v_mfma_f32_16x16x32_bf16 v[76:79], v[206:209], v[182:185], v[76:79]
	v_mfma_f32_16x16x32_bf16 v[68:71], v[198:201], v[190:193], v[68:71]
	v_mfma_f32_16x16x32_bf16 v[64:67], v[206:209], v[190:193], v[64:67]
	v_mfma_f32_16x16x32_bf16 v[116:119], v[202:205], v[170:173], v[116:119]
	v_mfma_f32_16x16x32_bf16 v[108:111], v[224:227], v[170:173], v[108:111]
	v_mfma_f32_16x16x32_bf16 v[100:103], v[202:205], v[178:181], v[100:103]
	v_mfma_f32_16x16x32_bf16 v[92:95], v[224:227], v[178:181], v[92:95]
	v_mfma_f32_16x16x32_bf16 v[84:87], v[202:205], v[186:189], v[84:87]
	v_mfma_f32_16x16x32_bf16 v[76:79], v[224:227], v[186:189], v[76:79]
	v_mfma_f32_16x16x32_bf16 v[68:71], v[202:205], v[194:197], v[68:71]
	v_mfma_f32_16x16x32_bf16 v[64:67], v[224:227], v[194:197], v[64:67]
	s_setprio 0
	s_mov_b32 m0, s20
	s_add_u32 s100, s52, s4
	s_addc_u32 s101, s53, s5
	s_barrier
	ds_read_b128 v[166:169], v147 offset:16384
	ds_read_b128 v[170:173], v147 offset:17408
	ds_read_b128 v[174:177], v147 offset:18432
	ds_read_b128 v[178:181], v147 offset:19456
	ds_read_b128 v[182:185], v147 offset:20480
	ds_read_b128 v[186:189], v147 offset:21504
	ds_read_b128 v[190:193], v147 offset:22528
	ds_read_b128 v[194:197], v147 offset:23552
	global_load_lds_dwordx4 v128, s[52:53]
	s_mov_b32 m0, s21
	s_nop 0
	global_load_lds_dwordx4 v132, s[52:53]
	s_barrier
	s_waitcnt lgkmcnt(0)
	s_setprio 1
	v_mfma_f32_16x16x32_bf16 v[60:63], v[150:153], v[166:169], v[60:63]
	v_mfma_f32_16x16x32_bf16 v[56:59], v[158:161], v[166:169], v[56:59]
	v_mfma_f32_16x16x32_bf16 v[52:55], v[150:153], v[174:177], v[52:55]
	v_mfma_f32_16x16x32_bf16 v[44:47], v[158:161], v[174:177], v[44:47]
	v_mfma_f32_16x16x32_bf16 v[36:39], v[150:153], v[182:185], v[36:39]
	v_mfma_f32_16x16x32_bf16 v[28:31], v[158:161], v[182:185], v[28:31]
	v_mfma_f32_16x16x32_bf16 v[20:23], v[150:153], v[190:193], v[20:23]
	v_mfma_f32_16x16x32_bf16 v[12:15], v[158:161], v[190:193], v[12:15]
	v_mfma_f32_16x16x32_bf16 v[60:63], v[154:157], v[170:173], v[60:63]
	v_mfma_f32_16x16x32_bf16 v[56:59], v[162:165], v[170:173], v[56:59]
	v_mfma_f32_16x16x32_bf16 v[52:55], v[154:157], v[178:181], v[52:55]
	v_mfma_f32_16x16x32_bf16 v[44:47], v[162:165], v[178:181], v[44:47]
	v_mfma_f32_16x16x32_bf16 v[36:39], v[154:157], v[186:189], v[36:39]
	v_mfma_f32_16x16x32_bf16 v[28:31], v[162:165], v[186:189], v[28:31]
	v_mfma_f32_16x16x32_bf16 v[20:23], v[154:157], v[194:197], v[20:23]
	v_mfma_f32_16x16x32_bf16 v[12:15], v[162:165], v[194:197], v[12:15]
	s_setprio 0
	s_barrier
	s_add_u32 s46, s50, 0x180000
	s_addc_u32 s47, s51, 0
	s_add_i32 s33, s89, s17
	s_mov_b32 m0, s33
	s_nop 0
	global_load_lds_dwordx4 v130, s[46:47]
	s_add_i32 m0, s33, 0x2000
	s_nop 0
	global_load_lds_dwordx4 v134, s[46:47]
	s_waitcnt vmcnt(6)
	s_barrier
; #define PG8_STAGE(bufoff, gbase, voff) do { _Pragma("unroll") for (int _i = 0; _i < 2; ++_i) \
;         __builtin_amdgcn_global_load_lds((const unsigned*)((const char*)(gbase) + (voff)[_i]), (LAS unsigned*)(lds + (bufoff) + ldsw + _i * 8192), 16, 0, 0); } while (0)
; #define PG8_LDA(dst, b, h) do { _Pragma("unroll") for (int m = 0; m < 4; ++m) _Pragma("unroll") for (int k = 0; k < 2; ++k) dst[m][k] = *(const LAS bf16x8*)(lds + PG8_SA(b, h) + aoff + m * 2048 + k * 1024); } while (0)
; #define PG8_LDB(dst, b, h) do { _Pragma("unroll") for (int n = 0; n < 2; ++n) _Pragma("unroll") for (int k = 0; k < 2; ++k) dst[n][k] = *(const LAS bf16x8*)(lds + PG8_SB(b, h) + boff + n * 2048 + k * 1024); } while (0)
; #define PG8_MMA(ai, bj, At, Bt) do { __builtin_amdgcn_s_setprio(1); _Pragma("unroll") for (int m = 0; m < 4; ++m) _Pragma("unroll") for (int n = 0; n < 2; ++n) _Pragma("unroll") for (int k = 0; k < 2; ++k) \
;         acc[ai][bj][m][n] = __builtin_amdgcn_mfma_f32_16x16x32_bf16(Bt[n][k], At[m][k], acc[ai][bj][m][n], 0, 0, 0); __builtin_amdgcn_s_setprio(0); } while (0)
; #define PG8_WAIT_V(n) asm volatile("s_waitcnt vmcnt(" #n ")" ::: "memory")
; #define PG8_WAIT_L(n) asm volatile("s_waitcnt lgkmcnt(" #n ")" ::: "memory")
; #define PG8_BAR __builtin_amdgcn_s_barrier()
; #define PG8_SCHED __builtin_amdgcn_sched_barrier(0)
; template <class Epi, class S_t>
; __device__ __forceinline__ void gemm_phase(LAS unsigned char* lds, int lda, int ldb, const S_t& S, const Epi& E) {
;     ...
;             PG8_WAIT_V(6); PG8_BAR; PG8_MMA(1, 1, At, B1); PG8_BAR;
;             PG8_LDB(B0, 1, 0); PG8_SCHED; PG8_LDA(At, 1, 0); PG8_STAGE(PG8_SA(0, 1), a2 + hstepA, voffA);
;             PG8_WAIT_L(8); PG8_BAR; PG8_WAIT_L(0); PG8_MMA(0, 0, At, B0); PG8_BAR; PG8_SCHED;
;             PG8_LDB(B1, 1, 1); PG8_STAGE(PG8_SB(1, 0), b3, voffB);
;             PG8_BAR; PG8_WAIT_L(0); PG8_MMA(0, 1, At, B1); PG8_BAR;
;             PG8_LDA(At, 1, 1); PG8_STAGE(PG8_SA(1, 0), a3, voffA);
;             PG8_BAR; PG8_WAIT_L(0); PG8_MMA(1, 0, At, B0); PG8_BAR; PG8_SCHED;
	s_setprio 1
	v_mfma_f32_16x16x32_bf16 v[48:51], v[198:201], v[166:169], v[48:51]
	v_mfma_f32_16x16x32_bf16 v[40:43], v[206:209], v[166:169], v[40:43]
	v_mfma_f32_16x16x32_bf16 v[32:35], v[198:201], v[174:177], v[32:35]
	v_mfma_f32_16x16x32_bf16 v[24:27], v[206:209], v[174:177], v[24:27]
	v_mfma_f32_16x16x32_bf16 v[16:19], v[198:201], v[182:185], v[16:19]
	v_mfma_f32_16x16x32_bf16 v[8:11], v[206:209], v[182:185], v[8:11]
	v_mfma_f32_16x16x32_bf16 v[4:7], v[198:201], v[190:193], v[4:7]
	v_mfma_f32_16x16x32_bf16 v[0:3], v[206:209], v[190:193], v[0:3]
	v_mfma_f32_16x16x32_bf16 v[48:51], v[202:205], v[170:173], v[48:51]
	v_mfma_f32_16x16x32_bf16 v[40:43], v[224:227], v[170:173], v[40:43]
	v_mfma_f32_16x16x32_bf16 v[32:35], v[202:205], v[178:181], v[32:35]
	v_mfma_f32_16x16x32_bf16 v[24:27], v[224:227], v[178:181], v[24:27]
	v_mfma_f32_16x16x32_bf16 v[16:19], v[202:205], v[186:189], v[16:19]
	v_mfma_f32_16x16x32_bf16 v[8:11], v[224:227], v[186:189], v[8:11]
	v_mfma_f32_16x16x32_bf16 v[4:7], v[202:205], v[194:197], v[4:7]
	v_mfma_f32_16x16x32_bf16 v[0:3], v[224:227], v[194:197], v[0:3]
	s_setprio 0
	v_add_u32_e32 v149, s90, v143
	s_barrier
	ds_read_b128 v[150:153], v149
	ds_read_b128 v[154:157], v149 offset:1024
	ds_read_b128 v[158:161], v149 offset:2048
	ds_read_b128 v[162:165], v149 offset:3072
	s_add_u32 s46, s52, 0x180000
	s_addc_u32 s47, s53, 0
	s_mov_b32 m0, s35
	ds_read_b128 v[166:169], v147 offset:32768
	ds_read_b128 v[170:173], v147 offset:33792
	ds_read_b128 v[174:177], v147 offset:34816
	ds_read_b128 v[178:181], v147 offset:35840
	ds_read_b128 v[182:185], v147 offset:36864
	ds_read_b128 v[186:189], v147 offset:37888
	ds_read_b128 v[190:193], v147 offset:38912
	ds_read_b128 v[194:197], v147 offset:39936
	global_load_lds_dwordx4 v128, s[46:47]
	s_mov_b32 m0, s54
	s_nop 0
	global_load_lds_dwordx4 v132, s[46:47]
	s_waitcnt lgkmcnt(8)
	s_barrier
	s_waitcnt lgkmcnt(0)
	s_setprio 1
	v_mfma_f32_16x16x32_bf16 v[124:127], v[150:153], v[166:169], v[124:127]
	v_mfma_f32_16x16x32_bf16 v[120:123], v[158:161], v[166:169], v[120:123]
	v_mfma_f32_16x16x32_bf16 v[112:115], v[150:153], v[174:177], v[112:115]
	v_mfma_f32_16x16x32_bf16 v[104:107], v[158:161], v[174:177], v[104:107]
	v_mfma_f32_16x16x32_bf16 v[96:99], v[150:153], v[182:185], v[96:99]
	v_mfma_f32_16x16x32_bf16 v[88:91], v[158:161], v[182:185], v[88:91]
	v_mfma_f32_16x16x32_bf16 v[80:83], v[150:153], v[190:193], v[80:83]
	v_mfma_f32_16x16x32_bf16 v[72:75], v[158:161], v[190:193], v[72:75]
	v_mfma_f32_16x16x32_bf16 v[124:127], v[154:157], v[170:173], v[124:127]
	v_mfma_f32_16x16x32_bf16 v[120:123], v[162:165], v[170:173], v[120:123]
	v_mfma_f32_16x16x32_bf16 v[112:115], v[154:157], v[178:181], v[112:115]
	v_mfma_f32_16x16x32_bf16 v[104:107], v[162:165], v[178:181], v[104:107]
	v_mfma_f32_16x16x32_bf16 v[96:99], v[154:157], v[186:189], v[96:99]
	v_mfma_f32_16x16x32_bf16 v[88:91], v[162:165], v[186:189], v[88:91]
	v_mfma_f32_16x16x32_bf16 v[80:83], v[154:157], v[194:197], v[80:83]
	v_mfma_f32_16x16x32_bf16 v[72:75], v[162:165], v[194:197], v[72:75]
	s_setprio 0
	s_barrier
	s_add_i32 s33, s90, s17
	v_add_u32_e32 v149, s91, v143
	s_mov_b32 m0, s33
	ds_read_b128 v[198:201], v149
	ds_read_b128 v[202:205], v149 offset:1024
	ds_read_b128 v[206:209], v149 offset:2048
	ds_read_b128 v[224:227], v149 offset:3072
	global_load_lds_dwordx4 v130, s[98:99]
	s_add_i32 m0, s33, 0x2000
	s_nop 0
	global_load_lds_dwordx4 v134, s[98:99]
	s_barrier
	s_waitcnt lgkmcnt(0)
	s_setprio 1
	v_mfma_f32_16x16x32_bf16 v[116:119], v[198:201], v[166:169], v[116:119]
	v_mfma_f32_16x16x32_bf16 v[108:111], v[206:209], v[166:169], v[108:111]
	v_mfma_f32_16x16x32_bf16 v[100:103], v[198:201], v[174:177], v[100:103]
	v_mfma_f32_16x16x32_bf16 v[92:95], v[206:209], v[174:177], v[92:95]
	v_mfma_f32_16x16x32_bf16 v[84:87], v[198:201], v[182:185], v[84:87]
	v_mfma_f32_16x16x32_bf16 v[76:79], v[206:209], v[182:185], v[76:79]
	v_mfma_f32_16x16x32_bf16 v[68:71], v[198:201], v[190:193], v[68:71]
	v_mfma_f32_16x16x32_bf16 v[64:67], v[206:209], v[190:193], v[64:67]
	v_mfma_f32_16x16x32_bf16 v[116:119], v[202:205], v[170:173], v[116:119]
	v_mfma_f32_16x16x32_bf16 v[108:111], v[224:227], v[170:173], v[108:111]
	v_mfma_f32_16x16x32_bf16 v[100:103], v[202:205], v[178:181], v[100:103]
	v_mfma_f32_16x16x32_bf16 v[92:95], v[224:227], v[178:181], v[92:95]
	v_mfma_f32_16x16x32_bf16 v[84:87], v[202:205], v[186:189], v[84:87]
	v_mfma_f32_16x16x32_bf16 v[76:79], v[224:227], v[186:189], v[76:79]
	v_mfma_f32_16x16x32_bf16 v[68:71], v[202:205], v[194:197], v[68:71]
	v_mfma_f32_16x16x32_bf16 v[64:67], v[224:227], v[194:197], v[64:67]
	s_setprio 0
	s_mov_b32 m0, s55
	s_barrier
	ds_read_b128 v[166:169], v147 offset:49152
	ds_read_b128 v[170:173], v147 offset:50176
	ds_read_b128 v[174:177], v147 offset:51200
	ds_read_b128 v[178:181], v147 offset:52224
	ds_read_b128 v[182:185], v147 offset:53248
	ds_read_b128 v[186:189], v147 offset:54272
	ds_read_b128 v[190:193], v147 offset:55296
	ds_read_b128 v[194:197], v147 offset:56320
	global_load_lds_dwordx4 v128, s[100:101]
	s_mov_b32 m0, s56
	s_nop 0
	global_load_lds_dwordx4 v132, s[100:101]
	s_barrier
; #define PG8_STAGE(bufoff, gbase, voff) do { _Pragma("unroll") for (int _i = 0; _i < 2; ++_i) \
;         __builtin_amdgcn_global_load_lds((const unsigned*)((const char*)(gbase) + (voff)[_i]), (LAS unsigned*)(lds + (bufoff) + ldsw + _i * 8192), 16, 0, 0); } while (0)
; #define PG8_MMA(ai, bj, At, Bt) do { __builtin_amdgcn_s_setprio(1); _Pragma("unroll") for (int m = 0; m < 4; ++m) _Pragma("unroll") for (int n = 0; n < 2; ++n) _Pragma("unroll") for (int k = 0; k < 2; ++k) \
;         acc[ai][bj][m][n] = __builtin_amdgcn_mfma_f32_16x16x32_bf16(Bt[n][k], At[m][k], acc[ai][bj][m][n], 0, 0, 0); __builtin_amdgcn_s_setprio(0); } while (0)
; #define PG8_WAIT_V(n) asm volatile("s_waitcnt vmcnt(" #n ")" ::: "memory")
; #define PG8_WAIT_L(n) asm volatile("s_waitcnt lgkmcnt(" #n ")" ::: "memory")
; #define PG8_BAR __builtin_amdgcn_s_barrier()
; #define PG8_SCHED __builtin_amdgcn_sched_barrier(0)
; template <class Epi, class S_t>
; __device__ __forceinline__ void gemm_phase(LAS unsigned char* lds, int lda, int ldb, const S_t& S, const Epi& E) {
;     ...
;             PG8_BAR; PG8_WAIT_L(0); PG8_MMA(1, 0, At, B0); PG8_BAR; PG8_SCHED;
;             PG8_STAGE(PG8_SB(1, 1), b3 + hstepB, voffB);
;             PG8_WAIT_V(6); PG8_BAR; PG8_MMA(1, 1, At, B1); PG8_BAR;
;         }
;         E(acc, cur, wr, wc, fr, fq);
;     __device__ __forceinline__ void operator()(const f32x4 (&acc)[2][2][4][2], const Unit& u, int wr, int wc, int fr, int fq) const {
;     ...
;             const int row0 = (u.pm - 32) * BM + wr * 64 + fr;
;             float* Op = Os + (size_t)(u.tag - 1) * (1024ull * DM);
; #pragma unroll
;             for (int ai = 0; ai < 2; ++ai)
; #pragma unroll
;                 for (int m = 0; m < 4; ++m) { float* rowp = Op + (size_t)(row0 + ai * HALF + m * 16) * DM + col0;
; #pragma unroll
;                     for (int bj = 0; bj < 2; ++bj)
; #pragma unroll
;                         for (int n = 0; n < 2; ++n) *(f32x4*)(rowp + bj * HALF + 4 * n) = acc[ai][bj][m][n]; }
	s_waitcnt lgkmcnt(0)
	s_setprio 1
	v_mfma_f32_16x16x32_bf16 v[60:63], v[150:153], v[166:169], v[60:63]
	v_mfma_f32_16x16x32_bf16 v[56:59], v[158:161], v[166:169], v[56:59]
	v_mfma_f32_16x16x32_bf16 v[52:55], v[150:153], v[174:177], v[52:55]
	v_mfma_f32_16x16x32_bf16 v[44:47], v[158:161], v[174:177], v[44:47]
	v_mfma_f32_16x16x32_bf16 v[36:39], v[150:153], v[182:185], v[36:39]
	v_mfma_f32_16x16x32_bf16 v[28:31], v[158:161], v[182:185], v[28:31]
	v_mfma_f32_16x16x32_bf16 v[20:23], v[150:153], v[190:193], v[20:23]
	v_mfma_f32_16x16x32_bf16 v[12:15], v[158:161], v[190:193], v[12:15]
	v_mfma_f32_16x16x32_bf16 v[60:63], v[154:157], v[170:173], v[60:63]
	v_mfma_f32_16x16x32_bf16 v[56:59], v[162:165], v[170:173], v[56:59]
	v_mfma_f32_16x16x32_bf16 v[52:55], v[154:157], v[178:181], v[52:55]
	v_mfma_f32_16x16x32_bf16 v[44:47], v[162:165], v[178:181], v[44:47]
	v_mfma_f32_16x16x32_bf16 v[36:39], v[154:157], v[186:189], v[36:39]
	v_mfma_f32_16x16x32_bf16 v[28:31], v[162:165], v[186:189], v[28:31]
	v_mfma_f32_16x16x32_bf16 v[20:23], v[154:157], v[194:197], v[20:23]
	v_mfma_f32_16x16x32_bf16 v[12:15], v[162:165], v[194:197], v[12:15]
	s_setprio 0
	s_barrier
	s_add_u32 s46, s50, 0x180080
	s_addc_u32 s47, s51, 0
	s_add_i32 s33, s91, s17
	s_mov_b32 m0, s33
	s_nop 0
	global_load_lds_dwordx4 v130, s[46:47]
	s_add_i32 m0, s33, 0x2000
	s_nop 0
	global_load_lds_dwordx4 v134, s[46:47]
	s_waitcnt vmcnt(6)
	s_barrier
	s_setprio 1
	v_mfma_f32_16x16x32_bf16 v[48:51], v[198:201], v[166:169], v[48:51]
	v_mfma_f32_16x16x32_bf16 v[40:43], v[206:209], v[166:169], v[40:43]
	v_mfma_f32_16x16x32_bf16 v[32:35], v[198:201], v[174:177], v[32:35]
	v_mfma_f32_16x16x32_bf16 v[24:27], v[206:209], v[174:177], v[24:27]
	v_mfma_f32_16x16x32_bf16 v[16:19], v[198:201], v[182:185], v[16:19]
	v_mfma_f32_16x16x32_bf16 v[8:11], v[206:209], v[182:185], v[8:11]
	v_mfma_f32_16x16x32_bf16 v[4:7], v[198:201], v[190:193], v[4:7]
	v_mfma_f32_16x16x32_bf16 v[0:3], v[206:209], v[190:193], v[0:3]
	v_mfma_f32_16x16x32_bf16 v[48:51], v[202:205], v[170:173], v[48:51]
	v_mfma_f32_16x16x32_bf16 v[40:43], v[224:227], v[170:173], v[40:43]
	v_mfma_f32_16x16x32_bf16 v[32:35], v[202:205], v[178:181], v[32:35]
	v_mfma_f32_16x16x32_bf16 v[24:27], v[224:227], v[178:181], v[24:27]
	v_mfma_f32_16x16x32_bf16 v[16:19], v[202:205], v[186:189], v[16:19]
	v_mfma_f32_16x16x32_bf16 v[8:11], v[224:227], v[186:189], v[8:11]
	v_mfma_f32_16x16x32_bf16 v[4:7], v[202:205], v[194:197], v[4:7]
	v_mfma_f32_16x16x32_bf16 v[0:3], v[224:227], v[194:197], v[0:3]
	s_setprio 0
	s_add_u32 s1, s1, 0x100
	s_addc_u32 s70, s70, 0
	s_cmp_ge_u32 s71, s69
	s_mov_b64 s[46:47], s[48:49]
	s_mov_b32 s50, s71
	s_barrier
	s_cbranch_scc0 .LBB0_1383
	v_lshl_or_b32 v140, s68, 8, v145
	s_lshl_b32 s33, s67, 8
	s_cmp_lg_u32 s2, 0
	v_ashrrev_i32_e32 v141, 31, v140
	s_cbranch_scc0 .LBB0_1386
	s_add_i32 s2, s2, -1
	s_lshl_b64 s[0:1], s[2:3], 23
	v_add_u32_e32 v150, s33, v144
	s_add_u32 s0, s6, s0
	v_or_b32_e32 v156, 16, v150
	s_addc_u32 s1, s7, s1
	v_ashrrev_i32_e32 v151, 31, v150
	v_ashrrev_i32_e32 v157, 31, v156
	v_lshl_add_u64 v[152:153], v[140:141], 2, s[0:1]
	v_lshlrev_b64 v[154:155], 13, v[150:151]
	v_lshlrev_b64 v[156:157], 13, v[156:157]
	v_lshl_add_u64 v[154:155], v[152:153], 0, v[154:155]
	v_lshl_add_u64 v[156:157], v[152:153], 0, v[156:157]
	global_store_dwordx4 v[154:155], v[124:127], off
	global_store_dwordx4 v[154:155], v[120:123], off offset:16
	global_store_dwordx4 v[154:155], v[116:119], off offset:512
	global_store_dwordx4 v[154:155], v[108:111], off offset:528
	global_store_dwordx4 v[156:157], v[112:115], off
	global_store_dwordx4 v[156:157], v[104:107], off offset:16
	global_store_dwordx4 v[156:157], v[100:103], off offset:512
	global_store_dwordx4 v[156:157], v[92:95], off offset:528
	v_or_b32_e32 v156, 32, v150
	v_or_b32_e32 v150, 48, v150
	v_ashrrev_i32_e32 v157, 31, v156
	v_ashrrev_i32_e32 v151, 31, v150
	v_lshlrev_b64 v[156:157], 13, v[156:157]
	v_lshlrev_b64 v[150:151], 13, v[150:151]
	v_lshl_add_u64 v[156:157], v[152:153], 0, v[156:157]
	v_lshl_add_u64 v[150:151], v[152:153], 0, v[150:151]
	v_add_co_u32_e32 v152, vcc, s60, v154
	global_store_dwordx4 v[156:157], v[96:99], off
	global_store_dwordx4 v[156:157], v[88:91], off offset:16
	global_store_dwordx4 v[156:157], v[84:87], off offset:512
	global_store_dwordx4 v[156:157], v[76:79], off offset:528
	v_addc_co_u32_e32 v153, vcc, 0, v155, vcc
	global_store_dwordx4 v[150:151], v[80:83], off
	global_store_dwordx4 v[150:151], v[72:75], off offset:16
	global_store_dwordx4 v[150:151], v[68:71], off offset:512
	global_store_dwordx4 v[150:151], v[64:67], off offset:528
	v_lshl_add_u64 v[150:151], v[154:155], 0, s[12:13]
	global_store_dwordx4 v[152:153], v[60:63], off
	global_store_dwordx4 v[150:151], v[56:59], off offset:16
	global_store_dwordx4 v[150:151], v[48:51], off offset:512
	global_store_dwordx4 v[150:151], v[40:43], off offset:528
	v_add_co_u32_e32 v152, vcc, s61, v154
	v_lshl_add_u64 v[150:151], v[154:155], 0, s[14:15]
	s_nop 0
	v_addc_co_u32_e32 v153, vcc, 0, v155, vcc
	global_store_dwordx4 v[152:153], v[52:55], off
	global_store_dwordx4 v[150:151], v[44:47], off offset:16
	global_store_dwordx4 v[150:151], v[32:35], off offset:512
	global_store_dwordx4 v[150:151], v[24:27], off offset:528
	v_add_co_u32_e32 v152, vcc, s62, v154
	v_lshl_add_u64 v[150:151], v[154:155], 0, s[18:19]
	s_nop 0
	v_addc_co_u32_e32 v153, vcc, 0, v155, vcc
	global_store_dwordx4 v[152:153], v[36:39], off
	global_store_dwordx4 v[150:151], v[28:31], off offset:16
	global_store_dwordx4 v[150:151], v[16:19], off offset:512
	global_store_dwordx4 v[150:151], v[8:11], off offset:528
	v_add_co_u32_e32 v152, vcc, 0x160000, v154
	v_lshl_add_u64 v[150:151], v[154:155], 0, s[22:23]
	s_nop 0
	v_addc_co_u32_e32 v153, vcc, 0, v155, vcc
	global_store_dwordx4 v[152:153], v[20:23], off
	global_store_dwordx4 v[150:151], v[12:15], off offset:16
	global_store_dwordx4 v[150:151], v[4:7], off offset:512
	global_store_dwordx4 v[150:151], v[0:3], off offset:528
	s_cbranch_execnz .LBB0_1379
	s_branch .LBB0_1378
